# A+Q+P with second first-iteration vmcnt wait dropped too (GEMM prologue retires all its stage loads)
# baseline (speedup 1.0000x reference)
;     __device__ bool next(int i, Unit& u) const { if (i != 0 || c >= 128) return false; const int t = c >> 2; u.pm = t & 3; u.pn = t >> 2; u.koff = koff_bytes; u.q = c & 3; return true; }
; #define PG8_BAR __builtin_amdgcn_s_barrier()
; template <class Epi, class Sched, bool ALIGN_EPI = false, bool SP2 = false>
; __device__ __forceinline__ void gemm_phase(LAS unsigned char* lds, const Gemm g, const Sched& S, const Epi& E) {
;     int tid = threadIdx.x; asm volatile("" : "+v"(tid));
;     const int wid = __builtin_amdgcn_readfirstlane(tid >> 6), lane = tid & 63, wr = wid >> 2, wc = wid & 3, fr = lane & 15, fq = lane >> 4;
;     const int K = g.ld, nt = g.K / BK;
;     unsigned voffA[2], voffB[2];
; #pragma unroll
;     for (int i = 0; i < 2; ++i) { int R, C; stage_rc(tid * 16 + i * 8192, R, C); const int Rb = (Epi::BCONT ? ((R >> 5) * 64) : (R & ~31)) + (Epi::PERM ? perm32(R & 31) : (R & 31));
;         voffA[i] = (unsigned)(R * K + C) * 2u; voffB[i] = (unsigned)(Rb * K + C) * 2u; }
;     const size_t kstep = (size_t)(BK * 2);
;     const size_t hstep = (size_t)HALF * K * 2;
;     const size_t hstepB = Epi::BCONT ? (size_t)32 * K * 2 : hstep;
;     const size_t tstep = 2 * hstep;
;     const unsigned ldsw = (unsigned)wid * 1024u;
;     const int aoff = lds_byte(wr * 64 + fr, fq * 8), boff = lds_byte(wc * 32 + fr, fq * 8);
;     ...
;     Unit cur, nxt; int ui = 0;
;     if (!S.next(0, cur)) return;
;     f32x4 acc[2][2][4][2];
; #pragma unroll
;     for (int a = 0; a < 2; ++a)
; #pragma unroll
;         for (int b = 0; b < 2; ++b)
; #pragma unroll
;             for (int m = 0; m < 4; ++m)
; #pragma unroll
;                 for (int n = 0; n < 2; ++n) acc[a][b][m][n] = (f32x4){0.f, 0.f, 0.f, 0.f};
;     bf16x8 At[4][2], B0[2][2], B1[2][2];
;     const char* cA = (const char*)g.A + (size_t)cur.pm * tstep + cur.koff; const char* cB = (const char*)g.Bt + (size_t)cur.pn * tstep + cur.koff;
;     S.a_ready(cur);
;     if constexpr (SP2) {
;         PG8_STAGE(PG8_SB(0, 0), cB, voffB); PG8_STAGE(PG8_SB(0, 1), cB + hstepB, voffB); PG8_STAGE(PG8_SA(0, 0), cA, voffA); PG8_STAGE(PG8_SA(0, 1), cA + hstep, voffA);
;         if (wr == 1) PG8_BAR;
;         PG8_WAIT_V(2); PG8_BAR;
;         PG8_STAGE(PG8_SB(1, 0), cB + kstep, voffB); PG8_STAGE(PG8_SA(1, 0), cA + kstep, voffA); PG8_STAGE(PG8_SB(1, 1), cB + hstepB + kstep, voffB);
;         PG8_WAIT_V(6); PG8_BAR;
.LBB0_182:
	s_lshl_b32 s0, s0, 5
	s_lshl_b32 s54, s8, 6
	s_lshl_b32 s3, s8, 13
	s_and_b32 s13, s0, 0x60
	v_readlane_b32 s8, v253, 38
	s_lshl_b32 s18, s13, 7
	v_readlane_b32 s10, v253, 40
	v_readlane_b32 s11, v253, 41
	v_readlane_b32 s9, v253, 39
	s_add_u32 s8, s8, 0x100000
	s_mov_b64 s[10:11], 0x80
	s_addc_u32 s9, s9, 0
	s_add_i32 m0, s33, 0x18000
	v_lshl_add_u64 v[8:9], v[8:9], 0, s[10:11]
	s_waitcnt vmcnt(2)
	s_barrier
	global_load_lds_dwordx4 v[8:9], off
	v_lshl_add_u64 v[6:7], v[6:7], 0, s[10:11]
	s_add_i32 m0, s33, 0x1a000
	s_add_i32 s55, s33, 0x8000
	s_add_i32 s56, s33, 0xa000
	global_load_lds_dwordx4 v[6:7], off
	v_lshl_add_u64 v[2:3], v[2:3], 0, s[10:11]
	s_mov_b32 m0, s55
	s_add_u32 s14, s50, 0x80080
	global_load_lds_dwordx4 v[2:3], off
	v_lshl_add_u64 v[2:3], v[4:5], 0, s[10:11]
	s_mov_b32 m0, s56
	s_addc_u32 s15, s51, 0
	global_load_lds_dwordx4 v[2:3], off
	s_add_i32 m0, s33, 0x1c000
	v_lshl_add_u64 v[2:3], s[14:15], 0, v[150:151]
	global_load_lds_dwordx4 v[2:3], off
	v_lshl_add_u64 v[2:3], s[14:15], 0, v[146:147]
	s_add_i32 m0, s33, 0x1e000
	v_and_b32_e32 v169, 15, v10
	global_load_lds_dwordx4 v[2:3], off
	v_bfe_u32 v3, v10, 4, 2
	v_lshlrev_b32_e32 v2, 3, v3
	v_lshlrev_b32_e32 v3, 4, v3
	v_lshlrev_b32_e32 v4, 2, v10
	v_lshl_or_b32 v3, v169, 6, v3
	v_and_b32_e32 v4, 32, v4
	v_bitop3_b32 v5, v3, s3, v4 bitop3:0xde
	v_bitop3_b32 v170, v3, s18, v4 bitop3:0xde
	v_lshlrev_b32_e32 v3, 15, v15
	v_and_b32_e32 v3, 0xffff0000, v3
	v_lshl_add_u32 v3, v14, 12, v3
	v_and_b32_e32 v4, 1, v15
	v_lshl_or_b32 v3, v4, 6, v3
	v_lshl_add_u32 v154, v16, 1, v3
	v_lshlrev_b32_e32 v3, 15, v11
	v_or_b32_e32 v173, s13, v2
	v_and_b32_e32 v3, 0xffff0000, v3
	v_lshlrev_b32_e32 v177, 2, v2
	v_mbcnt_lo_u32_b32 v2, -1, 0
	s_waitcnt vmcnt(0)
	s_cmpk_lt_u32 s12, 0x100
	v_lshl_add_u32 v3, v12, 12, v3
	v_and_b32_e32 v4, 1, v11
	v_mbcnt_hi_u32_b32 v2, -1, v2
	s_cselect_b64 s[40:41], -1, 0
	v_and_b32_e32 v171, 63, v10
	v_lshl_or_b32 v3, v4, 6, v3
	s_add_i32 s57, 0, 0x10000
	s_add_i32 s58, 0, 0x14000
	v_and_or_b32 v2, v2, 64, v169
	s_sext_i32_i16 s0, s38
	v_or_b32_e32 v172, 0x80, v171
	v_mov_b32_e32 v155, v151
	v_lshl_add_u32 v156, v13, 1, v3
	v_mov_b32_e32 v157, v151
	v_mov_b64_e32 v[158:159], 0x16b0
	v_mov_b64_e32 v[160:161], 0x16af
	v_add_u32_e32 v174, s57, v170
	v_add_u32_e32 v175, s58, v170
	v_add_u32_e32 v176, 0, v5
	s_movk_i32 s59, 0x2c00
	s_lshl_b32 s60, s13, 2
	v_mov_b32_e32 v178, 0x358637bd
	s_mov_b32 s61, 0xf800000
	v_mov_b32_e32 v179, 0x260
	v_lshlrev_b32_e32 v180, 2, v2
	s_barrier
	s_branch .LBB0_185

; __device__ __forceinline__ float row_rstd(const float* ss, int row) { return 1.0f / sqrtf(ss[row] * (1.0f / DM) + 1e-6f); }
;     __device__ bool next(int i, Unit& u) const { if (i != 0 || c >= 128) return false; const int t = c >> 2; u.pm = t & 3; u.pn = t >> 2; u.koff = koff_bytes; u.q = c & 3; return true; }
; #define PG8_WAIT_V(n) asm volatile("s_waitcnt vmcnt(" #n ")" ::: "memory")
;     __device__ __forceinline__ void operator()(const f32x4 (&acc)[2][2][4][2], const Unit& u, int wr, int wc, int fr, int fq) const {
;     ...
;         const int s = (u.pm < ML / BM) ? (u.pm >> 5) : 4;
;         const float* bp = bias + (size_t)s * BIAS_N + u.pn * BM + wc * 32 + 8 * fq;
;         const f32x4 ba0 = *(const f32x4*)bp, ba1 = *(const f32x4*)(bp + 4), bb0 = *(const f32x4*)(bp + HALF), bb1 = *(const f32x4*)(bp + HALF + 4);
;         const int lane = fq * 16 + fr;
;         const float rsl0 = row_rstd(ss, u.pm * BM + wr * 64 + lane), rsl1 = row_rstd(ss, u.pm * BM + HALF + wr * 64 + lane);
; template <class Epi, class Sched, bool ALIGN_EPI = false, bool SP2 = false>
; __device__ __forceinline__ void gemm_phase(LAS unsigned char* lds, const Gemm g, const Sched& S, const Epi& E) {
;     ...
;         const bool has_next = S.next(ui + 1, nxt);
;         const char* nA = has_next ? (const char*)g.A + (size_t)nxt.pm * tstep + nxt.koff : cA; const char* nB = has_next ? (const char*)g.Bt + (size_t)nxt.pn * tstep + nxt.koff : cB;
;         for (int t = 0; t < nt; t += 2) {
;             const bool last = (t == nt - 2);
;             const char* a1 = cA + (size_t)(t + 1) * kstep;
;             const char* a2 = last ? nA : cA + (size_t)(t + 2) * kstep; const char* b2 = last ? nB : cB + (size_t)(t + 2) * kstep;
;             const char* a3 = a2 + kstep; const char* b3 = b2 + kstep;
;             if (last && has_next) S.a_ready(nxt);
;             if constexpr (SP2) {
;             PG8_LDB(B0, 0, 0); PG8_LDB(B1, 0, 1); PG8_SCHED; PG8_LDA(At, 0, 0); PG8_STAGE(PG8_SA(1, 1), a1 + hstep, voffA);
;             PG8_WAIT_V(8); PG8_WAIT_L(0); PG8_BAR; PG8_MMA(0, 0, At, B0); PG8_MMA(0, 1, At, B1); PG8_BAR; PG8_SCHED;
;             PG8_LDA(At, 0, 1); PG8_STAGE(PG8_SB(0, 0), b2, voffB); PG8_STAGE(PG8_SB(0, 1), b2 + hstepB, voffB); PG8_STAGE(PG8_SA(0, 0), a2, voffA);
;             PG8_WAIT_V(8); PG8_WAIT_L(0); PG8_BAR; PG8_MMA(1, 0, At, B0); PG8_MMA(1, 1, At, B1); PG8_BAR; PG8_SCHED;
.Lpre_up1l0:
	s_lshl_b64 s[98:99], s[98:99], 2
	s_add_u32 s98, s68, s98
	s_addc_u32 s99, s69, s99
	s_lshl_b32 s100, s0, 8
	s_ashr_i32 s101, s100, 31
	s_lshl_b64 s[100:101], s[100:101], 2
	s_add_u32 s98, s98, s100
	s_addc_u32 s99, s99, s101
	s_add_u32 s98, s98, s60
	s_addc_u32 s99, s99, 0
	s_lshl_b32 s100, s2, 8
	s_add_i32 s100, s100, s54
	v_or_b32_e32 v162, s100, v171
	v_ashrrev_i32_e32 v163, 31, v162
	v_lshl_add_u64 v[162:163], v[162:163], 2, s[8:9]
	v_add_u32_e32 v164, s100, v172
	v_ashrrev_i32_e32 v165, 31, v164
	v_lshl_add_u64 v[164:165], v[164:165], 2, s[8:9]
	global_load_dwordx4 v[234:237], v177, s[98:99] offset:16
	global_load_dwordx4 v[238:241], v177, s[98:99]
	global_load_dwordx4 v[242:245], v177, s[98:99] offset:528
	global_load_dwordx4 v[246:249], v177, s[98:99] offset:512
	global_load_dword v250, v[162:163], off
	global_load_dword v251, v[164:165], off
	ds_read_b128 v[66:69], v174
	ds_read_b128 v[70:73], v174 offset:1024
	ds_read_b128 v[74:77], v174 offset:2048
	ds_read_b128 v[78:81], v174 offset:3072
	ds_read_b128 v[162:165], v175
	ds_read_b128 v[182:185], v175 offset:1024
	ds_read_b128 v[186:189], v175 offset:2048
	ds_read_b128 v[190:193], v175 offset:3072
	s_add_u32 s20, s16, 0xfff80080
	s_addc_u32 s21, s17, -1
	s_cmp_eq_u32 s19, 28
	s_cselect_b32 s53, s3, s21
	s_cselect_b32 s52, s12, s20
	s_cselect_b32 s51, s13, s18
	s_cselect_b32 s50, s14, s15
	v_lshl_add_u64 v[166:167], s[16:17], 0, v[154:155]
	s_add_i32 m0, s33, 0xc000
	ds_read_b128 v[194:197], v176
	ds_read_b128 v[198:201], v176 offset:1024
	ds_read_b128 v[202:205], v176 offset:2048
	ds_read_b128 v[206:209], v176 offset:3072
	ds_read_b128 v[210:213], v176 offset:4096
	ds_read_b128 v[214:217], v176 offset:5120
	ds_read_b128 v[218:221], v176 offset:6144
	ds_read_b128 v[222:225], v176 offset:7168
	global_load_lds_dwordx4 v[166:167], off
	v_lshl_add_u64 v[166:167], s[16:17], 0, v[156:157]
	s_add_i32 m0, s33, 0xe000
	s_nop 0
	global_load_lds_dwordx4 v[166:167], off
	s_waitcnt lgkmcnt(0)
	s_barrier
	s_setprio 1
	s_waitcnt lgkmcnt(0)
	v_mfma_f32_16x16x32_bf16 v[142:145], v[66:69], v[194:197], 0
	v_mfma_f32_16x16x32_bf16 v[138:141], v[74:77], v[194:197], 0
	v_mfma_f32_16x16x32_bf16 v[126:129], v[66:69], v[202:205], 0
	v_mfma_f32_16x16x32_bf16 v[122:125], v[74:77], v[202:205], 0
	v_mfma_f32_16x16x32_bf16 v[110:113], v[66:69], v[210:213], 0
	v_mfma_f32_16x16x32_bf16 v[106:109], v[74:77], v[210:213], 0
	v_mfma_f32_16x16x32_bf16 v[94:97], v[66:69], v[218:221], 0
	v_mfma_f32_16x16x32_bf16 v[90:93], v[74:77], v[218:221], 0
	v_mfma_f32_16x16x32_bf16 v[142:145], v[70:73], v[198:201], v[142:145]
	v_mfma_f32_16x16x32_bf16 v[138:141], v[78:81], v[198:201], v[138:141]
	v_mfma_f32_16x16x32_bf16 v[126:129], v[70:73], v[206:209], v[126:129]
	v_mfma_f32_16x16x32_bf16 v[122:125], v[78:81], v[206:209], v[122:125]
	v_mfma_f32_16x16x32_bf16 v[110:113], v[70:73], v[214:217], v[110:113]
	v_mfma_f32_16x16x32_bf16 v[106:109], v[78:81], v[214:217], v[106:109]
	v_mfma_f32_16x16x32_bf16 v[94:97], v[70:73], v[222:225], v[94:97]
	v_mfma_f32_16x16x32_bf16 v[90:93], v[78:81], v[222:225], v[90:93]
	s_setprio 0
	s_setprio 1
	v_mfma_f32_16x16x32_bf16 v[134:137], v[162:165], v[194:197], 0
	v_mfma_f32_16x16x32_bf16 v[130:133], v[186:189], v[194:197], 0
	v_mfma_f32_16x16x32_bf16 v[118:121], v[162:165], v[202:205], 0
	v_mfma_f32_16x16x32_bf16 v[114:117], v[186:189], v[202:205], 0
	v_mfma_f32_16x16x32_bf16 v[102:105], v[162:165], v[210:213], 0
	v_mfma_f32_16x16x32_bf16 v[98:101], v[186:189], v[210:213], 0
	v_mfma_f32_16x16x32_bf16 v[86:89], v[162:165], v[218:221], 0
	v_mfma_f32_16x16x32_bf16 v[82:85], v[186:189], v[218:221], 0
	v_mfma_f32_16x16x32_bf16 v[134:137], v[182:185], v[198:201], v[134:137]
	v_mfma_f32_16x16x32_bf16 v[130:133], v[190:193], v[198:201], v[130:133]
	v_mfma_f32_16x16x32_bf16 v[118:121], v[182:185], v[206:209], v[118:121]
	v_mfma_f32_16x16x32_bf16 v[114:117], v[190:193], v[206:209], v[114:117]
	v_mfma_f32_16x16x32_bf16 v[102:105], v[182:185], v[214:217], v[102:105]
	v_mfma_f32_16x16x32_bf16 v[98:101], v[190:193], v[214:217], v[98:101]
	v_mfma_f32_16x16x32_bf16 v[86:89], v[182:185], v[222:225], v[86:89]
	v_mfma_f32_16x16x32_bf16 v[82:85], v[190:193], v[222:225], v[82:85]
	s_setprio 0
	s_barrier
	s_add_i32 s20, s57, s27
	v_lshl_add_u64 v[166:167], s[50:51], 0, v[150:151]
	s_mov_b32 m0, s20
	ds_read_b128 v[194:197], v176 offset:16384
	ds_read_b128 v[198:201], v176 offset:17408
	ds_read_b128 v[202:205], v176 offset:18432
	ds_read_b128 v[206:209], v176 offset:19456
	ds_read_b128 v[210:213], v176 offset:20480
	ds_read_b128 v[214:217], v176 offset:21504
	ds_read_b128 v[218:221], v176 offset:22528
	ds_read_b128 v[222:225], v176 offset:23552
	global_load_lds_dwordx4 v[166:167], off
	s_add_i32 m0, s20, 0x2000
	s_add_u32 s20, s50, 0x80000
	v_lshl_add_u64 v[226:227], s[50:51], 0, v[146:147]
	s_addc_u32 s21, s51, 0
	s_add_i32 s22, s58, s27
	global_load_lds_dwordx4 v[226:227], off
	v_lshl_add_u64 v[228:229], s[20:21], 0, v[150:151]
	s_mov_b32 m0, s22
	v_lshl_add_u64 v[230:231], s[52:53], 0, v[148:149]
	global_load_lds_dwordx4 v[228:229], off
	v_lshl_add_u64 v[228:229], s[20:21], 0, v[146:147]
	s_add_i32 m0, s22, 0x2000
	s_nop 0
	global_load_lds_dwordx4 v[228:229], off
	v_lshl_add_u64 v[228:229], s[52:53], 0, v[152:153]
	s_mov_b32 m0, s33
	s_nop 0
	global_load_lds_dwordx4 v[228:229], off
	s_mov_b32 m0, s34
	s_nop 0
	global_load_lds_dwordx4 v[230:231], off
	s_waitcnt lgkmcnt(0)
	s_barrier
; #define PG8_STAGE(bufoff, gbase, voff) do { _Pragma("unroll") for (int _i = 0; _i < 2; ++_i) \
;         __builtin_amdgcn_global_load_lds((const unsigned*)((const char*)(gbase) + (voff)[_i]), (LAS unsigned*)(lds + (bufoff) + ldsw + _i * 8192), 16, 0, 0); } while (0)
; #define PG8_LDA(dst, b, h) do { _Pragma("unroll") for (int m = 0; m < 4; ++m) _Pragma("unroll") for (int k = 0; k < 2; ++k) dst[m][k] = *(const LAS bf16x8*)(lds + PG8_SA(b, h) + aoff + m * 2048 + k * 1024); } while (0)
; #define PG8_LDB(dst, b, h) do { _Pragma("unroll") for (int n = 0; n < 2; ++n) _Pragma("unroll") for (int k = 0; k < 2; ++k) dst[n][k] = *(const LAS bf16x8*)(lds + PG8_SB(b, h) + boff + n * 2048 + k * 1024); } while (0)
; #define PG8_MMA(ai, bj, At, Bt) do { __builtin_amdgcn_s_setprio(1); _Pragma("unroll") for (int m = 0; m < 4; ++m) _Pragma("unroll") for (int n = 0; n < 2; ++n) _Pragma("unroll") for (int k = 0; k < 2; ++k) \
;         acc[ai][bj][m][n] = __builtin_amdgcn_mfma_f32_16x16x32_bf16(Bt[n][k], At[m][k], acc[ai][bj][m][n], 0, 0, 0); __builtin_amdgcn_s_setprio(0); } while (0)
; #define PG8_WAIT_V(n) asm volatile("s_waitcnt vmcnt(" #n ")" ::: "memory")
; #define PG8_WAIT_L(n) asm volatile("s_waitcnt lgkmcnt(" #n ")" ::: "memory")
; #define PG8_BAR __builtin_amdgcn_s_barrier()
; #define PG8_SCHED __builtin_amdgcn_sched_barrier(0)
; template <class Epi, class Sched, bool ALIGN_EPI = false, bool SP2 = false>
; __device__ __forceinline__ void gemm_phase(LAS unsigned char* lds, const Gemm g, const Sched& S, const Epi& E) {
;     ...
;             PG8_WAIT_V(8); PG8_WAIT_L(0); PG8_BAR; PG8_MMA(1, 0, At, B0); PG8_MMA(1, 1, At, B1); PG8_BAR; PG8_SCHED;
;             PG8_LDB(B0, 1, 0); PG8_LDB(B1, 1, 1); PG8_SCHED; PG8_LDA(At, 1, 0); PG8_STAGE(PG8_SA(0, 1), a2 + hstep, voffA);
;             PG8_WAIT_V(8); PG8_WAIT_L(0); PG8_BAR; PG8_MMA(0, 0, At, B0); PG8_MMA(0, 1, At, B1); PG8_BAR; PG8_SCHED;
	s_setprio 1
	s_waitcnt lgkmcnt(0)
	v_mfma_f32_16x16x32_bf16 v[62:65], v[66:69], v[194:197], 0
	v_mfma_f32_16x16x32_bf16 v[58:61], v[74:77], v[194:197], 0
	v_mfma_f32_16x16x32_bf16 v[46:49], v[66:69], v[202:205], 0
	v_mfma_f32_16x16x32_bf16 v[42:45], v[74:77], v[202:205], 0
	v_mfma_f32_16x16x32_bf16 v[30:33], v[66:69], v[210:213], 0
	v_mfma_f32_16x16x32_bf16 v[26:29], v[74:77], v[210:213], 0
	v_mfma_f32_16x16x32_bf16 v[14:17], v[66:69], v[218:221], 0
	v_mfma_f32_16x16x32_bf16 v[10:13], v[74:77], v[218:221], 0
	v_mfma_f32_16x16x32_bf16 v[62:65], v[70:73], v[198:201], v[62:65]
	v_mfma_f32_16x16x32_bf16 v[58:61], v[78:81], v[198:201], v[58:61]
	v_mfma_f32_16x16x32_bf16 v[46:49], v[70:73], v[206:209], v[46:49]
	v_mfma_f32_16x16x32_bf16 v[42:45], v[78:81], v[206:209], v[42:45]
	v_mfma_f32_16x16x32_bf16 v[30:33], v[70:73], v[214:217], v[30:33]
	v_mfma_f32_16x16x32_bf16 v[26:29], v[78:81], v[214:217], v[26:29]
	v_mfma_f32_16x16x32_bf16 v[14:17], v[70:73], v[222:225], v[14:17]
	v_mfma_f32_16x16x32_bf16 v[10:13], v[78:81], v[222:225], v[10:13]
	s_setprio 0
	s_setprio 1
	v_mfma_f32_16x16x32_bf16 v[54:57], v[162:165], v[194:197], 0
	v_mfma_f32_16x16x32_bf16 v[50:53], v[186:189], v[194:197], 0
	v_mfma_f32_16x16x32_bf16 v[38:41], v[162:165], v[202:205], 0
	v_mfma_f32_16x16x32_bf16 v[34:37], v[186:189], v[202:205], 0
	v_mfma_f32_16x16x32_bf16 v[22:25], v[162:165], v[210:213], 0
	v_mfma_f32_16x16x32_bf16 v[18:21], v[186:189], v[210:213], 0
	v_mfma_f32_16x16x32_bf16 v[6:9], v[162:165], v[218:221], 0
	v_mfma_f32_16x16x32_bf16 v[2:5], v[186:189], v[218:221], 0
	v_mfma_f32_16x16x32_bf16 v[54:57], v[182:185], v[198:201], v[54:57]
	v_mfma_f32_16x16x32_bf16 v[50:53], v[190:193], v[198:201], v[50:53]
	v_mfma_f32_16x16x32_bf16 v[38:41], v[182:185], v[206:209], v[38:41]
	v_mfma_f32_16x16x32_bf16 v[34:37], v[190:193], v[206:209], v[34:37]
	v_mfma_f32_16x16x32_bf16 v[22:25], v[182:185], v[214:217], v[22:25]
	v_mfma_f32_16x16x32_bf16 v[18:21], v[190:193], v[214:217], v[18:21]
	v_mfma_f32_16x16x32_bf16 v[6:9], v[182:185], v[222:225], v[6:9]
	v_mfma_f32_16x16x32_bf16 v[2:5], v[190:193], v[222:225], v[2:5]
	s_setprio 0
	s_barrier
	s_add_i32 s22, 0, 0x18000
	s_add_i32 s23, 0, 0x1c000
	v_add_u32_e32 v78, s22, v170
	v_add_u32_e32 v168, s23, v170
	ds_read_b128 v[66:69], v78
	ds_read_b128 v[70:73], v78 offset:1024
	ds_read_b128 v[74:77], v78 offset:2048
	ds_read_b128 v[78:81], v78 offset:3072
	ds_read_b128 v[162:165], v168
	ds_read_b128 v[182:185], v168 offset:1024
	ds_read_b128 v[186:189], v168 offset:2048
	ds_read_b128 v[190:193], v168 offset:3072
	s_add_u32 s20, s52, 0x80000
	s_addc_u32 s21, s53, 0
	s_mov_b32 m0, s35
	v_lshl_add_u64 v[232:233], s[20:21], 0, v[152:153]
	ds_read_b128 v[194:197], v176 offset:32768
	ds_read_b128 v[198:201], v176 offset:33792
	ds_read_b128 v[202:205], v176 offset:34816
	ds_read_b128 v[206:209], v176 offset:35840
	ds_read_b128 v[210:213], v176 offset:36864
	ds_read_b128 v[214:217], v176 offset:37888
	ds_read_b128 v[218:221], v176 offset:38912
	ds_read_b128 v[222:225], v176 offset:39936
	global_load_lds_dwordx4 v[232:233], off
	v_lshl_add_u64 v[232:233], s[20:21], 0, v[148:149]
	s_mov_b32 m0, s36
	s_nop 0
	global_load_lds_dwordx4 v[232:233], off
	s_waitcnt vmcnt(8)
	s_waitcnt lgkmcnt(0)
	s_barrier
	s_setprio 1
	s_waitcnt lgkmcnt(0)
	v_mfma_f32_16x16x32_bf16 v[142:145], v[66:69], v[194:197], v[142:145]
	v_mfma_f32_16x16x32_bf16 v[138:141], v[74:77], v[194:197], v[138:141]
	v_mfma_f32_16x16x32_bf16 v[126:129], v[66:69], v[202:205], v[126:129]
	v_mfma_f32_16x16x32_bf16 v[122:125], v[74:77], v[202:205], v[122:125]
	v_mfma_f32_16x16x32_bf16 v[110:113], v[66:69], v[210:213], v[110:113]
	v_mfma_f32_16x16x32_bf16 v[106:109], v[74:77], v[210:213], v[106:109]
	v_mfma_f32_16x16x32_bf16 v[94:97], v[66:69], v[218:221], v[94:97]
	v_mfma_f32_16x16x32_bf16 v[90:93], v[74:77], v[218:221], v[90:93]
	v_mfma_f32_16x16x32_bf16 v[142:145], v[70:73], v[198:201], v[142:145]
	v_mfma_f32_16x16x32_bf16 v[138:141], v[78:81], v[198:201], v[138:141]
	v_mfma_f32_16x16x32_bf16 v[126:129], v[70:73], v[206:209], v[126:129]
	v_mfma_f32_16x16x32_bf16 v[122:125], v[78:81], v[206:209], v[122:125]
	v_mfma_f32_16x16x32_bf16 v[110:113], v[70:73], v[214:217], v[110:113]
	v_mfma_f32_16x16x32_bf16 v[106:109], v[78:81], v[214:217], v[106:109]
	v_mfma_f32_16x16x32_bf16 v[94:97], v[70:73], v[222:225], v[94:97]
	v_mfma_f32_16x16x32_bf16 v[90:93], v[78:81], v[222:225], v[90:93]
	s_setprio 0
	s_setprio 1
	v_mfma_f32_16x16x32_bf16 v[134:137], v[162:165], v[194:197], v[134:137]
	v_mfma_f32_16x16x32_bf16 v[130:133], v[186:189], v[194:197], v[130:133]
	v_mfma_f32_16x16x32_bf16 v[118:121], v[162:165], v[202:205], v[118:121]
	v_mfma_f32_16x16x32_bf16 v[114:117], v[186:189], v[202:205], v[114:117]
	v_mfma_f32_16x16x32_bf16 v[102:105], v[162:165], v[210:213], v[102:105]
	v_mfma_f32_16x16x32_bf16 v[98:101], v[186:189], v[210:213], v[98:101]
	v_mfma_f32_16x16x32_bf16 v[86:89], v[162:165], v[218:221], v[86:89]
	v_mfma_f32_16x16x32_bf16 v[82:85], v[186:189], v[218:221], v[82:85]
	v_mfma_f32_16x16x32_bf16 v[134:137], v[182:185], v[198:201], v[134:137]
	v_mfma_f32_16x16x32_bf16 v[130:133], v[190:193], v[198:201], v[130:133]
	v_mfma_f32_16x16x32_bf16 v[118:121], v[182:185], v[206:209], v[118:121]
	v_mfma_f32_16x16x32_bf16 v[114:117], v[190:193], v[206:209], v[114:117]
	v_mfma_f32_16x16x32_bf16 v[102:105], v[182:185], v[214:217], v[102:105]
	v_mfma_f32_16x16x32_bf16 v[98:101], v[190:193], v[214:217], v[98:101]
	v_mfma_f32_16x16x32_bf16 v[86:89], v[182:185], v[222:225], v[86:89]
	v_mfma_f32_16x16x32_bf16 v[82:85], v[190:193], v[222:225], v[82:85]
	s_setprio 0
	s_barrier
; #define PG8_STAGE(bufoff, gbase, voff) do { _Pragma("unroll") for (int _i = 0; _i < 2; ++_i) \
;         __builtin_amdgcn_global_load_lds((const unsigned*)((const char*)(gbase) + (voff)[_i]), (LAS unsigned*)(lds + (bufoff) + ldsw + _i * 8192), 16, 0, 0); } while (0)
; #define PG8_LDA(dst, b, h) do { _Pragma("unroll") for (int m = 0; m < 4; ++m) _Pragma("unroll") for (int k = 0; k < 2; ++k) dst[m][k] = *(const LAS bf16x8*)(lds + PG8_SA(b, h) + aoff + m * 2048 + k * 1024); } while (0)
; #define PG8_LDB(dst, b, h) do { _Pragma("unroll") for (int n = 0; n < 2; ++n) _Pragma("unroll") for (int k = 0; k < 2; ++k) dst[n][k] = *(const LAS bf16x8*)(lds + PG8_SB(b, h) + boff + n * 2048 + k * 1024); } while (0)
; template <class Epi, class Sched, bool ALIGN_EPI = false, bool SP2 = false>
; __device__ __forceinline__ void gemm_phase(LAS unsigned char* lds, const Gemm g, const Sched& S, const Epi& E) {
;     ...
;         for (int t = 0; t < nt; t += 2) {
;             const bool last = (t == nt - 2);
;             const char* a1 = cA + (size_t)(t + 1) * kstep;
;             const char* a2 = last ? nA : cA + (size_t)(t + 2) * kstep; const char* b2 = last ? nB : cB + (size_t)(t + 2) * kstep;
;             const char* a3 = a2 + kstep; const char* b3 = b2 + kstep;
;             if (last && has_next) S.a_ready(nxt);
;             if constexpr (SP2) {
;             PG8_LDB(B0, 0, 0); PG8_LDB(B1, 0, 1); PG8_SCHED; PG8_LDA(At, 0, 0); PG8_STAGE(PG8_SA(1, 1), a1 + hstep, voffA);
;             PG8_WAIT_V(8); PG8_WAIT_L(0); PG8_BAR; PG8_MMA(0, 0, At, B0); PG8_MMA(0, 1, At, B1); PG8_BAR; PG8_SCHED;
;             PG8_LDA(At, 0, 1); PG8_STAGE(PG8_SB(0, 0), b2, voffB); PG8_STAGE(PG8_SB(0, 1), b2 + hstepB, voffB); PG8_STAGE(PG8_SA(0, 0), a2, voffA);
;             PG8_WAIT_V(8); PG8_WAIT_L(0); PG8_BAR; PG8_MMA(1, 0, At, B0); PG8_MMA(1, 1, At, B1); PG8_BAR; PG8_SCHED;
;             PG8_LDB(B0, 1, 0); PG8_LDB(B1, 1, 1); PG8_SCHED; PG8_LDA(At, 1, 0); PG8_STAGE(PG8_SA(0, 1), a2 + hstep, voffA);
;             PG8_WAIT_V(8); PG8_WAIT_L(0); PG8_BAR; PG8_MMA(0, 0, At, B0); PG8_MMA(0, 1, At, B1); PG8_BAR; PG8_SCHED;
;             PG8_LDA(At, 1, 1); PG8_STAGE(PG8_SB(1, 0), b3, voffB); PG8_STAGE(PG8_SB(1, 1), b3 + hstepB, voffB); PG8_STAGE(PG8_SA(1, 0), a3, voffA);
;             PG8_WAIT_V(8); PG8_WAIT_L(0); PG8_BAR; PG8_MMA(1, 0, At, B0); PG8_MMA(1, 1, At, B1); PG8_BAR; PG8_SCHED;
	s_add_i32 s20, s22, s27
	v_lshl_add_u64 v[166:167], v[166:167], 0, s[10:11]
	s_mov_b32 m0, s20
	ds_read_b128 v[194:197], v176 offset:49152
	ds_read_b128 v[198:201], v176 offset:50176
	ds_read_b128 v[202:205], v176 offset:51200
	ds_read_b128 v[206:209], v176 offset:52224
	ds_read_b128 v[210:213], v176 offset:53248
	ds_read_b128 v[214:217], v176 offset:54272
	ds_read_b128 v[218:221], v176 offset:55296
	ds_read_b128 v[222:225], v176 offset:56320
	global_load_lds_dwordx4 v[166:167], off
	s_add_i32 m0, s20, 0x2000
	s_add_u32 s20, s50, 0x80080
	v_lshl_add_u64 v[166:167], v[226:227], 0, s[10:11]
	s_addc_u32 s21, s51, 0
	s_add_i32 s22, s23, s27
	global_load_lds_dwordx4 v[166:167], off
	v_lshl_add_u64 v[166:167], s[20:21], 0, v[150:151]
	s_mov_b32 m0, s22
	s_nop 0
	global_load_lds_dwordx4 v[166:167], off
	v_lshl_add_u64 v[166:167], s[20:21], 0, v[146:147]
	s_add_i32 m0, s22, 0x2000
	s_nop 0
	global_load_lds_dwordx4 v[166:167], off
	v_lshl_add_u64 v[166:167], v[228:229], 0, s[10:11]
	s_mov_b32 m0, s55
	s_nop 0
	global_load_lds_dwordx4 v[166:167], off
	v_lshl_add_u64 v[166:167], v[230:231], 0, s[10:11]
	s_mov_b32 m0, s56
	s_nop 0
	global_load_lds_dwordx4 v[166:167], off
	s_waitcnt vmcnt(8)
	s_waitcnt lgkmcnt(0)
	s_barrier
	s_setprio 1
	s_waitcnt lgkmcnt(0)
	v_mfma_f32_16x16x32_bf16 v[62:65], v[66:69], v[194:197], v[62:65]
	v_mfma_f32_16x16x32_bf16 v[58:61], v[74:77], v[194:197], v[58:61]
	v_mfma_f32_16x16x32_bf16 v[46:49], v[66:69], v[202:205], v[46:49]
	v_mfma_f32_16x16x32_bf16 v[42:45], v[74:77], v[202:205], v[42:45]
	v_mfma_f32_16x16x32_bf16 v[30:33], v[66:69], v[210:213], v[30:33]
	v_mfma_f32_16x16x32_bf16 v[26:29], v[74:77], v[210:213], v[26:29]
	v_mfma_f32_16x16x32_bf16 v[14:17], v[66:69], v[218:221], v[14:17]
	v_mfma_f32_16x16x32_bf16 v[10:13], v[74:77], v[218:221], v[10:13]
	v_mfma_f32_16x16x32_bf16 v[62:65], v[70:73], v[198:201], v[62:65]
	v_mfma_f32_16x16x32_bf16 v[58:61], v[78:81], v[198:201], v[58:61]
	v_mfma_f32_16x16x32_bf16 v[46:49], v[70:73], v[206:209], v[46:49]
	v_mfma_f32_16x16x32_bf16 v[42:45], v[78:81], v[206:209], v[42:45]
	v_mfma_f32_16x16x32_bf16 v[30:33], v[70:73], v[214:217], v[30:33]
	v_mfma_f32_16x16x32_bf16 v[26:29], v[78:81], v[214:217], v[26:29]
	v_mfma_f32_16x16x32_bf16 v[14:17], v[70:73], v[222:225], v[14:17]
	v_mfma_f32_16x16x32_bf16 v[10:13], v[78:81], v[222:225], v[10:13]
	s_setprio 0
	s_setprio 1
	v_mfma_f32_16x16x32_bf16 v[54:57], v[162:165], v[194:197], v[54:57]
	v_mfma_f32_16x16x32_bf16 v[50:53], v[186:189], v[194:197], v[50:53]
	v_mfma_f32_16x16x32_bf16 v[38:41], v[162:165], v[202:205], v[38:41]
	v_mfma_f32_16x16x32_bf16 v[34:37], v[186:189], v[202:205], v[34:37]
	v_mfma_f32_16x16x32_bf16 v[22:25], v[162:165], v[210:213], v[22:25]
	v_mfma_f32_16x16x32_bf16 v[18:21], v[186:189], v[210:213], v[18:21]
	v_mfma_f32_16x16x32_bf16 v[6:9], v[162:165], v[218:221], v[6:9]
	v_mfma_f32_16x16x32_bf16 v[2:5], v[186:189], v[218:221], v[2:5]
	v_mfma_f32_16x16x32_bf16 v[54:57], v[182:185], v[198:201], v[54:57]
	v_mfma_f32_16x16x32_bf16 v[50:53], v[190:193], v[198:201], v[50:53]
	v_mfma_f32_16x16x32_bf16 v[38:41], v[182:185], v[206:209], v[38:41]
	v_mfma_f32_16x16x32_bf16 v[34:37], v[190:193], v[206:209], v[34:37]
	v_mfma_f32_16x16x32_bf16 v[22:25], v[182:185], v[214:217], v[22:25]
	v_mfma_f32_16x16x32_bf16 v[18:21], v[190:193], v[214:217], v[18:21]
	v_mfma_f32_16x16x32_bf16 v[6:9], v[182:185], v[222:225], v[6:9]
	v_mfma_f32_16x16x32_bf16 v[2:5], v[190:193], v[222:225], v[2:5]
	s_setprio 0
	s_barrier
	s_add_i32 s19, s19, 2
	s_add_u32 s16, s16, 0x100
	s_addc_u32 s17, s17, 0
	s_add_u32 s15, s15, 0x100
	s_addc_u32 s18, s18, 0
	s_cmp_gt_u32 s19, 29

; #define LAS __attribute__((address_space(3)))
; #define PG8_STAGE(bufoff, gbase, voff) do { _Pragma("unroll") for (int _i = 0; _i < 2; ++_i) \
;         __builtin_amdgcn_global_load_lds((const unsigned*)((const char*)(gbase) + (voff)[_i]), (LAS unsigned*)(lds + (bufoff) + ldsw + _i * 8192), 16, 0, 0); } while (0)
; #define PG8_WAIT_V(n) asm volatile("s_waitcnt vmcnt(" #n ")" ::: "memory")
; #define PG8_BAR __builtin_amdgcn_s_barrier()
;     __device__ __forceinline__ void operator()(const f32x4 (&acc)[2][2][4][2], const Unit& u, int wr, int wc, int fr, int fq) const {
;         const int s = u.pm >> 5, lane = fq * 16 + fr, rr = lane >> 3, pc = lane & 7;
;         const float* __restrict__ xi = xin + (size_t)u.pm * BM * DM; float* __restrict__ xo = xout + (size_t)u.pm * BM * DM; bf16_t* __restrict__ ho = Hn + (size_t)u.pm * BM * DM;
;         LAS unsigned char* st = lds_epi + (wr * 4 + wc) * 2304;
;         LAS float* sst = (LAS float*)(lds_epi + 18432 + (wr * 4 + wc) * 512);
;         const int colr = u.pn * BM + wc * 64 + 4 * pc;
;         const unsigned eb = (unsigned)((wr * 64 + rr) * DM + colr);
;         f32x4 gv[2], gsn[2];
; #pragma unroll
;         for (int bj = 0; bj < 2; ++bj) { gv[bj] = *(const f32x4*)(gate + (size_t)s * MODW + colr + bj * 32) * (0.5f * GS2);
;             if (!PLAIN) gsn[bj] = *(const f32x4*)(gnext + colr + bj * 32) * (*(const f32x4*)(scnext + (size_t)s * MODW + colr + bj * 32) + 1.0f); else gsn[bj] = gv[bj]; }
;         const unsigned wr_off = (unsigned)(fr * 144 + 16 * fq), rd_off = (unsigned)(rr * 144 + pc * 16);
; template <class Epi, class Sched, bool ALIGN_EPI = false, bool SP2 = false>
; __device__ __forceinline__ void gemm_phase(LAS unsigned char* lds, const Gemm g, const Sched& S, const Epi& E) {
;     ...
;     if constexpr (SP2) {
;         PG8_STAGE(PG8_SB(0, 0), cB, voffB); PG8_STAGE(PG8_SB(0, 1), cB + hstepB, voffB); PG8_STAGE(PG8_SA(0, 0), cA, voffA); PG8_STAGE(PG8_SA(0, 1), cA + hstep, voffA);
;         if (wr == 1) PG8_BAR;
;         PG8_WAIT_V(2); PG8_BAR;
;         PG8_STAGE(PG8_SB(1, 0), cB + kstep, voffB); PG8_STAGE(PG8_SA(1, 0), cA + kstep, voffA); PG8_STAGE(PG8_SB(1, 1), cB + hstepB + kstep, voffB);
;         PG8_WAIT_V(6); PG8_BAR;
.LBB0_303:
	s_and_b32 s3, s3, 3
	s_lshl_b32 s14, s5, 6
	s_lshl_b32 s15, s5, 13
	s_lshl_b32 s20, s3, 12
	s_add_u32 s35, s48, 0x44000
	s_mov_b64 s[24:25], s[48:49]
	s_addc_u32 s36, s49, 0
	s_mov_b64 s[26:27], s[50:51]
	v_readlane_b32 s40, v253, 2
	v_readlane_b32 s46, v253, 8
	v_readlane_b32 s52, v253, 14
	v_readlane_b32 s47, v253, 9
	v_readlane_b32 s53, v253, 15
	s_add_u32 s46, s52, 0x2000
	v_readlane_b32 s48, v253, 10
	v_readlane_b32 s49, v253, 11
	s_addc_u32 s47, s53, 0
	s_add_u32 s37, s24, 0x48000
	s_mov_b64 s[48:49], 0x80
	s_addc_u32 s60, s25, 0
	s_add_i32 m0, s29, 0x18000
	v_lshl_add_u64 v[8:9], v[8:9], 0, s[48:49]
	s_waitcnt vmcnt(2)
	s_barrier
	global_load_lds_dwordx4 v[8:9], off
	v_lshl_add_u64 v[4:5], v[4:5], 0, s[48:49]
	s_add_i32 m0, s29, 0x1a000
	s_add_i32 s61, s29, 0x8000
	s_add_i32 s62, s29, 0xa000
	global_load_lds_dwordx4 v[4:5], off
	v_lshl_add_u64 v[2:3], v[2:3], 0, s[48:49]
	s_mov_b32 m0, s61
	s_add_u32 s18, s22, 0x58080
	global_load_lds_dwordx4 v[2:3], off
	v_lshl_add_u64 v[2:3], v[6:7], 0, s[48:49]
	s_mov_b32 m0, s62
	s_addc_u32 s19, s23, 0
	global_load_lds_dwordx4 v[2:3], off
	s_add_i32 m0, s29, 0x1c000
	v_lshl_add_u64 v[2:3], s[18:19], 0, v[148:149]
	global_load_lds_dwordx4 v[2:3], off
	v_lshl_add_u64 v[2:3], s[18:19], 0, v[152:153]
	s_add_i32 m0, s29, 0x1e000
	v_readlane_b32 s50, v253, 12
	global_load_lds_dwordx4 v[2:3], off
	v_readlane_b32 s51, v253, 13
	v_and_b32_e32 v2, 15, v10
	v_and_b32_e32 v4, 48, v10
	v_lshlrev_b32_e32 v3, 2, v10
	s_cmpk_lt_u32 s12, 0x100
	v_lshl_or_b32 v1, v2, 6, v4
	v_and_b32_e32 v3, 32, v3
	s_cselect_b64 s[50:51], -1, 0
	v_and_b32_e32 v7, 7, v10
	s_lshl_b32 s5, s5, 2
	v_bitop3_b32 v5, v1, s15, v3 bitop3:0xde
	v_bfe_u32 v6, v10, 3, 3
	s_or_b32 s5, s5, s3
	v_lshlrev_b32_e32 v8, 2, v7
	s_ashr_i32 s15, s14, 31
	s_mul_i32 s12, s5, 0x900
	s_lshl_b32 s5, s5, 9
	v_lshl_or_b32 v192, s3, 6, v8
	v_or_b32_e32 v8, s14, v6
	s_ashr_i32 s63, s1, 31
	s_lshl_b64 s[14:15], s[14:15], 2
	s_add_u32 s14, s74, s14
	s_addc_u32 s15, s75, s15
	s_add_i32 s3, s12, 0
	v_bitop3_b32 v1, v1, s20, v3 bitop3:0xde
	v_and_b32_e32 v3, 63, v10
	s_add_i32 s3, s3, 0x20000
	v_readlane_b32 s41, v253, 3
	v_readlane_b32 s42, v253, 4
	v_readlane_b32 s43, v253, 5
	v_lshlrev_b32_e32 v154, 2, v3
	s_movk_i32 s12, 0x90
	v_mov_b32_e32 v3, s3
	v_lshlrev_b32_e32 v193, 11, v8
	v_lshlrev_b32_e32 v8, 4, v7
	v_cmp_gt_u32_e64 s[38:39], 8, v2
	v_cmp_lt_u32_e64 s[40:41], 7, v2
	v_cmp_eq_u32_e64 s[42:43], 0, v7
	v_mad_u32_u24 v7, v2, s12, v3
	v_mad_u32_u24 v9, v6, s12, v3
	v_lshrrev_b32_e32 v3, 1, v11
	v_mul_lo_u32 v2, v12, s2
	v_lshl_add_u64 v[156:157], s[14:15], 0, v[154:155]
	s_add_i32 s5, s5, 0
	v_mad_u64_u32 v[2:3], s[14:15], v3, s13, v[2:3]
	s_add_i32 s5, s5, 0x24800
	v_or_b32_e32 v2, v2, v13
	v_add_u32_e32 v195, s5, v154
	v_add_lshl_u32 v154, v2, v14, 1
	v_lshrrev_b32_e32 v3, 1, v15
	v_mul_lo_u32 v2, v16, s2
	v_mad_u64_u32 v[2:3], s[2:3], v3, s13, v[2:3]
	s_waitcnt vmcnt(0)
	s_mov_b64 s[14:15], 0x160080
	v_or_b32_e32 v2, v2, v17
	v_lshl_add_u64 v[158:159], v[154:155], 0, s[14:15]
	v_add_lshl_u32 v154, v2, v18, 1
	s_add_i32 s64, 0, 0x10000
	s_add_i32 s65, 0, 0x14000
	v_mbcnt_lo_u32_b32 v2, -1, 0
	v_lshl_add_u32 v194, v6, 2, s5
	v_lshl_add_u64 v[160:161], v[154:155], 0, s[14:15]
	v_mov_b64_e32 v[162:163], 0x400
	v_mov_b64_e32 v[164:165], 0x3ff
	v_add_u32_e32 v196, s64, v1
	v_add_u32_e32 v197, s65, v1
	v_add_u32_e32 v198, 0, v5
	v_mbcnt_hi_u32_b32 v199, -1, v2
	v_add_u32_e32 v200, v7, v4
	v_add_u32_e32 v201, v9, v8
	v_readlane_b32 s44, v253, 6
	v_readlane_b32 s45, v253, 7
	v_readlane_b32 s54, v253, 16
	v_readlane_b32 s55, v253, 17
	s_barrier
	s_branch .LBB0_306

;     __device__ bool next(int i, Unit& u) const { if (i != 0 || c >= 128) return false; const int t = c >> 2; u.pm = t & 3; u.pn = t >> 2; u.koff = koff_bytes; u.q = c & 3; return true; }
; #define PG8_STAGE(bufoff, gbase, voff) do { _Pragma("unroll") for (int _i = 0; _i < 2; ++_i) \
;         __builtin_amdgcn_global_load_lds((const unsigned*)((const char*)(gbase) + (voff)[_i]), (LAS unsigned*)(lds + (bufoff) + ldsw + _i * 8192), 16, 0, 0); } while (0)
; #define PG8_LDA(dst, b, h) do { _Pragma("unroll") for (int m = 0; m < 4; ++m) _Pragma("unroll") for (int k = 0; k < 2; ++k) dst[m][k] = *(const LAS bf16x8*)(lds + PG8_SA(b, h) + aoff + m * 2048 + k * 1024); } while (0)
; #define PG8_LDB(dst, b, h) do { _Pragma("unroll") for (int n = 0; n < 2; ++n) _Pragma("unroll") for (int k = 0; k < 2; ++k) dst[n][k] = *(const LAS bf16x8*)(lds + PG8_SB(b, h) + boff + n * 2048 + k * 1024); } while (0)
; #define PG8_WAIT_V(n) asm volatile("s_waitcnt vmcnt(" #n ")" ::: "memory")
; template <class Epi, class Sched, bool ALIGN_EPI = false, bool SP2 = false>
; __device__ __forceinline__ void gemm_phase(LAS unsigned char* lds, const Gemm g, const Sched& S, const Epi& E) {
;     ...
;         const bool has_next = S.next(ui + 1, nxt);
;         const char* nA = has_next ? (const char*)g.A + (size_t)nxt.pm * tstep + nxt.koff : cA; const char* nB = has_next ? (const char*)g.Bt + (size_t)nxt.pn * tstep + nxt.koff : cB;
;         for (int t = 0; t < nt; t += 2) {
;             const bool last = (t == nt - 2);
;             const char* a1 = cA + (size_t)(t + 1) * kstep;
;             const char* a2 = last ? nA : cA + (size_t)(t + 2) * kstep; const char* b2 = last ? nB : cB + (size_t)(t + 2) * kstep;
;             const char* a3 = a2 + kstep; const char* b3 = b2 + kstep;
;             if (last && has_next) S.a_ready(nxt);
;             if constexpr (SP2) {
;             PG8_LDB(B0, 0, 0); PG8_LDB(B1, 0, 1); PG8_SCHED; PG8_LDA(At, 0, 0); PG8_STAGE(PG8_SA(1, 1), a1 + hstep, voffA);
;             PG8_WAIT_V(8); PG8_WAIT_L(0); PG8_BAR; PG8_MMA(0, 0, At, B0); PG8_MMA(0, 1, At, B1); PG8_BAR; PG8_SCHED;
;             PG8_LDA(At, 0, 1); PG8_STAGE(PG8_SB(0, 0), b2, voffB); PG8_STAGE(PG8_SB(0, 1), b2 + hstepB, voffB); PG8_STAGE(PG8_SA(0, 0), a2, voffA);
;             PG8_WAIT_V(8); PG8_WAIT_L(0); PG8_BAR; PG8_MMA(1, 0, At, B0); PG8_MMA(1, 1, At, B1); PG8_BAR; PG8_SCHED;
.LBB0_316:
	s_add_u32 s5, s22, 0x100
	s_addc_u32 s12, s23, 0
	s_mov_b32 s13, -2
	ds_read_b128 v[130:133], v196
	ds_read_b128 v[134:137], v196 offset:1024
	ds_read_b128 v[138:141], v196 offset:2048
	ds_read_b128 v[142:145], v196 offset:3072
	ds_read_b128 v[166:169], v197
	ds_read_b128 v[170:173], v197 offset:1024
	ds_read_b128 v[174:177], v197 offset:2048
	ds_read_b128 v[178:181], v197 offset:3072
	s_add_u32 s54, s16, 0x100
	s_addc_u32 s55, s17, 0
	s_cmpk_eq_i32 s13, 0x54
	s_cselect_b32 s59, s3, s55
	s_cselect_b32 s58, s2, s54
	s_cselect_b32 s57, s53, s12
	s_cselect_b32 s56, s52, s5
	v_lshl_add_u64 v[190:191], s[16:17], 0, v[158:159]
	s_add_i32 m0, s29, 0xc000
	ds_read_b128 v[182:185], v198
	ds_read_b128 v[186:189], v198 offset:1024
	ds_read_b128 v[202:205], v198 offset:2048
	ds_read_b128 v[206:209], v198 offset:3072
	ds_read_b128 v[210:213], v198 offset:4096
	ds_read_b128 v[214:217], v198 offset:5120
	ds_read_b128 v[218:221], v198 offset:6144
	ds_read_b128 v[222:225], v198 offset:7168
	global_load_lds_dwordx4 v[190:191], off
	v_lshl_add_u64 v[190:191], s[16:17], 0, v[160:161]
	s_add_i32 m0, s29, 0xe000
	s_nop 0
	global_load_lds_dwordx4 v[190:191], off
	s_waitcnt lgkmcnt(0)
	s_barrier
	s_setprio 1
	s_waitcnt lgkmcnt(0)
	v_mfma_f32_16x16x32_bf16 v[126:129], v[130:133], v[182:185], 0
	v_mfma_f32_16x16x32_bf16 v[122:125], v[138:141], v[182:185], 0
	v_mfma_f32_16x16x32_bf16 v[110:113], v[130:133], v[202:205], 0
	v_mfma_f32_16x16x32_bf16 v[106:109], v[138:141], v[202:205], 0
	v_mfma_f32_16x16x32_bf16 v[94:97], v[130:133], v[210:213], 0
	v_mfma_f32_16x16x32_bf16 v[90:93], v[138:141], v[210:213], 0
	v_mfma_f32_16x16x32_bf16 v[78:81], v[130:133], v[218:221], 0
	v_mfma_f32_16x16x32_bf16 v[74:77], v[138:141], v[218:221], 0
	v_mfma_f32_16x16x32_bf16 v[126:129], v[134:137], v[186:189], v[126:129]
	v_mfma_f32_16x16x32_bf16 v[122:125], v[142:145], v[186:189], v[122:125]
	v_mfma_f32_16x16x32_bf16 v[110:113], v[134:137], v[206:209], v[110:113]
	v_mfma_f32_16x16x32_bf16 v[106:109], v[142:145], v[206:209], v[106:109]
	v_mfma_f32_16x16x32_bf16 v[94:97], v[134:137], v[214:217], v[94:97]
	v_mfma_f32_16x16x32_bf16 v[90:93], v[142:145], v[214:217], v[90:93]
	v_mfma_f32_16x16x32_bf16 v[78:81], v[134:137], v[222:225], v[78:81]
	v_mfma_f32_16x16x32_bf16 v[74:77], v[142:145], v[222:225], v[74:77]
	s_setprio 0
	s_setprio 1
	v_mfma_f32_16x16x32_bf16 v[118:121], v[166:169], v[182:185], 0
	v_mfma_f32_16x16x32_bf16 v[114:117], v[174:177], v[182:185], 0
	v_mfma_f32_16x16x32_bf16 v[102:105], v[166:169], v[202:205], 0
	v_mfma_f32_16x16x32_bf16 v[98:101], v[174:177], v[202:205], 0
	v_mfma_f32_16x16x32_bf16 v[86:89], v[166:169], v[210:213], 0
	v_mfma_f32_16x16x32_bf16 v[82:85], v[174:177], v[210:213], 0
	v_mfma_f32_16x16x32_bf16 v[70:73], v[166:169], v[218:221], 0
	v_mfma_f32_16x16x32_bf16 v[66:69], v[174:177], v[218:221], 0
	v_mfma_f32_16x16x32_bf16 v[118:121], v[170:173], v[186:189], v[118:121]
	v_mfma_f32_16x16x32_bf16 v[114:117], v[178:181], v[186:189], v[114:117]
	v_mfma_f32_16x16x32_bf16 v[102:105], v[170:173], v[206:209], v[102:105]
	v_mfma_f32_16x16x32_bf16 v[98:101], v[178:181], v[206:209], v[98:101]
	v_mfma_f32_16x16x32_bf16 v[86:89], v[170:173], v[214:217], v[86:89]
	v_mfma_f32_16x16x32_bf16 v[82:85], v[178:181], v[214:217], v[82:85]
	v_mfma_f32_16x16x32_bf16 v[70:73], v[170:173], v[222:225], v[70:73]
	v_mfma_f32_16x16x32_bf16 v[66:69], v[178:181], v[222:225], v[66:69]
	s_setprio 0
	s_barrier
	s_add_i32 s14, s64, s28
	v_lshl_add_u64 v[190:191], s[56:57], 0, v[148:149]
	s_mov_b32 m0, s14
	ds_read_b128 v[182:185], v198 offset:16384
	ds_read_b128 v[186:189], v198 offset:17408
	ds_read_b128 v[202:205], v198 offset:18432
	ds_read_b128 v[206:209], v198 offset:19456
	ds_read_b128 v[210:213], v198 offset:20480
	ds_read_b128 v[214:217], v198 offset:21504
	ds_read_b128 v[218:221], v198 offset:22528
	ds_read_b128 v[222:225], v198 offset:23552
	global_load_lds_dwordx4 v[190:191], off
	s_add_i32 m0, s14, 0x2000
	s_add_u32 s14, s56, 0x58000
	v_lshl_add_u64 v[226:227], s[56:57], 0, v[152:153]
	s_addc_u32 s15, s57, 0
	s_add_i32 s16, s65, s28
	global_load_lds_dwordx4 v[226:227], off
	v_lshl_add_u64 v[228:229], s[14:15], 0, v[148:149]
	s_mov_b32 m0, s16
	v_lshl_add_u64 v[230:231], s[58:59], 0, v[150:151]
	global_load_lds_dwordx4 v[228:229], off
	v_lshl_add_u64 v[228:229], s[14:15], 0, v[152:153]
	s_add_i32 m0, s16, 0x2000
	s_nop 0
	global_load_lds_dwordx4 v[228:229], off
	v_lshl_add_u64 v[228:229], s[58:59], 0, v[146:147]
	s_mov_b32 m0, s29
	s_nop 0
	global_load_lds_dwordx4 v[228:229], off
	s_mov_b32 m0, s30
	s_nop 0
	global_load_lds_dwordx4 v[230:231], off
	s_waitcnt lgkmcnt(0)
	s_barrier
; #define PG8_STAGE(bufoff, gbase, voff) do { _Pragma("unroll") for (int _i = 0; _i < 2; ++_i) \
;         __builtin_amdgcn_global_load_lds((const unsigned*)((const char*)(gbase) + (voff)[_i]), (LAS unsigned*)(lds + (bufoff) + ldsw + _i * 8192), 16, 0, 0); } while (0)
; #define PG8_LDA(dst, b, h) do { _Pragma("unroll") for (int m = 0; m < 4; ++m) _Pragma("unroll") for (int k = 0; k < 2; ++k) dst[m][k] = *(const LAS bf16x8*)(lds + PG8_SA(b, h) + aoff + m * 2048 + k * 1024); } while (0)
; #define PG8_LDB(dst, b, h) do { _Pragma("unroll") for (int n = 0; n < 2; ++n) _Pragma("unroll") for (int k = 0; k < 2; ++k) dst[n][k] = *(const LAS bf16x8*)(lds + PG8_SB(b, h) + boff + n * 2048 + k * 1024); } while (0)
; #define PG8_MMA(ai, bj, At, Bt) do { __builtin_amdgcn_s_setprio(1); _Pragma("unroll") for (int m = 0; m < 4; ++m) _Pragma("unroll") for (int n = 0; n < 2; ++n) _Pragma("unroll") for (int k = 0; k < 2; ++k) \
;         acc[ai][bj][m][n] = __builtin_amdgcn_mfma_f32_16x16x32_bf16(Bt[n][k], At[m][k], acc[ai][bj][m][n], 0, 0, 0); __builtin_amdgcn_s_setprio(0); } while (0)
; #define PG8_WAIT_V(n) asm volatile("s_waitcnt vmcnt(" #n ")" ::: "memory")
; #define PG8_WAIT_L(n) asm volatile("s_waitcnt lgkmcnt(" #n ")" ::: "memory")
; #define PG8_BAR __builtin_amdgcn_s_barrier()
; #define PG8_SCHED __builtin_amdgcn_sched_barrier(0)
; template <class Epi, class Sched, bool ALIGN_EPI = false, bool SP2 = false>
; __device__ __forceinline__ void gemm_phase(LAS unsigned char* lds, const Gemm g, const Sched& S, const Epi& E) {
;     ...
;             PG8_WAIT_V(8); PG8_WAIT_L(0); PG8_BAR; PG8_MMA(1, 0, At, B0); PG8_MMA(1, 1, At, B1); PG8_BAR; PG8_SCHED;
;             PG8_LDB(B0, 1, 0); PG8_LDB(B1, 1, 1); PG8_SCHED; PG8_LDA(At, 1, 0); PG8_STAGE(PG8_SA(0, 1), a2 + hstep, voffA);
;             PG8_WAIT_V(8); PG8_WAIT_L(0); PG8_BAR; PG8_MMA(0, 0, At, B0); PG8_MMA(0, 1, At, B1); PG8_BAR; PG8_SCHED;
	s_setprio 1
	s_waitcnt lgkmcnt(0)
	v_mfma_f32_16x16x32_bf16 v[62:65], v[130:133], v[182:185], 0
	v_mfma_f32_16x16x32_bf16 v[58:61], v[138:141], v[182:185], 0
	v_mfma_f32_16x16x32_bf16 v[46:49], v[130:133], v[202:205], 0
	v_mfma_f32_16x16x32_bf16 v[42:45], v[138:141], v[202:205], 0
	v_mfma_f32_16x16x32_bf16 v[30:33], v[130:133], v[210:213], 0
	v_mfma_f32_16x16x32_bf16 v[26:29], v[138:141], v[210:213], 0
	v_mfma_f32_16x16x32_bf16 v[14:17], v[130:133], v[218:221], 0
	v_mfma_f32_16x16x32_bf16 v[10:13], v[138:141], v[218:221], 0
	v_mfma_f32_16x16x32_bf16 v[62:65], v[134:137], v[186:189], v[62:65]
	v_mfma_f32_16x16x32_bf16 v[58:61], v[142:145], v[186:189], v[58:61]
	v_mfma_f32_16x16x32_bf16 v[46:49], v[134:137], v[206:209], v[46:49]
	v_mfma_f32_16x16x32_bf16 v[42:45], v[142:145], v[206:209], v[42:45]
	v_mfma_f32_16x16x32_bf16 v[30:33], v[134:137], v[214:217], v[30:33]
	v_mfma_f32_16x16x32_bf16 v[26:29], v[142:145], v[214:217], v[26:29]
	v_mfma_f32_16x16x32_bf16 v[14:17], v[134:137], v[222:225], v[14:17]
	v_mfma_f32_16x16x32_bf16 v[10:13], v[142:145], v[222:225], v[10:13]
	s_setprio 0
	s_setprio 1
	v_mfma_f32_16x16x32_bf16 v[54:57], v[166:169], v[182:185], 0
	v_mfma_f32_16x16x32_bf16 v[50:53], v[174:177], v[182:185], 0
	v_mfma_f32_16x16x32_bf16 v[38:41], v[166:169], v[202:205], 0
	v_mfma_f32_16x16x32_bf16 v[34:37], v[174:177], v[202:205], 0
	v_mfma_f32_16x16x32_bf16 v[22:25], v[166:169], v[210:213], 0
	v_mfma_f32_16x16x32_bf16 v[18:21], v[174:177], v[210:213], 0
	v_mfma_f32_16x16x32_bf16 v[6:9], v[166:169], v[218:221], 0
	v_mfma_f32_16x16x32_bf16 v[2:5], v[174:177], v[218:221], 0
	v_mfma_f32_16x16x32_bf16 v[54:57], v[170:173], v[186:189], v[54:57]
	v_mfma_f32_16x16x32_bf16 v[50:53], v[178:181], v[186:189], v[50:53]
	v_mfma_f32_16x16x32_bf16 v[38:41], v[170:173], v[206:209], v[38:41]
	v_mfma_f32_16x16x32_bf16 v[34:37], v[178:181], v[206:209], v[34:37]
	v_mfma_f32_16x16x32_bf16 v[22:25], v[170:173], v[214:217], v[22:25]
	v_mfma_f32_16x16x32_bf16 v[18:21], v[178:181], v[214:217], v[18:21]
	v_mfma_f32_16x16x32_bf16 v[6:9], v[170:173], v[222:225], v[6:9]
	v_mfma_f32_16x16x32_bf16 v[2:5], v[178:181], v[222:225], v[2:5]
	s_setprio 0
	s_barrier
	s_add_i32 s16, 0, 0x18000
	s_add_i32 s17, 0, 0x1c000
	v_add_u32_e32 v142, s16, v1
	v_add_u32_e32 v154, s17, v1
	ds_read_b128 v[130:133], v142
	ds_read_b128 v[134:137], v142 offset:1024
	ds_read_b128 v[138:141], v142 offset:2048
	ds_read_b128 v[142:145], v142 offset:3072
	ds_read_b128 v[166:169], v154
	ds_read_b128 v[170:173], v154 offset:1024
	ds_read_b128 v[174:177], v154 offset:2048
	ds_read_b128 v[178:181], v154 offset:3072
	s_add_u32 s14, s58, 0x160000
	s_addc_u32 s15, s59, 0
	s_mov_b32 m0, s31
	v_lshl_add_u64 v[232:233], s[14:15], 0, v[146:147]
	ds_read_b128 v[182:185], v198 offset:32768
	ds_read_b128 v[186:189], v198 offset:33792
	ds_read_b128 v[202:205], v198 offset:34816
	ds_read_b128 v[206:209], v198 offset:35840
	ds_read_b128 v[210:213], v198 offset:36864
	ds_read_b128 v[214:217], v198 offset:37888
	ds_read_b128 v[218:221], v198 offset:38912
	ds_read_b128 v[222:225], v198 offset:39936
	global_load_lds_dwordx4 v[232:233], off
	v_lshl_add_u64 v[232:233], s[14:15], 0, v[150:151]
	s_mov_b32 m0, s33
	s_nop 0
	global_load_lds_dwordx4 v[232:233], off
	s_waitcnt vmcnt(8)
	s_waitcnt lgkmcnt(0)
	s_barrier
	s_setprio 1
	s_waitcnt lgkmcnt(0)
	v_mfma_f32_16x16x32_bf16 v[126:129], v[130:133], v[182:185], v[126:129]
	v_mfma_f32_16x16x32_bf16 v[122:125], v[138:141], v[182:185], v[122:125]
	v_mfma_f32_16x16x32_bf16 v[110:113], v[130:133], v[202:205], v[110:113]
	v_mfma_f32_16x16x32_bf16 v[106:109], v[138:141], v[202:205], v[106:109]
	v_mfma_f32_16x16x32_bf16 v[94:97], v[130:133], v[210:213], v[94:97]
	v_mfma_f32_16x16x32_bf16 v[90:93], v[138:141], v[210:213], v[90:93]
	v_mfma_f32_16x16x32_bf16 v[78:81], v[130:133], v[218:221], v[78:81]
	v_mfma_f32_16x16x32_bf16 v[74:77], v[138:141], v[218:221], v[74:77]
	v_mfma_f32_16x16x32_bf16 v[126:129], v[134:137], v[186:189], v[126:129]
	v_mfma_f32_16x16x32_bf16 v[122:125], v[142:145], v[186:189], v[122:125]
	v_mfma_f32_16x16x32_bf16 v[110:113], v[134:137], v[206:209], v[110:113]
	v_mfma_f32_16x16x32_bf16 v[106:109], v[142:145], v[206:209], v[106:109]
	v_mfma_f32_16x16x32_bf16 v[94:97], v[134:137], v[214:217], v[94:97]
	v_mfma_f32_16x16x32_bf16 v[90:93], v[142:145], v[214:217], v[90:93]
	v_mfma_f32_16x16x32_bf16 v[78:81], v[134:137], v[222:225], v[78:81]
	v_mfma_f32_16x16x32_bf16 v[74:77], v[142:145], v[222:225], v[74:77]
	s_setprio 0
	s_setprio 1
	v_mfma_f32_16x16x32_bf16 v[118:121], v[166:169], v[182:185], v[118:121]
	v_mfma_f32_16x16x32_bf16 v[114:117], v[174:177], v[182:185], v[114:117]
	v_mfma_f32_16x16x32_bf16 v[102:105], v[166:169], v[202:205], v[102:105]
	v_mfma_f32_16x16x32_bf16 v[98:101], v[174:177], v[202:205], v[98:101]
	v_mfma_f32_16x16x32_bf16 v[86:89], v[166:169], v[210:213], v[86:89]
	v_mfma_f32_16x16x32_bf16 v[82:85], v[174:177], v[210:213], v[82:85]
	v_mfma_f32_16x16x32_bf16 v[70:73], v[166:169], v[218:221], v[70:73]
	v_mfma_f32_16x16x32_bf16 v[66:69], v[174:177], v[218:221], v[66:69]
	v_mfma_f32_16x16x32_bf16 v[118:121], v[170:173], v[186:189], v[118:121]
	v_mfma_f32_16x16x32_bf16 v[114:117], v[178:181], v[186:189], v[114:117]
	v_mfma_f32_16x16x32_bf16 v[102:105], v[170:173], v[206:209], v[102:105]
	v_mfma_f32_16x16x32_bf16 v[98:101], v[178:181], v[206:209], v[98:101]
	v_mfma_f32_16x16x32_bf16 v[86:89], v[170:173], v[214:217], v[86:89]
	v_mfma_f32_16x16x32_bf16 v[82:85], v[178:181], v[214:217], v[82:85]
	v_mfma_f32_16x16x32_bf16 v[70:73], v[170:173], v[222:225], v[70:73]
	v_mfma_f32_16x16x32_bf16 v[66:69], v[178:181], v[222:225], v[66:69]
	s_setprio 0
	s_barrier
; #define PG8_STAGE(bufoff, gbase, voff) do { _Pragma("unroll") for (int _i = 0; _i < 2; ++_i) \
;         __builtin_amdgcn_global_load_lds((const unsigned*)((const char*)(gbase) + (voff)[_i]), (LAS unsigned*)(lds + (bufoff) + ldsw + _i * 8192), 16, 0, 0); } while (0)
; #define PG8_LDA(dst, b, h) do { _Pragma("unroll") for (int m = 0; m < 4; ++m) _Pragma("unroll") for (int k = 0; k < 2; ++k) dst[m][k] = *(const LAS bf16x8*)(lds + PG8_SA(b, h) + aoff + m * 2048 + k * 1024); } while (0)
; #define PG8_LDB(dst, b, h) do { _Pragma("unroll") for (int n = 0; n < 2; ++n) _Pragma("unroll") for (int k = 0; k < 2; ++k) dst[n][k] = *(const LAS bf16x8*)(lds + PG8_SB(b, h) + boff + n * 2048 + k * 1024); } while (0)
; template <class Epi, class Sched, bool ALIGN_EPI = false, bool SP2 = false>
; __device__ __forceinline__ void gemm_phase(LAS unsigned char* lds, const Gemm g, const Sched& S, const Epi& E) {
;     ...
;         for (int t = 0; t < nt; t += 2) {
;             const bool last = (t == nt - 2);
;             const char* a1 = cA + (size_t)(t + 1) * kstep;
;             const char* a2 = last ? nA : cA + (size_t)(t + 2) * kstep; const char* b2 = last ? nB : cB + (size_t)(t + 2) * kstep;
;             const char* a3 = a2 + kstep; const char* b3 = b2 + kstep;
;             if (last && has_next) S.a_ready(nxt);
;             if constexpr (SP2) {
;             PG8_LDB(B0, 0, 0); PG8_LDB(B1, 0, 1); PG8_SCHED; PG8_LDA(At, 0, 0); PG8_STAGE(PG8_SA(1, 1), a1 + hstep, voffA);
;             PG8_WAIT_V(8); PG8_WAIT_L(0); PG8_BAR; PG8_MMA(0, 0, At, B0); PG8_MMA(0, 1, At, B1); PG8_BAR; PG8_SCHED;
;             PG8_LDA(At, 0, 1); PG8_STAGE(PG8_SB(0, 0), b2, voffB); PG8_STAGE(PG8_SB(0, 1), b2 + hstepB, voffB); PG8_STAGE(PG8_SA(0, 0), a2, voffA);
;             PG8_WAIT_V(8); PG8_WAIT_L(0); PG8_BAR; PG8_MMA(1, 0, At, B0); PG8_MMA(1, 1, At, B1); PG8_BAR; PG8_SCHED;
;             PG8_LDB(B0, 1, 0); PG8_LDB(B1, 1, 1); PG8_SCHED; PG8_LDA(At, 1, 0); PG8_STAGE(PG8_SA(0, 1), a2 + hstep, voffA);
;             PG8_WAIT_V(8); PG8_WAIT_L(0); PG8_BAR; PG8_MMA(0, 0, At, B0); PG8_MMA(0, 1, At, B1); PG8_BAR; PG8_SCHED;
;             PG8_LDA(At, 1, 1); PG8_STAGE(PG8_SB(1, 0), b3, voffB); PG8_STAGE(PG8_SB(1, 1), b3 + hstepB, voffB); PG8_STAGE(PG8_SA(1, 0), a3, voffA);
;             PG8_WAIT_V(8); PG8_WAIT_L(0); PG8_BAR; PG8_MMA(1, 0, At, B0); PG8_MMA(1, 1, At, B1); PG8_BAR; PG8_SCHED;
	s_add_i32 s14, s16, s28
	v_lshl_add_u64 v[190:191], v[190:191], 0, s[48:49]
	s_mov_b32 m0, s14
	ds_read_b128 v[182:185], v198 offset:49152
	ds_read_b128 v[186:189], v198 offset:50176
	ds_read_b128 v[202:205], v198 offset:51200
	ds_read_b128 v[206:209], v198 offset:52224
	ds_read_b128 v[210:213], v198 offset:53248
	ds_read_b128 v[214:217], v198 offset:54272
	ds_read_b128 v[218:221], v198 offset:55296
	ds_read_b128 v[222:225], v198 offset:56320
	global_load_lds_dwordx4 v[190:191], off
	s_add_i32 m0, s14, 0x2000
	s_add_u32 s14, s56, 0x58080
	v_lshl_add_u64 v[190:191], v[226:227], 0, s[48:49]
	s_addc_u32 s15, s57, 0
	s_add_i32 s16, s17, s28
	global_load_lds_dwordx4 v[190:191], off
	v_lshl_add_u64 v[190:191], s[14:15], 0, v[148:149]
	s_mov_b32 m0, s16
	s_nop 0
	global_load_lds_dwordx4 v[190:191], off
	v_lshl_add_u64 v[190:191], s[14:15], 0, v[152:153]
	s_add_i32 m0, s16, 0x2000
	s_nop 0
	global_load_lds_dwordx4 v[190:191], off
	v_lshl_add_u64 v[190:191], v[228:229], 0, s[48:49]
	s_mov_b32 m0, s61
	s_nop 0
	global_load_lds_dwordx4 v[190:191], off
	v_lshl_add_u64 v[190:191], v[230:231], 0, s[48:49]
	s_mov_b32 m0, s62
	s_nop 0
	global_load_lds_dwordx4 v[190:191], off
	s_waitcnt vmcnt(8)
	s_waitcnt lgkmcnt(0)
	s_barrier
	s_setprio 1
	s_waitcnt lgkmcnt(0)
	v_mfma_f32_16x16x32_bf16 v[62:65], v[130:133], v[182:185], v[62:65]
	v_mfma_f32_16x16x32_bf16 v[58:61], v[138:141], v[182:185], v[58:61]
	v_mfma_f32_16x16x32_bf16 v[46:49], v[130:133], v[202:205], v[46:49]
	v_mfma_f32_16x16x32_bf16 v[42:45], v[138:141], v[202:205], v[42:45]
	v_mfma_f32_16x16x32_bf16 v[30:33], v[130:133], v[210:213], v[30:33]
	v_mfma_f32_16x16x32_bf16 v[26:29], v[138:141], v[210:213], v[26:29]
	v_mfma_f32_16x16x32_bf16 v[14:17], v[130:133], v[218:221], v[14:17]
	v_mfma_f32_16x16x32_bf16 v[10:13], v[138:141], v[218:221], v[10:13]
	v_mfma_f32_16x16x32_bf16 v[62:65], v[134:137], v[186:189], v[62:65]
	v_mfma_f32_16x16x32_bf16 v[58:61], v[142:145], v[186:189], v[58:61]
	v_mfma_f32_16x16x32_bf16 v[46:49], v[134:137], v[206:209], v[46:49]
	v_mfma_f32_16x16x32_bf16 v[42:45], v[142:145], v[206:209], v[42:45]
	v_mfma_f32_16x16x32_bf16 v[30:33], v[134:137], v[214:217], v[30:33]
	v_mfma_f32_16x16x32_bf16 v[26:29], v[142:145], v[214:217], v[26:29]
	v_mfma_f32_16x16x32_bf16 v[14:17], v[134:137], v[222:225], v[14:17]
	v_mfma_f32_16x16x32_bf16 v[10:13], v[142:145], v[222:225], v[10:13]
	s_setprio 0
	s_setprio 1
	v_mfma_f32_16x16x32_bf16 v[54:57], v[166:169], v[182:185], v[54:57]
	v_mfma_f32_16x16x32_bf16 v[50:53], v[174:177], v[182:185], v[50:53]
	v_mfma_f32_16x16x32_bf16 v[38:41], v[166:169], v[202:205], v[38:41]
	v_mfma_f32_16x16x32_bf16 v[34:37], v[174:177], v[202:205], v[34:37]
	v_mfma_f32_16x16x32_bf16 v[22:25], v[166:169], v[210:213], v[22:25]
	v_mfma_f32_16x16x32_bf16 v[18:21], v[174:177], v[210:213], v[18:21]
	v_mfma_f32_16x16x32_bf16 v[6:9], v[166:169], v[218:221], v[6:9]
	v_mfma_f32_16x16x32_bf16 v[2:5], v[174:177], v[218:221], v[2:5]
	v_mfma_f32_16x16x32_bf16 v[54:57], v[170:173], v[186:189], v[54:57]
	v_mfma_f32_16x16x32_bf16 v[50:53], v[178:181], v[186:189], v[50:53]
	v_mfma_f32_16x16x32_bf16 v[38:41], v[170:173], v[206:209], v[38:41]
	v_mfma_f32_16x16x32_bf16 v[34:37], v[178:181], v[206:209], v[34:37]
	v_mfma_f32_16x16x32_bf16 v[22:25], v[170:173], v[214:217], v[22:25]
	v_mfma_f32_16x16x32_bf16 v[18:21], v[178:181], v[214:217], v[18:21]
	v_mfma_f32_16x16x32_bf16 v[6:9], v[170:173], v[222:225], v[6:9]
	v_mfma_f32_16x16x32_bf16 v[2:5], v[178:181], v[222:225], v[2:5]
	s_setprio 0
	s_barrier
	s_add_i32 s13, s13, 2
	s_add_u32 s5, s5, 0x100
	s_addc_u32 s12, s12, 0
	s_cmpk_gt_u32 s13, 0x55
	s_mov_b64 s[16:17], s[54:55]

; __device__ __forceinline__ float row_rstd(const float* ss, int row) { return 1.0f / sqrtf(ss[row] * (1.0f / DM) + 1e-6f); }
; #define PG8_STAGE(bufoff, gbase, voff) do { _Pragma("unroll") for (int _i = 0; _i < 2; ++_i) \
;         __builtin_amdgcn_global_load_lds((const unsigned*)((const char*)(gbase) + (voff)[_i]), (LAS unsigned*)(lds + (bufoff) + ldsw + _i * 8192), 16, 0, 0); } while (0)
; #define PG8_WAIT_V(n) asm volatile("s_waitcnt vmcnt(" #n ")" ::: "memory")
; #define PG8_BAR __builtin_amdgcn_s_barrier()
;     __device__ __forceinline__ void operator()(const f32x4 (&acc)[2][2][4][2], const Unit& u, int wr, int wc, int fr, int fq) const {
;         const int row0 = u.pm * BM + wr * 64 + fr, col0 = u.pn * BM + wc * 64 + 8 * fq;
;         const bool lat = u.pm < ML / BM; const int s = lat ? (u.pm >> 5) : 4;
;         const float* bp = bias + (size_t)s * BIAS_N + col0;
;         const f32x4 b00 = *(const f32x4*)bp, b01 = *(const f32x4*)(bp + 4), b10 = *(const f32x4*)(bp + 32), b11 = *(const f32x4*)(bp + 36);
;         const int lane = fq * 16 + fr;
;         const float rsl0 = row_rstd(ss, u.pm * BM + wr * 64 + lane), rsl1 = row_rstd(ss, u.pm * BM + HALF + wr * 64 + lane);
;         const bool odd = (fr & 1) != 0;
;         const bool ktile = (u.pn == 2) || (u.pn == 3) || (u.pn == 12), wa = (u.pn == 12);
; template <class Epi, class Sched, bool ALIGN_EPI = false, bool SP2 = false>
; __device__ __forceinline__ void gemm_phase(LAS unsigned char* lds, const Gemm g, const Sched& S, const Epi& E) {
;     ...
;     if constexpr (SP2) {
;         PG8_STAGE(PG8_SB(0, 0), cB, voffB); PG8_STAGE(PG8_SB(0, 1), cB + hstepB, voffB); PG8_STAGE(PG8_SA(0, 0), cA, voffA); PG8_STAGE(PG8_SA(0, 1), cA + hstep, voffA);
;         if (wr == 1) PG8_BAR;
;         PG8_WAIT_V(2); PG8_BAR;
;         PG8_STAGE(PG8_SB(1, 0), cB + kstep, voffB); PG8_STAGE(PG8_SA(1, 0), cA + kstep, voffA); PG8_STAGE(PG8_SB(1, 1), cB + hstepB + kstep, voffB);
;         PG8_WAIT_V(6); PG8_BAR;
.LBB0_529:
	v_and_b32_e32 v184, 15, v10
	s_lshl_b32 s62, s11, 6
	v_bfe_u32 v17, v10, 4, 2
	v_or_b32_e32 v19, s62, v184
	v_lshlrev_b32_e32 v185, 4, v17
	v_lshlrev_b32_e32 v21, 2, v19
	s_and_b32 s3, s10, 3
	v_lshl_or_b32 v20, v184, 6, v185
	s_lshl_b32 s10, s11, 13
	v_and_b32_e32 v22, 32, v21
	v_lshlrev_b32_e32 v23, 2, v10
	v_bitop3_b32 v22, v20, s10, v22 bitop3:0xde
	s_lshl_b32 s10, s3, 12
	v_and_b32_e32 v23, 32, v23
	v_bitop3_b32 v186, v20, s10, v23 bitop3:0xde
	v_readlane_b32 s8, v253, 38
	v_readlane_b32 s9, v253, 39
	s_add_u32 s63, s8, 0x247000
	s_mov_b64 s[34:35], 0x80
	s_addc_u32 s64, s9, 0
	s_add_i32 m0, s30, 0x18000
	v_lshl_add_u64 v[8:9], v[8:9], 0, s[34:35]
	s_waitcnt vmcnt(2)
	s_barrier
	global_load_lds_dwordx4 v[8:9], off
	v_lshl_add_u64 v[6:7], v[6:7], 0, s[34:35]
	s_add_i32 m0, s30, 0x1a000
	s_add_i32 s65, s30, 0x8000
	s_add_i32 s66, s30, 0xa000
	global_load_lds_dwordx4 v[6:7], off
	v_lshl_add_u64 v[2:3], v[2:3], 0, s[34:35]
	s_mov_b32 m0, s65
	s_add_u32 s12, s48, 0x20080
	global_load_lds_dwordx4 v[2:3], off
	v_lshl_add_u64 v[2:3], v[4:5], 0, s[34:35]
	s_mov_b32 m0, s66
	s_addc_u32 s13, s49, 0
	global_load_lds_dwordx4 v[2:3], off
	s_add_i32 m0, s30, 0x1c000
	v_lshl_add_u64 v[2:3], s[12:13], 0, v[164:165]
	global_load_lds_dwordx4 v[2:3], off
	v_lshl_add_u64 v[2:3], s[12:13], 0, v[168:169]
	s_add_i32 m0, s30, 0x1e000
	s_cmpk_lt_u32 s0, 0x100
	global_load_lds_dwordx4 v[2:3], off
	s_cselect_b64 s[76:77], -1, 0
	s_lshl_b32 s14, s3, 6
	s_and_b32 s15, s14, 64
	v_and_b32_e32 v3, 1, v10
	s_bitcmp0_b32 s0, 6
	v_mov_b32_e32 v6, s3
	s_movk_i32 s0, 0x41
	v_lshlrev_b32_e32 v2, 5, v3
	v_cmp_eq_u32_e64 s[42:43], 1, v3
	v_or_b32_e32 v3, s3, v21
	v_bitop3_b32 v8, v21, s0, v6 bitop3:0x36
	s_movk_i32 s0, 0x81
	v_lshlrev_b32_e32 v18, 3, v17
	v_and_b32_e32 v187, 63, v10
	v_cmp_eq_u32_e64 s[38:39], 0, v17
	v_lshlrev_b32_e32 v5, 4, v19
	v_bfe_i32 v188, v10, 0, 1
	v_bitop3_b32 v189, v10, 1, v10 bitop3:0xc
	v_bitop3_b32 v9, v21, s0, v6 bitop3:0x36
	s_movk_i32 s0, 0xc1
	v_add_u32_e32 v10, 0x200, v3
	v_add_u32_e32 v17, 0x240, v3
	v_add_u32_e32 v19, 0x280, v3
	v_add_u32_e32 v3, 0x2c0, v3
	s_cselect_b64 s[40:41], -1, 0
	v_bitop3_b32 v6, v21, s0, v6 bitop3:0x36
	v_xor_b32_e32 v3, 1, v3
	s_add_i32 s0, 0, 0x25000
	v_lshl_add_u32 v201, v3, 2, s0
	v_lshlrev_b32_e32 v3, 15, v11
	v_and_b32_e32 v3, 0xffff0000, v3
	v_lshl_add_u32 v197, v6, 2, s0
	v_lshl_add_u32 v3, v12, 12, v3
	v_and_b32_e32 v6, 1, v11
	v_lshl_or_b32 v3, v6, 6, v3
	v_lshl_add_u32 v172, v13, 1, v3
	v_lshlrev_b32_e32 v3, 15, v14
	v_and_b32_e32 v3, 0xffff0000, v3
	v_lshl_add_u32 v3, v15, 12, v3
	v_and_b32_e32 v6, 1, v14
	s_waitcnt vmcnt(0)
	v_bitop3_b32 v7, v21, 1, s3 bitop3:0x36
	s_lshl_b32 s3, s3, 2
	v_lshl_or_b32 v3, v6, 6, v3
	v_cndmask_b32_e64 v4, 32, 0, s[42:43]
	v_xor_b32_e32 v10, 1, v10
	v_xor_b32_e32 v17, 1, v17
	v_xor_b32_e32 v19, 1, v19
	s_add_i32 s3, s0, s3
	v_lshl_add_u32 v174, v16, 1, v3
	s_add_i32 s68, 0, 0x10000
	s_add_i32 s69, 0, 0x14000
	v_mbcnt_lo_u32_b32 v3, -1, 0
	v_or_b32_e32 v190, 16, v184
	v_or_b32_e32 v191, 32, v184
	v_or_b32_e32 v192, 48, v184
	s_ashr_i32 s67, s26, 31
	v_or_b32_e32 v193, 0x80, v187
	v_lshl_add_u32 v194, v7, 2, s0
	v_lshl_add_u32 v195, v8, 2, s0
	v_lshl_add_u32 v196, v9, 2, s0
	v_lshl_add_u32 v198, v10, 2, s0
	v_lshl_add_u32 v199, v17, 2, s0
	v_lshl_add_u32 v200, v19, 2, s0
	v_or_b32_e32 v202, s14, v18
	v_mov_b32_e32 v173, v171
	v_mov_b32_e32 v175, v171
	v_mov_b64_e32 v[176:177], 0x738
	v_mov_b64_e32 v[178:179], 0x737
	v_add_u32_e32 v203, s68, v186
	v_add_u32_e32 v204, s69, v186
	v_add_u32_e32 v205, 0, v22
	v_mov_b32_e32 v206, 0x358637bd
	s_mov_b32 s70, 0xf800000
	v_mov_b32_e32 v207, 0x260
	v_mbcnt_hi_u32_b32 v208, -1, v3
	s_lshl_b32 s71, s15, 2
	v_lshlrev_b32_e32 v209, 2, v18
	s_movk_i32 s72, 0x1c00
	v_lshlrev_b32_e32 v170, 1, v2
	v_lshlrev_b32_e32 v180, 1, v4
	v_add_u32_e32 v210, s3, v5
	v_readlane_b32 s10, v253, 40
	v_readlane_b32 s11, v253, 41
	s_barrier
	s_branch .LBB0_532

;     __device__ bool next(int i, Unit& u) const { if (i != 0 || c >= 128) return false; const int t = c >> 2; u.pm = t & 3; u.pn = t >> 2; u.koff = koff_bytes; u.q = c & 3; return true; }
; #define PG8_STAGE(bufoff, gbase, voff) do { _Pragma("unroll") for (int _i = 0; _i < 2; ++_i) \
;         __builtin_amdgcn_global_load_lds((const unsigned*)((const char*)(gbase) + (voff)[_i]), (LAS unsigned*)(lds + (bufoff) + ldsw + _i * 8192), 16, 0, 0); } while (0)
; #define PG8_LDA(dst, b, h) do { _Pragma("unroll") for (int m = 0; m < 4; ++m) _Pragma("unroll") for (int k = 0; k < 2; ++k) dst[m][k] = *(const LAS bf16x8*)(lds + PG8_SA(b, h) + aoff + m * 2048 + k * 1024); } while (0)
; #define PG8_LDB(dst, b, h) do { _Pragma("unroll") for (int n = 0; n < 2; ++n) _Pragma("unroll") for (int k = 0; k < 2; ++k) dst[n][k] = *(const LAS bf16x8*)(lds + PG8_SB(b, h) + boff + n * 2048 + k * 1024); } while (0)
; #define PG8_WAIT_V(n) asm volatile("s_waitcnt vmcnt(" #n ")" ::: "memory")
; template <class Epi, class Sched, bool ALIGN_EPI = false, bool SP2 = false>
; __device__ __forceinline__ void gemm_phase(LAS unsigned char* lds, const Gemm g, const Sched& S, const Epi& E) {
;     ...
;         const bool has_next = S.next(ui + 1, nxt);
;         const char* nA = has_next ? (const char*)g.A + (size_t)nxt.pm * tstep + nxt.koff : cA; const char* nB = has_next ? (const char*)g.Bt + (size_t)nxt.pn * tstep + nxt.koff : cB;
;         for (int t = 0; t < nt; t += 2) {
;             const bool last = (t == nt - 2);
;             const char* a1 = cA + (size_t)(t + 1) * kstep;
;             const char* a2 = last ? nA : cA + (size_t)(t + 2) * kstep; const char* b2 = last ? nB : cB + (size_t)(t + 2) * kstep;
;             const char* a3 = a2 + kstep; const char* b3 = b2 + kstep;
;             if (last && has_next) S.a_ready(nxt);
;             if constexpr (SP2) {
;             PG8_LDB(B0, 0, 0); PG8_LDB(B1, 0, 1); PG8_SCHED; PG8_LDA(At, 0, 0); PG8_STAGE(PG8_SA(1, 1), a1 + hstep, voffA);
;             PG8_WAIT_V(8); PG8_WAIT_L(0); PG8_BAR; PG8_MMA(0, 0, At, B0); PG8_MMA(0, 1, At, B1); PG8_BAR; PG8_SCHED;
;             PG8_LDA(At, 0, 1); PG8_STAGE(PG8_SB(0, 0), b2, voffB); PG8_STAGE(PG8_SB(0, 1), b2 + hstepB, voffB); PG8_STAGE(PG8_SA(0, 0), a2, voffA);
;             PG8_WAIT_V(8); PG8_WAIT_L(0); PG8_BAR; PG8_MMA(1, 0, At, B0); PG8_MMA(1, 1, At, B1); PG8_BAR; PG8_SCHED;
.LBB0_534:
	s_ashr_i32 s53, s52, 31
	s_lshl_b64 s[14:15], s[52:53], 20
	s_add_u32 s54, s93, s14
	s_addc_u32 s55, s92, s15
	s_and_b64 s[14:15], s[44:45], exec
	s_cselect_b32 s0, s55, s17
	s_cselect_b32 s3, s54, s16
	s_ashr_i32 s51, s50, 31
	s_lshl_b64 s[14:15], s[50:51], 20
	s_add_u32 s56, s27, s14
	s_addc_u32 s57, s28, s15
	s_and_b64 s[14:15], s[44:45], exec
	s_cselect_b32 s14, s57, s49
	s_cselect_b32 s15, s56, s48
	s_add_u32 s16, s16, 0x80080
	s_addc_u32 s17, s17, 0
	s_add_u32 s18, s48, 0x100
	s_addc_u32 s19, s49, 0
	s_mov_b32 s20, -2
	ds_read_b128 v[34:37], v203
	ds_read_b128 v[38:41], v203 offset:1024
	ds_read_b128 v[42:45], v203 offset:2048
	ds_read_b128 v[46:49], v203 offset:3072
	s_waitcnt vmcnt(0)
	ds_read_b128 v[98:101], v204
	ds_read_b128 v[102:105], v204 offset:1024
	ds_read_b128 v[106:109], v204 offset:2048
	ds_read_b128 v[110:113], v204 offset:3072
	s_add_u32 s21, s16, 0xfff80080
	s_addc_u32 s22, s17, -1
	s_cmp_eq_u32 s20, 28
	s_cselect_b32 s59, s0, s22
	s_cselect_b32 s58, s3, s21
	s_cselect_b32 s49, s14, s19
	s_cselect_b32 s48, s15, s18
	v_lshl_add_u64 v[182:183], s[16:17], 0, v[172:173]
	s_add_i32 m0, s30, 0xc000
	ds_read_b128 v[212:215], v205
	ds_read_b128 v[216:219], v205 offset:1024
	ds_read_b128 v[220:223], v205 offset:2048
	ds_read_b128 v[224:227], v205 offset:3072
	ds_read_b128 v[228:231], v205 offset:4096
	ds_read_b128 v[232:235], v205 offset:5120
	ds_read_b128 v[236:239], v205 offset:6144
	ds_read_b128 v[240:243], v205 offset:7168
	global_load_lds_dwordx4 v[182:183], off
	v_lshl_add_u64 v[182:183], s[16:17], 0, v[174:175]
	s_add_i32 m0, s30, 0xe000
	s_nop 0
	global_load_lds_dwordx4 v[182:183], off
	s_waitcnt lgkmcnt(0)
	s_barrier
	s_setprio 1
	s_waitcnt lgkmcnt(0)
	v_mfma_f32_16x16x32_bf16 v[158:161], v[34:37], v[212:215], 0
	v_mfma_f32_16x16x32_bf16 v[154:157], v[42:45], v[212:215], 0
	v_mfma_f32_16x16x32_bf16 v[142:145], v[34:37], v[220:223], 0
	v_mfma_f32_16x16x32_bf16 v[138:141], v[42:45], v[220:223], 0
	v_mfma_f32_16x16x32_bf16 v[126:129], v[34:37], v[228:231], 0
	v_mfma_f32_16x16x32_bf16 v[122:125], v[42:45], v[228:231], 0
	v_mfma_f32_16x16x32_bf16 v[94:97], v[34:37], v[236:239], 0
	v_mfma_f32_16x16x32_bf16 v[90:93], v[42:45], v[236:239], 0
	v_mfma_f32_16x16x32_bf16 v[158:161], v[38:41], v[216:219], v[158:161]
	v_mfma_f32_16x16x32_bf16 v[154:157], v[46:49], v[216:219], v[154:157]
	v_mfma_f32_16x16x32_bf16 v[142:145], v[38:41], v[224:227], v[142:145]
	v_mfma_f32_16x16x32_bf16 v[138:141], v[46:49], v[224:227], v[138:141]
	v_mfma_f32_16x16x32_bf16 v[126:129], v[38:41], v[232:235], v[126:129]
	v_mfma_f32_16x16x32_bf16 v[122:125], v[46:49], v[232:235], v[122:125]
	v_mfma_f32_16x16x32_bf16 v[94:97], v[38:41], v[240:243], v[94:97]
	v_mfma_f32_16x16x32_bf16 v[90:93], v[46:49], v[240:243], v[90:93]
	s_setprio 0
	s_setprio 1
	v_mfma_f32_16x16x32_bf16 v[150:153], v[98:101], v[212:215], 0
	v_mfma_f32_16x16x32_bf16 v[146:149], v[106:109], v[212:215], 0
	v_mfma_f32_16x16x32_bf16 v[134:137], v[98:101], v[220:223], 0
	v_mfma_f32_16x16x32_bf16 v[130:133], v[106:109], v[220:223], 0
	v_mfma_f32_16x16x32_bf16 v[118:121], v[98:101], v[228:231], 0
	v_mfma_f32_16x16x32_bf16 v[114:117], v[106:109], v[228:231], 0
	v_mfma_f32_16x16x32_bf16 v[86:89], v[98:101], v[236:239], 0
	v_mfma_f32_16x16x32_bf16 v[82:85], v[106:109], v[236:239], 0
	v_mfma_f32_16x16x32_bf16 v[150:153], v[102:105], v[216:219], v[150:153]
	v_mfma_f32_16x16x32_bf16 v[146:149], v[110:113], v[216:219], v[146:149]
	v_mfma_f32_16x16x32_bf16 v[134:137], v[102:105], v[224:227], v[134:137]
	v_mfma_f32_16x16x32_bf16 v[130:133], v[110:113], v[224:227], v[130:133]
	v_mfma_f32_16x16x32_bf16 v[118:121], v[102:105], v[232:235], v[118:121]
	v_mfma_f32_16x16x32_bf16 v[114:117], v[110:113], v[232:235], v[114:117]
	v_mfma_f32_16x16x32_bf16 v[86:89], v[102:105], v[240:243], v[86:89]
	v_mfma_f32_16x16x32_bf16 v[82:85], v[110:113], v[240:243], v[82:85]
	s_setprio 0
	s_barrier
	s_add_i32 s21, s68, s29
	v_lshl_add_u64 v[182:183], s[48:49], 0, v[164:165]
	s_mov_b32 m0, s21
	ds_read_b128 v[212:215], v205 offset:16384
	ds_read_b128 v[216:219], v205 offset:17408
	ds_read_b128 v[220:223], v205 offset:18432
	ds_read_b128 v[224:227], v205 offset:19456
	ds_read_b128 v[228:231], v205 offset:20480
	ds_read_b128 v[232:235], v205 offset:21504
	ds_read_b128 v[236:239], v205 offset:22528
	ds_read_b128 v[240:243], v205 offset:23552
	global_load_lds_dwordx4 v[182:183], off
	s_add_i32 m0, s21, 0x2000
	s_add_u32 s22, s48, 0x20000
	v_lshl_add_u64 v[244:245], s[48:49], 0, v[168:169]
	s_addc_u32 s23, s49, 0
	s_add_i32 s21, s69, s29
	global_load_lds_dwordx4 v[244:245], off
	v_lshl_add_u64 v[246:247], s[22:23], 0, v[164:165]
	s_mov_b32 m0, s21
	v_lshl_add_u64 v[248:249], s[58:59], 0, v[166:167]
	global_load_lds_dwordx4 v[246:247], off
	v_lshl_add_u64 v[246:247], s[22:23], 0, v[168:169]
	s_add_i32 m0, s21, 0x2000
	s_nop 0
	global_load_lds_dwordx4 v[246:247], off
	v_lshl_add_u64 v[246:247], s[58:59], 0, v[162:163]
	s_mov_b32 m0, s30
	s_nop 0
	global_load_lds_dwordx4 v[246:247], off
	s_mov_b32 m0, s31
	s_nop 0
	global_load_lds_dwordx4 v[248:249], off
	s_waitcnt lgkmcnt(0)
	s_barrier
; #define PG8_STAGE(bufoff, gbase, voff) do { _Pragma("unroll") for (int _i = 0; _i < 2; ++_i) \
;         __builtin_amdgcn_global_load_lds((const unsigned*)((const char*)(gbase) + (voff)[_i]), (LAS unsigned*)(lds + (bufoff) + ldsw + _i * 8192), 16, 0, 0); } while (0)
; #define PG8_LDA(dst, b, h) do { _Pragma("unroll") for (int m = 0; m < 4; ++m) _Pragma("unroll") for (int k = 0; k < 2; ++k) dst[m][k] = *(const LAS bf16x8*)(lds + PG8_SA(b, h) + aoff + m * 2048 + k * 1024); } while (0)
; #define PG8_LDB(dst, b, h) do { _Pragma("unroll") for (int n = 0; n < 2; ++n) _Pragma("unroll") for (int k = 0; k < 2; ++k) dst[n][k] = *(const LAS bf16x8*)(lds + PG8_SB(b, h) + boff + n * 2048 + k * 1024); } while (0)
; #define PG8_MMA(ai, bj, At, Bt) do { __builtin_amdgcn_s_setprio(1); _Pragma("unroll") for (int m = 0; m < 4; ++m) _Pragma("unroll") for (int n = 0; n < 2; ++n) _Pragma("unroll") for (int k = 0; k < 2; ++k) \
;         acc[ai][bj][m][n] = __builtin_amdgcn_mfma_f32_16x16x32_bf16(Bt[n][k], At[m][k], acc[ai][bj][m][n], 0, 0, 0); __builtin_amdgcn_s_setprio(0); } while (0)
; #define PG8_WAIT_V(n) asm volatile("s_waitcnt vmcnt(" #n ")" ::: "memory")
; #define PG8_WAIT_L(n) asm volatile("s_waitcnt lgkmcnt(" #n ")" ::: "memory")
; #define PG8_BAR __builtin_amdgcn_s_barrier()
; #define PG8_SCHED __builtin_amdgcn_sched_barrier(0)
; template <class Epi, class Sched, bool ALIGN_EPI = false, bool SP2 = false>
; __device__ __forceinline__ void gemm_phase(LAS unsigned char* lds, const Gemm g, const Sched& S, const Epi& E) {
;     ...
;             PG8_WAIT_V(8); PG8_WAIT_L(0); PG8_BAR; PG8_MMA(1, 0, At, B0); PG8_MMA(1, 1, At, B1); PG8_BAR; PG8_SCHED;
;             PG8_LDB(B0, 1, 0); PG8_LDB(B1, 1, 1); PG8_SCHED; PG8_LDA(At, 1, 0); PG8_STAGE(PG8_SA(0, 1), a2 + hstep, voffA);
;             PG8_WAIT_V(8); PG8_WAIT_L(0); PG8_BAR; PG8_MMA(0, 0, At, B0); PG8_MMA(0, 1, At, B1); PG8_BAR; PG8_SCHED;
	s_setprio 1
	s_waitcnt lgkmcnt(0)
	v_mfma_f32_16x16x32_bf16 v[78:81], v[34:37], v[212:215], 0
	v_mfma_f32_16x16x32_bf16 v[74:77], v[42:45], v[212:215], 0
	v_mfma_f32_16x16x32_bf16 v[62:65], v[34:37], v[220:223], 0
	v_mfma_f32_16x16x32_bf16 v[58:61], v[42:45], v[220:223], 0
	v_mfma_f32_16x16x32_bf16 v[30:33], v[34:37], v[228:231], 0
	v_mfma_f32_16x16x32_bf16 v[26:29], v[42:45], v[228:231], 0
	v_mfma_f32_16x16x32_bf16 v[14:17], v[34:37], v[236:239], 0
	v_mfma_f32_16x16x32_bf16 v[10:13], v[42:45], v[236:239], 0
	v_mfma_f32_16x16x32_bf16 v[78:81], v[38:41], v[216:219], v[78:81]
	v_mfma_f32_16x16x32_bf16 v[74:77], v[46:49], v[216:219], v[74:77]
	v_mfma_f32_16x16x32_bf16 v[62:65], v[38:41], v[224:227], v[62:65]
	v_mfma_f32_16x16x32_bf16 v[58:61], v[46:49], v[224:227], v[58:61]
	v_mfma_f32_16x16x32_bf16 v[30:33], v[38:41], v[232:235], v[30:33]
	v_mfma_f32_16x16x32_bf16 v[26:29], v[46:49], v[232:235], v[26:29]
	v_mfma_f32_16x16x32_bf16 v[14:17], v[38:41], v[240:243], v[14:17]
	v_mfma_f32_16x16x32_bf16 v[10:13], v[46:49], v[240:243], v[10:13]
	s_setprio 0
	s_setprio 1
	v_mfma_f32_16x16x32_bf16 v[22:25], v[98:101], v[228:231], 0
	v_mfma_f32_16x16x32_bf16 v[18:21], v[106:109], v[228:231], 0
	v_mfma_f32_16x16x32_bf16 v[6:9], v[98:101], v[236:239], 0
	v_mfma_f32_16x16x32_bf16 v[2:5], v[106:109], v[236:239], 0
	v_mfma_f32_16x16x32_bf16 v[34:37], v[98:101], v[212:215], 0
	v_mfma_f32_16x16x32_bf16 v[38:41], v[106:109], v[212:215], 0
	v_mfma_f32_16x16x32_bf16 v[42:45], v[98:101], v[220:223], 0
	v_mfma_f32_16x16x32_bf16 v[46:49], v[106:109], v[220:223], 0
	v_mfma_f32_16x16x32_bf16 v[22:25], v[102:105], v[232:235], v[22:25]
	v_mfma_f32_16x16x32_bf16 v[18:21], v[110:113], v[232:235], v[18:21]
	v_mfma_f32_16x16x32_bf16 v[6:9], v[102:105], v[240:243], v[6:9]
	v_mfma_f32_16x16x32_bf16 v[2:5], v[110:113], v[240:243], v[2:5]
	v_mfma_f32_16x16x32_bf16 v[34:37], v[102:105], v[216:219], v[34:37]
	v_mfma_f32_16x16x32_bf16 v[38:41], v[110:113], v[216:219], v[38:41]
	v_mfma_f32_16x16x32_bf16 v[42:45], v[102:105], v[224:227], v[42:45]
	v_mfma_f32_16x16x32_bf16 v[46:49], v[110:113], v[224:227], v[46:49]
	s_setprio 0
	s_barrier
	s_add_i32 s21, 0, 0x18000
	s_add_i32 s24, 0, 0x1c000
	v_add_u32_e32 v70, s21, v186
	v_add_u32_e32 v110, s24, v186
	ds_read_b128 v[50:53], v70
	ds_read_b128 v[54:57], v70 offset:1024
	ds_read_b128 v[66:69], v70 offset:2048
	ds_read_b128 v[70:73], v70 offset:3072
	ds_read_b128 v[98:101], v110
	ds_read_b128 v[102:105], v110 offset:1024
	ds_read_b128 v[106:109], v110 offset:2048
	ds_read_b128 v[110:113], v110 offset:3072
	s_add_u32 s22, s58, 0x80000
	s_addc_u32 s23, s59, 0
	s_mov_b32 m0, s33
	v_lshl_add_u64 v[250:251], s[22:23], 0, v[162:163]
	ds_read_b128 v[212:215], v205 offset:32768
	ds_read_b128 v[216:219], v205 offset:33792
	ds_read_b128 v[220:223], v205 offset:34816
	ds_read_b128 v[224:227], v205 offset:35840
	ds_read_b128 v[228:231], v205 offset:36864
	ds_read_b128 v[232:235], v205 offset:37888
	ds_read_b128 v[236:239], v205 offset:38912
	ds_read_b128 v[240:243], v205 offset:39936
	global_load_lds_dwordx4 v[250:251], off
	v_lshl_add_u64 v[250:251], s[22:23], 0, v[166:167]
	s_mov_b32 m0, s60
	s_nop 0
	global_load_lds_dwordx4 v[250:251], off
	s_waitcnt vmcnt(8)
	s_waitcnt lgkmcnt(0)
	s_barrier
	s_setprio 1
	s_waitcnt lgkmcnt(0)
	v_mfma_f32_16x16x32_bf16 v[158:161], v[50:53], v[212:215], v[158:161]
	v_mfma_f32_16x16x32_bf16 v[154:157], v[66:69], v[212:215], v[154:157]
	v_mfma_f32_16x16x32_bf16 v[142:145], v[50:53], v[220:223], v[142:145]
	v_mfma_f32_16x16x32_bf16 v[138:141], v[66:69], v[220:223], v[138:141]
	v_mfma_f32_16x16x32_bf16 v[126:129], v[50:53], v[228:231], v[126:129]
	v_mfma_f32_16x16x32_bf16 v[122:125], v[66:69], v[228:231], v[122:125]
	v_mfma_f32_16x16x32_bf16 v[94:97], v[50:53], v[236:239], v[94:97]
	v_mfma_f32_16x16x32_bf16 v[90:93], v[66:69], v[236:239], v[90:93]
	v_mfma_f32_16x16x32_bf16 v[158:161], v[54:57], v[216:219], v[158:161]
	v_mfma_f32_16x16x32_bf16 v[154:157], v[70:73], v[216:219], v[154:157]
	v_mfma_f32_16x16x32_bf16 v[142:145], v[54:57], v[224:227], v[142:145]
	v_mfma_f32_16x16x32_bf16 v[138:141], v[70:73], v[224:227], v[138:141]
	v_mfma_f32_16x16x32_bf16 v[126:129], v[54:57], v[232:235], v[126:129]
	v_mfma_f32_16x16x32_bf16 v[122:125], v[70:73], v[232:235], v[122:125]
	v_mfma_f32_16x16x32_bf16 v[94:97], v[54:57], v[240:243], v[94:97]
	v_mfma_f32_16x16x32_bf16 v[90:93], v[70:73], v[240:243], v[90:93]
	s_setprio 0
	s_setprio 1
	v_mfma_f32_16x16x32_bf16 v[150:153], v[98:101], v[212:215], v[150:153]
	v_mfma_f32_16x16x32_bf16 v[146:149], v[106:109], v[212:215], v[146:149]
	v_mfma_f32_16x16x32_bf16 v[134:137], v[98:101], v[220:223], v[134:137]
	v_mfma_f32_16x16x32_bf16 v[130:133], v[106:109], v[220:223], v[130:133]
	v_mfma_f32_16x16x32_bf16 v[118:121], v[98:101], v[228:231], v[118:121]
	v_mfma_f32_16x16x32_bf16 v[114:117], v[106:109], v[228:231], v[114:117]
	v_mfma_f32_16x16x32_bf16 v[86:89], v[98:101], v[236:239], v[86:89]
	v_mfma_f32_16x16x32_bf16 v[82:85], v[106:109], v[236:239], v[82:85]
	v_mfma_f32_16x16x32_bf16 v[150:153], v[102:105], v[216:219], v[150:153]
	v_mfma_f32_16x16x32_bf16 v[146:149], v[110:113], v[216:219], v[146:149]
	v_mfma_f32_16x16x32_bf16 v[134:137], v[102:105], v[224:227], v[134:137]
	v_mfma_f32_16x16x32_bf16 v[130:133], v[110:113], v[224:227], v[130:133]
	v_mfma_f32_16x16x32_bf16 v[118:121], v[102:105], v[232:235], v[118:121]
	v_mfma_f32_16x16x32_bf16 v[114:117], v[110:113], v[232:235], v[114:117]
	v_mfma_f32_16x16x32_bf16 v[86:89], v[102:105], v[240:243], v[86:89]
	v_mfma_f32_16x16x32_bf16 v[82:85], v[110:113], v[240:243], v[82:85]
	s_setprio 0
	s_barrier
; #define PG8_STAGE(bufoff, gbase, voff) do { _Pragma("unroll") for (int _i = 0; _i < 2; ++_i) \
;         __builtin_amdgcn_global_load_lds((const unsigned*)((const char*)(gbase) + (voff)[_i]), (LAS unsigned*)(lds + (bufoff) + ldsw + _i * 8192), 16, 0, 0); } while (0)
; #define PG8_LDA(dst, b, h) do { _Pragma("unroll") for (int m = 0; m < 4; ++m) _Pragma("unroll") for (int k = 0; k < 2; ++k) dst[m][k] = *(const LAS bf16x8*)(lds + PG8_SA(b, h) + aoff + m * 2048 + k * 1024); } while (0)
; #define PG8_LDB(dst, b, h) do { _Pragma("unroll") for (int n = 0; n < 2; ++n) _Pragma("unroll") for (int k = 0; k < 2; ++k) dst[n][k] = *(const LAS bf16x8*)(lds + PG8_SB(b, h) + boff + n * 2048 + k * 1024); } while (0)
; template <class Epi, class Sched, bool ALIGN_EPI = false, bool SP2 = false>
; __device__ __forceinline__ void gemm_phase(LAS unsigned char* lds, const Gemm g, const Sched& S, const Epi& E) {
;     ...
;         for (int t = 0; t < nt; t += 2) {
;             const bool last = (t == nt - 2);
;             const char* a1 = cA + (size_t)(t + 1) * kstep;
;             const char* a2 = last ? nA : cA + (size_t)(t + 2) * kstep; const char* b2 = last ? nB : cB + (size_t)(t + 2) * kstep;
;             const char* a3 = a2 + kstep; const char* b3 = b2 + kstep;
;             if (last && has_next) S.a_ready(nxt);
;             if constexpr (SP2) {
;             PG8_LDB(B0, 0, 0); PG8_LDB(B1, 0, 1); PG8_SCHED; PG8_LDA(At, 0, 0); PG8_STAGE(PG8_SA(1, 1), a1 + hstep, voffA);
;             PG8_WAIT_V(8); PG8_WAIT_L(0); PG8_BAR; PG8_MMA(0, 0, At, B0); PG8_MMA(0, 1, At, B1); PG8_BAR; PG8_SCHED;
;             PG8_LDA(At, 0, 1); PG8_STAGE(PG8_SB(0, 0), b2, voffB); PG8_STAGE(PG8_SB(0, 1), b2 + hstepB, voffB); PG8_STAGE(PG8_SA(0, 0), a2, voffA);
;             PG8_WAIT_V(8); PG8_WAIT_L(0); PG8_BAR; PG8_MMA(1, 0, At, B0); PG8_MMA(1, 1, At, B1); PG8_BAR; PG8_SCHED;
;             PG8_LDB(B0, 1, 0); PG8_LDB(B1, 1, 1); PG8_SCHED; PG8_LDA(At, 1, 0); PG8_STAGE(PG8_SA(0, 1), a2 + hstep, voffA);
;             PG8_WAIT_V(8); PG8_WAIT_L(0); PG8_BAR; PG8_MMA(0, 0, At, B0); PG8_MMA(0, 1, At, B1); PG8_BAR; PG8_SCHED;
;             PG8_LDA(At, 1, 1); PG8_STAGE(PG8_SB(1, 0), b3, voffB); PG8_STAGE(PG8_SB(1, 1), b3 + hstepB, voffB); PG8_STAGE(PG8_SA(1, 0), a3, voffA);
;             PG8_WAIT_V(8); PG8_WAIT_L(0); PG8_BAR; PG8_MMA(1, 0, At, B0); PG8_MMA(1, 1, At, B1); PG8_BAR; PG8_SCHED;
	s_add_i32 s21, s21, s29
	v_lshl_add_u64 v[182:183], v[182:183], 0, s[34:35]
	s_mov_b32 m0, s21
	ds_read_b128 v[212:215], v205 offset:49152
	ds_read_b128 v[216:219], v205 offset:50176
	ds_read_b128 v[220:223], v205 offset:51200
	ds_read_b128 v[224:227], v205 offset:52224
	ds_read_b128 v[228:231], v205 offset:53248
	ds_read_b128 v[232:235], v205 offset:54272
	ds_read_b128 v[236:239], v205 offset:55296
	ds_read_b128 v[240:243], v205 offset:56320
	global_load_lds_dwordx4 v[182:183], off
	s_add_i32 m0, s21, 0x2000
	s_add_u32 s22, s48, 0x20080
	v_lshl_add_u64 v[182:183], v[244:245], 0, s[34:35]
	s_addc_u32 s23, s49, 0
	s_add_i32 s21, s24, s29
	global_load_lds_dwordx4 v[182:183], off
	v_lshl_add_u64 v[182:183], s[22:23], 0, v[164:165]
	s_mov_b32 m0, s21
	s_nop 0
	global_load_lds_dwordx4 v[182:183], off
	v_lshl_add_u64 v[182:183], s[22:23], 0, v[168:169]
	s_add_i32 m0, s21, 0x2000
	s_nop 0
	global_load_lds_dwordx4 v[182:183], off
	v_lshl_add_u64 v[182:183], v[246:247], 0, s[34:35]
	s_mov_b32 m0, s65
	s_nop 0
	global_load_lds_dwordx4 v[182:183], off
	v_lshl_add_u64 v[182:183], v[248:249], 0, s[34:35]
	s_mov_b32 m0, s66
	s_nop 0
	global_load_lds_dwordx4 v[182:183], off
	s_waitcnt vmcnt(8)
	s_waitcnt lgkmcnt(0)
	s_barrier
	s_setprio 1
	s_waitcnt lgkmcnt(0)
	v_mfma_f32_16x16x32_bf16 v[78:81], v[50:53], v[212:215], v[78:81]
	v_mfma_f32_16x16x32_bf16 v[74:77], v[66:69], v[212:215], v[74:77]
	v_mfma_f32_16x16x32_bf16 v[62:65], v[50:53], v[220:223], v[62:65]
	v_mfma_f32_16x16x32_bf16 v[58:61], v[66:69], v[220:223], v[58:61]
	v_mfma_f32_16x16x32_bf16 v[30:33], v[50:53], v[228:231], v[30:33]
	v_mfma_f32_16x16x32_bf16 v[26:29], v[66:69], v[228:231], v[26:29]
	v_mfma_f32_16x16x32_bf16 v[14:17], v[50:53], v[236:239], v[14:17]
	v_mfma_f32_16x16x32_bf16 v[10:13], v[66:69], v[236:239], v[10:13]
	v_mfma_f32_16x16x32_bf16 v[78:81], v[54:57], v[216:219], v[78:81]
	v_mfma_f32_16x16x32_bf16 v[74:77], v[70:73], v[216:219], v[74:77]
	v_mfma_f32_16x16x32_bf16 v[62:65], v[54:57], v[224:227], v[62:65]
	v_mfma_f32_16x16x32_bf16 v[58:61], v[70:73], v[224:227], v[58:61]
	v_mfma_f32_16x16x32_bf16 v[30:33], v[54:57], v[232:235], v[30:33]
	v_mfma_f32_16x16x32_bf16 v[26:29], v[70:73], v[232:235], v[26:29]
	v_mfma_f32_16x16x32_bf16 v[14:17], v[54:57], v[240:243], v[14:17]
	v_mfma_f32_16x16x32_bf16 v[10:13], v[70:73], v[240:243], v[10:13]
	s_setprio 0
	s_setprio 1
	v_mfma_f32_16x16x32_bf16 v[34:37], v[98:101], v[212:215], v[34:37]
	v_mfma_f32_16x16x32_bf16 v[70:73], v[102:105], v[216:219], v[34:37]
	v_mfma_f32_16x16x32_bf16 v[34:37], v[106:109], v[212:215], v[38:41]
	v_mfma_f32_16x16x32_bf16 v[66:69], v[110:113], v[216:219], v[34:37]
	v_mfma_f32_16x16x32_bf16 v[34:37], v[98:101], v[220:223], v[42:45]
	v_mfma_f32_16x16x32_bf16 v[54:57], v[102:105], v[224:227], v[34:37]
	v_mfma_f32_16x16x32_bf16 v[34:37], v[106:109], v[220:223], v[46:49]
	v_mfma_f32_16x16x32_bf16 v[22:25], v[98:101], v[228:231], v[22:25]
	v_mfma_f32_16x16x32_bf16 v[18:21], v[106:109], v[228:231], v[18:21]
	v_mfma_f32_16x16x32_bf16 v[6:9], v[98:101], v[236:239], v[6:9]
	v_mfma_f32_16x16x32_bf16 v[2:5], v[106:109], v[236:239], v[2:5]
	v_mfma_f32_16x16x32_bf16 v[50:53], v[110:113], v[224:227], v[34:37]
	v_mfma_f32_16x16x32_bf16 v[22:25], v[102:105], v[232:235], v[22:25]
	v_mfma_f32_16x16x32_bf16 v[18:21], v[110:113], v[232:235], v[18:21]
	v_mfma_f32_16x16x32_bf16 v[6:9], v[102:105], v[240:243], v[6:9]
	v_mfma_f32_16x16x32_bf16 v[2:5], v[110:113], v[240:243], v[2:5]
	s_setprio 0
	s_barrier
	s_add_i32 s20, s20, 2
	s_add_u32 s16, s16, 0x100
	s_addc_u32 s17, s17, 0
	s_add_u32 s18, s18, 0x100
	s_addc_u32 s19, s19, 0
	s_cmp_gt_u32 s20, 29

; #define LAS __attribute__((address_space(3)))
; #define PG8_STAGE(bufoff, gbase, voff) do { _Pragma("unroll") for (int _i = 0; _i < 2; ++_i) \
;         __builtin_amdgcn_global_load_lds((const unsigned*)((const char*)(gbase) + (voff)[_i]), (LAS unsigned*)(lds + (bufoff) + ldsw + _i * 8192), 16, 0, 0); } while (0)
; #define PG8_WAIT_V(n) asm volatile("s_waitcnt vmcnt(" #n ")" ::: "memory")
; #define PG8_BAR __builtin_amdgcn_s_barrier()
;     __device__ __forceinline__ void operator()(const f32x4 (&acc)[2][2][4][2], const Unit& u, int wr, int wc, int fr, int fq) const {
;         const int s = u.pm >> 5, lane = fq * 16 + fr, rr = lane >> 3, pc = lane & 7;
;         const float* __restrict__ xi = xin + (size_t)u.pm * BM * DM; float* __restrict__ xo = xout + (size_t)u.pm * BM * DM; bf16_t* __restrict__ ho = Hn + (size_t)u.pm * BM * DM;
;         LAS unsigned char* st = lds_epi + (wr * 4 + wc) * 2304;
;         LAS float* sst = (LAS float*)(lds_epi + 18432 + (wr * 4 + wc) * 512);
;         const int colr = u.pn * BM + wc * 64 + 4 * pc;
;         const unsigned eb = (unsigned)((wr * 64 + rr) * DM + colr);
;         f32x4 gv[2], gsn[2];
; #pragma unroll
;         for (int bj = 0; bj < 2; ++bj) { gv[bj] = *(const f32x4*)(gate + (size_t)s * MODW + colr + bj * 32) * (0.5f * GS2);
;             if (!PLAIN) gsn[bj] = *(const f32x4*)(gnext + colr + bj * 32) * (*(const f32x4*)(scnext + (size_t)s * MODW + colr + bj * 32) + 1.0f); else gsn[bj] = gv[bj]; }
;         const unsigned wr_off = (unsigned)(fr * 144 + 16 * fq), rd_off = (unsigned)(rr * 144 + pc * 16);
; template <class Epi, class Sched, bool ALIGN_EPI = false, bool SP2 = false>
; __device__ __forceinline__ void gemm_phase(LAS unsigned char* lds, const Gemm g, const Sched& S, const Epi& E) {
;     ...
;     if constexpr (SP2) {
;         PG8_STAGE(PG8_SB(0, 0), cB, voffB); PG8_STAGE(PG8_SB(0, 1), cB + hstepB, voffB); PG8_STAGE(PG8_SA(0, 0), cA, voffA); PG8_STAGE(PG8_SA(0, 1), cA + hstep, voffA);
;         if (wr == 1) PG8_BAR;
;         PG8_WAIT_V(2); PG8_BAR;
;         PG8_STAGE(PG8_SB(1, 0), cB + kstep, voffB); PG8_STAGE(PG8_SA(1, 0), cA + kstep, voffA); PG8_STAGE(PG8_SB(1, 1), cB + hstepB + kstep, voffB);
;         PG8_WAIT_V(6); PG8_BAR;
.LBB0_1240:
	s_and_b32 s22, s8, 3
	s_lshl_b32 s18, s21, 6
	s_lshl_b32 s23, s21, 13
	s_lshl_b32 s19, s22, 12
	v_readlane_b32 s40, v253, 38
	v_readlane_b32 s41, v253, 39
	s_add_u32 s35, s40, 0x4a000
	v_readlane_b32 s0, v253, 2
	s_addc_u32 s36, s41, 0
	v_readlane_b32 s8, v253, 10
	v_readlane_b32 s12, v253, 14
	v_readlane_b32 s9, v253, 11
	v_readlane_b32 s13, v253, 15
	s_add_u32 s8, s12, 0x4000
	v_readlane_b32 s10, v253, 12
	v_readlane_b32 s11, v253, 13
	s_addc_u32 s9, s13, 0
	s_add_u32 s37, s40, 0x4e000
	s_mov_b64 s[10:11], 0x80
	s_addc_u32 s52, s41, 0
	s_add_i32 m0, s29, 0x18000
	v_lshl_add_u64 v[8:9], v[8:9], 0, s[10:11]
	s_waitcnt vmcnt(2)
	s_barrier
	global_load_lds_dwordx4 v[8:9], off
	v_lshl_add_u64 v[6:7], v[6:7], 0, s[10:11]
	s_add_i32 m0, s29, 0x1a000
	s_add_i32 s53, s29, 0x8000
	s_add_i32 s54, s29, 0xa000
	global_load_lds_dwordx4 v[6:7], off
	v_lshl_add_u64 v[2:3], v[2:3], 0, s[10:11]
	s_mov_b32 m0, s53
	s_add_u32 s12, s48, 0x20080
	global_load_lds_dwordx4 v[2:3], off
	v_lshl_add_u64 v[2:3], v[4:5], 0, s[10:11]
	s_mov_b32 m0, s54
	s_addc_u32 s13, s49, 0
	global_load_lds_dwordx4 v[2:3], off
	s_add_i32 m0, s29, 0x1c000
	v_lshl_add_u64 v[2:3], s[12:13], 0, v[156:157]
	global_load_lds_dwordx4 v[2:3], off
	v_lshl_add_u64 v[2:3], s[12:13], 0, v[160:161]
	s_add_i32 m0, s29, 0x1e000
	v_lshlrev_b32_e32 v4, 2, v10
	global_load_lds_dwordx4 v[2:3], off
	v_and_b32_e32 v2, 15, v10
	v_and_b32_e32 v3, 48, v10
	s_cmpk_lt_u32 s20, 0x100
	v_lshl_or_b32 v1, v2, 6, v3
	v_and_b32_e32 v4, 32, v4
	s_cselect_b64 s[12:13], -1, 0
	s_lshl_b32 s0, s21, 2
	v_readlane_b32 s14, v253, 16
	v_readlane_b32 s15, v253, 17
	v_bitop3_b32 v5, v1, s23, v4 bitop3:0xde
	v_bitop3_b32 v1, v1, s19, v4 bitop3:0xde
	s_or_b32 s0, s0, s22
	s_ashr_i32 s19, s18, 31
	s_mul_i32 s20, s0, 0x900
	s_lshl_b32 s0, s0, 9
	s_ashr_i32 s55, s72, 31
	s_lshl_b64 s[14:15], s[18:19], 2
	v_readlane_b32 s3, v253, 5
	s_add_u32 s14, s64, s14
	v_and_b32_e32 v4, 63, v10
	s_addc_u32 s15, s65, s15
	s_add_i32 s3, s20, 0
	v_and_b32_e32 v7, 7, v10
	v_lshlrev_b32_e32 v162, 2, v4
	s_add_i32 s3, s3, 0x20000
	s_add_i32 s0, s0, 0
	v_bfe_u32 v6, v10, 3, 3
	v_lshlrev_b32_e32 v8, 2, v7
	v_lshl_add_u64 v[164:165], s[14:15], 0, v[162:163]
	s_add_i32 s0, s0, 0x24800
	s_movk_i32 s14, 0x90
	v_mov_b32_e32 v4, s3
	v_lshl_or_b32 v192, s22, 6, v8
	v_or_b32_e32 v8, s18, v6
	v_cmp_gt_u32_e64 s[38:39], 8, v2
	v_cmp_lt_u32_e64 s[40:41], 7, v2
	v_mad_u32_u24 v2, v2, s14, v4
	v_mad_u32_u24 v4, v6, s14, v4
	v_lshl_add_u32 v194, v6, 2, s0
	v_lshlrev_b32_e32 v6, 15, v11
	v_readlane_b32 s42, v253, 40
	v_readlane_b32 s43, v253, 41
	v_and_b32_e32 v6, 0xffff0000, v6
	v_lshlrev_b32_e32 v193, 11, v8
	v_lshlrev_b32_e32 v8, 4, v7
	v_cmp_eq_u32_e64 s[42:43], 0, v7
	v_lshl_add_u32 v6, v12, 12, v6
	v_and_b32_e32 v7, 1, v11
	v_lshl_or_b32 v6, v7, 6, v6
	v_lshl_add_u32 v166, v13, 1, v6
	v_lshlrev_b32_e32 v6, 15, v14
	v_and_b32_e32 v6, 0xffff0000, v6
	s_waitcnt vmcnt(0)
	v_lshl_add_u32 v6, v15, 12, v6
	v_and_b32_e32 v7, 1, v14
	v_lshl_or_b32 v6, v7, 6, v6
	s_add_i32 s56, 0, 0x10000
	s_add_i32 s57, 0, 0x14000
	v_add_u32_e32 v198, 0, v5
	v_mbcnt_lo_u32_b32 v5, -1, 0
	v_add_u32_e32 v195, s0, v162
	v_mov_b32_e32 v167, v163
	v_lshl_add_u32 v168, v16, 1, v6
	v_mov_b32_e32 v169, v163
	v_mov_b64_e32 v[170:171], 0x400
	v_mov_b64_e32 v[172:173], 0x3ff
	v_add_u32_e32 v196, s56, v1
	v_add_u32_e32 v197, s57, v1
	v_mbcnt_hi_u32_b32 v199, -1, v5
	v_add_u32_e32 v200, v2, v3
	v_add_u32_e32 v201, v4, v8
	v_readlane_b32 s1, v253, 3
	v_readlane_b32 s2, v253, 4
	v_readlane_b32 s4, v253, 6
	v_readlane_b32 s5, v253, 7
	v_readlane_b32 s6, v253, 8
	v_readlane_b32 s7, v253, 9
	s_barrier
	s_branch .LBB0_1243

;     __device__ bool next(int i, Unit& u) const { if (i != 0 || c >= 128) return false; const int t = c >> 2; u.pm = t & 3; u.pn = t >> 2; u.koff = koff_bytes; u.q = c & 3; return true; }
; #define PG8_STAGE(bufoff, gbase, voff) do { _Pragma("unroll") for (int _i = 0; _i < 2; ++_i) \
;         __builtin_amdgcn_global_load_lds((const unsigned*)((const char*)(gbase) + (voff)[_i]), (LAS unsigned*)(lds + (bufoff) + ldsw + _i * 8192), 16, 0, 0); } while (0)
; #define PG8_LDA(dst, b, h) do { _Pragma("unroll") for (int m = 0; m < 4; ++m) _Pragma("unroll") for (int k = 0; k < 2; ++k) dst[m][k] = *(const LAS bf16x8*)(lds + PG8_SA(b, h) + aoff + m * 2048 + k * 1024); } while (0)
; #define PG8_LDB(dst, b, h) do { _Pragma("unroll") for (int n = 0; n < 2; ++n) _Pragma("unroll") for (int k = 0; k < 2; ++k) dst[n][k] = *(const LAS bf16x8*)(lds + PG8_SB(b, h) + boff + n * 2048 + k * 1024); } while (0)
; #define PG8_WAIT_V(n) asm volatile("s_waitcnt vmcnt(" #n ")" ::: "memory")
; template <class Epi, class Sched, bool ALIGN_EPI = false, bool SP2 = false>
; __device__ __forceinline__ void gemm_phase(LAS unsigned char* lds, const Gemm g, const Sched& S, const Epi& E) {
;     ...
;         const bool has_next = S.next(ui + 1, nxt);
;         const char* nA = has_next ? (const char*)g.A + (size_t)nxt.pm * tstep + nxt.koff : cA; const char* nB = has_next ? (const char*)g.Bt + (size_t)nxt.pn * tstep + nxt.koff : cB;
;         for (int t = 0; t < nt; t += 2) {
;             const bool last = (t == nt - 2);
;             const char* a1 = cA + (size_t)(t + 1) * kstep;
;             const char* a2 = last ? nA : cA + (size_t)(t + 2) * kstep; const char* b2 = last ? nB : cB + (size_t)(t + 2) * kstep;
;             const char* a3 = a2 + kstep; const char* b3 = b2 + kstep;
;             if (last && has_next) S.a_ready(nxt);
;             if constexpr (SP2) {
;             PG8_LDB(B0, 0, 0); PG8_LDB(B1, 0, 1); PG8_SCHED; PG8_LDA(At, 0, 0); PG8_STAGE(PG8_SA(1, 1), a1 + hstep, voffA);
;             PG8_WAIT_V(8); PG8_WAIT_L(0); PG8_BAR; PG8_MMA(0, 0, At, B0); PG8_MMA(0, 1, At, B1); PG8_BAR; PG8_SCHED;
;             PG8_LDA(At, 0, 1); PG8_STAGE(PG8_SB(0, 0), b2, voffB); PG8_STAGE(PG8_SB(0, 1), b2 + hstepB, voffB); PG8_STAGE(PG8_SA(0, 0), a2, voffA);
;             PG8_WAIT_V(8); PG8_WAIT_L(0); PG8_BAR; PG8_MMA(1, 0, At, B0); PG8_MMA(1, 1, At, B1); PG8_BAR; PG8_SCHED;
.LBB0_1249:
	s_ashr_i32 s19, s18, 31
	s_lshl_b64 s[20:21], s[18:19], 20
	v_readlane_b32 s0, v252, 25
	s_add_u32 s20, s0, s20
	v_readlane_b32 s0, v252, 26
	s_addc_u32 s21, s0, s21
	s_and_b64 s[22:23], s[44:45], exec
	s_cselect_b32 s0, s21, s17
	s_cselect_b32 s3, s20, s16
	s_ashr_i32 s15, s14, 31
	s_lshl_b64 s[22:23], s[14:15], 20
	s_add_u32 s22, s26, s22
	s_addc_u32 s23, s27, s23
	s_and_b64 s[24:25], s[44:45], exec
	s_cselect_b32 s15, s23, s49
	s_cselect_b32 s19, s22, s48
	s_add_u32 s16, s16, 0x80080
	s_addc_u32 s17, s17, 0
	s_add_u32 s24, s48, 0x100
	s_addc_u32 s25, s49, 0
	s_mov_b32 s47, -2
	s_waitcnt vmcnt(0)
	ds_read_b128 v[50:53], v196
	ds_read_b128 v[54:57], v196 offset:1024
	ds_read_b128 v[138:141], v196 offset:2048
	ds_read_b128 v[142:145], v196 offset:3072
	ds_read_b128 v[146:149], v197
	ds_read_b128 v[150:153], v197 offset:1024
	ds_read_b128 v[174:177], v197 offset:2048
	ds_read_b128 v[178:181], v197 offset:3072
	s_add_u32 s48, s16, 0xfff80080
	s_addc_u32 s49, s17, -1
	s_cmp_eq_u32 s47, 28
	s_cselect_b32 s51, s0, s49
	s_cselect_b32 s50, s3, s48
	s_cselect_b32 s49, s15, s25
	s_cselect_b32 s48, s19, s24
	v_lshl_add_u64 v[190:191], s[16:17], 0, v[166:167]
	s_add_i32 m0, s29, 0xc000
	ds_read_b128 v[182:185], v198
	ds_read_b128 v[186:189], v198 offset:1024
	ds_read_b128 v[202:205], v198 offset:2048
	ds_read_b128 v[206:209], v198 offset:3072
	ds_read_b128 v[210:213], v198 offset:4096
	ds_read_b128 v[214:217], v198 offset:5120
	ds_read_b128 v[218:221], v198 offset:6144
	ds_read_b128 v[222:225], v198 offset:7168
	global_load_lds_dwordx4 v[190:191], off
	v_lshl_add_u64 v[190:191], s[16:17], 0, v[168:169]
	s_add_i32 m0, s29, 0xe000
	s_nop 0
	global_load_lds_dwordx4 v[190:191], off
	s_waitcnt lgkmcnt(0)
	s_barrier
	s_setprio 1
	s_waitcnt lgkmcnt(0)
	v_mfma_f32_16x16x32_bf16 v[134:137], v[50:53], v[182:185], 0
	v_mfma_f32_16x16x32_bf16 v[130:133], v[138:141], v[182:185], 0
	v_mfma_f32_16x16x32_bf16 v[118:121], v[50:53], v[202:205], 0
	v_mfma_f32_16x16x32_bf16 v[114:117], v[138:141], v[202:205], 0
	v_mfma_f32_16x16x32_bf16 v[102:105], v[50:53], v[210:213], 0
	v_mfma_f32_16x16x32_bf16 v[98:101], v[138:141], v[210:213], 0
	v_mfma_f32_16x16x32_bf16 v[86:89], v[50:53], v[218:221], 0
	v_mfma_f32_16x16x32_bf16 v[82:85], v[138:141], v[218:221], 0
	v_mfma_f32_16x16x32_bf16 v[134:137], v[54:57], v[186:189], v[134:137]
	v_mfma_f32_16x16x32_bf16 v[130:133], v[142:145], v[186:189], v[130:133]
	v_mfma_f32_16x16x32_bf16 v[118:121], v[54:57], v[206:209], v[118:121]
	v_mfma_f32_16x16x32_bf16 v[114:117], v[142:145], v[206:209], v[114:117]
	v_mfma_f32_16x16x32_bf16 v[102:105], v[54:57], v[214:217], v[102:105]
	v_mfma_f32_16x16x32_bf16 v[98:101], v[142:145], v[214:217], v[98:101]
	v_mfma_f32_16x16x32_bf16 v[86:89], v[54:57], v[222:225], v[86:89]
	v_mfma_f32_16x16x32_bf16 v[82:85], v[142:145], v[222:225], v[82:85]
	s_setprio 0
	s_setprio 1
	v_mfma_f32_16x16x32_bf16 v[126:129], v[146:149], v[182:185], 0
	v_mfma_f32_16x16x32_bf16 v[122:125], v[174:177], v[182:185], 0
	v_mfma_f32_16x16x32_bf16 v[110:113], v[146:149], v[202:205], 0
	v_mfma_f32_16x16x32_bf16 v[106:109], v[174:177], v[202:205], 0
	v_mfma_f32_16x16x32_bf16 v[94:97], v[146:149], v[210:213], 0
	v_mfma_f32_16x16x32_bf16 v[90:93], v[174:177], v[210:213], 0
	v_mfma_f32_16x16x32_bf16 v[78:81], v[146:149], v[218:221], 0
	v_mfma_f32_16x16x32_bf16 v[74:77], v[174:177], v[218:221], 0
	v_mfma_f32_16x16x32_bf16 v[126:129], v[150:153], v[186:189], v[126:129]
	v_mfma_f32_16x16x32_bf16 v[122:125], v[178:181], v[186:189], v[122:125]
	v_mfma_f32_16x16x32_bf16 v[110:113], v[150:153], v[206:209], v[110:113]
	v_mfma_f32_16x16x32_bf16 v[106:109], v[178:181], v[206:209], v[106:109]
	v_mfma_f32_16x16x32_bf16 v[94:97], v[150:153], v[214:217], v[94:97]
	v_mfma_f32_16x16x32_bf16 v[90:93], v[178:181], v[214:217], v[90:93]
	v_mfma_f32_16x16x32_bf16 v[78:81], v[150:153], v[222:225], v[78:81]
	v_mfma_f32_16x16x32_bf16 v[74:77], v[178:181], v[222:225], v[74:77]
	s_setprio 0
	s_barrier
	s_add_i32 s58, s56, s28
	v_lshl_add_u64 v[190:191], s[48:49], 0, v[156:157]
	s_mov_b32 m0, s58
	ds_read_b128 v[182:185], v198 offset:16384
	ds_read_b128 v[186:189], v198 offset:17408
	ds_read_b128 v[202:205], v198 offset:18432
	ds_read_b128 v[206:209], v198 offset:19456
	ds_read_b128 v[210:213], v198 offset:20480
	ds_read_b128 v[214:217], v198 offset:21504
	ds_read_b128 v[218:221], v198 offset:22528
	ds_read_b128 v[222:225], v198 offset:23552
	global_load_lds_dwordx4 v[190:191], off
	s_add_i32 m0, s58, 0x2000
	s_add_u32 s58, s48, 0x20000
	v_lshl_add_u64 v[226:227], s[48:49], 0, v[160:161]
	s_addc_u32 s59, s49, 0
	s_add_i32 s60, s57, s28
	global_load_lds_dwordx4 v[226:227], off
	v_lshl_add_u64 v[228:229], s[58:59], 0, v[156:157]
	s_mov_b32 m0, s60
	v_lshl_add_u64 v[230:231], s[50:51], 0, v[158:159]
	global_load_lds_dwordx4 v[228:229], off
	v_lshl_add_u64 v[228:229], s[58:59], 0, v[160:161]
	s_add_i32 m0, s60, 0x2000
	s_nop 0
	global_load_lds_dwordx4 v[228:229], off
	v_lshl_add_u64 v[228:229], s[50:51], 0, v[154:155]
	s_mov_b32 m0, s29
	s_nop 0
	global_load_lds_dwordx4 v[228:229], off
	s_mov_b32 m0, s30
	s_nop 0
	global_load_lds_dwordx4 v[230:231], off
	s_waitcnt lgkmcnt(0)
	s_barrier
; #define PG8_STAGE(bufoff, gbase, voff) do { _Pragma("unroll") for (int _i = 0; _i < 2; ++_i) \
;         __builtin_amdgcn_global_load_lds((const unsigned*)((const char*)(gbase) + (voff)[_i]), (LAS unsigned*)(lds + (bufoff) + ldsw + _i * 8192), 16, 0, 0); } while (0)
; #define PG8_LDA(dst, b, h) do { _Pragma("unroll") for (int m = 0; m < 4; ++m) _Pragma("unroll") for (int k = 0; k < 2; ++k) dst[m][k] = *(const LAS bf16x8*)(lds + PG8_SA(b, h) + aoff + m * 2048 + k * 1024); } while (0)
; #define PG8_LDB(dst, b, h) do { _Pragma("unroll") for (int n = 0; n < 2; ++n) _Pragma("unroll") for (int k = 0; k < 2; ++k) dst[n][k] = *(const LAS bf16x8*)(lds + PG8_SB(b, h) + boff + n * 2048 + k * 1024); } while (0)
; #define PG8_MMA(ai, bj, At, Bt) do { __builtin_amdgcn_s_setprio(1); _Pragma("unroll") for (int m = 0; m < 4; ++m) _Pragma("unroll") for (int n = 0; n < 2; ++n) _Pragma("unroll") for (int k = 0; k < 2; ++k) \
;         acc[ai][bj][m][n] = __builtin_amdgcn_mfma_f32_16x16x32_bf16(Bt[n][k], At[m][k], acc[ai][bj][m][n], 0, 0, 0); __builtin_amdgcn_s_setprio(0); } while (0)
; #define PG8_WAIT_V(n) asm volatile("s_waitcnt vmcnt(" #n ")" ::: "memory")
; #define PG8_WAIT_L(n) asm volatile("s_waitcnt lgkmcnt(" #n ")" ::: "memory")
; #define PG8_BAR __builtin_amdgcn_s_barrier()
; #define PG8_SCHED __builtin_amdgcn_sched_barrier(0)
; template <class Epi, class Sched, bool ALIGN_EPI = false, bool SP2 = false>
; __device__ __forceinline__ void gemm_phase(LAS unsigned char* lds, const Gemm g, const Sched& S, const Epi& E) {
;     ...
;             PG8_WAIT_V(8); PG8_WAIT_L(0); PG8_BAR; PG8_MMA(1, 0, At, B0); PG8_MMA(1, 1, At, B1); PG8_BAR; PG8_SCHED;
;             PG8_LDB(B0, 1, 0); PG8_LDB(B1, 1, 1); PG8_SCHED; PG8_LDA(At, 1, 0); PG8_STAGE(PG8_SA(0, 1), a2 + hstep, voffA);
;             PG8_WAIT_V(8); PG8_WAIT_L(0); PG8_BAR; PG8_MMA(0, 0, At, B0); PG8_MMA(0, 1, At, B1); PG8_BAR; PG8_SCHED;
	s_setprio 1
	s_waitcnt lgkmcnt(0)
	v_mfma_f32_16x16x32_bf16 v[70:73], v[50:53], v[182:185], 0
	v_mfma_f32_16x16x32_bf16 v[66:69], v[138:141], v[182:185], 0
	v_mfma_f32_16x16x32_bf16 v[46:49], v[50:53], v[202:205], 0
	v_mfma_f32_16x16x32_bf16 v[42:45], v[138:141], v[202:205], 0
	v_mfma_f32_16x16x32_bf16 v[30:33], v[50:53], v[210:213], 0
	v_mfma_f32_16x16x32_bf16 v[26:29], v[138:141], v[210:213], 0
	v_mfma_f32_16x16x32_bf16 v[14:17], v[50:53], v[218:221], 0
	v_mfma_f32_16x16x32_bf16 v[10:13], v[138:141], v[218:221], 0
	v_mfma_f32_16x16x32_bf16 v[70:73], v[54:57], v[186:189], v[70:73]
	v_mfma_f32_16x16x32_bf16 v[66:69], v[142:145], v[186:189], v[66:69]
	v_mfma_f32_16x16x32_bf16 v[46:49], v[54:57], v[206:209], v[46:49]
	v_mfma_f32_16x16x32_bf16 v[42:45], v[142:145], v[206:209], v[42:45]
	v_mfma_f32_16x16x32_bf16 v[30:33], v[54:57], v[214:217], v[30:33]
	v_mfma_f32_16x16x32_bf16 v[26:29], v[142:145], v[214:217], v[26:29]
	v_mfma_f32_16x16x32_bf16 v[14:17], v[54:57], v[222:225], v[14:17]
	v_mfma_f32_16x16x32_bf16 v[10:13], v[142:145], v[222:225], v[10:13]
	s_setprio 0
	s_setprio 1
	v_mfma_f32_16x16x32_bf16 v[38:41], v[146:149], v[202:205], 0
	v_mfma_f32_16x16x32_bf16 v[34:37], v[174:177], v[202:205], 0
	v_mfma_f32_16x16x32_bf16 v[22:25], v[146:149], v[210:213], 0
	v_mfma_f32_16x16x32_bf16 v[18:21], v[174:177], v[210:213], 0
	v_mfma_f32_16x16x32_bf16 v[6:9], v[146:149], v[218:221], 0
	v_mfma_f32_16x16x32_bf16 v[2:5], v[174:177], v[218:221], 0
	v_mfma_f32_16x16x32_bf16 v[50:53], v[146:149], v[182:185], 0
	v_mfma_f32_16x16x32_bf16 v[54:57], v[174:177], v[182:185], 0
	v_mfma_f32_16x16x32_bf16 v[38:41], v[150:153], v[206:209], v[38:41]
	v_mfma_f32_16x16x32_bf16 v[34:37], v[178:181], v[206:209], v[34:37]
	v_mfma_f32_16x16x32_bf16 v[22:25], v[150:153], v[214:217], v[22:25]
	v_mfma_f32_16x16x32_bf16 v[18:21], v[178:181], v[214:217], v[18:21]
	v_mfma_f32_16x16x32_bf16 v[6:9], v[150:153], v[222:225], v[6:9]
	v_mfma_f32_16x16x32_bf16 v[2:5], v[178:181], v[222:225], v[2:5]
	v_mfma_f32_16x16x32_bf16 v[50:53], v[150:153], v[186:189], v[50:53]
	v_mfma_f32_16x16x32_bf16 v[54:57], v[178:181], v[186:189], v[54:57]
	s_setprio 0
	s_barrier
	s_add_i32 s58, 0, 0x18000
	s_add_i32 s59, 0, 0x1c000
	v_add_u32_e32 v142, s58, v1
	v_add_u32_e32 v162, s59, v1
	ds_read_b128 v[58:61], v142
	ds_read_b128 v[62:65], v142 offset:1024
	ds_read_b128 v[138:141], v142 offset:2048
	ds_read_b128 v[142:145], v142 offset:3072
	ds_read_b128 v[146:149], v162
	ds_read_b128 v[150:153], v162 offset:1024
	ds_read_b128 v[174:177], v162 offset:2048
	ds_read_b128 v[178:181], v162 offset:3072
	s_add_u32 s50, s50, 0x80000
	s_addc_u32 s51, s51, 0
	s_mov_b32 m0, s31
	v_lshl_add_u64 v[232:233], s[50:51], 0, v[154:155]
	ds_read_b128 v[182:185], v198 offset:32768
	ds_read_b128 v[186:189], v198 offset:33792
	ds_read_b128 v[202:205], v198 offset:34816
	ds_read_b128 v[206:209], v198 offset:35840
	ds_read_b128 v[210:213], v198 offset:36864
	ds_read_b128 v[214:217], v198 offset:37888
	ds_read_b128 v[218:221], v198 offset:38912
	ds_read_b128 v[222:225], v198 offset:39936
	global_load_lds_dwordx4 v[232:233], off
	v_lshl_add_u64 v[232:233], s[50:51], 0, v[158:159]
	s_mov_b32 m0, s33
	s_nop 0
	global_load_lds_dwordx4 v[232:233], off
	s_waitcnt vmcnt(8)
	s_waitcnt lgkmcnt(0)
	s_barrier
	s_setprio 1
	s_waitcnt lgkmcnt(0)
	v_mfma_f32_16x16x32_bf16 v[134:137], v[58:61], v[182:185], v[134:137]
	v_mfma_f32_16x16x32_bf16 v[130:133], v[138:141], v[182:185], v[130:133]
	v_mfma_f32_16x16x32_bf16 v[118:121], v[58:61], v[202:205], v[118:121]
	v_mfma_f32_16x16x32_bf16 v[114:117], v[138:141], v[202:205], v[114:117]
	v_mfma_f32_16x16x32_bf16 v[102:105], v[58:61], v[210:213], v[102:105]
	v_mfma_f32_16x16x32_bf16 v[98:101], v[138:141], v[210:213], v[98:101]
	v_mfma_f32_16x16x32_bf16 v[86:89], v[58:61], v[218:221], v[86:89]
	v_mfma_f32_16x16x32_bf16 v[82:85], v[138:141], v[218:221], v[82:85]
	v_mfma_f32_16x16x32_bf16 v[134:137], v[62:65], v[186:189], v[134:137]
	v_mfma_f32_16x16x32_bf16 v[130:133], v[142:145], v[186:189], v[130:133]
	v_mfma_f32_16x16x32_bf16 v[118:121], v[62:65], v[206:209], v[118:121]
	v_mfma_f32_16x16x32_bf16 v[114:117], v[142:145], v[206:209], v[114:117]
	v_mfma_f32_16x16x32_bf16 v[102:105], v[62:65], v[214:217], v[102:105]
	v_mfma_f32_16x16x32_bf16 v[98:101], v[142:145], v[214:217], v[98:101]
	v_mfma_f32_16x16x32_bf16 v[86:89], v[62:65], v[222:225], v[86:89]
	v_mfma_f32_16x16x32_bf16 v[82:85], v[142:145], v[222:225], v[82:85]
	s_setprio 0
	s_setprio 1
	v_mfma_f32_16x16x32_bf16 v[126:129], v[146:149], v[182:185], v[126:129]
	v_mfma_f32_16x16x32_bf16 v[122:125], v[174:177], v[182:185], v[122:125]
	v_mfma_f32_16x16x32_bf16 v[110:113], v[146:149], v[202:205], v[110:113]
	v_mfma_f32_16x16x32_bf16 v[106:109], v[174:177], v[202:205], v[106:109]
	v_mfma_f32_16x16x32_bf16 v[94:97], v[146:149], v[210:213], v[94:97]
	v_mfma_f32_16x16x32_bf16 v[90:93], v[174:177], v[210:213], v[90:93]
	v_mfma_f32_16x16x32_bf16 v[78:81], v[146:149], v[218:221], v[78:81]
	v_mfma_f32_16x16x32_bf16 v[74:77], v[174:177], v[218:221], v[74:77]
	v_mfma_f32_16x16x32_bf16 v[126:129], v[150:153], v[186:189], v[126:129]
	v_mfma_f32_16x16x32_bf16 v[122:125], v[178:181], v[186:189], v[122:125]
	v_mfma_f32_16x16x32_bf16 v[110:113], v[150:153], v[206:209], v[110:113]
	v_mfma_f32_16x16x32_bf16 v[106:109], v[178:181], v[206:209], v[106:109]
	v_mfma_f32_16x16x32_bf16 v[94:97], v[150:153], v[214:217], v[94:97]
	v_mfma_f32_16x16x32_bf16 v[90:93], v[178:181], v[214:217], v[90:93]
	v_mfma_f32_16x16x32_bf16 v[78:81], v[150:153], v[222:225], v[78:81]
	v_mfma_f32_16x16x32_bf16 v[74:77], v[178:181], v[222:225], v[74:77]
	s_setprio 0
	s_barrier
; #define PG8_STAGE(bufoff, gbase, voff) do { _Pragma("unroll") for (int _i = 0; _i < 2; ++_i) \
;         __builtin_amdgcn_global_load_lds((const unsigned*)((const char*)(gbase) + (voff)[_i]), (LAS unsigned*)(lds + (bufoff) + ldsw + _i * 8192), 16, 0, 0); } while (0)
; #define PG8_LDA(dst, b, h) do { _Pragma("unroll") for (int m = 0; m < 4; ++m) _Pragma("unroll") for (int k = 0; k < 2; ++k) dst[m][k] = *(const LAS bf16x8*)(lds + PG8_SA(b, h) + aoff + m * 2048 + k * 1024); } while (0)
; #define PG8_LDB(dst, b, h) do { _Pragma("unroll") for (int n = 0; n < 2; ++n) _Pragma("unroll") for (int k = 0; k < 2; ++k) dst[n][k] = *(const LAS bf16x8*)(lds + PG8_SB(b, h) + boff + n * 2048 + k * 1024); } while (0)
; template <class Epi, class Sched, bool ALIGN_EPI = false, bool SP2 = false>
; __device__ __forceinline__ void gemm_phase(LAS unsigned char* lds, const Gemm g, const Sched& S, const Epi& E) {
;     ...
;         for (int t = 0; t < nt; t += 2) {
;             const bool last = (t == nt - 2);
;             const char* a1 = cA + (size_t)(t + 1) * kstep;
;             const char* a2 = last ? nA : cA + (size_t)(t + 2) * kstep; const char* b2 = last ? nB : cB + (size_t)(t + 2) * kstep;
;             const char* a3 = a2 + kstep; const char* b3 = b2 + kstep;
;             if (last && has_next) S.a_ready(nxt);
;             if constexpr (SP2) {
;             PG8_LDB(B0, 0, 0); PG8_LDB(B1, 0, 1); PG8_SCHED; PG8_LDA(At, 0, 0); PG8_STAGE(PG8_SA(1, 1), a1 + hstep, voffA);
;             PG8_WAIT_V(8); PG8_WAIT_L(0); PG8_BAR; PG8_MMA(0, 0, At, B0); PG8_MMA(0, 1, At, B1); PG8_BAR; PG8_SCHED;
;             PG8_LDA(At, 0, 1); PG8_STAGE(PG8_SB(0, 0), b2, voffB); PG8_STAGE(PG8_SB(0, 1), b2 + hstepB, voffB); PG8_STAGE(PG8_SA(0, 0), a2, voffA);
;             PG8_WAIT_V(8); PG8_WAIT_L(0); PG8_BAR; PG8_MMA(1, 0, At, B0); PG8_MMA(1, 1, At, B1); PG8_BAR; PG8_SCHED;
;             PG8_LDB(B0, 1, 0); PG8_LDB(B1, 1, 1); PG8_SCHED; PG8_LDA(At, 1, 0); PG8_STAGE(PG8_SA(0, 1), a2 + hstep, voffA);
;             PG8_WAIT_V(8); PG8_WAIT_L(0); PG8_BAR; PG8_MMA(0, 0, At, B0); PG8_MMA(0, 1, At, B1); PG8_BAR; PG8_SCHED;
;             PG8_LDA(At, 1, 1); PG8_STAGE(PG8_SB(1, 0), b3, voffB); PG8_STAGE(PG8_SB(1, 1), b3 + hstepB, voffB); PG8_STAGE(PG8_SA(1, 0), a3, voffA);
;             PG8_WAIT_V(8); PG8_WAIT_L(0); PG8_BAR; PG8_MMA(1, 0, At, B0); PG8_MMA(1, 1, At, B1); PG8_BAR; PG8_SCHED;
	s_add_i32 s50, s58, s28
	v_lshl_add_u64 v[190:191], v[190:191], 0, s[10:11]
	s_mov_b32 m0, s50
	ds_read_b128 v[182:185], v198 offset:49152
	ds_read_b128 v[186:189], v198 offset:50176
	ds_read_b128 v[202:205], v198 offset:51200
	ds_read_b128 v[206:209], v198 offset:52224
	ds_read_b128 v[210:213], v198 offset:53248
	ds_read_b128 v[214:217], v198 offset:54272
	ds_read_b128 v[218:221], v198 offset:55296
	ds_read_b128 v[222:225], v198 offset:56320
	global_load_lds_dwordx4 v[190:191], off
	s_add_i32 m0, s50, 0x2000
	s_add_u32 s48, s48, 0x20080
	v_lshl_add_u64 v[190:191], v[226:227], 0, s[10:11]
	s_addc_u32 s49, s49, 0
	s_add_i32 s50, s59, s28
	global_load_lds_dwordx4 v[190:191], off
	v_lshl_add_u64 v[190:191], s[48:49], 0, v[156:157]
	s_mov_b32 m0, s50
	s_nop 0
	global_load_lds_dwordx4 v[190:191], off
	v_lshl_add_u64 v[190:191], s[48:49], 0, v[160:161]
	s_add_i32 m0, s50, 0x2000
	s_nop 0
	global_load_lds_dwordx4 v[190:191], off
	v_lshl_add_u64 v[190:191], v[228:229], 0, s[10:11]
	s_mov_b32 m0, s53
	s_nop 0
	global_load_lds_dwordx4 v[190:191], off
	v_lshl_add_u64 v[190:191], v[230:231], 0, s[10:11]
	s_mov_b32 m0, s54
	s_nop 0
	global_load_lds_dwordx4 v[190:191], off
	s_waitcnt vmcnt(8)
	s_waitcnt lgkmcnt(0)
	s_barrier
	s_setprio 1
	s_waitcnt lgkmcnt(0)
	v_mfma_f32_16x16x32_bf16 v[70:73], v[58:61], v[182:185], v[70:73]
	v_mfma_f32_16x16x32_bf16 v[66:69], v[138:141], v[182:185], v[66:69]
	v_mfma_f32_16x16x32_bf16 v[46:49], v[58:61], v[202:205], v[46:49]
	v_mfma_f32_16x16x32_bf16 v[42:45], v[138:141], v[202:205], v[42:45]
	v_mfma_f32_16x16x32_bf16 v[30:33], v[58:61], v[210:213], v[30:33]
	v_mfma_f32_16x16x32_bf16 v[26:29], v[138:141], v[210:213], v[26:29]
	v_mfma_f32_16x16x32_bf16 v[14:17], v[58:61], v[218:221], v[14:17]
	v_mfma_f32_16x16x32_bf16 v[10:13], v[138:141], v[218:221], v[10:13]
	v_mfma_f32_16x16x32_bf16 v[70:73], v[62:65], v[186:189], v[70:73]
	v_mfma_f32_16x16x32_bf16 v[66:69], v[142:145], v[186:189], v[66:69]
	v_mfma_f32_16x16x32_bf16 v[46:49], v[62:65], v[206:209], v[46:49]
	v_mfma_f32_16x16x32_bf16 v[42:45], v[142:145], v[206:209], v[42:45]
	v_mfma_f32_16x16x32_bf16 v[30:33], v[62:65], v[214:217], v[30:33]
	v_mfma_f32_16x16x32_bf16 v[26:29], v[142:145], v[214:217], v[26:29]
	v_mfma_f32_16x16x32_bf16 v[14:17], v[62:65], v[222:225], v[14:17]
	v_mfma_f32_16x16x32_bf16 v[10:13], v[142:145], v[222:225], v[10:13]
	s_setprio 0
	s_setprio 1
	v_mfma_f32_16x16x32_bf16 v[50:53], v[146:149], v[182:185], v[50:53]
	v_mfma_f32_16x16x32_bf16 v[62:65], v[150:153], v[186:189], v[50:53]
	v_mfma_f32_16x16x32_bf16 v[50:53], v[174:177], v[182:185], v[54:57]
	v_mfma_f32_16x16x32_bf16 v[38:41], v[146:149], v[202:205], v[38:41]
	v_mfma_f32_16x16x32_bf16 v[34:37], v[174:177], v[202:205], v[34:37]
	v_mfma_f32_16x16x32_bf16 v[22:25], v[146:149], v[210:213], v[22:25]
	v_mfma_f32_16x16x32_bf16 v[18:21], v[174:177], v[210:213], v[18:21]
	v_mfma_f32_16x16x32_bf16 v[6:9], v[146:149], v[218:221], v[6:9]
	v_mfma_f32_16x16x32_bf16 v[2:5], v[174:177], v[218:221], v[2:5]
	v_mfma_f32_16x16x32_bf16 v[58:61], v[178:181], v[186:189], v[50:53]
	v_mfma_f32_16x16x32_bf16 v[38:41], v[150:153], v[206:209], v[38:41]
	v_mfma_f32_16x16x32_bf16 v[34:37], v[178:181], v[206:209], v[34:37]
	v_mfma_f32_16x16x32_bf16 v[22:25], v[150:153], v[214:217], v[22:25]
	v_mfma_f32_16x16x32_bf16 v[18:21], v[178:181], v[214:217], v[18:21]
	v_mfma_f32_16x16x32_bf16 v[6:9], v[150:153], v[222:225], v[6:9]
	v_mfma_f32_16x16x32_bf16 v[2:5], v[178:181], v[222:225], v[2:5]
	s_setprio 0
	s_barrier
	s_add_i32 s47, s47, 2
	s_add_u32 s16, s16, 0x100
	s_addc_u32 s17, s17, 0
	s_add_u32 s24, s24, 0x100
	s_addc_u32 s25, s25, 0
	s_cmp_gt_u32 s47, 29

; __device__ __forceinline__ float row_rstd(const float* ss, int row) { return 1.0f / sqrtf(ss[row] * (1.0f / DM) + 1e-6f); }
; #define PG8_STAGE(bufoff, gbase, voff) do { _Pragma("unroll") for (int _i = 0; _i < 2; ++_i) \
;         __builtin_amdgcn_global_load_lds((const unsigned*)((const char*)(gbase) + (voff)[_i]), (LAS unsigned*)(lds + (bufoff) + ldsw + _i * 8192), 16, 0, 0); } while (0)
; #define PG8_WAIT_V(n) asm volatile("s_waitcnt vmcnt(" #n ")" ::: "memory")
; #define PG8_BAR __builtin_amdgcn_s_barrier()
;     __device__ __forceinline__ void operator()(const f32x4 (&acc)[2][2][4][2], const Unit& u, int wr, int wc, int fr, int fq) const {
;         const int row0 = u.pm * BM + wr * 64 + fr, col0 = u.pn * HALF + wc * 32 + 8 * fq;
;         const int s = (u.pm < ML / BM) ? (u.pm >> 5) : 4;
;         const float* bp = bias + (size_t)s * BIAS_N + u.pn * BM + wc * 32 + 8 * fq;
;         const f32x4 ba0 = *(const f32x4*)bp, ba1 = *(const f32x4*)(bp + 4), bb0 = *(const f32x4*)(bp + HALF), bb1 = *(const f32x4*)(bp + HALF + 4);
;         const int lane = fq * 16 + fr;
;         const float rsl0 = row_rstd(ss, u.pm * BM + wr * 64 + lane), rsl1 = row_rstd(ss, u.pm * BM + HALF + wr * 64 + lane);
; template <class Epi, class Sched, bool ALIGN_EPI = false, bool SP2 = false>
; __device__ __forceinline__ void gemm_phase(LAS unsigned char* lds, const Gemm g, const Sched& S, const Epi& E) {
;     ...
;     if constexpr (SP2) {
;         PG8_STAGE(PG8_SB(0, 0), cB, voffB); PG8_STAGE(PG8_SB(0, 1), cB + hstepB, voffB); PG8_STAGE(PG8_SA(0, 0), cA, voffA); PG8_STAGE(PG8_SA(0, 1), cA + hstep, voffA);
;         if (wr == 1) PG8_BAR;
;         PG8_WAIT_V(2); PG8_BAR;
;         PG8_STAGE(PG8_SB(1, 0), cB + kstep, voffB); PG8_STAGE(PG8_SA(1, 0), cA + kstep, voffA); PG8_STAGE(PG8_SB(1, 1), cB + hstepB + kstep, voffB);
;         PG8_WAIT_V(6); PG8_BAR;
.LBB0_1459:
	s_lshl_b32 s0, s0, 5
	s_and_b32 s14, s0, 0x60
	s_lshl_b32 s42, s8, 6
	s_lshl_b32 s3, s8, 13
	s_lshl_b32 s15, s14, 7
	s_add_u32 s43, s48, 0x27e000
	s_mov_b64 s[8:9], 0x80
	s_addc_u32 s44, s49, 0
	s_add_i32 m0, s33, 0x18000
	v_lshl_add_u64 v[8:9], v[8:9], 0, s[8:9]
	s_waitcnt vmcnt(2)
	s_barrier
	global_load_lds_dwordx4 v[8:9], off
	v_lshl_add_u64 v[6:7], v[6:7], 0, s[8:9]
	s_add_i32 m0, s33, 0x1a000
	s_add_i32 s45, s33, 0x8000
	s_add_i32 s46, s33, 0xa000
	global_load_lds_dwordx4 v[6:7], off
	v_lshl_add_u64 v[2:3], v[2:3], 0, s[8:9]
	s_mov_b32 m0, s45
	s_add_u32 s12, s22, 0x80080
	global_load_lds_dwordx4 v[2:3], off
	v_lshl_add_u64 v[2:3], v[4:5], 0, s[8:9]
	s_mov_b32 m0, s46
	s_addc_u32 s13, s23, 0
	global_load_lds_dwordx4 v[2:3], off
	s_add_i32 m0, s33, 0x1c000
	v_lshl_add_u64 v[2:3], s[12:13], 0, v[150:151]
	global_load_lds_dwordx4 v[2:3], off
	v_lshl_add_u64 v[2:3], s[12:13], 0, v[146:147]
	s_add_i32 m0, s33, 0x1e000
	v_and_b32_e32 v169, 15, v10
	global_load_lds_dwordx4 v[2:3], off
	v_bfe_u32 v3, v10, 4, 2
	v_lshlrev_b32_e32 v2, 3, v3
	v_lshlrev_b32_e32 v3, 4, v3
	v_lshlrev_b32_e32 v4, 2, v10
	v_lshl_or_b32 v3, v169, 6, v3
	v_and_b32_e32 v4, 32, v4
	v_bitop3_b32 v5, v3, s3, v4 bitop3:0xde
	v_bitop3_b32 v170, v3, s15, v4 bitop3:0xde
	v_lshlrev_b32_e32 v3, 15, v15
	v_and_b32_e32 v3, 0xffff0000, v3
	v_lshl_add_u32 v3, v14, 12, v3
	v_and_b32_e32 v4, 1, v15
	v_lshl_or_b32 v3, v4, 6, v3
	v_lshl_add_u32 v154, v16, 1, v3
	v_lshlrev_b32_e32 v3, 15, v11
	v_or_b32_e32 v173, s14, v2
	v_and_b32_e32 v3, 0xffff0000, v3
	v_lshlrev_b32_e32 v177, 2, v2
	v_mbcnt_lo_u32_b32 v2, -1, 0
	s_waitcnt vmcnt(0)
	s_cmpk_lt_u32 s11, 0x100
	v_lshl_add_u32 v3, v12, 12, v3
	v_and_b32_e32 v4, 1, v11
	v_mbcnt_hi_u32_b32 v2, -1, v2
	s_sext_i32_i16 s0, s10
	s_cselect_b64 s[10:11], -1, 0
	v_and_b32_e32 v171, 63, v10
	v_lshl_or_b32 v3, v4, 6, v3
	s_add_i32 s47, 0, 0x10000
	s_add_i32 s48, 0, 0x14000
	v_and_or_b32 v2, v2, 64, v169
	v_or_b32_e32 v172, 0x80, v171
	v_mov_b32_e32 v155, v151
	v_lshl_add_u32 v156, v13, 1, v3
	v_mov_b32_e32 v157, v151
	v_mov_b64_e32 v[158:159], 0x16b0
	v_mov_b64_e32 v[160:161], 0x16af
	v_add_u32_e32 v174, s47, v170
	v_add_u32_e32 v175, s48, v170
	v_add_u32_e32 v176, 0, v5
	s_movk_i32 s49, 0x2c00
	s_lshl_b32 s50, s14, 2
	v_mov_b32_e32 v178, 0x358637bd
	s_mov_b32 s51, 0xf800000
	v_mov_b32_e32 v179, 0x260
	v_lshlrev_b32_e32 v180, 2, v2
	s_barrier
	s_branch .LBB0_1462

; __device__ __forceinline__ float row_rstd(const float* ss, int row) { return 1.0f / sqrtf(ss[row] * (1.0f / DM) + 1e-6f); }
; #define PG8_STAGE(bufoff, gbase, voff) do { _Pragma("unroll") for (int _i = 0; _i < 2; ++_i) \
;         __builtin_amdgcn_global_load_lds((const unsigned*)((const char*)(gbase) + (voff)[_i]), (LAS unsigned*)(lds + (bufoff) + ldsw + _i * 8192), 16, 0, 0); } while (0)
; #define PG8_LDA(dst, b, h) do { _Pragma("unroll") for (int m = 0; m < 4; ++m) _Pragma("unroll") for (int k = 0; k < 2; ++k) dst[m][k] = *(const LAS bf16x8*)(lds + PG8_SA(b, h) + aoff + m * 2048 + k * 1024); } while (0)
; #define PG8_WAIT_V(n) asm volatile("s_waitcnt vmcnt(" #n ")" ::: "memory")
;     __device__ __forceinline__ void operator()(const f32x4 (&acc)[2][2][4][2], const Unit& u, int wr, int wc, int fr, int fq) const {
;     ...
;         const float* bp = bias + (size_t)s * BIAS_N + u.pn * BM + wc * 32 + 8 * fq;
;         const f32x4 ba0 = *(const f32x4*)bp, ba1 = *(const f32x4*)(bp + 4), bb0 = *(const f32x4*)(bp + HALF), bb1 = *(const f32x4*)(bp + HALF + 4);
;         const int lane = fq * 16 + fr;
;         const float rsl0 = row_rstd(ss, u.pm * BM + wr * 64 + lane), rsl1 = row_rstd(ss, u.pm * BM + HALF + wr * 64 + lane);
; template <class Epi, class Sched, bool ALIGN_EPI = false, bool SP2 = false>
; __device__ __forceinline__ void gemm_phase(LAS unsigned char* lds, const Gemm g, const Sched& S, const Epi& E) {
;     ...
;         for (int t = 0; t < nt; t += 2) {
;             const bool last = (t == nt - 2);
;             const char* a1 = cA + (size_t)(t + 1) * kstep;
;             const char* a2 = last ? nA : cA + (size_t)(t + 2) * kstep; const char* b2 = last ? nB : cB + (size_t)(t + 2) * kstep;
;             const char* a3 = a2 + kstep; const char* b3 = b2 + kstep;
;             if (last && has_next) S.a_ready(nxt);
;             if constexpr (SP2) {
;             PG8_LDB(B0, 0, 0); PG8_LDB(B1, 0, 1); PG8_SCHED; PG8_LDA(At, 0, 0); PG8_STAGE(PG8_SA(1, 1), a1 + hstep, voffA);
;             PG8_WAIT_V(8); PG8_WAIT_L(0); PG8_BAR; PG8_MMA(0, 0, At, B0); PG8_MMA(0, 1, At, B1); PG8_BAR; PG8_SCHED;
;             PG8_LDA(At, 0, 1); PG8_STAGE(PG8_SB(0, 0), b2, voffB); PG8_STAGE(PG8_SB(0, 1), b2 + hstepB, voffB); PG8_STAGE(PG8_SA(0, 0), a2, voffA);
;             PG8_WAIT_V(8); PG8_WAIT_L(0); PG8_BAR; PG8_MMA(1, 0, At, B0); PG8_MMA(1, 1, At, B1); PG8_BAR; PG8_SCHED;
.Lpre_up2l0:
	s_lshl_b64 s[98:99], s[98:99], 2
	s_add_u32 s98, s43, s98
	s_addc_u32 s99, s44, s99
	s_lshl_b32 s100, s0, 8
	s_ashr_i32 s101, s100, 31
	s_lshl_b64 s[100:101], s[100:101], 2
	s_add_u32 s98, s98, s100
	s_addc_u32 s99, s99, s101
	s_add_u32 s98, s98, s50
	s_addc_u32 s99, s99, 0
	s_lshl_b32 s100, s2, 8
	s_add_i32 s100, s100, s42
	v_or_b32_e32 v162, s100, v171
	v_ashrrev_i32_e32 v163, 31, v162
	v_lshl_add_u64 v[162:163], v[162:163], 2, s[64:65]
	v_add_u32_e32 v164, s100, v172
	v_ashrrev_i32_e32 v165, 31, v164
	v_lshl_add_u64 v[164:165], v[164:165], 2, s[64:65]
	global_load_dwordx4 v[234:237], v177, s[98:99] offset:16
	global_load_dwordx4 v[238:241], v177, s[98:99]
	global_load_dwordx4 v[242:245], v177, s[98:99] offset:528
	global_load_dwordx4 v[246:249], v177, s[98:99] offset:512
	global_load_dword v250, v[162:163], off
	global_load_dword v251, v[164:165], off
	ds_read_b128 v[66:69], v174
	ds_read_b128 v[70:73], v174 offset:1024
	ds_read_b128 v[74:77], v174 offset:2048
	ds_read_b128 v[78:81], v174 offset:3072
	ds_read_b128 v[162:165], v175
	ds_read_b128 v[182:185], v175 offset:1024
	ds_read_b128 v[186:189], v175 offset:2048
	ds_read_b128 v[190:193], v175 offset:3072
	s_add_u32 s22, s16, 0xfff80080
	s_addc_u32 s23, s17, -1
	s_cmp_eq_u32 s53, 28
	s_cselect_b32 s41, s3, s23
	s_cselect_b32 s40, s15, s22
	s_cselect_b32 s23, s13, s52
	s_cselect_b32 s22, s24, s25
	v_lshl_add_u64 v[166:167], s[16:17], 0, v[154:155]
	s_add_i32 m0, s33, 0xc000
	ds_read_b128 v[194:197], v176
	ds_read_b128 v[198:201], v176 offset:1024
	ds_read_b128 v[202:205], v176 offset:2048
	ds_read_b128 v[206:209], v176 offset:3072
	ds_read_b128 v[210:213], v176 offset:4096
	ds_read_b128 v[214:217], v176 offset:5120
	ds_read_b128 v[218:221], v176 offset:6144
	ds_read_b128 v[222:225], v176 offset:7168
	global_load_lds_dwordx4 v[166:167], off
	v_lshl_add_u64 v[166:167], s[16:17], 0, v[156:157]
	s_add_i32 m0, s33, 0xe000
	s_nop 0
	global_load_lds_dwordx4 v[166:167], off
	s_waitcnt lgkmcnt(0)
	s_barrier
	s_setprio 1
	s_waitcnt lgkmcnt(0)
	v_mfma_f32_16x16x32_bf16 v[142:145], v[66:69], v[194:197], 0
	v_mfma_f32_16x16x32_bf16 v[138:141], v[74:77], v[194:197], 0
	v_mfma_f32_16x16x32_bf16 v[126:129], v[66:69], v[202:205], 0
	v_mfma_f32_16x16x32_bf16 v[122:125], v[74:77], v[202:205], 0
	v_mfma_f32_16x16x32_bf16 v[110:113], v[66:69], v[210:213], 0
	v_mfma_f32_16x16x32_bf16 v[106:109], v[74:77], v[210:213], 0
	v_mfma_f32_16x16x32_bf16 v[94:97], v[66:69], v[218:221], 0
	v_mfma_f32_16x16x32_bf16 v[90:93], v[74:77], v[218:221], 0
	v_mfma_f32_16x16x32_bf16 v[142:145], v[70:73], v[198:201], v[142:145]
	v_mfma_f32_16x16x32_bf16 v[138:141], v[78:81], v[198:201], v[138:141]
	v_mfma_f32_16x16x32_bf16 v[126:129], v[70:73], v[206:209], v[126:129]
	v_mfma_f32_16x16x32_bf16 v[122:125], v[78:81], v[206:209], v[122:125]
	v_mfma_f32_16x16x32_bf16 v[110:113], v[70:73], v[214:217], v[110:113]
	v_mfma_f32_16x16x32_bf16 v[106:109], v[78:81], v[214:217], v[106:109]
	v_mfma_f32_16x16x32_bf16 v[94:97], v[70:73], v[222:225], v[94:97]
	v_mfma_f32_16x16x32_bf16 v[90:93], v[78:81], v[222:225], v[90:93]
	s_setprio 0
	s_setprio 1
	v_mfma_f32_16x16x32_bf16 v[134:137], v[162:165], v[194:197], 0
	v_mfma_f32_16x16x32_bf16 v[130:133], v[186:189], v[194:197], 0
	v_mfma_f32_16x16x32_bf16 v[118:121], v[162:165], v[202:205], 0
	v_mfma_f32_16x16x32_bf16 v[114:117], v[186:189], v[202:205], 0
	v_mfma_f32_16x16x32_bf16 v[102:105], v[162:165], v[210:213], 0
	v_mfma_f32_16x16x32_bf16 v[98:101], v[186:189], v[210:213], 0
	v_mfma_f32_16x16x32_bf16 v[86:89], v[162:165], v[218:221], 0
	v_mfma_f32_16x16x32_bf16 v[82:85], v[186:189], v[218:221], 0
	v_mfma_f32_16x16x32_bf16 v[134:137], v[182:185], v[198:201], v[134:137]
	v_mfma_f32_16x16x32_bf16 v[130:133], v[190:193], v[198:201], v[130:133]
	v_mfma_f32_16x16x32_bf16 v[118:121], v[182:185], v[206:209], v[118:121]
	v_mfma_f32_16x16x32_bf16 v[114:117], v[190:193], v[206:209], v[114:117]
	v_mfma_f32_16x16x32_bf16 v[102:105], v[182:185], v[214:217], v[102:105]
	v_mfma_f32_16x16x32_bf16 v[98:101], v[190:193], v[214:217], v[98:101]
	v_mfma_f32_16x16x32_bf16 v[86:89], v[182:185], v[222:225], v[86:89]
	v_mfma_f32_16x16x32_bf16 v[82:85], v[190:193], v[222:225], v[82:85]
	s_setprio 0
	s_barrier
	s_add_i32 s54, s47, s29
	v_lshl_add_u64 v[166:167], s[22:23], 0, v[150:151]
	s_mov_b32 m0, s54
	ds_read_b128 v[194:197], v176 offset:16384
	ds_read_b128 v[198:201], v176 offset:17408
	ds_read_b128 v[202:205], v176 offset:18432
	ds_read_b128 v[206:209], v176 offset:19456
	ds_read_b128 v[210:213], v176 offset:20480
	ds_read_b128 v[214:217], v176 offset:21504
	ds_read_b128 v[218:221], v176 offset:22528
	ds_read_b128 v[222:225], v176 offset:23552
	global_load_lds_dwordx4 v[166:167], off
	s_add_i32 m0, s54, 0x2000
	s_add_u32 s54, s22, 0x80000
	v_lshl_add_u64 v[226:227], s[22:23], 0, v[146:147]
	s_addc_u32 s55, s23, 0
	s_add_i32 s56, s48, s29
	global_load_lds_dwordx4 v[226:227], off
	v_lshl_add_u64 v[228:229], s[54:55], 0, v[150:151]
	s_mov_b32 m0, s56
	v_lshl_add_u64 v[230:231], s[40:41], 0, v[148:149]
	global_load_lds_dwordx4 v[228:229], off
	v_lshl_add_u64 v[228:229], s[54:55], 0, v[146:147]
	s_add_i32 m0, s56, 0x2000
	s_nop 0
	global_load_lds_dwordx4 v[228:229], off
	v_lshl_add_u64 v[228:229], s[40:41], 0, v[152:153]
	s_mov_b32 m0, s33
	s_nop 0
	global_load_lds_dwordx4 v[228:229], off
	s_mov_b32 m0, s34
	s_nop 0
	global_load_lds_dwordx4 v[230:231], off
	s_waitcnt lgkmcnt(0)
	s_barrier
; #define PG8_STAGE(bufoff, gbase, voff) do { _Pragma("unroll") for (int _i = 0; _i < 2; ++_i) \
;         __builtin_amdgcn_global_load_lds((const unsigned*)((const char*)(gbase) + (voff)[_i]), (LAS unsigned*)(lds + (bufoff) + ldsw + _i * 8192), 16, 0, 0); } while (0)
; #define PG8_LDA(dst, b, h) do { _Pragma("unroll") for (int m = 0; m < 4; ++m) _Pragma("unroll") for (int k = 0; k < 2; ++k) dst[m][k] = *(const LAS bf16x8*)(lds + PG8_SA(b, h) + aoff + m * 2048 + k * 1024); } while (0)
; #define PG8_LDB(dst, b, h) do { _Pragma("unroll") for (int n = 0; n < 2; ++n) _Pragma("unroll") for (int k = 0; k < 2; ++k) dst[n][k] = *(const LAS bf16x8*)(lds + PG8_SB(b, h) + boff + n * 2048 + k * 1024); } while (0)
; #define PG8_MMA(ai, bj, At, Bt) do { __builtin_amdgcn_s_setprio(1); _Pragma("unroll") for (int m = 0; m < 4; ++m) _Pragma("unroll") for (int n = 0; n < 2; ++n) _Pragma("unroll") for (int k = 0; k < 2; ++k) \
;         acc[ai][bj][m][n] = __builtin_amdgcn_mfma_f32_16x16x32_bf16(Bt[n][k], At[m][k], acc[ai][bj][m][n], 0, 0, 0); __builtin_amdgcn_s_setprio(0); } while (0)
; #define PG8_WAIT_V(n) asm volatile("s_waitcnt vmcnt(" #n ")" ::: "memory")
; #define PG8_WAIT_L(n) asm volatile("s_waitcnt lgkmcnt(" #n ")" ::: "memory")
; #define PG8_BAR __builtin_amdgcn_s_barrier()
; #define PG8_SCHED __builtin_amdgcn_sched_barrier(0)
; template <class Epi, class Sched, bool ALIGN_EPI = false, bool SP2 = false>
; __device__ __forceinline__ void gemm_phase(LAS unsigned char* lds, const Gemm g, const Sched& S, const Epi& E) {
;     ...
;             PG8_WAIT_V(8); PG8_WAIT_L(0); PG8_BAR; PG8_MMA(1, 0, At, B0); PG8_MMA(1, 1, At, B1); PG8_BAR; PG8_SCHED;
;             PG8_LDB(B0, 1, 0); PG8_LDB(B1, 1, 1); PG8_SCHED; PG8_LDA(At, 1, 0); PG8_STAGE(PG8_SA(0, 1), a2 + hstep, voffA);
;             PG8_WAIT_V(8); PG8_WAIT_L(0); PG8_BAR; PG8_MMA(0, 0, At, B0); PG8_MMA(0, 1, At, B1); PG8_BAR; PG8_SCHED;
	s_setprio 1
	s_waitcnt lgkmcnt(0)
	v_mfma_f32_16x16x32_bf16 v[62:65], v[66:69], v[194:197], 0
	v_mfma_f32_16x16x32_bf16 v[58:61], v[74:77], v[194:197], 0
	v_mfma_f32_16x16x32_bf16 v[46:49], v[66:69], v[202:205], 0
	v_mfma_f32_16x16x32_bf16 v[42:45], v[74:77], v[202:205], 0
	v_mfma_f32_16x16x32_bf16 v[30:33], v[66:69], v[210:213], 0
	v_mfma_f32_16x16x32_bf16 v[26:29], v[74:77], v[210:213], 0
	v_mfma_f32_16x16x32_bf16 v[14:17], v[66:69], v[218:221], 0
	v_mfma_f32_16x16x32_bf16 v[10:13], v[74:77], v[218:221], 0
	v_mfma_f32_16x16x32_bf16 v[62:65], v[70:73], v[198:201], v[62:65]
	v_mfma_f32_16x16x32_bf16 v[58:61], v[78:81], v[198:201], v[58:61]
	v_mfma_f32_16x16x32_bf16 v[46:49], v[70:73], v[206:209], v[46:49]
	v_mfma_f32_16x16x32_bf16 v[42:45], v[78:81], v[206:209], v[42:45]
	v_mfma_f32_16x16x32_bf16 v[30:33], v[70:73], v[214:217], v[30:33]
	v_mfma_f32_16x16x32_bf16 v[26:29], v[78:81], v[214:217], v[26:29]
	v_mfma_f32_16x16x32_bf16 v[14:17], v[70:73], v[222:225], v[14:17]
	v_mfma_f32_16x16x32_bf16 v[10:13], v[78:81], v[222:225], v[10:13]
	s_setprio 0
	s_setprio 1
	v_mfma_f32_16x16x32_bf16 v[54:57], v[162:165], v[194:197], 0
	v_mfma_f32_16x16x32_bf16 v[50:53], v[186:189], v[194:197], 0
	v_mfma_f32_16x16x32_bf16 v[38:41], v[162:165], v[202:205], 0
	v_mfma_f32_16x16x32_bf16 v[34:37], v[186:189], v[202:205], 0
	v_mfma_f32_16x16x32_bf16 v[22:25], v[162:165], v[210:213], 0
	v_mfma_f32_16x16x32_bf16 v[18:21], v[186:189], v[210:213], 0
	v_mfma_f32_16x16x32_bf16 v[6:9], v[162:165], v[218:221], 0
	v_mfma_f32_16x16x32_bf16 v[2:5], v[186:189], v[218:221], 0
	v_mfma_f32_16x16x32_bf16 v[54:57], v[182:185], v[198:201], v[54:57]
	v_mfma_f32_16x16x32_bf16 v[50:53], v[190:193], v[198:201], v[50:53]
	v_mfma_f32_16x16x32_bf16 v[38:41], v[182:185], v[206:209], v[38:41]
	v_mfma_f32_16x16x32_bf16 v[34:37], v[190:193], v[206:209], v[34:37]
	v_mfma_f32_16x16x32_bf16 v[22:25], v[182:185], v[214:217], v[22:25]
	v_mfma_f32_16x16x32_bf16 v[18:21], v[190:193], v[214:217], v[18:21]
	v_mfma_f32_16x16x32_bf16 v[6:9], v[182:185], v[222:225], v[6:9]
	v_mfma_f32_16x16x32_bf16 v[2:5], v[190:193], v[222:225], v[2:5]
	s_setprio 0
	s_barrier
	s_add_i32 s54, 0, 0x18000
	s_add_i32 s55, 0, 0x1c000
	v_add_u32_e32 v78, s54, v170
	v_add_u32_e32 v168, s55, v170
	ds_read_b128 v[66:69], v78
	ds_read_b128 v[70:73], v78 offset:1024
	ds_read_b128 v[74:77], v78 offset:2048
	ds_read_b128 v[78:81], v78 offset:3072
	ds_read_b128 v[162:165], v168
	ds_read_b128 v[182:185], v168 offset:1024
	ds_read_b128 v[186:189], v168 offset:2048
	ds_read_b128 v[190:193], v168 offset:3072
	s_add_u32 s40, s40, 0x80000
	s_addc_u32 s41, s41, 0
	s_mov_b32 m0, s35
	v_lshl_add_u64 v[232:233], s[40:41], 0, v[152:153]
	ds_read_b128 v[194:197], v176 offset:32768
	ds_read_b128 v[198:201], v176 offset:33792
	ds_read_b128 v[202:205], v176 offset:34816
	ds_read_b128 v[206:209], v176 offset:35840
	ds_read_b128 v[210:213], v176 offset:36864
	ds_read_b128 v[214:217], v176 offset:37888
	ds_read_b128 v[218:221], v176 offset:38912
	ds_read_b128 v[222:225], v176 offset:39936
	global_load_lds_dwordx4 v[232:233], off
	v_lshl_add_u64 v[232:233], s[40:41], 0, v[148:149]
	s_mov_b32 m0, s36
	s_nop 0
	global_load_lds_dwordx4 v[232:233], off
	s_waitcnt vmcnt(8)
	s_waitcnt lgkmcnt(0)
	s_barrier
	s_setprio 1
	s_waitcnt lgkmcnt(0)
	v_mfma_f32_16x16x32_bf16 v[142:145], v[66:69], v[194:197], v[142:145]
	v_mfma_f32_16x16x32_bf16 v[138:141], v[74:77], v[194:197], v[138:141]
	v_mfma_f32_16x16x32_bf16 v[126:129], v[66:69], v[202:205], v[126:129]
	v_mfma_f32_16x16x32_bf16 v[122:125], v[74:77], v[202:205], v[122:125]
	v_mfma_f32_16x16x32_bf16 v[110:113], v[66:69], v[210:213], v[110:113]
	v_mfma_f32_16x16x32_bf16 v[106:109], v[74:77], v[210:213], v[106:109]
	v_mfma_f32_16x16x32_bf16 v[94:97], v[66:69], v[218:221], v[94:97]
	v_mfma_f32_16x16x32_bf16 v[90:93], v[74:77], v[218:221], v[90:93]
	v_mfma_f32_16x16x32_bf16 v[142:145], v[70:73], v[198:201], v[142:145]
	v_mfma_f32_16x16x32_bf16 v[138:141], v[78:81], v[198:201], v[138:141]
	v_mfma_f32_16x16x32_bf16 v[126:129], v[70:73], v[206:209], v[126:129]
	v_mfma_f32_16x16x32_bf16 v[122:125], v[78:81], v[206:209], v[122:125]
	v_mfma_f32_16x16x32_bf16 v[110:113], v[70:73], v[214:217], v[110:113]
	v_mfma_f32_16x16x32_bf16 v[106:109], v[78:81], v[214:217], v[106:109]
	v_mfma_f32_16x16x32_bf16 v[94:97], v[70:73], v[222:225], v[94:97]
	v_mfma_f32_16x16x32_bf16 v[90:93], v[78:81], v[222:225], v[90:93]
	s_setprio 0
	s_setprio 1
	v_mfma_f32_16x16x32_bf16 v[134:137], v[162:165], v[194:197], v[134:137]
	v_mfma_f32_16x16x32_bf16 v[130:133], v[186:189], v[194:197], v[130:133]
	v_mfma_f32_16x16x32_bf16 v[118:121], v[162:165], v[202:205], v[118:121]
	v_mfma_f32_16x16x32_bf16 v[114:117], v[186:189], v[202:205], v[114:117]
	v_mfma_f32_16x16x32_bf16 v[102:105], v[162:165], v[210:213], v[102:105]
	v_mfma_f32_16x16x32_bf16 v[98:101], v[186:189], v[210:213], v[98:101]
	v_mfma_f32_16x16x32_bf16 v[86:89], v[162:165], v[218:221], v[86:89]
	v_mfma_f32_16x16x32_bf16 v[82:85], v[186:189], v[218:221], v[82:85]
	v_mfma_f32_16x16x32_bf16 v[134:137], v[182:185], v[198:201], v[134:137]
	v_mfma_f32_16x16x32_bf16 v[130:133], v[190:193], v[198:201], v[130:133]
	v_mfma_f32_16x16x32_bf16 v[118:121], v[182:185], v[206:209], v[118:121]
	v_mfma_f32_16x16x32_bf16 v[114:117], v[190:193], v[206:209], v[114:117]
	v_mfma_f32_16x16x32_bf16 v[102:105], v[182:185], v[214:217], v[102:105]
	v_mfma_f32_16x16x32_bf16 v[98:101], v[190:193], v[214:217], v[98:101]
	v_mfma_f32_16x16x32_bf16 v[86:89], v[182:185], v[222:225], v[86:89]
	v_mfma_f32_16x16x32_bf16 v[82:85], v[190:193], v[222:225], v[82:85]
	s_setprio 0
	s_barrier
; #define PG8_STAGE(bufoff, gbase, voff) do { _Pragma("unroll") for (int _i = 0; _i < 2; ++_i) \
;         __builtin_amdgcn_global_load_lds((const unsigned*)((const char*)(gbase) + (voff)[_i]), (LAS unsigned*)(lds + (bufoff) + ldsw + _i * 8192), 16, 0, 0); } while (0)
; #define PG8_LDA(dst, b, h) do { _Pragma("unroll") for (int m = 0; m < 4; ++m) _Pragma("unroll") for (int k = 0; k < 2; ++k) dst[m][k] = *(const LAS bf16x8*)(lds + PG8_SA(b, h) + aoff + m * 2048 + k * 1024); } while (0)
; #define PG8_MMA(ai, bj, At, Bt) do { __builtin_amdgcn_s_setprio(1); _Pragma("unroll") for (int m = 0; m < 4; ++m) _Pragma("unroll") for (int n = 0; n < 2; ++n) _Pragma("unroll") for (int k = 0; k < 2; ++k) \
;         acc[ai][bj][m][n] = __builtin_amdgcn_mfma_f32_16x16x32_bf16(Bt[n][k], At[m][k], acc[ai][bj][m][n], 0, 0, 0); __builtin_amdgcn_s_setprio(0); } while (0)
; #define PG8_WAIT_V(n) asm volatile("s_waitcnt vmcnt(" #n ")" ::: "memory")
; #define PG8_WAIT_L(n) asm volatile("s_waitcnt lgkmcnt(" #n ")" ::: "memory")
; #define PG8_BAR __builtin_amdgcn_s_barrier()
; #define PG8_SCHED __builtin_amdgcn_sched_barrier(0)
; template <class Epi, class Sched, bool ALIGN_EPI = false, bool SP2 = false>
; __device__ __forceinline__ void gemm_phase(LAS unsigned char* lds, const Gemm g, const Sched& S, const Epi& E) {
;     ...
;         for (int t = 0; t < nt; t += 2) {
;             const bool last = (t == nt - 2);
;             const char* a1 = cA + (size_t)(t + 1) * kstep;
;             const char* a2 = last ? nA : cA + (size_t)(t + 2) * kstep; const char* b2 = last ? nB : cB + (size_t)(t + 2) * kstep;
;     ...
;             PG8_LDA(At, 1, 1); PG8_STAGE(PG8_SB(1, 0), b3, voffB); PG8_STAGE(PG8_SB(1, 1), b3 + hstepB, voffB); PG8_STAGE(PG8_SA(1, 0), a3, voffA);
;             PG8_WAIT_V(8); PG8_WAIT_L(0); PG8_BAR; PG8_MMA(1, 0, At, B0); PG8_MMA(1, 1, At, B1); PG8_BAR; PG8_SCHED;
	s_add_i32 s40, s54, s29
	v_lshl_add_u64 v[166:167], v[166:167], 0, s[8:9]
	s_mov_b32 m0, s40
	ds_read_b128 v[194:197], v176 offset:49152
	ds_read_b128 v[198:201], v176 offset:50176
	ds_read_b128 v[202:205], v176 offset:51200
	ds_read_b128 v[206:209], v176 offset:52224
	ds_read_b128 v[210:213], v176 offset:53248
	ds_read_b128 v[214:217], v176 offset:54272
	ds_read_b128 v[218:221], v176 offset:55296
	ds_read_b128 v[222:225], v176 offset:56320
	global_load_lds_dwordx4 v[166:167], off
	s_add_i32 m0, s40, 0x2000
	s_add_u32 s22, s22, 0x80080
	v_lshl_add_u64 v[166:167], v[226:227], 0, s[8:9]
	s_addc_u32 s23, s23, 0
	s_add_i32 s40, s55, s29
	global_load_lds_dwordx4 v[166:167], off
	v_lshl_add_u64 v[166:167], s[22:23], 0, v[150:151]
	s_mov_b32 m0, s40
	s_nop 0
	global_load_lds_dwordx4 v[166:167], off
	v_lshl_add_u64 v[166:167], s[22:23], 0, v[146:147]
	s_add_i32 m0, s40, 0x2000
	s_nop 0
	global_load_lds_dwordx4 v[166:167], off
	v_lshl_add_u64 v[166:167], v[228:229], 0, s[8:9]
	s_mov_b32 m0, s45
	s_nop 0
	global_load_lds_dwordx4 v[166:167], off
	v_lshl_add_u64 v[166:167], v[230:231], 0, s[8:9]
	s_mov_b32 m0, s46
	s_nop 0
	global_load_lds_dwordx4 v[166:167], off
	s_waitcnt vmcnt(8)
	s_waitcnt lgkmcnt(0)
	s_barrier
	s_setprio 1
	s_waitcnt lgkmcnt(0)
	v_mfma_f32_16x16x32_bf16 v[62:65], v[66:69], v[194:197], v[62:65]
	v_mfma_f32_16x16x32_bf16 v[58:61], v[74:77], v[194:197], v[58:61]
	v_mfma_f32_16x16x32_bf16 v[46:49], v[66:69], v[202:205], v[46:49]
	v_mfma_f32_16x16x32_bf16 v[42:45], v[74:77], v[202:205], v[42:45]
	v_mfma_f32_16x16x32_bf16 v[30:33], v[66:69], v[210:213], v[30:33]
	v_mfma_f32_16x16x32_bf16 v[26:29], v[74:77], v[210:213], v[26:29]
	v_mfma_f32_16x16x32_bf16 v[14:17], v[66:69], v[218:221], v[14:17]
	v_mfma_f32_16x16x32_bf16 v[10:13], v[74:77], v[218:221], v[10:13]
	v_mfma_f32_16x16x32_bf16 v[62:65], v[70:73], v[198:201], v[62:65]
	v_mfma_f32_16x16x32_bf16 v[58:61], v[78:81], v[198:201], v[58:61]
	v_mfma_f32_16x16x32_bf16 v[46:49], v[70:73], v[206:209], v[46:49]
	v_mfma_f32_16x16x32_bf16 v[42:45], v[78:81], v[206:209], v[42:45]
	v_mfma_f32_16x16x32_bf16 v[30:33], v[70:73], v[214:217], v[30:33]
	v_mfma_f32_16x16x32_bf16 v[26:29], v[78:81], v[214:217], v[26:29]
	v_mfma_f32_16x16x32_bf16 v[14:17], v[70:73], v[222:225], v[14:17]
	v_mfma_f32_16x16x32_bf16 v[10:13], v[78:81], v[222:225], v[10:13]
	s_setprio 0
	s_setprio 1
	v_mfma_f32_16x16x32_bf16 v[54:57], v[162:165], v[194:197], v[54:57]
	v_mfma_f32_16x16x32_bf16 v[50:53], v[186:189], v[194:197], v[50:53]
	v_mfma_f32_16x16x32_bf16 v[38:41], v[162:165], v[202:205], v[38:41]
	v_mfma_f32_16x16x32_bf16 v[34:37], v[186:189], v[202:205], v[34:37]
	v_mfma_f32_16x16x32_bf16 v[22:25], v[162:165], v[210:213], v[22:25]
	v_mfma_f32_16x16x32_bf16 v[18:21], v[186:189], v[210:213], v[18:21]
	v_mfma_f32_16x16x32_bf16 v[6:9], v[162:165], v[218:221], v[6:9]
	v_mfma_f32_16x16x32_bf16 v[2:5], v[186:189], v[218:221], v[2:5]
	v_mfma_f32_16x16x32_bf16 v[54:57], v[182:185], v[198:201], v[54:57]
	v_mfma_f32_16x16x32_bf16 v[50:53], v[190:193], v[198:201], v[50:53]
	v_mfma_f32_16x16x32_bf16 v[38:41], v[182:185], v[206:209], v[38:41]
	v_mfma_f32_16x16x32_bf16 v[34:37], v[190:193], v[206:209], v[34:37]
	v_mfma_f32_16x16x32_bf16 v[22:25], v[182:185], v[214:217], v[22:25]
	v_mfma_f32_16x16x32_bf16 v[18:21], v[190:193], v[214:217], v[18:21]
	v_mfma_f32_16x16x32_bf16 v[6:9], v[182:185], v[222:225], v[6:9]
	v_mfma_f32_16x16x32_bf16 v[2:5], v[190:193], v[222:225], v[2:5]
	s_setprio 0
	s_barrier
	s_add_i32 s53, s53, 2
	s_add_u32 s16, s16, 0x100
	s_addc_u32 s17, s17, 0
	s_add_u32 s25, s25, 0x100
	s_addc_u32 s52, s52, 0
	s_cmp_gt_u32 s53, 29

; #define LAS __attribute__((address_space(3)))
; #define PG8_STAGE(bufoff, gbase, voff) do { _Pragma("unroll") for (int _i = 0; _i < 2; ++_i) \
;         __builtin_amdgcn_global_load_lds((const unsigned*)((const char*)(gbase) + (voff)[_i]), (LAS unsigned*)(lds + (bufoff) + ldsw + _i * 8192), 16, 0, 0); } while (0)
; #define PG8_WAIT_V(n) asm volatile("s_waitcnt vmcnt(" #n ")" ::: "memory")
; #define PG8_BAR __builtin_amdgcn_s_barrier()
;     __device__ __forceinline__ void operator()(const f32x4 (&acc)[2][2][4][2], const Unit& u, int wr, int wc, int fr, int fq) const {
;         const int s = u.pm >> 5, lane = fq * 16 + fr, rr = lane >> 3, pc = lane & 7;
;         const float* __restrict__ xi = xin + (size_t)u.pm * BM * DM; float* __restrict__ xo = xout + (size_t)u.pm * BM * DM; bf16_t* __restrict__ ho = Hn + (size_t)u.pm * BM * DM;
;         LAS unsigned char* st = lds_epi + (wr * 4 + wc) * 2304;
;         LAS float* sst = (LAS float*)(lds_epi + 18432 + (wr * 4 + wc) * 512);
;         const int colr = u.pn * BM + wc * 64 + 4 * pc;
;         const unsigned eb = (unsigned)((wr * 64 + rr) * DM + colr);
;         f32x4 gv[2], gsn[2];
; #pragma unroll
;         for (int bj = 0; bj < 2; ++bj) { gv[bj] = *(const f32x4*)(gate + (size_t)s * MODW + colr + bj * 32) * (0.5f * GS2);
;             if (!PLAIN) gsn[bj] = *(const f32x4*)(gnext + colr + bj * 32) * (*(const f32x4*)(scnext + (size_t)s * MODW + colr + bj * 32) + 1.0f); else gsn[bj] = gv[bj]; }
;         const unsigned wr_off = (unsigned)(fr * 144 + 16 * fq), rd_off = (unsigned)(rr * 144 + pc * 16);
;         const bool odd = (rr & 1) != 0;
; template <class Epi, class Sched, bool ALIGN_EPI = false, bool SP2 = false>
; __device__ __forceinline__ void gemm_phase(LAS unsigned char* lds, const Gemm g, const Sched& S, const Epi& E) {
;     ...
;     if constexpr (SP2) {
;         PG8_STAGE(PG8_SB(0, 0), cB, voffB); PG8_STAGE(PG8_SB(0, 1), cB + hstepB, voffB); PG8_STAGE(PG8_SA(0, 0), cA, voffA); PG8_STAGE(PG8_SA(0, 1), cA + hstep, voffA);
;         if (wr == 1) PG8_BAR;
;         PG8_WAIT_V(2); PG8_BAR;
;         PG8_STAGE(PG8_SB(1, 0), cB + kstep, voffB); PG8_STAGE(PG8_SA(1, 0), cA + kstep, voffA); PG8_STAGE(PG8_SB(1, 1), cB + hstepB + kstep, voffB);
;         PG8_WAIT_V(6); PG8_BAR;
.LBB0_1581:
	s_and_b32 s3, s3, 3
	s_lshl_b32 s22, s9, 6
	s_lshl_b32 s15, s9, 13
	s_lshl_b32 s19, s3, 12
	s_add_u32 s37, s48, 0x50000
	s_mov_b64 s[12:13], 0x80
	s_addc_u32 s48, s49, 0
	s_add_i32 m0, s31, 0x18000
	v_lshl_add_u64 v[8:9], v[8:9], 0, s[12:13]
	s_waitcnt vmcnt(2)
	s_barrier
	global_load_lds_dwordx4 v[8:9], off
	v_lshl_add_u64 v[4:5], v[4:5], 0, s[12:13]
	s_add_i32 m0, s31, 0x1a000
	s_add_i32 s49, s31, 0x8000
	s_add_i32 s50, s31, 0xa000
	global_load_lds_dwordx4 v[4:5], off
	v_lshl_add_u64 v[2:3], v[2:3], 0, s[12:13]
	s_mov_b32 m0, s49
	s_add_u32 s24, s20, 0x58080
	global_load_lds_dwordx4 v[2:3], off
	v_lshl_add_u64 v[2:3], v[6:7], 0, s[12:13]
	s_mov_b32 m0, s50
	s_addc_u32 s25, s21, 0
	global_load_lds_dwordx4 v[2:3], off
	s_add_i32 m0, s31, 0x1c000
	v_lshl_add_u64 v[2:3], s[24:25], 0, v[148:149]
	global_load_lds_dwordx4 v[2:3], off
	v_lshl_add_u64 v[2:3], s[24:25], 0, v[152:153]
	s_add_i32 m0, s31, 0x1e000
	v_and_b32_e32 v4, 48, v10
	global_load_lds_dwordx4 v[2:3], off
	v_and_b32_e32 v2, 15, v10
	v_lshlrev_b32_e32 v3, 2, v10
	v_lshl_or_b32 v1, v2, 6, v4
	v_and_b32_e32 v3, 32, v3
	s_cmpk_lt_u32 s14, 0x100
	v_bitop3_b32 v5, v1, s15, v3 bitop3:0xde
	s_cselect_b64 s[14:15], -1, 0
	v_and_b32_e32 v7, 7, v10
	s_lshl_b32 s9, s9, 2
	v_bfe_u32 v6, v10, 3, 3
	s_or_b32 s9, s9, s3
	v_lshlrev_b32_e32 v8, 2, v7
	s_ashr_i32 s23, s22, 31
	v_bitop3_b32 v1, v1, s19, v3 bitop3:0xde
	s_mul_i32 s19, s9, 0x900
	s_lshl_b32 s9, s9, 9
	v_lshl_or_b32 v192, s3, 6, v8
	v_or_b32_e32 v8, s22, v6
	s_ashr_i32 s51, s1, 31
	s_lshl_b64 s[22:23], s[22:23], 2
	s_add_u32 s22, s6, s22
	s_addc_u32 s23, s7, s23
	s_add_i32 s3, s19, 0
	v_and_b32_e32 v3, 63, v10
	s_add_i32 s3, s3, 0x20000
	v_lshlrev_b32_e32 v154, 2, v3
	s_movk_i32 s19, 0x90
	v_mov_b32_e32 v3, s3
	v_lshlrev_b32_e32 v193, 11, v8
	v_lshlrev_b32_e32 v8, 4, v7
	v_cmp_gt_u32_e64 s[38:39], 8, v2
	v_cmp_lt_u32_e64 s[40:41], 7, v2
	v_cmp_eq_u32_e64 s[42:43], 0, v7
	v_mad_u32_u24 v7, v2, s19, v3
	v_mad_u32_u24 v9, v6, s19, v3
	v_lshrrev_b32_e32 v3, 1, v11
	v_mul_lo_u32 v2, v12, s2
	v_lshl_add_u64 v[156:157], s[22:23], 0, v[154:155]
	s_add_i32 s9, s9, 0
	v_mad_u64_u32 v[2:3], s[22:23], v3, s18, v[2:3]
	s_add_i32 s9, s9, 0x24800
	v_or_b32_e32 v2, v2, v13
	v_add_u32_e32 v195, s9, v154
	v_add_lshl_u32 v154, v2, v14, 1
	v_lshrrev_b32_e32 v3, 1, v15
	v_mul_lo_u32 v2, v16, s2
	v_mad_u64_u32 v[2:3], s[2:3], v3, s18, v[2:3]
	s_waitcnt vmcnt(0)
	s_mov_b64 s[22:23], 0x160080
	v_or_b32_e32 v2, v2, v17
	v_lshl_add_u64 v[158:159], v[154:155], 0, s[22:23]
	v_add_lshl_u32 v154, v2, v18, 1
	s_add_i32 s52, 0, 0x10000
	s_add_i32 s53, 0, 0x14000
	v_mbcnt_lo_u32_b32 v2, -1, 0
	v_lshl_add_u32 v194, v6, 2, s9
	v_lshl_add_u64 v[160:161], v[154:155], 0, s[22:23]
	v_mov_b64_e32 v[162:163], 0x400
	v_mov_b64_e32 v[164:165], 0x3ff
	v_add_u32_e32 v196, s52, v1
	v_add_u32_e32 v197, s53, v1
	v_add_u32_e32 v198, 0, v5
	v_mbcnt_hi_u32_b32 v199, -1, v2
	v_add_u32_e32 v200, v7, v4
	v_add_u32_e32 v201, v9, v8
	s_barrier
	s_branch .LBB0_1584

; #define PG8_STAGE(bufoff, gbase, voff) do { _Pragma("unroll") for (int _i = 0; _i < 2; ++_i) \
;         __builtin_amdgcn_global_load_lds((const unsigned*)((const char*)(gbase) + (voff)[_i]), (LAS unsigned*)(lds + (bufoff) + ldsw + _i * 8192), 16, 0, 0); } while (0)
; #define PG8_LDA(dst, b, h) do { _Pragma("unroll") for (int m = 0; m < 4; ++m) _Pragma("unroll") for (int k = 0; k < 2; ++k) dst[m][k] = *(const LAS bf16x8*)(lds + PG8_SA(b, h) + aoff + m * 2048 + k * 1024); } while (0)
; #define PG8_LDB(dst, b, h) do { _Pragma("unroll") for (int n = 0; n < 2; ++n) _Pragma("unroll") for (int k = 0; k < 2; ++k) dst[n][k] = *(const LAS bf16x8*)(lds + PG8_SB(b, h) + boff + n * 2048 + k * 1024); } while (0)
; #define PG8_MMA(ai, bj, At, Bt) do { __builtin_amdgcn_s_setprio(1); _Pragma("unroll") for (int m = 0; m < 4; ++m) _Pragma("unroll") for (int n = 0; n < 2; ++n) _Pragma("unroll") for (int k = 0; k < 2; ++k) \
;         acc[ai][bj][m][n] = __builtin_amdgcn_mfma_f32_16x16x32_bf16(Bt[n][k], At[m][k], acc[ai][bj][m][n], 0, 0, 0); __builtin_amdgcn_s_setprio(0); } while (0)
; #define PG8_WAIT_V(n) asm volatile("s_waitcnt vmcnt(" #n ")" ::: "memory")
; #define PG8_WAIT_L(n) asm volatile("s_waitcnt lgkmcnt(" #n ")" ::: "memory")
; template <class Epi, class Sched, bool ALIGN_EPI = false, bool SP2 = false>
; __device__ __forceinline__ void gemm_phase(LAS unsigned char* lds, const Gemm g, const Sched& S, const Epi& E) {
;     ...
;         for (int t = 0; t < nt; t += 2) {
;             const bool last = (t == nt - 2);
;             const char* a1 = cA + (size_t)(t + 1) * kstep;
;             const char* a2 = last ? nA : cA + (size_t)(t + 2) * kstep; const char* b2 = last ? nB : cB + (size_t)(t + 2) * kstep;
;             const char* a3 = a2 + kstep; const char* b3 = b2 + kstep;
;             if (last && has_next) S.a_ready(nxt);
;             if constexpr (SP2) {
;             PG8_LDB(B0, 0, 0); PG8_LDB(B1, 0, 1); PG8_SCHED; PG8_LDA(At, 0, 0); PG8_STAGE(PG8_SA(1, 1), a1 + hstep, voffA);
;             PG8_WAIT_V(8); PG8_WAIT_L(0); PG8_BAR; PG8_MMA(0, 0, At, B0); PG8_MMA(0, 1, At, B1); PG8_BAR; PG8_SCHED;
;             PG8_LDA(At, 0, 1); PG8_STAGE(PG8_SB(0, 0), b2, voffB); PG8_STAGE(PG8_SB(0, 1), b2 + hstepB, voffB); PG8_STAGE(PG8_SA(0, 0), a2, voffA);
;             PG8_WAIT_V(8); PG8_WAIT_L(0); PG8_BAR; PG8_MMA(1, 0, At, B0); PG8_MMA(1, 1, At, B1); PG8_BAR; PG8_SCHED;
.LBB0_1594:
	s_add_u32 s9, s20, 0x100
	s_addc_u32 s24, s21, 0
	s_mov_b32 s25, -2
	s_waitcnt vmcnt(0)
	ds_read_b128 v[130:133], v196
	ds_read_b128 v[134:137], v196 offset:1024
	ds_read_b128 v[138:141], v196 offset:2048
	ds_read_b128 v[142:145], v196 offset:3072
	ds_read_b128 v[166:169], v197
	ds_read_b128 v[170:173], v197 offset:1024
	ds_read_b128 v[174:177], v197 offset:2048
	ds_read_b128 v[178:181], v197 offset:3072
	s_add_u32 s20, s16, 0x100
	s_addc_u32 s21, s17, 0
	s_cmpk_eq_i32 s25, 0x54
	s_cselect_b32 s47, s3, s21
	s_cselect_b32 s46, s2, s20
	s_cselect_b32 s23, s19, s24
	s_cselect_b32 s22, s18, s9
	v_lshl_add_u64 v[190:191], s[16:17], 0, v[158:159]
	s_add_i32 m0, s31, 0xc000
	ds_read_b128 v[182:185], v198
	ds_read_b128 v[186:189], v198 offset:1024
	ds_read_b128 v[202:205], v198 offset:2048
	ds_read_b128 v[206:209], v198 offset:3072
	ds_read_b128 v[210:213], v198 offset:4096
	ds_read_b128 v[214:217], v198 offset:5120
	ds_read_b128 v[218:221], v198 offset:6144
	ds_read_b128 v[222:225], v198 offset:7168
	global_load_lds_dwordx4 v[190:191], off
	v_lshl_add_u64 v[190:191], s[16:17], 0, v[160:161]
	s_add_i32 m0, s31, 0xe000
	s_nop 0
	global_load_lds_dwordx4 v[190:191], off
	s_waitcnt lgkmcnt(0)
	s_barrier
	s_setprio 1
	s_waitcnt lgkmcnt(0)
	v_mfma_f32_16x16x32_bf16 v[126:129], v[130:133], v[182:185], 0
	v_mfma_f32_16x16x32_bf16 v[122:125], v[138:141], v[182:185], 0
	v_mfma_f32_16x16x32_bf16 v[110:113], v[130:133], v[202:205], 0
	v_mfma_f32_16x16x32_bf16 v[106:109], v[138:141], v[202:205], 0
	v_mfma_f32_16x16x32_bf16 v[94:97], v[130:133], v[210:213], 0
	v_mfma_f32_16x16x32_bf16 v[90:93], v[138:141], v[210:213], 0
	v_mfma_f32_16x16x32_bf16 v[78:81], v[130:133], v[218:221], 0
	v_mfma_f32_16x16x32_bf16 v[74:77], v[138:141], v[218:221], 0
	v_mfma_f32_16x16x32_bf16 v[126:129], v[134:137], v[186:189], v[126:129]
	v_mfma_f32_16x16x32_bf16 v[122:125], v[142:145], v[186:189], v[122:125]
	v_mfma_f32_16x16x32_bf16 v[110:113], v[134:137], v[206:209], v[110:113]
	v_mfma_f32_16x16x32_bf16 v[106:109], v[142:145], v[206:209], v[106:109]
	v_mfma_f32_16x16x32_bf16 v[94:97], v[134:137], v[214:217], v[94:97]
	v_mfma_f32_16x16x32_bf16 v[90:93], v[142:145], v[214:217], v[90:93]
	v_mfma_f32_16x16x32_bf16 v[78:81], v[134:137], v[222:225], v[78:81]
	v_mfma_f32_16x16x32_bf16 v[74:77], v[142:145], v[222:225], v[74:77]
	s_setprio 0
	s_setprio 1
	v_mfma_f32_16x16x32_bf16 v[118:121], v[166:169], v[182:185], 0
	v_mfma_f32_16x16x32_bf16 v[114:117], v[174:177], v[182:185], 0
	v_mfma_f32_16x16x32_bf16 v[102:105], v[166:169], v[202:205], 0
	v_mfma_f32_16x16x32_bf16 v[98:101], v[174:177], v[202:205], 0
	v_mfma_f32_16x16x32_bf16 v[86:89], v[166:169], v[210:213], 0
	v_mfma_f32_16x16x32_bf16 v[82:85], v[174:177], v[210:213], 0
	v_mfma_f32_16x16x32_bf16 v[70:73], v[166:169], v[218:221], 0
	v_mfma_f32_16x16x32_bf16 v[66:69], v[174:177], v[218:221], 0
	v_mfma_f32_16x16x32_bf16 v[118:121], v[170:173], v[186:189], v[118:121]
	v_mfma_f32_16x16x32_bf16 v[114:117], v[178:181], v[186:189], v[114:117]
	v_mfma_f32_16x16x32_bf16 v[102:105], v[170:173], v[206:209], v[102:105]
	v_mfma_f32_16x16x32_bf16 v[98:101], v[178:181], v[206:209], v[98:101]
	v_mfma_f32_16x16x32_bf16 v[86:89], v[170:173], v[214:217], v[86:89]
	v_mfma_f32_16x16x32_bf16 v[82:85], v[178:181], v[214:217], v[82:85]
	v_mfma_f32_16x16x32_bf16 v[70:73], v[170:173], v[222:225], v[70:73]
	v_mfma_f32_16x16x32_bf16 v[66:69], v[178:181], v[222:225], v[66:69]
	s_setprio 0
	s_barrier
	s_add_i32 s16, s52, s30
	v_lshl_add_u64 v[190:191], s[22:23], 0, v[148:149]
	s_mov_b32 m0, s16
	ds_read_b128 v[182:185], v198 offset:16384
	ds_read_b128 v[186:189], v198 offset:17408
	ds_read_b128 v[202:205], v198 offset:18432
	ds_read_b128 v[206:209], v198 offset:19456
	ds_read_b128 v[210:213], v198 offset:20480
	ds_read_b128 v[214:217], v198 offset:21504
	ds_read_b128 v[218:221], v198 offset:22528
	ds_read_b128 v[222:225], v198 offset:23552
	global_load_lds_dwordx4 v[190:191], off
	s_add_i32 m0, s16, 0x2000
	s_add_u32 s16, s22, 0x58000
	v_lshl_add_u64 v[226:227], s[22:23], 0, v[152:153]
	s_addc_u32 s17, s23, 0
	s_add_i32 s56, s53, s30
	global_load_lds_dwordx4 v[226:227], off
	v_lshl_add_u64 v[228:229], s[16:17], 0, v[148:149]
	s_mov_b32 m0, s56
	v_lshl_add_u64 v[230:231], s[46:47], 0, v[150:151]
	global_load_lds_dwordx4 v[228:229], off
	v_lshl_add_u64 v[228:229], s[16:17], 0, v[152:153]
	s_add_i32 m0, s56, 0x2000
	s_nop 0
	global_load_lds_dwordx4 v[228:229], off
	v_lshl_add_u64 v[228:229], s[46:47], 0, v[146:147]
	s_mov_b32 m0, s31
	s_nop 0
	global_load_lds_dwordx4 v[228:229], off
	s_mov_b32 m0, s33
	s_nop 0
	global_load_lds_dwordx4 v[230:231], off
	s_waitcnt lgkmcnt(0)
	s_barrier
; #define PG8_STAGE(bufoff, gbase, voff) do { _Pragma("unroll") for (int _i = 0; _i < 2; ++_i) \
;         __builtin_amdgcn_global_load_lds((const unsigned*)((const char*)(gbase) + (voff)[_i]), (LAS unsigned*)(lds + (bufoff) + ldsw + _i * 8192), 16, 0, 0); } while (0)
; #define PG8_LDA(dst, b, h) do { _Pragma("unroll") for (int m = 0; m < 4; ++m) _Pragma("unroll") for (int k = 0; k < 2; ++k) dst[m][k] = *(const LAS bf16x8*)(lds + PG8_SA(b, h) + aoff + m * 2048 + k * 1024); } while (0)
; #define PG8_LDB(dst, b, h) do { _Pragma("unroll") for (int n = 0; n < 2; ++n) _Pragma("unroll") for (int k = 0; k < 2; ++k) dst[n][k] = *(const LAS bf16x8*)(lds + PG8_SB(b, h) + boff + n * 2048 + k * 1024); } while (0)
; #define PG8_MMA(ai, bj, At, Bt) do { __builtin_amdgcn_s_setprio(1); _Pragma("unroll") for (int m = 0; m < 4; ++m) _Pragma("unroll") for (int n = 0; n < 2; ++n) _Pragma("unroll") for (int k = 0; k < 2; ++k) \
;         acc[ai][bj][m][n] = __builtin_amdgcn_mfma_f32_16x16x32_bf16(Bt[n][k], At[m][k], acc[ai][bj][m][n], 0, 0, 0); __builtin_amdgcn_s_setprio(0); } while (0)
; #define PG8_WAIT_V(n) asm volatile("s_waitcnt vmcnt(" #n ")" ::: "memory")
; #define PG8_WAIT_L(n) asm volatile("s_waitcnt lgkmcnt(" #n ")" ::: "memory")
; #define PG8_BAR __builtin_amdgcn_s_barrier()
; #define PG8_SCHED __builtin_amdgcn_sched_barrier(0)
; template <class Epi, class Sched, bool ALIGN_EPI = false, bool SP2 = false>
; __device__ __forceinline__ void gemm_phase(LAS unsigned char* lds, const Gemm g, const Sched& S, const Epi& E) {
;     ...
;             PG8_WAIT_V(8); PG8_WAIT_L(0); PG8_BAR; PG8_MMA(1, 0, At, B0); PG8_MMA(1, 1, At, B1); PG8_BAR; PG8_SCHED;
;             PG8_LDB(B0, 1, 0); PG8_LDB(B1, 1, 1); PG8_SCHED; PG8_LDA(At, 1, 0); PG8_STAGE(PG8_SA(0, 1), a2 + hstep, voffA);
;             PG8_WAIT_V(8); PG8_WAIT_L(0); PG8_BAR; PG8_MMA(0, 0, At, B0); PG8_MMA(0, 1, At, B1); PG8_BAR; PG8_SCHED;
	s_setprio 1
	s_waitcnt lgkmcnt(0)
	v_mfma_f32_16x16x32_bf16 v[62:65], v[130:133], v[182:185], 0
	v_mfma_f32_16x16x32_bf16 v[58:61], v[138:141], v[182:185], 0
	v_mfma_f32_16x16x32_bf16 v[46:49], v[130:133], v[202:205], 0
	v_mfma_f32_16x16x32_bf16 v[42:45], v[138:141], v[202:205], 0
	v_mfma_f32_16x16x32_bf16 v[30:33], v[130:133], v[210:213], 0
	v_mfma_f32_16x16x32_bf16 v[26:29], v[138:141], v[210:213], 0
	v_mfma_f32_16x16x32_bf16 v[14:17], v[130:133], v[218:221], 0
	v_mfma_f32_16x16x32_bf16 v[10:13], v[138:141], v[218:221], 0
	v_mfma_f32_16x16x32_bf16 v[62:65], v[134:137], v[186:189], v[62:65]
	v_mfma_f32_16x16x32_bf16 v[58:61], v[142:145], v[186:189], v[58:61]
	v_mfma_f32_16x16x32_bf16 v[46:49], v[134:137], v[206:209], v[46:49]
	v_mfma_f32_16x16x32_bf16 v[42:45], v[142:145], v[206:209], v[42:45]
	v_mfma_f32_16x16x32_bf16 v[30:33], v[134:137], v[214:217], v[30:33]
	v_mfma_f32_16x16x32_bf16 v[26:29], v[142:145], v[214:217], v[26:29]
	v_mfma_f32_16x16x32_bf16 v[14:17], v[134:137], v[222:225], v[14:17]
	v_mfma_f32_16x16x32_bf16 v[10:13], v[142:145], v[222:225], v[10:13]
	s_setprio 0
	s_setprio 1
	v_mfma_f32_16x16x32_bf16 v[54:57], v[166:169], v[182:185], 0
	v_mfma_f32_16x16x32_bf16 v[50:53], v[174:177], v[182:185], 0
	v_mfma_f32_16x16x32_bf16 v[38:41], v[166:169], v[202:205], 0
	v_mfma_f32_16x16x32_bf16 v[34:37], v[174:177], v[202:205], 0
	v_mfma_f32_16x16x32_bf16 v[22:25], v[166:169], v[210:213], 0
	v_mfma_f32_16x16x32_bf16 v[18:21], v[174:177], v[210:213], 0
	v_mfma_f32_16x16x32_bf16 v[6:9], v[166:169], v[218:221], 0
	v_mfma_f32_16x16x32_bf16 v[2:5], v[174:177], v[218:221], 0
	v_mfma_f32_16x16x32_bf16 v[54:57], v[170:173], v[186:189], v[54:57]
	v_mfma_f32_16x16x32_bf16 v[50:53], v[178:181], v[186:189], v[50:53]
	v_mfma_f32_16x16x32_bf16 v[38:41], v[170:173], v[206:209], v[38:41]
	v_mfma_f32_16x16x32_bf16 v[34:37], v[178:181], v[206:209], v[34:37]
	v_mfma_f32_16x16x32_bf16 v[22:25], v[170:173], v[214:217], v[22:25]
	v_mfma_f32_16x16x32_bf16 v[18:21], v[178:181], v[214:217], v[18:21]
	v_mfma_f32_16x16x32_bf16 v[6:9], v[170:173], v[222:225], v[6:9]
	v_mfma_f32_16x16x32_bf16 v[2:5], v[178:181], v[222:225], v[2:5]
	s_setprio 0
	s_barrier
	s_add_i32 s56, 0, 0x18000
	s_add_i32 s57, 0, 0x1c000
	v_add_u32_e32 v142, s56, v1
	v_add_u32_e32 v154, s57, v1
	ds_read_b128 v[130:133], v142
	ds_read_b128 v[134:137], v142 offset:1024
	ds_read_b128 v[138:141], v142 offset:2048
	ds_read_b128 v[142:145], v142 offset:3072
	ds_read_b128 v[166:169], v154
	ds_read_b128 v[170:173], v154 offset:1024
	ds_read_b128 v[174:177], v154 offset:2048
	ds_read_b128 v[178:181], v154 offset:3072
	s_add_u32 s16, s46, 0x160000
	s_addc_u32 s17, s47, 0
	s_mov_b32 m0, s34
	v_lshl_add_u64 v[232:233], s[16:17], 0, v[146:147]
	ds_read_b128 v[182:185], v198 offset:32768
	ds_read_b128 v[186:189], v198 offset:33792
	ds_read_b128 v[202:205], v198 offset:34816
	ds_read_b128 v[206:209], v198 offset:35840
	ds_read_b128 v[210:213], v198 offset:36864
	ds_read_b128 v[214:217], v198 offset:37888
	ds_read_b128 v[218:221], v198 offset:38912
	ds_read_b128 v[222:225], v198 offset:39936
	global_load_lds_dwordx4 v[232:233], off
	v_lshl_add_u64 v[232:233], s[16:17], 0, v[150:151]
	s_mov_b32 m0, s35
	s_nop 0
	global_load_lds_dwordx4 v[232:233], off
	s_waitcnt vmcnt(8)
	s_waitcnt lgkmcnt(0)
	s_barrier
	s_setprio 1
	s_waitcnt lgkmcnt(0)
	v_mfma_f32_16x16x32_bf16 v[126:129], v[130:133], v[182:185], v[126:129]
	v_mfma_f32_16x16x32_bf16 v[122:125], v[138:141], v[182:185], v[122:125]
	v_mfma_f32_16x16x32_bf16 v[110:113], v[130:133], v[202:205], v[110:113]
	v_mfma_f32_16x16x32_bf16 v[106:109], v[138:141], v[202:205], v[106:109]
	v_mfma_f32_16x16x32_bf16 v[94:97], v[130:133], v[210:213], v[94:97]
	v_mfma_f32_16x16x32_bf16 v[90:93], v[138:141], v[210:213], v[90:93]
	v_mfma_f32_16x16x32_bf16 v[78:81], v[130:133], v[218:221], v[78:81]
	v_mfma_f32_16x16x32_bf16 v[74:77], v[138:141], v[218:221], v[74:77]
	v_mfma_f32_16x16x32_bf16 v[126:129], v[134:137], v[186:189], v[126:129]
	v_mfma_f32_16x16x32_bf16 v[122:125], v[142:145], v[186:189], v[122:125]
	v_mfma_f32_16x16x32_bf16 v[110:113], v[134:137], v[206:209], v[110:113]
	v_mfma_f32_16x16x32_bf16 v[106:109], v[142:145], v[206:209], v[106:109]
	v_mfma_f32_16x16x32_bf16 v[94:97], v[134:137], v[214:217], v[94:97]
	v_mfma_f32_16x16x32_bf16 v[90:93], v[142:145], v[214:217], v[90:93]
	v_mfma_f32_16x16x32_bf16 v[78:81], v[134:137], v[222:225], v[78:81]
	v_mfma_f32_16x16x32_bf16 v[74:77], v[142:145], v[222:225], v[74:77]
	s_setprio 0
	s_setprio 1
	v_mfma_f32_16x16x32_bf16 v[118:121], v[166:169], v[182:185], v[118:121]
	v_mfma_f32_16x16x32_bf16 v[114:117], v[174:177], v[182:185], v[114:117]
	v_mfma_f32_16x16x32_bf16 v[102:105], v[166:169], v[202:205], v[102:105]
	v_mfma_f32_16x16x32_bf16 v[98:101], v[174:177], v[202:205], v[98:101]
	v_mfma_f32_16x16x32_bf16 v[86:89], v[166:169], v[210:213], v[86:89]
	v_mfma_f32_16x16x32_bf16 v[82:85], v[174:177], v[210:213], v[82:85]
	v_mfma_f32_16x16x32_bf16 v[70:73], v[166:169], v[218:221], v[70:73]
	v_mfma_f32_16x16x32_bf16 v[66:69], v[174:177], v[218:221], v[66:69]
	v_mfma_f32_16x16x32_bf16 v[118:121], v[170:173], v[186:189], v[118:121]
	v_mfma_f32_16x16x32_bf16 v[114:117], v[178:181], v[186:189], v[114:117]
	v_mfma_f32_16x16x32_bf16 v[102:105], v[170:173], v[206:209], v[102:105]
	v_mfma_f32_16x16x32_bf16 v[98:101], v[178:181], v[206:209], v[98:101]
	v_mfma_f32_16x16x32_bf16 v[86:89], v[170:173], v[214:217], v[86:89]
	v_mfma_f32_16x16x32_bf16 v[82:85], v[178:181], v[214:217], v[82:85]
	v_mfma_f32_16x16x32_bf16 v[70:73], v[170:173], v[222:225], v[70:73]
	v_mfma_f32_16x16x32_bf16 v[66:69], v[178:181], v[222:225], v[66:69]
	s_setprio 0
	s_barrier
; #define PG8_STAGE(bufoff, gbase, voff) do { _Pragma("unroll") for (int _i = 0; _i < 2; ++_i) \
;         __builtin_amdgcn_global_load_lds((const unsigned*)((const char*)(gbase) + (voff)[_i]), (LAS unsigned*)(lds + (bufoff) + ldsw + _i * 8192), 16, 0, 0); } while (0)
; #define PG8_LDA(dst, b, h) do { _Pragma("unroll") for (int m = 0; m < 4; ++m) _Pragma("unroll") for (int k = 0; k < 2; ++k) dst[m][k] = *(const LAS bf16x8*)(lds + PG8_SA(b, h) + aoff + m * 2048 + k * 1024); } while (0)
; #define PG8_MMA(ai, bj, At, Bt) do { __builtin_amdgcn_s_setprio(1); _Pragma("unroll") for (int m = 0; m < 4; ++m) _Pragma("unroll") for (int n = 0; n < 2; ++n) _Pragma("unroll") for (int k = 0; k < 2; ++k) \
;         acc[ai][bj][m][n] = __builtin_amdgcn_mfma_f32_16x16x32_bf16(Bt[n][k], At[m][k], acc[ai][bj][m][n], 0, 0, 0); __builtin_amdgcn_s_setprio(0); } while (0)
; #define PG8_WAIT_V(n) asm volatile("s_waitcnt vmcnt(" #n ")" ::: "memory")
; #define PG8_WAIT_L(n) asm volatile("s_waitcnt lgkmcnt(" #n ")" ::: "memory")
; #define PG8_BAR __builtin_amdgcn_s_barrier()
; #define PG8_SCHED __builtin_amdgcn_sched_barrier(0)
; template <class Epi, class Sched, bool ALIGN_EPI = false, bool SP2 = false>
; __device__ __forceinline__ void gemm_phase(LAS unsigned char* lds, const Gemm g, const Sched& S, const Epi& E) {
;     ...
;         for (int t = 0; t < nt; t += 2) {
;             const bool last = (t == nt - 2);
;             const char* a1 = cA + (size_t)(t + 1) * kstep;
;             const char* a2 = last ? nA : cA + (size_t)(t + 2) * kstep; const char* b2 = last ? nB : cB + (size_t)(t + 2) * kstep;
;     ...
;             PG8_LDA(At, 1, 1); PG8_STAGE(PG8_SB(1, 0), b3, voffB); PG8_STAGE(PG8_SB(1, 1), b3 + hstepB, voffB); PG8_STAGE(PG8_SA(1, 0), a3, voffA);
;             PG8_WAIT_V(8); PG8_WAIT_L(0); PG8_BAR; PG8_MMA(1, 0, At, B0); PG8_MMA(1, 1, At, B1); PG8_BAR; PG8_SCHED;
	s_add_i32 s16, s56, s30
	v_lshl_add_u64 v[190:191], v[190:191], 0, s[12:13]
	s_mov_b32 m0, s16
	ds_read_b128 v[182:185], v198 offset:49152
	ds_read_b128 v[186:189], v198 offset:50176
	ds_read_b128 v[202:205], v198 offset:51200
	ds_read_b128 v[206:209], v198 offset:52224
	ds_read_b128 v[210:213], v198 offset:53248
	ds_read_b128 v[214:217], v198 offset:54272
	ds_read_b128 v[218:221], v198 offset:55296
	ds_read_b128 v[222:225], v198 offset:56320
	global_load_lds_dwordx4 v[190:191], off
	s_add_i32 m0, s16, 0x2000
	s_add_u32 s16, s22, 0x58080
	v_lshl_add_u64 v[190:191], v[226:227], 0, s[12:13]
	s_addc_u32 s17, s23, 0
	s_add_i32 s22, s57, s30
	global_load_lds_dwordx4 v[190:191], off
	v_lshl_add_u64 v[190:191], s[16:17], 0, v[148:149]
	s_mov_b32 m0, s22
	s_nop 0
	global_load_lds_dwordx4 v[190:191], off
	v_lshl_add_u64 v[190:191], s[16:17], 0, v[152:153]
	s_add_i32 m0, s22, 0x2000
	s_nop 0
	global_load_lds_dwordx4 v[190:191], off
	v_lshl_add_u64 v[190:191], v[228:229], 0, s[12:13]
	s_mov_b32 m0, s49
	s_nop 0
	global_load_lds_dwordx4 v[190:191], off
	v_lshl_add_u64 v[190:191], v[230:231], 0, s[12:13]
	s_mov_b32 m0, s50
	s_nop 0
	global_load_lds_dwordx4 v[190:191], off
	s_waitcnt vmcnt(8)
	s_waitcnt lgkmcnt(0)
	s_barrier
	s_setprio 1
	s_waitcnt lgkmcnt(0)
	v_mfma_f32_16x16x32_bf16 v[62:65], v[130:133], v[182:185], v[62:65]
	v_mfma_f32_16x16x32_bf16 v[58:61], v[138:141], v[182:185], v[58:61]
	v_mfma_f32_16x16x32_bf16 v[46:49], v[130:133], v[202:205], v[46:49]
	v_mfma_f32_16x16x32_bf16 v[42:45], v[138:141], v[202:205], v[42:45]
	v_mfma_f32_16x16x32_bf16 v[30:33], v[130:133], v[210:213], v[30:33]
	v_mfma_f32_16x16x32_bf16 v[26:29], v[138:141], v[210:213], v[26:29]
	v_mfma_f32_16x16x32_bf16 v[14:17], v[130:133], v[218:221], v[14:17]
	v_mfma_f32_16x16x32_bf16 v[10:13], v[138:141], v[218:221], v[10:13]
	v_mfma_f32_16x16x32_bf16 v[62:65], v[134:137], v[186:189], v[62:65]
	v_mfma_f32_16x16x32_bf16 v[58:61], v[142:145], v[186:189], v[58:61]
	v_mfma_f32_16x16x32_bf16 v[46:49], v[134:137], v[206:209], v[46:49]
	v_mfma_f32_16x16x32_bf16 v[42:45], v[142:145], v[206:209], v[42:45]
	v_mfma_f32_16x16x32_bf16 v[30:33], v[134:137], v[214:217], v[30:33]
	v_mfma_f32_16x16x32_bf16 v[26:29], v[142:145], v[214:217], v[26:29]
	v_mfma_f32_16x16x32_bf16 v[14:17], v[134:137], v[222:225], v[14:17]
	v_mfma_f32_16x16x32_bf16 v[10:13], v[142:145], v[222:225], v[10:13]
	s_setprio 0
	s_setprio 1
	v_mfma_f32_16x16x32_bf16 v[54:57], v[166:169], v[182:185], v[54:57]
	v_mfma_f32_16x16x32_bf16 v[50:53], v[174:177], v[182:185], v[50:53]
	v_mfma_f32_16x16x32_bf16 v[38:41], v[166:169], v[202:205], v[38:41]
	v_mfma_f32_16x16x32_bf16 v[34:37], v[174:177], v[202:205], v[34:37]
	v_mfma_f32_16x16x32_bf16 v[22:25], v[166:169], v[210:213], v[22:25]
	v_mfma_f32_16x16x32_bf16 v[18:21], v[174:177], v[210:213], v[18:21]
	v_mfma_f32_16x16x32_bf16 v[6:9], v[166:169], v[218:221], v[6:9]
	v_mfma_f32_16x16x32_bf16 v[2:5], v[174:177], v[218:221], v[2:5]
	v_mfma_f32_16x16x32_bf16 v[54:57], v[170:173], v[186:189], v[54:57]
	v_mfma_f32_16x16x32_bf16 v[50:53], v[178:181], v[186:189], v[50:53]
	v_mfma_f32_16x16x32_bf16 v[38:41], v[170:173], v[206:209], v[38:41]
	v_mfma_f32_16x16x32_bf16 v[34:37], v[178:181], v[206:209], v[34:37]
	v_mfma_f32_16x16x32_bf16 v[22:25], v[170:173], v[214:217], v[22:25]
	v_mfma_f32_16x16x32_bf16 v[18:21], v[178:181], v[214:217], v[18:21]
	v_mfma_f32_16x16x32_bf16 v[6:9], v[170:173], v[222:225], v[6:9]
	v_mfma_f32_16x16x32_bf16 v[2:5], v[178:181], v[222:225], v[2:5]
	s_setprio 0
	s_barrier
	s_add_i32 s25, s25, 2
	s_add_u32 s9, s9, 0x100
	s_addc_u32 s24, s24, 0
	s_cmpk_gt_u32 s25, 0x55
	s_mov_b64 s[16:17], s[20:21]

; #define PG8_STAGE(bufoff, gbase, voff) do { _Pragma("unroll") for (int _i = 0; _i < 2; ++_i) \
;         __builtin_amdgcn_global_load_lds((const unsigned*)((const char*)(gbase) + (voff)[_i]), (LAS unsigned*)(lds + (bufoff) + ldsw + _i * 8192), 16, 0, 0); } while (0)
; #define PG8_WAIT_V(n) asm volatile("s_waitcnt vmcnt(" #n ")" ::: "memory")
; #define PG8_BAR __builtin_amdgcn_s_barrier()
; template <class Epi, class Sched, bool ALIGN_EPI = false, bool SP2 = false>
; __device__ __forceinline__ void gemm_phase(LAS unsigned char* lds, const Gemm g, const Sched& S, const Epi& E) {
;     int tid = threadIdx.x; asm volatile("" : "+v"(tid));
;     const int wid = __builtin_amdgcn_readfirstlane(tid >> 6), lane = tid & 63, wr = wid >> 2, wc = wid & 3, fr = lane & 15, fq = lane >> 4;
;     const int K = g.ld, nt = g.K / BK;
;     unsigned voffA[2], voffB[2];
; #pragma unroll
;     for (int i = 0; i < 2; ++i) { int R, C; stage_rc(tid * 16 + i * 8192, R, C); const int Rb = (Epi::BCONT ? ((R >> 5) * 64) : (R & ~31)) + (Epi::PERM ? perm32(R & 31) : (R & 31));
;         voffA[i] = (unsigned)(R * K + C) * 2u; voffB[i] = (unsigned)(Rb * K + C) * 2u; }
;     const size_t kstep = (size_t)(BK * 2);
;     const size_t hstep = (size_t)HALF * K * 2;
;     const size_t hstepB = Epi::BCONT ? (size_t)32 * K * 2 : hstep;
;     const size_t tstep = 2 * hstep;
;     const unsigned ldsw = (unsigned)wid * 1024u;
;     const int aoff = lds_byte(wr * 64 + fr, fq * 8), boff = lds_byte(wc * 32 + fr, fq * 8);
;     ...
;     if constexpr (SP2) {
;         PG8_STAGE(PG8_SB(0, 0), cB, voffB); PG8_STAGE(PG8_SB(0, 1), cB + hstepB, voffB); PG8_STAGE(PG8_SA(0, 0), cA, voffA); PG8_STAGE(PG8_SA(0, 1), cA + hstep, voffA);
;         if (wr == 1) PG8_BAR;
;         PG8_WAIT_V(2); PG8_BAR;
;         PG8_STAGE(PG8_SB(1, 0), cB + kstep, voffB); PG8_STAGE(PG8_SA(1, 0), cA + kstep, voffA); PG8_STAGE(PG8_SB(1, 1), cB + hstepB + kstep, voffB);
;         PG8_WAIT_V(6); PG8_BAR;
.LBB0_1816:
	s_lshl_b32 s0, s0, 5
	s_and_b32 s14, s0, 0x60
	s_lshl_b32 s35, s8, 6
	s_lshl_b32 s3, s8, 13
	s_lshl_b32 s15, s14, 7
	s_add_u32 s36, s48, 0x2b5000
	s_mov_b64 s[8:9], 0x80
	s_addc_u32 s37, s49, 0
	s_add_i32 m0, s29, 0x18000
	v_lshl_add_u64 v[8:9], v[8:9], 0, s[8:9]
	s_waitcnt vmcnt(2)
	s_barrier
	global_load_lds_dwordx4 v[8:9], off
	v_lshl_add_u64 v[6:7], v[6:7], 0, s[8:9]
	s_add_i32 m0, s29, 0x1a000
	s_add_i32 s42, s29, 0x8000
	s_add_i32 s43, s29, 0xa000
	global_load_lds_dwordx4 v[6:7], off
	v_lshl_add_u64 v[2:3], v[2:3], 0, s[8:9]
	s_mov_b32 m0, s42
	s_add_u32 s12, s16, 0x80080
	global_load_lds_dwordx4 v[2:3], off
	v_lshl_add_u64 v[2:3], v[4:5], 0, s[8:9]
	s_mov_b32 m0, s43
	s_addc_u32 s13, s17, 0
	global_load_lds_dwordx4 v[2:3], off
	s_add_i32 m0, s29, 0x1c000
	v_lshl_add_u64 v[2:3], s[12:13], 0, v[150:151]
	global_load_lds_dwordx4 v[2:3], off
	v_lshl_add_u64 v[2:3], s[12:13], 0, v[146:147]
	s_add_i32 m0, s29, 0x1e000
	v_and_b32_e32 v1, 15, v10
	global_load_lds_dwordx4 v[2:3], off
	v_bfe_u32 v3, v10, 4, 2
	v_lshlrev_b32_e32 v2, 3, v3
	v_lshlrev_b32_e32 v3, 4, v3
	v_lshlrev_b32_e32 v4, 2, v10
	v_lshl_or_b32 v3, v1, 6, v3
	v_and_b32_e32 v4, 32, v4
	v_bitop3_b32 v5, v3, s3, v4 bitop3:0xde
	v_bitop3_b32 v169, v3, s15, v4 bitop3:0xde
	v_lshlrev_b32_e32 v3, 15, v11
	v_and_b32_e32 v3, 0xffff0000, v3
	v_lshl_add_u32 v3, v12, 12, v3
	v_and_b32_e32 v4, 1, v11
	v_lshl_or_b32 v3, v4, 6, v3
	v_lshl_add_u32 v154, v13, 1, v3
	v_lshlrev_b32_e32 v3, 15, v15
	v_or_b32_e32 v172, s14, v2
	v_and_b32_e32 v3, 0xffff0000, v3
	v_lshlrev_b32_e32 v176, 2, v2
	v_mbcnt_lo_u32_b32 v2, -1, 0
	s_waitcnt vmcnt(0)
	s_cmpk_lt_u32 s11, 0x100
	v_lshl_add_u32 v3, v14, 12, v3
	v_and_b32_e32 v4, 1, v15
	v_mbcnt_hi_u32_b32 v2, -1, v2
	s_sext_i32_i16 s0, s10
	s_cselect_b64 s[10:11], -1, 0
	v_and_b32_e32 v170, 63, v10
	v_lshl_or_b32 v3, v4, 6, v3
	s_add_i32 s44, 0, 0x10000
	s_add_i32 s45, 0, 0x14000
	v_and_or_b32 v2, v2, 64, v1
	v_or_b32_e32 v171, 0x80, v170
	v_mov_b32_e32 v155, v151
	v_lshl_add_u32 v156, v16, 1, v3
	v_mov_b32_e32 v157, v151
	v_mov_b64_e32 v[158:159], 0x16b0
	v_mov_b64_e32 v[160:161], 0x16af
	v_add_u32_e32 v173, s44, v169
	v_add_u32_e32 v174, s45, v169
	v_add_u32_e32 v175, 0, v5
	s_movk_i32 s46, 0x2c00
	s_lshl_b32 s47, s14, 2
	v_mov_b32_e32 v177, 0x358637bd
	s_mov_b32 s48, 0xf800000
	v_mov_b32_e32 v178, 0x260
	v_lshlrev_b32_e32 v179, 2, v2
	s_barrier
	s_branch .LBB0_1819

; __device__ __forceinline__ float row_rstd(const float* ss, int row) { return 1.0f / sqrtf(ss[row] * (1.0f / DM) + 1e-6f); }
; #define PG8_STAGE(bufoff, gbase, voff) do { _Pragma("unroll") for (int _i = 0; _i < 2; ++_i) \
;         __builtin_amdgcn_global_load_lds((const unsigned*)((const char*)(gbase) + (voff)[_i]), (LAS unsigned*)(lds + (bufoff) + ldsw + _i * 8192), 16, 0, 0); } while (0)
; #define PG8_LDA(dst, b, h) do { _Pragma("unroll") for (int m = 0; m < 4; ++m) _Pragma("unroll") for (int k = 0; k < 2; ++k) dst[m][k] = *(const LAS bf16x8*)(lds + PG8_SA(b, h) + aoff + m * 2048 + k * 1024); } while (0)
; #define PG8_WAIT_V(n) asm volatile("s_waitcnt vmcnt(" #n ")" ::: "memory")
;     __device__ __forceinline__ void operator()(const f32x4 (&acc)[2][2][4][2], const Unit& u, int wr, int wc, int fr, int fq) const {
;     ...
;         const float* bp = bias + (size_t)s * BIAS_N + u.pn * BM + wc * 32 + 8 * fq;
;         const f32x4 ba0 = *(const f32x4*)bp, ba1 = *(const f32x4*)(bp + 4), bb0 = *(const f32x4*)(bp + HALF), bb1 = *(const f32x4*)(bp + HALF + 4);
;         const int lane = fq * 16 + fr;
;         const float rsl0 = row_rstd(ss, u.pm * BM + wr * 64 + lane), rsl1 = row_rstd(ss, u.pm * BM + HALF + wr * 64 + lane);
; template <class Epi, class Sched, bool ALIGN_EPI = false, bool SP2 = false>
; __device__ __forceinline__ void gemm_phase(LAS unsigned char* lds, const Gemm g, const Sched& S, const Epi& E) {
;     ...
;         for (int t = 0; t < nt; t += 2) {
;             const bool last = (t == nt - 2);
;             const char* a1 = cA + (size_t)(t + 1) * kstep;
;             const char* a2 = last ? nA : cA + (size_t)(t + 2) * kstep; const char* b2 = last ? nB : cB + (size_t)(t + 2) * kstep;
;             const char* a3 = a2 + kstep; const char* b3 = b2 + kstep;
;             if (last && has_next) S.a_ready(nxt);
;             if constexpr (SP2) {
;             PG8_LDB(B0, 0, 0); PG8_LDB(B1, 0, 1); PG8_SCHED; PG8_LDA(At, 0, 0); PG8_STAGE(PG8_SA(1, 1), a1 + hstep, voffA);
;             PG8_WAIT_V(8); PG8_WAIT_L(0); PG8_BAR; PG8_MMA(0, 0, At, B0); PG8_MMA(0, 1, At, B1); PG8_BAR; PG8_SCHED;
;             PG8_LDA(At, 0, 1); PG8_STAGE(PG8_SB(0, 0), b2, voffB); PG8_STAGE(PG8_SB(0, 1), b2 + hstepB, voffB); PG8_STAGE(PG8_SA(0, 0), a2, voffA);
;             PG8_WAIT_V(8); PG8_WAIT_L(0); PG8_BAR; PG8_MMA(1, 0, At, B0); PG8_MMA(1, 1, At, B1); PG8_BAR; PG8_SCHED;
.Lpre_up1l1:
	s_lshl_b64 s[98:99], s[98:99], 2
	s_add_u32 s98, s36, s98
	s_addc_u32 s99, s37, s99
	s_lshl_b32 s100, s0, 8
	s_ashr_i32 s101, s100, 31
	s_lshl_b64 s[100:101], s[100:101], 2
	s_add_u32 s98, s98, s100
	s_addc_u32 s99, s99, s101
	s_add_u32 s98, s98, s47
	s_addc_u32 s99, s99, 0
	s_lshl_b32 s100, s2, 8
	s_add_i32 s100, s100, s35
	v_or_b32_e32 v162, s100, v170
	v_ashrrev_i32_e32 v163, 31, v162
	v_lshl_add_u64 v[162:163], v[162:163], 2, s[6:7]
	v_add_u32_e32 v164, s100, v171
	v_ashrrev_i32_e32 v165, 31, v164
	v_lshl_add_u64 v[164:165], v[164:165], 2, s[6:7]
	global_load_dwordx4 v[234:237], v176, s[98:99] offset:16
	global_load_dwordx4 v[238:241], v176, s[98:99]
	global_load_dwordx4 v[242:245], v176, s[98:99] offset:528
	global_load_dwordx4 v[246:249], v176, s[98:99] offset:512
	global_load_dword v250, v[162:163], off
	global_load_dword v251, v[164:165], off
	ds_read_b128 v[66:69], v173
	ds_read_b128 v[70:73], v173 offset:1024
	ds_read_b128 v[74:77], v173 offset:2048
	ds_read_b128 v[78:81], v173 offset:3072
	ds_read_b128 v[162:165], v174
	ds_read_b128 v[180:183], v174 offset:1024
	ds_read_b128 v[184:187], v174 offset:2048
	ds_read_b128 v[188:191], v174 offset:3072
	s_add_u32 s22, s16, 0xfff80080
	s_addc_u32 s23, s17, -1
	s_cmp_eq_u32 s50, 28
	s_cselect_b32 s41, s3, s23
	s_cselect_b32 s40, s15, s22
	s_cselect_b32 s23, s13, s49
	s_cselect_b32 s22, s24, s25
	v_lshl_add_u64 v[166:167], s[16:17], 0, v[156:157]
	s_add_i32 m0, s29, 0xc000
	ds_read_b128 v[192:195], v175
	ds_read_b128 v[196:199], v175 offset:1024
	ds_read_b128 v[200:203], v175 offset:2048
	ds_read_b128 v[204:207], v175 offset:3072
	ds_read_b128 v[208:211], v175 offset:4096
	ds_read_b128 v[212:215], v175 offset:5120
	ds_read_b128 v[216:219], v175 offset:6144
	ds_read_b128 v[220:223], v175 offset:7168
	global_load_lds_dwordx4 v[166:167], off
	v_lshl_add_u64 v[166:167], s[16:17], 0, v[154:155]
	s_add_i32 m0, s29, 0xe000
	s_nop 0
	global_load_lds_dwordx4 v[166:167], off
	s_waitcnt lgkmcnt(0)
	s_barrier
	s_setprio 1
	s_waitcnt lgkmcnt(0)
	v_mfma_f32_16x16x32_bf16 v[142:145], v[66:69], v[192:195], 0
	v_mfma_f32_16x16x32_bf16 v[138:141], v[74:77], v[192:195], 0
	v_mfma_f32_16x16x32_bf16 v[126:129], v[66:69], v[200:203], 0
	v_mfma_f32_16x16x32_bf16 v[122:125], v[74:77], v[200:203], 0
	v_mfma_f32_16x16x32_bf16 v[110:113], v[66:69], v[208:211], 0
	v_mfma_f32_16x16x32_bf16 v[106:109], v[74:77], v[208:211], 0
	v_mfma_f32_16x16x32_bf16 v[94:97], v[66:69], v[216:219], 0
	v_mfma_f32_16x16x32_bf16 v[90:93], v[74:77], v[216:219], 0
	v_mfma_f32_16x16x32_bf16 v[142:145], v[70:73], v[196:199], v[142:145]
	v_mfma_f32_16x16x32_bf16 v[138:141], v[78:81], v[196:199], v[138:141]
	v_mfma_f32_16x16x32_bf16 v[126:129], v[70:73], v[204:207], v[126:129]
	v_mfma_f32_16x16x32_bf16 v[122:125], v[78:81], v[204:207], v[122:125]
	v_mfma_f32_16x16x32_bf16 v[110:113], v[70:73], v[212:215], v[110:113]
	v_mfma_f32_16x16x32_bf16 v[106:109], v[78:81], v[212:215], v[106:109]
	v_mfma_f32_16x16x32_bf16 v[94:97], v[70:73], v[220:223], v[94:97]
	v_mfma_f32_16x16x32_bf16 v[90:93], v[78:81], v[220:223], v[90:93]
	s_setprio 0
	s_setprio 1
	v_mfma_f32_16x16x32_bf16 v[134:137], v[162:165], v[192:195], 0
	v_mfma_f32_16x16x32_bf16 v[130:133], v[184:187], v[192:195], 0
	v_mfma_f32_16x16x32_bf16 v[118:121], v[162:165], v[200:203], 0
	v_mfma_f32_16x16x32_bf16 v[114:117], v[184:187], v[200:203], 0
	v_mfma_f32_16x16x32_bf16 v[102:105], v[162:165], v[208:211], 0
	v_mfma_f32_16x16x32_bf16 v[98:101], v[184:187], v[208:211], 0
	v_mfma_f32_16x16x32_bf16 v[86:89], v[162:165], v[216:219], 0
	v_mfma_f32_16x16x32_bf16 v[82:85], v[184:187], v[216:219], 0
	v_mfma_f32_16x16x32_bf16 v[134:137], v[180:183], v[196:199], v[134:137]
	v_mfma_f32_16x16x32_bf16 v[130:133], v[188:191], v[196:199], v[130:133]
	v_mfma_f32_16x16x32_bf16 v[118:121], v[180:183], v[204:207], v[118:121]
	v_mfma_f32_16x16x32_bf16 v[114:117], v[188:191], v[204:207], v[114:117]
	v_mfma_f32_16x16x32_bf16 v[102:105], v[180:183], v[212:215], v[102:105]
	v_mfma_f32_16x16x32_bf16 v[98:101], v[188:191], v[212:215], v[98:101]
	v_mfma_f32_16x16x32_bf16 v[86:89], v[180:183], v[220:223], v[86:89]
	v_mfma_f32_16x16x32_bf16 v[82:85], v[188:191], v[220:223], v[82:85]
	s_setprio 0
	s_barrier
	s_add_i32 s51, s44, s26
	v_lshl_add_u64 v[166:167], s[22:23], 0, v[150:151]
	s_mov_b32 m0, s51
	ds_read_b128 v[192:195], v175 offset:16384
	ds_read_b128 v[196:199], v175 offset:17408
	ds_read_b128 v[200:203], v175 offset:18432
	ds_read_b128 v[204:207], v175 offset:19456
	ds_read_b128 v[208:211], v175 offset:20480
	ds_read_b128 v[212:215], v175 offset:21504
	ds_read_b128 v[216:219], v175 offset:22528
	ds_read_b128 v[220:223], v175 offset:23552
	global_load_lds_dwordx4 v[166:167], off
	s_add_i32 m0, s51, 0x2000
	s_add_u32 s52, s22, 0x80000
	v_lshl_add_u64 v[224:225], s[22:23], 0, v[146:147]
	s_addc_u32 s53, s23, 0
	s_add_i32 s51, s45, s26
	global_load_lds_dwordx4 v[224:225], off
	v_lshl_add_u64 v[226:227], s[52:53], 0, v[150:151]
	s_mov_b32 m0, s51
	v_lshl_add_u64 v[228:229], s[40:41], 0, v[148:149]
	global_load_lds_dwordx4 v[226:227], off
	v_lshl_add_u64 v[226:227], s[52:53], 0, v[146:147]
	s_add_i32 m0, s51, 0x2000
	s_nop 0
	global_load_lds_dwordx4 v[226:227], off
	v_lshl_add_u64 v[226:227], s[40:41], 0, v[152:153]
	s_mov_b32 m0, s29
	s_nop 0
	global_load_lds_dwordx4 v[226:227], off
	s_mov_b32 m0, s30
	s_nop 0
	global_load_lds_dwordx4 v[228:229], off
	s_waitcnt lgkmcnt(0)
	s_barrier
; #define PG8_STAGE(bufoff, gbase, voff) do { _Pragma("unroll") for (int _i = 0; _i < 2; ++_i) \
;         __builtin_amdgcn_global_load_lds((const unsigned*)((const char*)(gbase) + (voff)[_i]), (LAS unsigned*)(lds + (bufoff) + ldsw + _i * 8192), 16, 0, 0); } while (0)
; #define PG8_LDA(dst, b, h) do { _Pragma("unroll") for (int m = 0; m < 4; ++m) _Pragma("unroll") for (int k = 0; k < 2; ++k) dst[m][k] = *(const LAS bf16x8*)(lds + PG8_SA(b, h) + aoff + m * 2048 + k * 1024); } while (0)
; #define PG8_LDB(dst, b, h) do { _Pragma("unroll") for (int n = 0; n < 2; ++n) _Pragma("unroll") for (int k = 0; k < 2; ++k) dst[n][k] = *(const LAS bf16x8*)(lds + PG8_SB(b, h) + boff + n * 2048 + k * 1024); } while (0)
; #define PG8_MMA(ai, bj, At, Bt) do { __builtin_amdgcn_s_setprio(1); _Pragma("unroll") for (int m = 0; m < 4; ++m) _Pragma("unroll") for (int n = 0; n < 2; ++n) _Pragma("unroll") for (int k = 0; k < 2; ++k) \
;         acc[ai][bj][m][n] = __builtin_amdgcn_mfma_f32_16x16x32_bf16(Bt[n][k], At[m][k], acc[ai][bj][m][n], 0, 0, 0); __builtin_amdgcn_s_setprio(0); } while (0)
; #define PG8_WAIT_V(n) asm volatile("s_waitcnt vmcnt(" #n ")" ::: "memory")
; #define PG8_WAIT_L(n) asm volatile("s_waitcnt lgkmcnt(" #n ")" ::: "memory")
; #define PG8_BAR __builtin_amdgcn_s_barrier()
; #define PG8_SCHED __builtin_amdgcn_sched_barrier(0)
; template <class Epi, class Sched, bool ALIGN_EPI = false, bool SP2 = false>
; __device__ __forceinline__ void gemm_phase(LAS unsigned char* lds, const Gemm g, const Sched& S, const Epi& E) {
;     ...
;             PG8_WAIT_V(8); PG8_WAIT_L(0); PG8_BAR; PG8_MMA(1, 0, At, B0); PG8_MMA(1, 1, At, B1); PG8_BAR; PG8_SCHED;
;             PG8_LDB(B0, 1, 0); PG8_LDB(B1, 1, 1); PG8_SCHED; PG8_LDA(At, 1, 0); PG8_STAGE(PG8_SA(0, 1), a2 + hstep, voffA);
;             PG8_WAIT_V(8); PG8_WAIT_L(0); PG8_BAR; PG8_MMA(0, 0, At, B0); PG8_MMA(0, 1, At, B1); PG8_BAR; PG8_SCHED;
	s_setprio 1
	s_waitcnt lgkmcnt(0)
	v_mfma_f32_16x16x32_bf16 v[62:65], v[66:69], v[192:195], 0
	v_mfma_f32_16x16x32_bf16 v[58:61], v[74:77], v[192:195], 0
	v_mfma_f32_16x16x32_bf16 v[46:49], v[66:69], v[200:203], 0
	v_mfma_f32_16x16x32_bf16 v[42:45], v[74:77], v[200:203], 0
	v_mfma_f32_16x16x32_bf16 v[30:33], v[66:69], v[208:211], 0
	v_mfma_f32_16x16x32_bf16 v[26:29], v[74:77], v[208:211], 0
	v_mfma_f32_16x16x32_bf16 v[14:17], v[66:69], v[216:219], 0
	v_mfma_f32_16x16x32_bf16 v[10:13], v[74:77], v[216:219], 0
	v_mfma_f32_16x16x32_bf16 v[62:65], v[70:73], v[196:199], v[62:65]
	v_mfma_f32_16x16x32_bf16 v[58:61], v[78:81], v[196:199], v[58:61]
	v_mfma_f32_16x16x32_bf16 v[46:49], v[70:73], v[204:207], v[46:49]
	v_mfma_f32_16x16x32_bf16 v[42:45], v[78:81], v[204:207], v[42:45]
	v_mfma_f32_16x16x32_bf16 v[30:33], v[70:73], v[212:215], v[30:33]
	v_mfma_f32_16x16x32_bf16 v[26:29], v[78:81], v[212:215], v[26:29]
	v_mfma_f32_16x16x32_bf16 v[14:17], v[70:73], v[220:223], v[14:17]
	v_mfma_f32_16x16x32_bf16 v[10:13], v[78:81], v[220:223], v[10:13]
	s_setprio 0
	s_setprio 1
	v_mfma_f32_16x16x32_bf16 v[54:57], v[162:165], v[192:195], 0
	v_mfma_f32_16x16x32_bf16 v[50:53], v[184:187], v[192:195], 0
	v_mfma_f32_16x16x32_bf16 v[38:41], v[162:165], v[200:203], 0
	v_mfma_f32_16x16x32_bf16 v[34:37], v[184:187], v[200:203], 0
	v_mfma_f32_16x16x32_bf16 v[22:25], v[162:165], v[208:211], 0
	v_mfma_f32_16x16x32_bf16 v[18:21], v[184:187], v[208:211], 0
	v_mfma_f32_16x16x32_bf16 v[6:9], v[162:165], v[216:219], 0
	v_mfma_f32_16x16x32_bf16 v[2:5], v[184:187], v[216:219], 0
	v_mfma_f32_16x16x32_bf16 v[54:57], v[180:183], v[196:199], v[54:57]
	v_mfma_f32_16x16x32_bf16 v[50:53], v[188:191], v[196:199], v[50:53]
	v_mfma_f32_16x16x32_bf16 v[38:41], v[180:183], v[204:207], v[38:41]
	v_mfma_f32_16x16x32_bf16 v[34:37], v[188:191], v[204:207], v[34:37]
	v_mfma_f32_16x16x32_bf16 v[22:25], v[180:183], v[212:215], v[22:25]
	v_mfma_f32_16x16x32_bf16 v[18:21], v[188:191], v[212:215], v[18:21]
	v_mfma_f32_16x16x32_bf16 v[6:9], v[180:183], v[220:223], v[6:9]
	v_mfma_f32_16x16x32_bf16 v[2:5], v[188:191], v[220:223], v[2:5]
	s_setprio 0
	s_barrier
	s_add_i32 s51, 0, 0x18000
	s_add_i32 s52, 0, 0x1c000
	v_add_u32_e32 v78, s51, v169
	v_add_u32_e32 v168, s52, v169
	ds_read_b128 v[66:69], v78
	ds_read_b128 v[70:73], v78 offset:1024
	ds_read_b128 v[74:77], v78 offset:2048
	ds_read_b128 v[78:81], v78 offset:3072
	ds_read_b128 v[162:165], v168
	ds_read_b128 v[180:183], v168 offset:1024
	ds_read_b128 v[184:187], v168 offset:2048
	ds_read_b128 v[188:191], v168 offset:3072
	s_add_u32 s40, s40, 0x80000
	s_addc_u32 s41, s41, 0
	s_mov_b32 m0, s31
	v_lshl_add_u64 v[230:231], s[40:41], 0, v[152:153]
	ds_read_b128 v[192:195], v175 offset:32768
	ds_read_b128 v[196:199], v175 offset:33792
	ds_read_b128 v[200:203], v175 offset:34816
	ds_read_b128 v[204:207], v175 offset:35840
	ds_read_b128 v[208:211], v175 offset:36864
	ds_read_b128 v[212:215], v175 offset:37888
	ds_read_b128 v[216:219], v175 offset:38912
	ds_read_b128 v[220:223], v175 offset:39936
	global_load_lds_dwordx4 v[230:231], off
	v_lshl_add_u64 v[230:231], s[40:41], 0, v[148:149]
	s_mov_b32 m0, s33
	s_nop 0
	global_load_lds_dwordx4 v[230:231], off
	s_waitcnt vmcnt(8)
	s_waitcnt lgkmcnt(0)
	s_barrier
	s_setprio 1
	s_waitcnt lgkmcnt(0)
	v_mfma_f32_16x16x32_bf16 v[142:145], v[66:69], v[192:195], v[142:145]
	v_mfma_f32_16x16x32_bf16 v[138:141], v[74:77], v[192:195], v[138:141]
	v_mfma_f32_16x16x32_bf16 v[126:129], v[66:69], v[200:203], v[126:129]
	v_mfma_f32_16x16x32_bf16 v[122:125], v[74:77], v[200:203], v[122:125]
	v_mfma_f32_16x16x32_bf16 v[110:113], v[66:69], v[208:211], v[110:113]
	v_mfma_f32_16x16x32_bf16 v[106:109], v[74:77], v[208:211], v[106:109]
	v_mfma_f32_16x16x32_bf16 v[94:97], v[66:69], v[216:219], v[94:97]
	v_mfma_f32_16x16x32_bf16 v[90:93], v[74:77], v[216:219], v[90:93]
	v_mfma_f32_16x16x32_bf16 v[142:145], v[70:73], v[196:199], v[142:145]
	v_mfma_f32_16x16x32_bf16 v[138:141], v[78:81], v[196:199], v[138:141]
	v_mfma_f32_16x16x32_bf16 v[126:129], v[70:73], v[204:207], v[126:129]
	v_mfma_f32_16x16x32_bf16 v[122:125], v[78:81], v[204:207], v[122:125]
	v_mfma_f32_16x16x32_bf16 v[110:113], v[70:73], v[212:215], v[110:113]
	v_mfma_f32_16x16x32_bf16 v[106:109], v[78:81], v[212:215], v[106:109]
	v_mfma_f32_16x16x32_bf16 v[94:97], v[70:73], v[220:223], v[94:97]
	v_mfma_f32_16x16x32_bf16 v[90:93], v[78:81], v[220:223], v[90:93]
	s_setprio 0
	s_setprio 1
	v_mfma_f32_16x16x32_bf16 v[134:137], v[162:165], v[192:195], v[134:137]
	v_mfma_f32_16x16x32_bf16 v[130:133], v[184:187], v[192:195], v[130:133]
	v_mfma_f32_16x16x32_bf16 v[118:121], v[162:165], v[200:203], v[118:121]
	v_mfma_f32_16x16x32_bf16 v[114:117], v[184:187], v[200:203], v[114:117]
	v_mfma_f32_16x16x32_bf16 v[102:105], v[162:165], v[208:211], v[102:105]
	v_mfma_f32_16x16x32_bf16 v[98:101], v[184:187], v[208:211], v[98:101]
	v_mfma_f32_16x16x32_bf16 v[86:89], v[162:165], v[216:219], v[86:89]
	v_mfma_f32_16x16x32_bf16 v[82:85], v[184:187], v[216:219], v[82:85]
	v_mfma_f32_16x16x32_bf16 v[134:137], v[180:183], v[196:199], v[134:137]
	v_mfma_f32_16x16x32_bf16 v[130:133], v[188:191], v[196:199], v[130:133]
	v_mfma_f32_16x16x32_bf16 v[118:121], v[180:183], v[204:207], v[118:121]
	v_mfma_f32_16x16x32_bf16 v[114:117], v[188:191], v[204:207], v[114:117]
	v_mfma_f32_16x16x32_bf16 v[102:105], v[180:183], v[212:215], v[102:105]
	v_mfma_f32_16x16x32_bf16 v[98:101], v[188:191], v[212:215], v[98:101]
	v_mfma_f32_16x16x32_bf16 v[86:89], v[180:183], v[220:223], v[86:89]
	v_mfma_f32_16x16x32_bf16 v[82:85], v[188:191], v[220:223], v[82:85]
	s_setprio 0
	s_barrier
; #define PG8_STAGE(bufoff, gbase, voff) do { _Pragma("unroll") for (int _i = 0; _i < 2; ++_i) \
;         __builtin_amdgcn_global_load_lds((const unsigned*)((const char*)(gbase) + (voff)[_i]), (LAS unsigned*)(lds + (bufoff) + ldsw + _i * 8192), 16, 0, 0); } while (0)
; #define PG8_LDA(dst, b, h) do { _Pragma("unroll") for (int m = 0; m < 4; ++m) _Pragma("unroll") for (int k = 0; k < 2; ++k) dst[m][k] = *(const LAS bf16x8*)(lds + PG8_SA(b, h) + aoff + m * 2048 + k * 1024); } while (0)
; #define PG8_MMA(ai, bj, At, Bt) do { __builtin_amdgcn_s_setprio(1); _Pragma("unroll") for (int m = 0; m < 4; ++m) _Pragma("unroll") for (int n = 0; n < 2; ++n) _Pragma("unroll") for (int k = 0; k < 2; ++k) \
;         acc[ai][bj][m][n] = __builtin_amdgcn_mfma_f32_16x16x32_bf16(Bt[n][k], At[m][k], acc[ai][bj][m][n], 0, 0, 0); __builtin_amdgcn_s_setprio(0); } while (0)
; #define PG8_WAIT_V(n) asm volatile("s_waitcnt vmcnt(" #n ")" ::: "memory")
; #define PG8_WAIT_L(n) asm volatile("s_waitcnt lgkmcnt(" #n ")" ::: "memory")
; #define PG8_BAR __builtin_amdgcn_s_barrier()
; #define PG8_SCHED __builtin_amdgcn_sched_barrier(0)
; template <class Epi, class Sched, bool ALIGN_EPI = false, bool SP2 = false>
; __device__ __forceinline__ void gemm_phase(LAS unsigned char* lds, const Gemm g, const Sched& S, const Epi& E) {
;     ...
;         for (int t = 0; t < nt; t += 2) {
;             const bool last = (t == nt - 2);
;             const char* a1 = cA + (size_t)(t + 1) * kstep;
;             const char* a2 = last ? nA : cA + (size_t)(t + 2) * kstep; const char* b2 = last ? nB : cB + (size_t)(t + 2) * kstep;
;     ...
;             PG8_LDA(At, 1, 1); PG8_STAGE(PG8_SB(1, 0), b3, voffB); PG8_STAGE(PG8_SB(1, 1), b3 + hstepB, voffB); PG8_STAGE(PG8_SA(1, 0), a3, voffA);
;             PG8_WAIT_V(8); PG8_WAIT_L(0); PG8_BAR; PG8_MMA(1, 0, At, B0); PG8_MMA(1, 1, At, B1); PG8_BAR; PG8_SCHED;
	s_add_i32 s40, s51, s26
	v_lshl_add_u64 v[166:167], v[166:167], 0, s[8:9]
	s_mov_b32 m0, s40
	ds_read_b128 v[192:195], v175 offset:49152
	ds_read_b128 v[196:199], v175 offset:50176
	ds_read_b128 v[200:203], v175 offset:51200
	ds_read_b128 v[204:207], v175 offset:52224
	ds_read_b128 v[208:211], v175 offset:53248
	ds_read_b128 v[212:215], v175 offset:54272
	ds_read_b128 v[216:219], v175 offset:55296
	ds_read_b128 v[220:223], v175 offset:56320
	global_load_lds_dwordx4 v[166:167], off
	s_add_i32 m0, s40, 0x2000
	s_add_u32 s22, s22, 0x80080
	v_lshl_add_u64 v[166:167], v[224:225], 0, s[8:9]
	s_addc_u32 s23, s23, 0
	s_add_i32 s40, s52, s26
	global_load_lds_dwordx4 v[166:167], off
	v_lshl_add_u64 v[166:167], s[22:23], 0, v[150:151]
	s_mov_b32 m0, s40
	s_nop 0
	global_load_lds_dwordx4 v[166:167], off
	v_lshl_add_u64 v[166:167], s[22:23], 0, v[146:147]
	s_add_i32 m0, s40, 0x2000
	s_nop 0
	global_load_lds_dwordx4 v[166:167], off
	v_lshl_add_u64 v[166:167], v[226:227], 0, s[8:9]
	s_mov_b32 m0, s42
	s_nop 0
	global_load_lds_dwordx4 v[166:167], off
	v_lshl_add_u64 v[166:167], v[228:229], 0, s[8:9]
	s_mov_b32 m0, s43
	s_nop 0
	global_load_lds_dwordx4 v[166:167], off
	s_waitcnt vmcnt(8)
	s_waitcnt lgkmcnt(0)
	s_barrier
	s_setprio 1
	s_waitcnt lgkmcnt(0)
	v_mfma_f32_16x16x32_bf16 v[62:65], v[66:69], v[192:195], v[62:65]
	v_mfma_f32_16x16x32_bf16 v[58:61], v[74:77], v[192:195], v[58:61]
	v_mfma_f32_16x16x32_bf16 v[46:49], v[66:69], v[200:203], v[46:49]
	v_mfma_f32_16x16x32_bf16 v[42:45], v[74:77], v[200:203], v[42:45]
	v_mfma_f32_16x16x32_bf16 v[30:33], v[66:69], v[208:211], v[30:33]
	v_mfma_f32_16x16x32_bf16 v[26:29], v[74:77], v[208:211], v[26:29]
	v_mfma_f32_16x16x32_bf16 v[14:17], v[66:69], v[216:219], v[14:17]
	v_mfma_f32_16x16x32_bf16 v[10:13], v[74:77], v[216:219], v[10:13]
	v_mfma_f32_16x16x32_bf16 v[62:65], v[70:73], v[196:199], v[62:65]
	v_mfma_f32_16x16x32_bf16 v[58:61], v[78:81], v[196:199], v[58:61]
	v_mfma_f32_16x16x32_bf16 v[46:49], v[70:73], v[204:207], v[46:49]
	v_mfma_f32_16x16x32_bf16 v[42:45], v[78:81], v[204:207], v[42:45]
	v_mfma_f32_16x16x32_bf16 v[30:33], v[70:73], v[212:215], v[30:33]
	v_mfma_f32_16x16x32_bf16 v[26:29], v[78:81], v[212:215], v[26:29]
	v_mfma_f32_16x16x32_bf16 v[14:17], v[70:73], v[220:223], v[14:17]
	v_mfma_f32_16x16x32_bf16 v[10:13], v[78:81], v[220:223], v[10:13]
	s_setprio 0
	s_setprio 1
	v_mfma_f32_16x16x32_bf16 v[54:57], v[162:165], v[192:195], v[54:57]
	v_mfma_f32_16x16x32_bf16 v[50:53], v[184:187], v[192:195], v[50:53]
	v_mfma_f32_16x16x32_bf16 v[38:41], v[162:165], v[200:203], v[38:41]
	v_mfma_f32_16x16x32_bf16 v[34:37], v[184:187], v[200:203], v[34:37]
	v_mfma_f32_16x16x32_bf16 v[22:25], v[162:165], v[208:211], v[22:25]
	v_mfma_f32_16x16x32_bf16 v[18:21], v[184:187], v[208:211], v[18:21]
	v_mfma_f32_16x16x32_bf16 v[6:9], v[162:165], v[216:219], v[6:9]
	v_mfma_f32_16x16x32_bf16 v[2:5], v[184:187], v[216:219], v[2:5]
	v_mfma_f32_16x16x32_bf16 v[54:57], v[180:183], v[196:199], v[54:57]
	v_mfma_f32_16x16x32_bf16 v[50:53], v[188:191], v[196:199], v[50:53]
	v_mfma_f32_16x16x32_bf16 v[38:41], v[180:183], v[204:207], v[38:41]
	v_mfma_f32_16x16x32_bf16 v[34:37], v[188:191], v[204:207], v[34:37]
	v_mfma_f32_16x16x32_bf16 v[22:25], v[180:183], v[212:215], v[22:25]
	v_mfma_f32_16x16x32_bf16 v[18:21], v[188:191], v[212:215], v[18:21]
	v_mfma_f32_16x16x32_bf16 v[6:9], v[180:183], v[220:223], v[6:9]
	v_mfma_f32_16x16x32_bf16 v[2:5], v[188:191], v[220:223], v[2:5]
	s_setprio 0
	s_barrier
	s_add_i32 s50, s50, 2
	s_add_u32 s25, s25, 0x100
	s_addc_u32 s49, s49, 0
	s_add_u32 s16, s16, 0x100
	s_addc_u32 s17, s17, 0
	s_cmp_lt_u32 s50, 30

; #define LAS __attribute__((address_space(3)))
; #define PG8_STAGE(bufoff, gbase, voff) do { _Pragma("unroll") for (int _i = 0; _i < 2; ++_i) \
;         __builtin_amdgcn_global_load_lds((const unsigned*)((const char*)(gbase) + (voff)[_i]), (LAS unsigned*)(lds + (bufoff) + ldsw + _i * 8192), 16, 0, 0); } while (0)
; #define PG8_WAIT_V(n) asm volatile("s_waitcnt vmcnt(" #n ")" ::: "memory")
; #define PG8_BAR __builtin_amdgcn_s_barrier()
;     __device__ __forceinline__ void operator()(const f32x4 (&acc)[2][2][4][2], const Unit& u, int wr, int wc, int fr, int fq) const {
;         const int s = u.pm >> 5, lane = fq * 16 + fr, rr = lane >> 3, pc = lane & 7;
;         const float* __restrict__ xi = xin + (size_t)u.pm * BM * DM; float* __restrict__ xo = xout + (size_t)u.pm * BM * DM; bf16_t* __restrict__ ho = Hn + (size_t)u.pm * BM * DM;
;         LAS unsigned char* st = lds_epi + (wr * 4 + wc) * 2304;
;         LAS float* sst = (LAS float*)(lds_epi + 18432 + (wr * 4 + wc) * 512);
;         const int colr = u.pn * BM + wc * 64 + 4 * pc;
;         const unsigned eb = (unsigned)((wr * 64 + rr) * DM + colr);
;         f32x4 gv[2], gsn[2];
; #pragma unroll
;         for (int bj = 0; bj < 2; ++bj) { gv[bj] = *(const f32x4*)(gate + (size_t)s * MODW + colr + bj * 32) * (0.5f * GS2);
;             if (!PLAIN) gsn[bj] = *(const f32x4*)(gnext + colr + bj * 32) * (*(const f32x4*)(scnext + (size_t)s * MODW + colr + bj * 32) + 1.0f); else gsn[bj] = gv[bj]; }
;         const unsigned wr_off = (unsigned)(fr * 144 + 16 * fq), rd_off = (unsigned)(rr * 144 + pc * 16);
;         const bool odd = (rr & 1) != 0;
; template <class Epi, class Sched, bool ALIGN_EPI = false, bool SP2 = false>
; __device__ __forceinline__ void gemm_phase(LAS unsigned char* lds, const Gemm g, const Sched& S, const Epi& E) {
;     ...
;     if constexpr (SP2) {
;         PG8_STAGE(PG8_SB(0, 0), cB, voffB); PG8_STAGE(PG8_SB(0, 1), cB + hstepB, voffB); PG8_STAGE(PG8_SA(0, 0), cA, voffA); PG8_STAGE(PG8_SA(0, 1), cA + hstep, voffA);
;         if (wr == 1) PG8_BAR;
;         PG8_WAIT_V(2); PG8_BAR;
;         PG8_STAGE(PG8_SB(1, 0), cB + kstep, voffB); PG8_STAGE(PG8_SA(1, 0), cA + kstep, voffA); PG8_STAGE(PG8_SB(1, 1), cB + hstepB + kstep, voffB);
;         PG8_WAIT_V(6); PG8_BAR;
.LBB0_1912:
	s_and_b32 s3, s3, 3
	s_lshl_b32 s22, s5, 6
	s_lshl_b32 s15, s5, 13
	s_lshl_b32 s17, s3, 12
	s_add_u32 s33, s48, 0x9e000
	s_mov_b64 s[54:55], s[50:51]
	s_addc_u32 s34, s49, 0
	s_mov_b64 s[52:53], s[48:49]
	v_readlane_b32 s36, v253, 2
	v_readlane_b32 s48, v253, 14
	v_readlane_b32 s49, v253, 15
	s_mov_b64 s[12:13], s[48:49]
	s_add_u32 s10, s12, 0x8000
	s_addc_u32 s11, s13, 0
	s_add_u32 s35, s52, 0xa2000
	s_mov_b64 s[12:13], 0x80
	v_readlane_b32 s37, v253, 3
	s_addc_u32 s36, s53, 0
	s_add_i32 m0, s27, 0x18000
	v_lshl_add_u64 v[8:9], v[8:9], 0, s[12:13]
	s_waitcnt vmcnt(2)
	s_barrier
	global_load_lds_dwordx4 v[8:9], off
	v_lshl_add_u64 v[4:5], v[4:5], 0, s[12:13]
	s_add_i32 m0, s27, 0x1a000
	s_add_i32 s37, s27, 0x8000
	s_add_i32 s48, s27, 0xa000
	global_load_lds_dwordx4 v[4:5], off
	v_lshl_add_u64 v[2:3], v[2:3], 0, s[12:13]
	s_mov_b32 m0, s37
	s_add_u32 s24, s20, 0x58080
	global_load_lds_dwordx4 v[2:3], off
	v_lshl_add_u64 v[2:3], v[6:7], 0, s[12:13]
	s_mov_b32 m0, s48
	s_addc_u32 s25, s21, 0
	global_load_lds_dwordx4 v[2:3], off
	s_add_i32 m0, s27, 0x1c000
	v_lshl_add_u64 v[2:3], s[24:25], 0, v[148:149]
	global_load_lds_dwordx4 v[2:3], off
	v_lshl_add_u64 v[2:3], s[24:25], 0, v[152:153]
	s_add_i32 m0, s27, 0x1e000
	v_and_b32_e32 v4, 48, v10
	global_load_lds_dwordx4 v[2:3], off
	v_and_b32_e32 v2, 15, v10
	v_lshlrev_b32_e32 v3, 2, v10
	v_lshl_or_b32 v1, v2, 6, v4
	v_and_b32_e32 v3, 32, v3
	s_cmpk_lt_u32 s14, 0x100
	v_bitop3_b32 v5, v1, s15, v3 bitop3:0xde
	s_cselect_b64 s[14:15], -1, 0
	v_and_b32_e32 v7, 7, v10
	s_lshl_b32 s5, s5, 2
	v_bfe_u32 v6, v10, 3, 3
	s_or_b32 s5, s5, s3
	v_lshlrev_b32_e32 v8, 2, v7
	s_ashr_i32 s23, s22, 31
	v_bitop3_b32 v1, v1, s17, v3 bitop3:0xde
	s_mul_i32 s17, s5, 0x900
	s_lshl_b32 s5, s5, 9
	v_lshl_or_b32 v192, s3, 6, v8
	v_or_b32_e32 v8, s22, v6
	s_ashr_i32 s49, s1, 31
	s_lshl_b64 s[22:23], s[22:23], 2
	s_add_u32 s22, s6, s22
	s_addc_u32 s23, s7, s23
	s_add_i32 s3, s17, 0
	v_and_b32_e32 v3, 63, v10
	s_add_i32 s3, s3, 0x20000
	v_readlane_b32 s38, v253, 4
	v_readlane_b32 s39, v253, 5
	v_readlane_b32 s40, v253, 6
	v_readlane_b32 s41, v253, 7
	v_readlane_b32 s42, v253, 8
	v_readlane_b32 s43, v253, 9
	v_lshlrev_b32_e32 v154, 2, v3
	s_movk_i32 s17, 0x90
	v_mov_b32_e32 v3, s3
	v_lshlrev_b32_e32 v193, 11, v8
	v_lshlrev_b32_e32 v8, 4, v7
	v_cmp_gt_u32_e64 s[38:39], 8, v2
	v_cmp_lt_u32_e64 s[40:41], 7, v2
	v_cmp_eq_u32_e64 s[42:43], 0, v7
	v_mad_u32_u24 v7, v2, s17, v3
	v_mad_u32_u24 v9, v6, s17, v3
	v_lshrrev_b32_e32 v3, 1, v15
	v_mul_lo_u32 v2, v16, s2
	v_lshl_add_u64 v[156:157], s[22:23], 0, v[154:155]
	s_add_i32 s5, s5, 0
	v_mad_u64_u32 v[2:3], s[22:23], v3, s16, v[2:3]
	s_add_i32 s5, s5, 0x24800
	v_or_b32_e32 v2, v2, v17
	v_add_u32_e32 v195, s5, v154
	v_add_lshl_u32 v154, v2, v18, 1
	v_lshrrev_b32_e32 v3, 1, v11
	v_mul_lo_u32 v2, v12, s2
	v_mad_u64_u32 v[2:3], s[2:3], v3, s16, v[2:3]
	v_readlane_b32 s50, v253, 16
	v_readlane_b32 s51, v253, 17
	s_waitcnt vmcnt(0)
	s_mov_b64 s[22:23], 0x160080
	v_or_b32_e32 v2, v2, v13
	v_lshl_add_u64 v[158:159], v[154:155], 0, s[22:23]
	v_add_lshl_u32 v154, v2, v14, 1
	s_add_i32 s50, 0, 0x10000
	s_add_i32 s51, 0, 0x14000
	v_mbcnt_lo_u32_b32 v2, -1, 0
	v_lshl_add_u32 v194, v6, 2, s5
	v_lshl_add_u64 v[160:161], v[154:155], 0, s[22:23]
	v_mov_b64_e32 v[162:163], 0x400
	v_mov_b64_e32 v[164:165], 0x3ff
	v_add_u32_e32 v196, s50, v1
	v_add_u32_e32 v197, s51, v1
	v_add_u32_e32 v198, 0, v5
	v_mbcnt_hi_u32_b32 v199, -1, v2
	v_add_u32_e32 v200, v7, v4
	v_add_u32_e32 v201, v9, v8
	v_readlane_b32 s44, v253, 10
	v_readlane_b32 s45, v253, 11
	v_readlane_b32 s46, v253, 12
	v_readlane_b32 s47, v253, 13
	s_barrier
	s_branch .LBB0_1915

; #define PG8_STAGE(bufoff, gbase, voff) do { _Pragma("unroll") for (int _i = 0; _i < 2; ++_i) \
;         __builtin_amdgcn_global_load_lds((const unsigned*)((const char*)(gbase) + (voff)[_i]), (LAS unsigned*)(lds + (bufoff) + ldsw + _i * 8192), 16, 0, 0); } while (0)
; #define PG8_LDA(dst, b, h) do { _Pragma("unroll") for (int m = 0; m < 4; ++m) _Pragma("unroll") for (int k = 0; k < 2; ++k) dst[m][k] = *(const LAS bf16x8*)(lds + PG8_SA(b, h) + aoff + m * 2048 + k * 1024); } while (0)
; #define PG8_LDB(dst, b, h) do { _Pragma("unroll") for (int n = 0; n < 2; ++n) _Pragma("unroll") for (int k = 0; k < 2; ++k) dst[n][k] = *(const LAS bf16x8*)(lds + PG8_SB(b, h) + boff + n * 2048 + k * 1024); } while (0)
; #define PG8_MMA(ai, bj, At, Bt) do { __builtin_amdgcn_s_setprio(1); _Pragma("unroll") for (int m = 0; m < 4; ++m) _Pragma("unroll") for (int n = 0; n < 2; ++n) _Pragma("unroll") for (int k = 0; k < 2; ++k) \
;         acc[ai][bj][m][n] = __builtin_amdgcn_mfma_f32_16x16x32_bf16(Bt[n][k], At[m][k], acc[ai][bj][m][n], 0, 0, 0); __builtin_amdgcn_s_setprio(0); } while (0)
; #define PG8_WAIT_V(n) asm volatile("s_waitcnt vmcnt(" #n ")" ::: "memory")
; #define PG8_WAIT_L(n) asm volatile("s_waitcnt lgkmcnt(" #n ")" ::: "memory")
; template <class Epi, class Sched, bool ALIGN_EPI = false, bool SP2 = false>
; __device__ __forceinline__ void gemm_phase(LAS unsigned char* lds, const Gemm g, const Sched& S, const Epi& E) {
;     ...
;         for (int t = 0; t < nt; t += 2) {
;             const bool last = (t == nt - 2);
;             const char* a1 = cA + (size_t)(t + 1) * kstep;
;             const char* a2 = last ? nA : cA + (size_t)(t + 2) * kstep; const char* b2 = last ? nB : cB + (size_t)(t + 2) * kstep;
;             const char* a3 = a2 + kstep; const char* b3 = b2 + kstep;
;             if (last && has_next) S.a_ready(nxt);
;             if constexpr (SP2) {
;             PG8_LDB(B0, 0, 0); PG8_LDB(B1, 0, 1); PG8_SCHED; PG8_LDA(At, 0, 0); PG8_STAGE(PG8_SA(1, 1), a1 + hstep, voffA);
;             PG8_WAIT_V(8); PG8_WAIT_L(0); PG8_BAR; PG8_MMA(0, 0, At, B0); PG8_MMA(0, 1, At, B1); PG8_BAR; PG8_SCHED;
;             PG8_LDA(At, 0, 1); PG8_STAGE(PG8_SB(0, 0), b2, voffB); PG8_STAGE(PG8_SB(0, 1), b2 + hstepB, voffB); PG8_STAGE(PG8_SA(0, 0), a2, voffA);
;             PG8_WAIT_V(8); PG8_WAIT_L(0); PG8_BAR; PG8_MMA(1, 0, At, B0); PG8_MMA(1, 1, At, B1); PG8_BAR; PG8_SCHED;
.LBB0_1925:
	s_add_u32 s5, s20, 0x100
	s_addc_u32 s24, s21, 0
	s_mov_b32 s25, -2
	s_waitcnt vmcnt(0)
	ds_read_b128 v[130:133], v196
	ds_read_b128 v[134:137], v196 offset:1024
	ds_read_b128 v[138:141], v196 offset:2048
	ds_read_b128 v[142:145], v196 offset:3072
	ds_read_b128 v[166:169], v197
	ds_read_b128 v[170:173], v197 offset:1024
	ds_read_b128 v[174:177], v197 offset:2048
	ds_read_b128 v[178:181], v197 offset:3072
	s_add_u32 s20, s18, 0x100
	s_addc_u32 s21, s19, 0
	s_cmpk_eq_i32 s25, 0x54
	s_cselect_b32 s47, s17, s21
	s_cselect_b32 s46, s16, s20
	s_cselect_b32 s23, s3, s24
	s_cselect_b32 s22, s2, s5
	v_lshl_add_u64 v[190:191], s[18:19], 0, v[160:161]
	s_add_i32 m0, s27, 0xc000
	ds_read_b128 v[182:185], v198
	ds_read_b128 v[186:189], v198 offset:1024
	ds_read_b128 v[202:205], v198 offset:2048
	ds_read_b128 v[206:209], v198 offset:3072
	ds_read_b128 v[210:213], v198 offset:4096
	ds_read_b128 v[214:217], v198 offset:5120
	ds_read_b128 v[218:221], v198 offset:6144
	ds_read_b128 v[222:225], v198 offset:7168
	global_load_lds_dwordx4 v[190:191], off
	v_lshl_add_u64 v[190:191], s[18:19], 0, v[158:159]
	s_add_i32 m0, s27, 0xe000
	s_nop 0
	global_load_lds_dwordx4 v[190:191], off
	s_waitcnt lgkmcnt(0)
	s_barrier
	s_setprio 1
	s_waitcnt lgkmcnt(0)
	v_mfma_f32_16x16x32_bf16 v[126:129], v[130:133], v[182:185], 0
	v_mfma_f32_16x16x32_bf16 v[122:125], v[138:141], v[182:185], 0
	v_mfma_f32_16x16x32_bf16 v[110:113], v[130:133], v[202:205], 0
	v_mfma_f32_16x16x32_bf16 v[106:109], v[138:141], v[202:205], 0
	v_mfma_f32_16x16x32_bf16 v[94:97], v[130:133], v[210:213], 0
	v_mfma_f32_16x16x32_bf16 v[90:93], v[138:141], v[210:213], 0
	v_mfma_f32_16x16x32_bf16 v[78:81], v[130:133], v[218:221], 0
	v_mfma_f32_16x16x32_bf16 v[74:77], v[138:141], v[218:221], 0
	v_mfma_f32_16x16x32_bf16 v[126:129], v[134:137], v[186:189], v[126:129]
	v_mfma_f32_16x16x32_bf16 v[122:125], v[142:145], v[186:189], v[122:125]
	v_mfma_f32_16x16x32_bf16 v[110:113], v[134:137], v[206:209], v[110:113]
	v_mfma_f32_16x16x32_bf16 v[106:109], v[142:145], v[206:209], v[106:109]
	v_mfma_f32_16x16x32_bf16 v[94:97], v[134:137], v[214:217], v[94:97]
	v_mfma_f32_16x16x32_bf16 v[90:93], v[142:145], v[214:217], v[90:93]
	v_mfma_f32_16x16x32_bf16 v[78:81], v[134:137], v[222:225], v[78:81]
	v_mfma_f32_16x16x32_bf16 v[74:77], v[142:145], v[222:225], v[74:77]
	s_setprio 0
	s_setprio 1
	v_mfma_f32_16x16x32_bf16 v[118:121], v[166:169], v[182:185], 0
	v_mfma_f32_16x16x32_bf16 v[114:117], v[174:177], v[182:185], 0
	v_mfma_f32_16x16x32_bf16 v[102:105], v[166:169], v[202:205], 0
	v_mfma_f32_16x16x32_bf16 v[98:101], v[174:177], v[202:205], 0
	v_mfma_f32_16x16x32_bf16 v[86:89], v[166:169], v[210:213], 0
	v_mfma_f32_16x16x32_bf16 v[82:85], v[174:177], v[210:213], 0
	v_mfma_f32_16x16x32_bf16 v[70:73], v[166:169], v[218:221], 0
	v_mfma_f32_16x16x32_bf16 v[66:69], v[174:177], v[218:221], 0
	v_mfma_f32_16x16x32_bf16 v[118:121], v[170:173], v[186:189], v[118:121]
	v_mfma_f32_16x16x32_bf16 v[114:117], v[178:181], v[186:189], v[114:117]
	v_mfma_f32_16x16x32_bf16 v[102:105], v[170:173], v[206:209], v[102:105]
	v_mfma_f32_16x16x32_bf16 v[98:101], v[178:181], v[206:209], v[98:101]
	v_mfma_f32_16x16x32_bf16 v[86:89], v[170:173], v[214:217], v[86:89]
	v_mfma_f32_16x16x32_bf16 v[82:85], v[178:181], v[214:217], v[82:85]
	v_mfma_f32_16x16x32_bf16 v[70:73], v[170:173], v[222:225], v[70:73]
	v_mfma_f32_16x16x32_bf16 v[66:69], v[178:181], v[222:225], v[66:69]
	s_setprio 0
	s_barrier
	s_add_i32 s18, s50, s26
	v_lshl_add_u64 v[190:191], s[22:23], 0, v[148:149]
	s_mov_b32 m0, s18
	ds_read_b128 v[182:185], v198 offset:16384
	ds_read_b128 v[186:189], v198 offset:17408
	ds_read_b128 v[202:205], v198 offset:18432
	ds_read_b128 v[206:209], v198 offset:19456
	ds_read_b128 v[210:213], v198 offset:20480
	ds_read_b128 v[214:217], v198 offset:21504
	ds_read_b128 v[218:221], v198 offset:22528
	ds_read_b128 v[222:225], v198 offset:23552
	global_load_lds_dwordx4 v[190:191], off
	s_add_i32 m0, s18, 0x2000
	s_add_u32 s18, s22, 0x58000
	v_lshl_add_u64 v[226:227], s[22:23], 0, v[152:153]
	s_addc_u32 s19, s23, 0
	s_add_i32 s54, s51, s26
	global_load_lds_dwordx4 v[226:227], off
	v_lshl_add_u64 v[228:229], s[18:19], 0, v[148:149]
	s_mov_b32 m0, s54
	v_lshl_add_u64 v[230:231], s[46:47], 0, v[150:151]
	global_load_lds_dwordx4 v[228:229], off
	v_lshl_add_u64 v[228:229], s[18:19], 0, v[152:153]
	s_add_i32 m0, s54, 0x2000
	s_nop 0
	global_load_lds_dwordx4 v[228:229], off
	v_lshl_add_u64 v[228:229], s[46:47], 0, v[146:147]
	s_mov_b32 m0, s27
	s_nop 0
	global_load_lds_dwordx4 v[228:229], off
	s_mov_b32 m0, s28
	s_nop 0
	global_load_lds_dwordx4 v[230:231], off
	s_waitcnt lgkmcnt(0)
	s_barrier
; #define PG8_STAGE(bufoff, gbase, voff) do { _Pragma("unroll") for (int _i = 0; _i < 2; ++_i) \
;         __builtin_amdgcn_global_load_lds((const unsigned*)((const char*)(gbase) + (voff)[_i]), (LAS unsigned*)(lds + (bufoff) + ldsw + _i * 8192), 16, 0, 0); } while (0)
; #define PG8_LDA(dst, b, h) do { _Pragma("unroll") for (int m = 0; m < 4; ++m) _Pragma("unroll") for (int k = 0; k < 2; ++k) dst[m][k] = *(const LAS bf16x8*)(lds + PG8_SA(b, h) + aoff + m * 2048 + k * 1024); } while (0)
; #define PG8_LDB(dst, b, h) do { _Pragma("unroll") for (int n = 0; n < 2; ++n) _Pragma("unroll") for (int k = 0; k < 2; ++k) dst[n][k] = *(const LAS bf16x8*)(lds + PG8_SB(b, h) + boff + n * 2048 + k * 1024); } while (0)
; #define PG8_MMA(ai, bj, At, Bt) do { __builtin_amdgcn_s_setprio(1); _Pragma("unroll") for (int m = 0; m < 4; ++m) _Pragma("unroll") for (int n = 0; n < 2; ++n) _Pragma("unroll") for (int k = 0; k < 2; ++k) \
;         acc[ai][bj][m][n] = __builtin_amdgcn_mfma_f32_16x16x32_bf16(Bt[n][k], At[m][k], acc[ai][bj][m][n], 0, 0, 0); __builtin_amdgcn_s_setprio(0); } while (0)
; #define PG8_WAIT_V(n) asm volatile("s_waitcnt vmcnt(" #n ")" ::: "memory")
; #define PG8_WAIT_L(n) asm volatile("s_waitcnt lgkmcnt(" #n ")" ::: "memory")
; #define PG8_BAR __builtin_amdgcn_s_barrier()
; #define PG8_SCHED __builtin_amdgcn_sched_barrier(0)
; template <class Epi, class Sched, bool ALIGN_EPI = false, bool SP2 = false>
; __device__ __forceinline__ void gemm_phase(LAS unsigned char* lds, const Gemm g, const Sched& S, const Epi& E) {
;     ...
;             PG8_WAIT_V(8); PG8_WAIT_L(0); PG8_BAR; PG8_MMA(1, 0, At, B0); PG8_MMA(1, 1, At, B1); PG8_BAR; PG8_SCHED;
;             PG8_LDB(B0, 1, 0); PG8_LDB(B1, 1, 1); PG8_SCHED; PG8_LDA(At, 1, 0); PG8_STAGE(PG8_SA(0, 1), a2 + hstep, voffA);
;             PG8_WAIT_V(8); PG8_WAIT_L(0); PG8_BAR; PG8_MMA(0, 0, At, B0); PG8_MMA(0, 1, At, B1); PG8_BAR; PG8_SCHED;
	s_setprio 1
	s_waitcnt lgkmcnt(0)
	v_mfma_f32_16x16x32_bf16 v[62:65], v[130:133], v[182:185], 0
	v_mfma_f32_16x16x32_bf16 v[58:61], v[138:141], v[182:185], 0
	v_mfma_f32_16x16x32_bf16 v[46:49], v[130:133], v[202:205], 0
	v_mfma_f32_16x16x32_bf16 v[42:45], v[138:141], v[202:205], 0
	v_mfma_f32_16x16x32_bf16 v[30:33], v[130:133], v[210:213], 0
	v_mfma_f32_16x16x32_bf16 v[26:29], v[138:141], v[210:213], 0
	v_mfma_f32_16x16x32_bf16 v[14:17], v[130:133], v[218:221], 0
	v_mfma_f32_16x16x32_bf16 v[10:13], v[138:141], v[218:221], 0
	v_mfma_f32_16x16x32_bf16 v[62:65], v[134:137], v[186:189], v[62:65]
	v_mfma_f32_16x16x32_bf16 v[58:61], v[142:145], v[186:189], v[58:61]
	v_mfma_f32_16x16x32_bf16 v[46:49], v[134:137], v[206:209], v[46:49]
	v_mfma_f32_16x16x32_bf16 v[42:45], v[142:145], v[206:209], v[42:45]
	v_mfma_f32_16x16x32_bf16 v[30:33], v[134:137], v[214:217], v[30:33]
	v_mfma_f32_16x16x32_bf16 v[26:29], v[142:145], v[214:217], v[26:29]
	v_mfma_f32_16x16x32_bf16 v[14:17], v[134:137], v[222:225], v[14:17]
	v_mfma_f32_16x16x32_bf16 v[10:13], v[142:145], v[222:225], v[10:13]
	s_setprio 0
	s_setprio 1
	v_mfma_f32_16x16x32_bf16 v[54:57], v[166:169], v[182:185], 0
	v_mfma_f32_16x16x32_bf16 v[50:53], v[174:177], v[182:185], 0
	v_mfma_f32_16x16x32_bf16 v[38:41], v[166:169], v[202:205], 0
	v_mfma_f32_16x16x32_bf16 v[34:37], v[174:177], v[202:205], 0
	v_mfma_f32_16x16x32_bf16 v[22:25], v[166:169], v[210:213], 0
	v_mfma_f32_16x16x32_bf16 v[18:21], v[174:177], v[210:213], 0
	v_mfma_f32_16x16x32_bf16 v[6:9], v[166:169], v[218:221], 0
	v_mfma_f32_16x16x32_bf16 v[2:5], v[174:177], v[218:221], 0
	v_mfma_f32_16x16x32_bf16 v[54:57], v[170:173], v[186:189], v[54:57]
	v_mfma_f32_16x16x32_bf16 v[50:53], v[178:181], v[186:189], v[50:53]
	v_mfma_f32_16x16x32_bf16 v[38:41], v[170:173], v[206:209], v[38:41]
	v_mfma_f32_16x16x32_bf16 v[34:37], v[178:181], v[206:209], v[34:37]
	v_mfma_f32_16x16x32_bf16 v[22:25], v[170:173], v[214:217], v[22:25]
	v_mfma_f32_16x16x32_bf16 v[18:21], v[178:181], v[214:217], v[18:21]
	v_mfma_f32_16x16x32_bf16 v[6:9], v[170:173], v[222:225], v[6:9]
	v_mfma_f32_16x16x32_bf16 v[2:5], v[178:181], v[222:225], v[2:5]
	s_setprio 0
	s_barrier
	s_add_i32 s54, 0, 0x18000
	s_add_i32 s55, 0, 0x1c000
	v_add_u32_e32 v142, s54, v1
	v_add_u32_e32 v154, s55, v1
	ds_read_b128 v[130:133], v142
	ds_read_b128 v[134:137], v142 offset:1024
	ds_read_b128 v[138:141], v142 offset:2048
	ds_read_b128 v[142:145], v142 offset:3072
	ds_read_b128 v[166:169], v154
	ds_read_b128 v[170:173], v154 offset:1024
	ds_read_b128 v[174:177], v154 offset:2048
	ds_read_b128 v[178:181], v154 offset:3072
	s_add_u32 s18, s46, 0x160000
	s_addc_u32 s19, s47, 0
	s_mov_b32 m0, s29
	v_lshl_add_u64 v[232:233], s[18:19], 0, v[146:147]
	ds_read_b128 v[182:185], v198 offset:32768
	ds_read_b128 v[186:189], v198 offset:33792
	ds_read_b128 v[202:205], v198 offset:34816
	ds_read_b128 v[206:209], v198 offset:35840
	ds_read_b128 v[210:213], v198 offset:36864
	ds_read_b128 v[214:217], v198 offset:37888
	ds_read_b128 v[218:221], v198 offset:38912
	ds_read_b128 v[222:225], v198 offset:39936
	global_load_lds_dwordx4 v[232:233], off
	v_lshl_add_u64 v[232:233], s[18:19], 0, v[150:151]
	s_mov_b32 m0, s30
	s_nop 0
	global_load_lds_dwordx4 v[232:233], off
	s_waitcnt vmcnt(8)
	s_waitcnt lgkmcnt(0)
	s_barrier
	s_setprio 1
	s_waitcnt lgkmcnt(0)
	v_mfma_f32_16x16x32_bf16 v[126:129], v[130:133], v[182:185], v[126:129]
	v_mfma_f32_16x16x32_bf16 v[122:125], v[138:141], v[182:185], v[122:125]
	v_mfma_f32_16x16x32_bf16 v[110:113], v[130:133], v[202:205], v[110:113]
	v_mfma_f32_16x16x32_bf16 v[106:109], v[138:141], v[202:205], v[106:109]
	v_mfma_f32_16x16x32_bf16 v[94:97], v[130:133], v[210:213], v[94:97]
	v_mfma_f32_16x16x32_bf16 v[90:93], v[138:141], v[210:213], v[90:93]
	v_mfma_f32_16x16x32_bf16 v[78:81], v[130:133], v[218:221], v[78:81]
	v_mfma_f32_16x16x32_bf16 v[74:77], v[138:141], v[218:221], v[74:77]
	v_mfma_f32_16x16x32_bf16 v[126:129], v[134:137], v[186:189], v[126:129]
	v_mfma_f32_16x16x32_bf16 v[122:125], v[142:145], v[186:189], v[122:125]
	v_mfma_f32_16x16x32_bf16 v[110:113], v[134:137], v[206:209], v[110:113]
	v_mfma_f32_16x16x32_bf16 v[106:109], v[142:145], v[206:209], v[106:109]
	v_mfma_f32_16x16x32_bf16 v[94:97], v[134:137], v[214:217], v[94:97]
	v_mfma_f32_16x16x32_bf16 v[90:93], v[142:145], v[214:217], v[90:93]
	v_mfma_f32_16x16x32_bf16 v[78:81], v[134:137], v[222:225], v[78:81]
	v_mfma_f32_16x16x32_bf16 v[74:77], v[142:145], v[222:225], v[74:77]
	s_setprio 0
	s_setprio 1
	v_mfma_f32_16x16x32_bf16 v[118:121], v[166:169], v[182:185], v[118:121]
	v_mfma_f32_16x16x32_bf16 v[114:117], v[174:177], v[182:185], v[114:117]
	v_mfma_f32_16x16x32_bf16 v[102:105], v[166:169], v[202:205], v[102:105]
	v_mfma_f32_16x16x32_bf16 v[98:101], v[174:177], v[202:205], v[98:101]
	v_mfma_f32_16x16x32_bf16 v[86:89], v[166:169], v[210:213], v[86:89]
	v_mfma_f32_16x16x32_bf16 v[82:85], v[174:177], v[210:213], v[82:85]
	v_mfma_f32_16x16x32_bf16 v[70:73], v[166:169], v[218:221], v[70:73]
	v_mfma_f32_16x16x32_bf16 v[66:69], v[174:177], v[218:221], v[66:69]
	v_mfma_f32_16x16x32_bf16 v[118:121], v[170:173], v[186:189], v[118:121]
	v_mfma_f32_16x16x32_bf16 v[114:117], v[178:181], v[186:189], v[114:117]
	v_mfma_f32_16x16x32_bf16 v[102:105], v[170:173], v[206:209], v[102:105]
	v_mfma_f32_16x16x32_bf16 v[98:101], v[178:181], v[206:209], v[98:101]
	v_mfma_f32_16x16x32_bf16 v[86:89], v[170:173], v[214:217], v[86:89]
	v_mfma_f32_16x16x32_bf16 v[82:85], v[178:181], v[214:217], v[82:85]
	v_mfma_f32_16x16x32_bf16 v[70:73], v[170:173], v[222:225], v[70:73]
	v_mfma_f32_16x16x32_bf16 v[66:69], v[178:181], v[222:225], v[66:69]
	s_setprio 0
	s_barrier
; #define PG8_STAGE(bufoff, gbase, voff) do { _Pragma("unroll") for (int _i = 0; _i < 2; ++_i) \
;         __builtin_amdgcn_global_load_lds((const unsigned*)((const char*)(gbase) + (voff)[_i]), (LAS unsigned*)(lds + (bufoff) + ldsw + _i * 8192), 16, 0, 0); } while (0)
; #define PG8_LDA(dst, b, h) do { _Pragma("unroll") for (int m = 0; m < 4; ++m) _Pragma("unroll") for (int k = 0; k < 2; ++k) dst[m][k] = *(const LAS bf16x8*)(lds + PG8_SA(b, h) + aoff + m * 2048 + k * 1024); } while (0)
; #define PG8_MMA(ai, bj, At, Bt) do { __builtin_amdgcn_s_setprio(1); _Pragma("unroll") for (int m = 0; m < 4; ++m) _Pragma("unroll") for (int n = 0; n < 2; ++n) _Pragma("unroll") for (int k = 0; k < 2; ++k) \
;         acc[ai][bj][m][n] = __builtin_amdgcn_mfma_f32_16x16x32_bf16(Bt[n][k], At[m][k], acc[ai][bj][m][n], 0, 0, 0); __builtin_amdgcn_s_setprio(0); } while (0)
; #define PG8_WAIT_V(n) asm volatile("s_waitcnt vmcnt(" #n ")" ::: "memory")
; #define PG8_WAIT_L(n) asm volatile("s_waitcnt lgkmcnt(" #n ")" ::: "memory")
; #define PG8_BAR __builtin_amdgcn_s_barrier()
; #define PG8_SCHED __builtin_amdgcn_sched_barrier(0)
; template <class Epi, class Sched, bool ALIGN_EPI = false, bool SP2 = false>
; __device__ __forceinline__ void gemm_phase(LAS unsigned char* lds, const Gemm g, const Sched& S, const Epi& E) {
;     ...
;         for (int t = 0; t < nt; t += 2) {
;             const bool last = (t == nt - 2);
;             const char* a1 = cA + (size_t)(t + 1) * kstep;
;             const char* a2 = last ? nA : cA + (size_t)(t + 2) * kstep; const char* b2 = last ? nB : cB + (size_t)(t + 2) * kstep;
;     ...
;             PG8_LDA(At, 1, 1); PG8_STAGE(PG8_SB(1, 0), b3, voffB); PG8_STAGE(PG8_SB(1, 1), b3 + hstepB, voffB); PG8_STAGE(PG8_SA(1, 0), a3, voffA);
;             PG8_WAIT_V(8); PG8_WAIT_L(0); PG8_BAR; PG8_MMA(1, 0, At, B0); PG8_MMA(1, 1, At, B1); PG8_BAR; PG8_SCHED;
	s_add_i32 s18, s54, s26
	v_lshl_add_u64 v[190:191], v[190:191], 0, s[12:13]
	s_mov_b32 m0, s18
	ds_read_b128 v[182:185], v198 offset:49152
	ds_read_b128 v[186:189], v198 offset:50176
	ds_read_b128 v[202:205], v198 offset:51200
	ds_read_b128 v[206:209], v198 offset:52224
	ds_read_b128 v[210:213], v198 offset:53248
	ds_read_b128 v[214:217], v198 offset:54272
	ds_read_b128 v[218:221], v198 offset:55296
	ds_read_b128 v[222:225], v198 offset:56320
	global_load_lds_dwordx4 v[190:191], off
	s_add_i32 m0, s18, 0x2000
	s_add_u32 s18, s22, 0x58080
	v_lshl_add_u64 v[190:191], v[226:227], 0, s[12:13]
	s_addc_u32 s19, s23, 0
	s_add_i32 s22, s55, s26
	global_load_lds_dwordx4 v[190:191], off
	v_lshl_add_u64 v[190:191], s[18:19], 0, v[148:149]
	s_mov_b32 m0, s22
	s_nop 0
	global_load_lds_dwordx4 v[190:191], off
	v_lshl_add_u64 v[190:191], s[18:19], 0, v[152:153]
	s_add_i32 m0, s22, 0x2000
	s_nop 0
	global_load_lds_dwordx4 v[190:191], off
	v_lshl_add_u64 v[190:191], v[228:229], 0, s[12:13]
	s_mov_b32 m0, s37
	s_nop 0
	global_load_lds_dwordx4 v[190:191], off
	v_lshl_add_u64 v[190:191], v[230:231], 0, s[12:13]
	s_mov_b32 m0, s48
	s_nop 0
	global_load_lds_dwordx4 v[190:191], off
	s_waitcnt vmcnt(8)
	s_waitcnt lgkmcnt(0)
	s_barrier
	s_setprio 1
	s_waitcnt lgkmcnt(0)
	v_mfma_f32_16x16x32_bf16 v[62:65], v[130:133], v[182:185], v[62:65]
	v_mfma_f32_16x16x32_bf16 v[58:61], v[138:141], v[182:185], v[58:61]
	v_mfma_f32_16x16x32_bf16 v[46:49], v[130:133], v[202:205], v[46:49]
	v_mfma_f32_16x16x32_bf16 v[42:45], v[138:141], v[202:205], v[42:45]
	v_mfma_f32_16x16x32_bf16 v[30:33], v[130:133], v[210:213], v[30:33]
	v_mfma_f32_16x16x32_bf16 v[26:29], v[138:141], v[210:213], v[26:29]
	v_mfma_f32_16x16x32_bf16 v[14:17], v[130:133], v[218:221], v[14:17]
	v_mfma_f32_16x16x32_bf16 v[10:13], v[138:141], v[218:221], v[10:13]
	v_mfma_f32_16x16x32_bf16 v[62:65], v[134:137], v[186:189], v[62:65]
	v_mfma_f32_16x16x32_bf16 v[58:61], v[142:145], v[186:189], v[58:61]
	v_mfma_f32_16x16x32_bf16 v[46:49], v[134:137], v[206:209], v[46:49]
	v_mfma_f32_16x16x32_bf16 v[42:45], v[142:145], v[206:209], v[42:45]
	v_mfma_f32_16x16x32_bf16 v[30:33], v[134:137], v[214:217], v[30:33]
	v_mfma_f32_16x16x32_bf16 v[26:29], v[142:145], v[214:217], v[26:29]
	v_mfma_f32_16x16x32_bf16 v[14:17], v[134:137], v[222:225], v[14:17]
	v_mfma_f32_16x16x32_bf16 v[10:13], v[142:145], v[222:225], v[10:13]
	s_setprio 0
	s_setprio 1
	v_mfma_f32_16x16x32_bf16 v[54:57], v[166:169], v[182:185], v[54:57]
	v_mfma_f32_16x16x32_bf16 v[50:53], v[174:177], v[182:185], v[50:53]
	v_mfma_f32_16x16x32_bf16 v[38:41], v[166:169], v[202:205], v[38:41]
	v_mfma_f32_16x16x32_bf16 v[34:37], v[174:177], v[202:205], v[34:37]
	v_mfma_f32_16x16x32_bf16 v[22:25], v[166:169], v[210:213], v[22:25]
	v_mfma_f32_16x16x32_bf16 v[18:21], v[174:177], v[210:213], v[18:21]
	v_mfma_f32_16x16x32_bf16 v[6:9], v[166:169], v[218:221], v[6:9]
	v_mfma_f32_16x16x32_bf16 v[2:5], v[174:177], v[218:221], v[2:5]
	v_mfma_f32_16x16x32_bf16 v[54:57], v[170:173], v[186:189], v[54:57]
	v_mfma_f32_16x16x32_bf16 v[50:53], v[178:181], v[186:189], v[50:53]
	v_mfma_f32_16x16x32_bf16 v[38:41], v[170:173], v[206:209], v[38:41]
	v_mfma_f32_16x16x32_bf16 v[34:37], v[178:181], v[206:209], v[34:37]
	v_mfma_f32_16x16x32_bf16 v[22:25], v[170:173], v[214:217], v[22:25]
	v_mfma_f32_16x16x32_bf16 v[18:21], v[178:181], v[214:217], v[18:21]
	v_mfma_f32_16x16x32_bf16 v[6:9], v[170:173], v[222:225], v[6:9]
	v_mfma_f32_16x16x32_bf16 v[2:5], v[178:181], v[222:225], v[2:5]
	s_setprio 0
	s_barrier
	s_add_i32 s25, s25, 2
	s_add_u32 s5, s5, 0x100
	s_addc_u32 s24, s24, 0
	s_cmpk_lt_u32 s25, 0x56
	s_mov_b64 s[18:19], s[20:21]

; __device__ __forceinline__ float row_rstd(const float* ss, int row) { return 1.0f / sqrtf(ss[row] * (1.0f / DM) + 1e-6f); }
; #define PG8_STAGE(bufoff, gbase, voff) do { _Pragma("unroll") for (int _i = 0; _i < 2; ++_i) \
;         __builtin_amdgcn_global_load_lds((const unsigned*)((const char*)(gbase) + (voff)[_i]), (LAS unsigned*)(lds + (bufoff) + ldsw + _i * 8192), 16, 0, 0); } while (0)
; #define PG8_WAIT_V(n) asm volatile("s_waitcnt vmcnt(" #n ")" ::: "memory")
; #define PG8_BAR __builtin_amdgcn_s_barrier()
;     __device__ __forceinline__ void operator()(const f32x4 (&acc)[2][2][4][2], const Unit& u, int wr, int wc, int fr, int fq) const {
;         const int row0 = u.pm * BM + wr * 64 + fr, col0 = u.pn * BM + wc * 64 + 8 * fq;
;         const bool lat = u.pm < ML / BM; const int s = lat ? (u.pm >> 5) : 4;
;         const float* bp = bias + (size_t)s * BIAS_N + col0;
;         const f32x4 b00 = *(const f32x4*)bp, b01 = *(const f32x4*)(bp + 4), b10 = *(const f32x4*)(bp + 32), b11 = *(const f32x4*)(bp + 36);
;         const int lane = fq * 16 + fr;
;         const float rsl0 = row_rstd(ss, u.pm * BM + wr * 64 + lane), rsl1 = row_rstd(ss, u.pm * BM + HALF + wr * 64 + lane);
;         const bool odd = (fr & 1) != 0;
;         const bool ktile = (u.pn == 2) || (u.pn == 3) || (u.pn == 12), wa = (u.pn == 12);
; template <class Epi, class Sched, bool ALIGN_EPI = false, bool SP2 = false>
; __device__ __forceinline__ void gemm_phase(LAS unsigned char* lds, const Gemm g, const Sched& S, const Epi& E) {
;     ...
;     if constexpr (SP2) {
;         PG8_STAGE(PG8_SB(0, 0), cB, voffB); PG8_STAGE(PG8_SB(0, 1), cB + hstepB, voffB); PG8_STAGE(PG8_SA(0, 0), cA, voffA); PG8_STAGE(PG8_SA(0, 1), cA + hstep, voffA);
;         if (wr == 1) PG8_BAR;
;         PG8_WAIT_V(2); PG8_BAR;
;         PG8_STAGE(PG8_SB(1, 0), cB + kstep, voffB); PG8_STAGE(PG8_SA(1, 0), cA + kstep, voffA); PG8_STAGE(PG8_SB(1, 1), cB + hstepB + kstep, voffB);
;         PG8_WAIT_V(6); PG8_BAR;
.LBB0_2137:
	v_and_b32_e32 v1, 15, v10
	s_lshl_b32 s50, s5, 6
	v_bfe_u32 v17, v10, 4, 2
	v_or_b32_e32 v19, s50, v1
	v_lshlrev_b32_e32 v184, 4, v17
	v_lshlrev_b32_e32 v21, 2, v19
	s_and_b32 s3, s4, 3
	v_lshl_or_b32 v20, v1, 6, v184
	s_lshl_b32 s4, s5, 13
	v_and_b32_e32 v22, 32, v21
	v_lshlrev_b32_e32 v23, 2, v10
	v_bitop3_b32 v22, v20, s4, v22 bitop3:0xde
	s_lshl_b32 s4, s3, 12
	v_and_b32_e32 v23, 32, v23
	v_readlane_b32 s12, v253, 38
	v_bitop3_b32 v185, v20, s4, v23 bitop3:0xde
	v_readlane_b32 s13, v253, 39
	s_add_u32 s51, s12, 0x2ec000
	s_mov_b64 s[4:5], 0x80
	s_addc_u32 s52, s13, 0
	s_add_i32 m0, s28, 0x18000
	v_lshl_add_u64 v[8:9], v[8:9], 0, s[4:5]
	s_waitcnt vmcnt(2)
	s_barrier
	global_load_lds_dwordx4 v[8:9], off
	v_lshl_add_u64 v[6:7], v[6:7], 0, s[4:5]
	s_add_i32 m0, s28, 0x1a000
	s_add_i32 s53, s28, 0x8000
	s_add_i32 s54, s28, 0xa000
	global_load_lds_dwordx4 v[6:7], off
	v_lshl_add_u64 v[2:3], v[2:3], 0, s[4:5]
	s_mov_b32 m0, s53
	s_add_u32 s8, s20, 0x20080
	global_load_lds_dwordx4 v[2:3], off
	v_lshl_add_u64 v[2:3], v[4:5], 0, s[4:5]
	s_mov_b32 m0, s54
	s_addc_u32 s9, s21, 0
	global_load_lds_dwordx4 v[2:3], off
	s_add_i32 m0, s28, 0x1c000
	v_lshl_add_u64 v[2:3], s[8:9], 0, v[164:165]
	global_load_lds_dwordx4 v[2:3], off
	v_lshl_add_u64 v[2:3], s[8:9], 0, v[168:169]
	s_add_i32 m0, s28, 0x1e000
	s_cmpk_lt_u32 s10, 0x100
	global_load_lds_dwordx4 v[2:3], off
	s_cselect_b64 s[8:9], -1, 0
	s_lshl_b32 s11, s3, 6
	s_and_b32 s12, s11, 64
	v_and_b32_e32 v3, 1, v10
	s_bitcmp0_b32 s10, 6
	v_mov_b32_e32 v6, s3
	s_movk_i32 s10, 0x41
	v_lshlrev_b32_e32 v2, 5, v3
	v_cmp_eq_u32_e64 s[42:43], 1, v3
	v_or_b32_e32 v3, s3, v21
	v_bitop3_b32 v8, v21, s10, v6 bitop3:0x36
	s_movk_i32 s10, 0x81
	v_lshlrev_b32_e32 v18, 3, v17
	v_and_b32_e32 v186, 63, v10
	v_cmp_eq_u32_e64 s[38:39], 0, v17
	v_lshlrev_b32_e32 v5, 4, v19
	v_bfe_i32 v187, v10, 0, 1
	v_bitop3_b32 v188, v10, 1, v10 bitop3:0xc
	v_bitop3_b32 v9, v21, s10, v6 bitop3:0x36
	s_movk_i32 s10, 0xc1
	v_add_u32_e32 v10, 0x200, v3
	v_add_u32_e32 v17, 0x240, v3
	v_add_u32_e32 v19, 0x280, v3
	v_add_u32_e32 v3, 0x2c0, v3
	s_cselect_b64 s[40:41], -1, 0
	v_bitop3_b32 v6, v21, s10, v6 bitop3:0x36
	v_xor_b32_e32 v3, 1, v3
	s_add_i32 s10, 0, 0x25000
	v_lshl_add_u32 v200, v3, 2, s10
	v_lshlrev_b32_e32 v3, 15, v14
	v_and_b32_e32 v3, 0xffff0000, v3
	v_lshl_add_u32 v196, v6, 2, s10
	v_lshl_add_u32 v3, v15, 12, v3
	v_and_b32_e32 v6, 1, v14
	v_lshl_or_b32 v3, v6, 6, v3
	v_lshl_add_u32 v172, v16, 1, v3
	v_lshlrev_b32_e32 v3, 15, v11
	v_and_b32_e32 v3, 0xffff0000, v3
	v_lshl_add_u32 v3, v12, 12, v3
	v_and_b32_e32 v6, 1, v11
	s_waitcnt vmcnt(0)
	v_bitop3_b32 v7, v21, 1, s3 bitop3:0x36
	s_lshl_b32 s3, s3, 2
	v_lshl_or_b32 v3, v6, 6, v3
	v_cndmask_b32_e64 v4, 32, 0, s[42:43]
	v_xor_b32_e32 v10, 1, v10
	v_xor_b32_e32 v17, 1, v17
	v_xor_b32_e32 v19, 1, v19
	s_add_i32 s3, s10, s3
	v_lshl_add_u32 v174, v13, 1, v3
	s_add_i32 s56, 0, 0x10000
	s_add_i32 s57, 0, 0x14000
	v_mbcnt_lo_u32_b32 v3, -1, 0
	v_or_b32_e32 v189, 16, v1
	v_or_b32_e32 v190, 32, v1
	v_or_b32_e32 v191, 48, v1
	s_ashr_i32 s55, s26, 31
	v_or_b32_e32 v192, 0x80, v186
	v_lshl_add_u32 v193, v7, 2, s10
	v_lshl_add_u32 v194, v8, 2, s10
	v_lshl_add_u32 v195, v9, 2, s10
	v_lshl_add_u32 v197, v10, 2, s10
	v_lshl_add_u32 v198, v17, 2, s10
	v_lshl_add_u32 v199, v19, 2, s10
	v_or_b32_e32 v201, s11, v18
	v_mov_b32_e32 v173, v171
	v_mov_b32_e32 v175, v171
	v_mov_b64_e32 v[176:177], 0x738
	v_mov_b64_e32 v[178:179], 0x737
	v_add_u32_e32 v202, s56, v185
	v_add_u32_e32 v203, s57, v185
	v_add_u32_e32 v204, 0, v22
	v_mov_b32_e32 v205, 0x358637bd
	s_mov_b32 s58, 0xf800000
	v_mov_b32_e32 v206, 0x260
	v_mbcnt_hi_u32_b32 v207, -1, v3
	s_lshl_b32 s59, s12, 2
	v_lshlrev_b32_e32 v208, 2, v18
	s_movk_i32 s60, 0x1c00
	v_lshlrev_b32_e32 v170, 1, v2
	v_lshlrev_b32_e32 v180, 1, v4
	v_add_u32_e32 v209, s3, v5
	v_readlane_b32 s14, v253, 40
	v_readlane_b32 s15, v253, 41
	s_barrier
	s_branch .LBB0_2140

;     __device__ bool next(int i, Unit& u) const { if (i != 0 || c >= 128) return false; const int t = c >> 2; u.pm = t & 3; u.pn = t >> 2; u.koff = koff_bytes; u.q = c & 3; return true; }
; #define PG8_STAGE(bufoff, gbase, voff) do { _Pragma("unroll") for (int _i = 0; _i < 2; ++_i) \
;         __builtin_amdgcn_global_load_lds((const unsigned*)((const char*)(gbase) + (voff)[_i]), (LAS unsigned*)(lds + (bufoff) + ldsw + _i * 8192), 16, 0, 0); } while (0)
; #define PG8_LDA(dst, b, h) do { _Pragma("unroll") for (int m = 0; m < 4; ++m) _Pragma("unroll") for (int k = 0; k < 2; ++k) dst[m][k] = *(const LAS bf16x8*)(lds + PG8_SA(b, h) + aoff + m * 2048 + k * 1024); } while (0)
; #define PG8_LDB(dst, b, h) do { _Pragma("unroll") for (int n = 0; n < 2; ++n) _Pragma("unroll") for (int k = 0; k < 2; ++k) dst[n][k] = *(const LAS bf16x8*)(lds + PG8_SB(b, h) + boff + n * 2048 + k * 1024); } while (0)
; #define PG8_WAIT_V(n) asm volatile("s_waitcnt vmcnt(" #n ")" ::: "memory")
; template <class Epi, class Sched, bool ALIGN_EPI = false, bool SP2 = false>
; __device__ __forceinline__ void gemm_phase(LAS unsigned char* lds, const Gemm g, const Sched& S, const Epi& E) {
;     ...
;         const bool has_next = S.next(ui + 1, nxt);
;         const char* nA = has_next ? (const char*)g.A + (size_t)nxt.pm * tstep + nxt.koff : cA; const char* nB = has_next ? (const char*)g.Bt + (size_t)nxt.pn * tstep + nxt.koff : cB;
;         for (int t = 0; t < nt; t += 2) {
;             const bool last = (t == nt - 2);
;             const char* a1 = cA + (size_t)(t + 1) * kstep;
;             const char* a2 = last ? nA : cA + (size_t)(t + 2) * kstep; const char* b2 = last ? nB : cB + (size_t)(t + 2) * kstep;
;             const char* a3 = a2 + kstep; const char* b3 = b2 + kstep;
;             if (last && has_next) S.a_ready(nxt);
;             if constexpr (SP2) {
;             PG8_LDB(B0, 0, 0); PG8_LDB(B1, 0, 1); PG8_SCHED; PG8_LDA(At, 0, 0); PG8_STAGE(PG8_SA(1, 1), a1 + hstep, voffA);
;             PG8_WAIT_V(8); PG8_WAIT_L(0); PG8_BAR; PG8_MMA(0, 0, At, B0); PG8_MMA(0, 1, At, B1); PG8_BAR; PG8_SCHED;
;             PG8_LDA(At, 0, 1); PG8_STAGE(PG8_SB(0, 0), b2, voffB); PG8_STAGE(PG8_SB(0, 1), b2 + hstepB, voffB); PG8_STAGE(PG8_SA(0, 0), a2, voffA);
;             PG8_WAIT_V(8); PG8_WAIT_L(0); PG8_BAR; PG8_MMA(1, 0, At, B0); PG8_MMA(1, 1, At, B1); PG8_BAR; PG8_SCHED;
.LBB0_2142:
	s_ashr_i32 s13, s12, 31
	v_cmp_lt_i64_e64 s[44:45], s[14:15], v[176:177]
	s_lshl_b64 s[14:15], s[12:13], 20
	s_add_u32 s14, s93, s14
	s_addc_u32 s15, s92, s15
	s_and_b64 s[16:17], s[44:45], exec
	s_cselect_b32 s3, s15, s23
	s_cselect_b32 s13, s14, s22
	s_ashr_i32 s11, s10, 31
	s_lshl_b64 s[16:17], s[10:11], 20
	v_readlane_b32 s24, v254, 58
	v_readlane_b32 s25, v254, 59
	s_add_u32 s16, s24, s16
	s_addc_u32 s17, s25, s17
	s_and_b64 s[24:25], s[44:45], exec
	s_cselect_b32 s11, s17, s21
	s_cselect_b32 s19, s16, s20
	s_add_u32 s24, s20, 0x100
	s_addc_u32 s25, s21, 0
	s_add_u32 s20, s22, 0x80080
	s_addc_u32 s21, s23, 0
	s_mov_b32 s34, -2
	s_waitcnt vmcnt(0)
	ds_read_b128 v[34:37], v202
	ds_read_b128 v[38:41], v202 offset:1024
	ds_read_b128 v[42:45], v202 offset:2048
	ds_read_b128 v[46:49], v202 offset:3072
	ds_read_b128 v[98:101], v203
	ds_read_b128 v[102:105], v203 offset:1024
	ds_read_b128 v[106:109], v203 offset:2048
	ds_read_b128 v[110:113], v203 offset:3072
	s_add_u32 s22, s20, 0xfff80080
	s_addc_u32 s23, s21, -1
	s_cmp_eq_u32 s34, 28
	s_cselect_b32 s37, s3, s23
	s_cselect_b32 s36, s13, s22
	s_cselect_b32 s23, s11, s25
	s_cselect_b32 s22, s19, s24
	v_lshl_add_u64 v[182:183], s[20:21], 0, v[174:175]
	s_add_i32 m0, s28, 0xc000
	ds_read_b128 v[210:213], v204
	ds_read_b128 v[214:217], v204 offset:1024
	ds_read_b128 v[218:221], v204 offset:2048
	ds_read_b128 v[222:225], v204 offset:3072
	ds_read_b128 v[226:229], v204 offset:4096
	ds_read_b128 v[230:233], v204 offset:5120
	ds_read_b128 v[234:237], v204 offset:6144
	ds_read_b128 v[238:241], v204 offset:7168
	global_load_lds_dwordx4 v[182:183], off
	v_lshl_add_u64 v[182:183], s[20:21], 0, v[172:173]
	s_add_i32 m0, s28, 0xe000
	s_nop 0
	global_load_lds_dwordx4 v[182:183], off
	s_waitcnt lgkmcnt(0)
	s_barrier
	s_setprio 1
	s_waitcnt lgkmcnt(0)
	v_mfma_f32_16x16x32_bf16 v[158:161], v[34:37], v[210:213], 0
	v_mfma_f32_16x16x32_bf16 v[154:157], v[42:45], v[210:213], 0
	v_mfma_f32_16x16x32_bf16 v[142:145], v[34:37], v[218:221], 0
	v_mfma_f32_16x16x32_bf16 v[138:141], v[42:45], v[218:221], 0
	v_mfma_f32_16x16x32_bf16 v[126:129], v[34:37], v[226:229], 0
	v_mfma_f32_16x16x32_bf16 v[122:125], v[42:45], v[226:229], 0
	v_mfma_f32_16x16x32_bf16 v[94:97], v[34:37], v[234:237], 0
	v_mfma_f32_16x16x32_bf16 v[90:93], v[42:45], v[234:237], 0
	v_mfma_f32_16x16x32_bf16 v[158:161], v[38:41], v[214:217], v[158:161]
	v_mfma_f32_16x16x32_bf16 v[154:157], v[46:49], v[214:217], v[154:157]
	v_mfma_f32_16x16x32_bf16 v[142:145], v[38:41], v[222:225], v[142:145]
	v_mfma_f32_16x16x32_bf16 v[138:141], v[46:49], v[222:225], v[138:141]
	v_mfma_f32_16x16x32_bf16 v[126:129], v[38:41], v[230:233], v[126:129]
	v_mfma_f32_16x16x32_bf16 v[122:125], v[46:49], v[230:233], v[122:125]
	v_mfma_f32_16x16x32_bf16 v[94:97], v[38:41], v[238:241], v[94:97]
	v_mfma_f32_16x16x32_bf16 v[90:93], v[46:49], v[238:241], v[90:93]
	s_setprio 0
	s_setprio 1
	v_mfma_f32_16x16x32_bf16 v[150:153], v[98:101], v[210:213], 0
	v_mfma_f32_16x16x32_bf16 v[146:149], v[106:109], v[210:213], 0
	v_mfma_f32_16x16x32_bf16 v[134:137], v[98:101], v[218:221], 0
	v_mfma_f32_16x16x32_bf16 v[130:133], v[106:109], v[218:221], 0
	v_mfma_f32_16x16x32_bf16 v[118:121], v[98:101], v[226:229], 0
	v_mfma_f32_16x16x32_bf16 v[114:117], v[106:109], v[226:229], 0
	v_mfma_f32_16x16x32_bf16 v[86:89], v[98:101], v[234:237], 0
	v_mfma_f32_16x16x32_bf16 v[82:85], v[106:109], v[234:237], 0
	v_mfma_f32_16x16x32_bf16 v[150:153], v[102:105], v[214:217], v[150:153]
	v_mfma_f32_16x16x32_bf16 v[146:149], v[110:113], v[214:217], v[146:149]
	v_mfma_f32_16x16x32_bf16 v[134:137], v[102:105], v[222:225], v[134:137]
	v_mfma_f32_16x16x32_bf16 v[130:133], v[110:113], v[222:225], v[130:133]
	v_mfma_f32_16x16x32_bf16 v[118:121], v[102:105], v[230:233], v[118:121]
	v_mfma_f32_16x16x32_bf16 v[114:117], v[110:113], v[230:233], v[114:117]
	v_mfma_f32_16x16x32_bf16 v[86:89], v[102:105], v[238:241], v[86:89]
	v_mfma_f32_16x16x32_bf16 v[82:85], v[110:113], v[238:241], v[82:85]
	s_setprio 0
	s_barrier
	s_add_i32 s35, s56, s27
	v_lshl_add_u64 v[182:183], s[22:23], 0, v[164:165]
	s_mov_b32 m0, s35
	ds_read_b128 v[210:213], v204 offset:16384
	ds_read_b128 v[214:217], v204 offset:17408
	ds_read_b128 v[218:221], v204 offset:18432
	ds_read_b128 v[222:225], v204 offset:19456
	ds_read_b128 v[226:229], v204 offset:20480
	ds_read_b128 v[230:233], v204 offset:21504
	ds_read_b128 v[234:237], v204 offset:22528
	ds_read_b128 v[238:241], v204 offset:23552
	global_load_lds_dwordx4 v[182:183], off
	s_add_i32 m0, s35, 0x2000
	s_add_u32 s46, s22, 0x20000
	v_lshl_add_u64 v[242:243], s[22:23], 0, v[168:169]
	s_addc_u32 s47, s23, 0
	s_add_i32 s35, s57, s27
	global_load_lds_dwordx4 v[242:243], off
	v_lshl_add_u64 v[244:245], s[46:47], 0, v[164:165]
	s_mov_b32 m0, s35
	v_lshl_add_u64 v[246:247], s[36:37], 0, v[166:167]
	global_load_lds_dwordx4 v[244:245], off
	v_lshl_add_u64 v[244:245], s[46:47], 0, v[168:169]
	s_add_i32 m0, s35, 0x2000
	s_nop 0
	global_load_lds_dwordx4 v[244:245], off
	v_lshl_add_u64 v[244:245], s[36:37], 0, v[162:163]
	s_mov_b32 m0, s28
	s_nop 0
	global_load_lds_dwordx4 v[244:245], off
	s_mov_b32 m0, s29
	s_nop 0
	global_load_lds_dwordx4 v[246:247], off
	s_waitcnt lgkmcnt(0)
	s_barrier
; #define PG8_STAGE(bufoff, gbase, voff) do { _Pragma("unroll") for (int _i = 0; _i < 2; ++_i) \
;         __builtin_amdgcn_global_load_lds((const unsigned*)((const char*)(gbase) + (voff)[_i]), (LAS unsigned*)(lds + (bufoff) + ldsw + _i * 8192), 16, 0, 0); } while (0)
; #define PG8_LDA(dst, b, h) do { _Pragma("unroll") for (int m = 0; m < 4; ++m) _Pragma("unroll") for (int k = 0; k < 2; ++k) dst[m][k] = *(const LAS bf16x8*)(lds + PG8_SA(b, h) + aoff + m * 2048 + k * 1024); } while (0)
; #define PG8_LDB(dst, b, h) do { _Pragma("unroll") for (int n = 0; n < 2; ++n) _Pragma("unroll") for (int k = 0; k < 2; ++k) dst[n][k] = *(const LAS bf16x8*)(lds + PG8_SB(b, h) + boff + n * 2048 + k * 1024); } while (0)
; #define PG8_MMA(ai, bj, At, Bt) do { __builtin_amdgcn_s_setprio(1); _Pragma("unroll") for (int m = 0; m < 4; ++m) _Pragma("unroll") for (int n = 0; n < 2; ++n) _Pragma("unroll") for (int k = 0; k < 2; ++k) \
;         acc[ai][bj][m][n] = __builtin_amdgcn_mfma_f32_16x16x32_bf16(Bt[n][k], At[m][k], acc[ai][bj][m][n], 0, 0, 0); __builtin_amdgcn_s_setprio(0); } while (0)
; #define PG8_WAIT_V(n) asm volatile("s_waitcnt vmcnt(" #n ")" ::: "memory")
; #define PG8_WAIT_L(n) asm volatile("s_waitcnt lgkmcnt(" #n ")" ::: "memory")
; #define PG8_BAR __builtin_amdgcn_s_barrier()
; #define PG8_SCHED __builtin_amdgcn_sched_barrier(0)
; template <class Epi, class Sched, bool ALIGN_EPI = false, bool SP2 = false>
; __device__ __forceinline__ void gemm_phase(LAS unsigned char* lds, const Gemm g, const Sched& S, const Epi& E) {
;     ...
;             PG8_WAIT_V(8); PG8_WAIT_L(0); PG8_BAR; PG8_MMA(1, 0, At, B0); PG8_MMA(1, 1, At, B1); PG8_BAR; PG8_SCHED;
;             PG8_LDB(B0, 1, 0); PG8_LDB(B1, 1, 1); PG8_SCHED; PG8_LDA(At, 1, 0); PG8_STAGE(PG8_SA(0, 1), a2 + hstep, voffA);
;             PG8_WAIT_V(8); PG8_WAIT_L(0); PG8_BAR; PG8_MMA(0, 0, At, B0); PG8_MMA(0, 1, At, B1); PG8_BAR; PG8_SCHED;
	s_setprio 1
	s_waitcnt lgkmcnt(0)
	v_mfma_f32_16x16x32_bf16 v[78:81], v[34:37], v[210:213], 0
	v_mfma_f32_16x16x32_bf16 v[74:77], v[42:45], v[210:213], 0
	v_mfma_f32_16x16x32_bf16 v[62:65], v[34:37], v[218:221], 0
	v_mfma_f32_16x16x32_bf16 v[58:61], v[42:45], v[218:221], 0
	v_mfma_f32_16x16x32_bf16 v[30:33], v[34:37], v[226:229], 0
	v_mfma_f32_16x16x32_bf16 v[26:29], v[42:45], v[226:229], 0
	v_mfma_f32_16x16x32_bf16 v[14:17], v[34:37], v[234:237], 0
	v_mfma_f32_16x16x32_bf16 v[10:13], v[42:45], v[234:237], 0
	v_mfma_f32_16x16x32_bf16 v[78:81], v[38:41], v[214:217], v[78:81]
	v_mfma_f32_16x16x32_bf16 v[74:77], v[46:49], v[214:217], v[74:77]
	v_mfma_f32_16x16x32_bf16 v[62:65], v[38:41], v[222:225], v[62:65]
	v_mfma_f32_16x16x32_bf16 v[58:61], v[46:49], v[222:225], v[58:61]
	v_mfma_f32_16x16x32_bf16 v[30:33], v[38:41], v[230:233], v[30:33]
	v_mfma_f32_16x16x32_bf16 v[26:29], v[46:49], v[230:233], v[26:29]
	v_mfma_f32_16x16x32_bf16 v[14:17], v[38:41], v[238:241], v[14:17]
	v_mfma_f32_16x16x32_bf16 v[10:13], v[46:49], v[238:241], v[10:13]
	s_setprio 0
	s_setprio 1
	v_mfma_f32_16x16x32_bf16 v[22:25], v[98:101], v[226:229], 0
	v_mfma_f32_16x16x32_bf16 v[18:21], v[106:109], v[226:229], 0
	v_mfma_f32_16x16x32_bf16 v[6:9], v[98:101], v[234:237], 0
	v_mfma_f32_16x16x32_bf16 v[2:5], v[106:109], v[234:237], 0
	v_mfma_f32_16x16x32_bf16 v[34:37], v[98:101], v[210:213], 0
	v_mfma_f32_16x16x32_bf16 v[38:41], v[106:109], v[210:213], 0
	v_mfma_f32_16x16x32_bf16 v[42:45], v[98:101], v[218:221], 0
	v_mfma_f32_16x16x32_bf16 v[46:49], v[106:109], v[218:221], 0
	v_mfma_f32_16x16x32_bf16 v[22:25], v[102:105], v[230:233], v[22:25]
	v_mfma_f32_16x16x32_bf16 v[18:21], v[110:113], v[230:233], v[18:21]
	v_mfma_f32_16x16x32_bf16 v[6:9], v[102:105], v[238:241], v[6:9]
	v_mfma_f32_16x16x32_bf16 v[2:5], v[110:113], v[238:241], v[2:5]
	v_mfma_f32_16x16x32_bf16 v[34:37], v[102:105], v[214:217], v[34:37]
	v_mfma_f32_16x16x32_bf16 v[38:41], v[110:113], v[214:217], v[38:41]
	v_mfma_f32_16x16x32_bf16 v[42:45], v[102:105], v[222:225], v[42:45]
	v_mfma_f32_16x16x32_bf16 v[46:49], v[110:113], v[222:225], v[46:49]
	s_setprio 0
	s_barrier
	s_add_i32 s35, 0, 0x18000
	s_add_i32 s46, 0, 0x1c000
	v_add_u32_e32 v70, s35, v185
	v_add_u32_e32 v110, s46, v185
	ds_read_b128 v[50:53], v70
	ds_read_b128 v[54:57], v70 offset:1024
	ds_read_b128 v[66:69], v70 offset:2048
	ds_read_b128 v[70:73], v70 offset:3072
	ds_read_b128 v[98:101], v110
	ds_read_b128 v[102:105], v110 offset:1024
	ds_read_b128 v[106:109], v110 offset:2048
	ds_read_b128 v[110:113], v110 offset:3072
	s_add_u32 s36, s36, 0x80000
	s_addc_u32 s37, s37, 0
	s_mov_b32 m0, s30
	v_lshl_add_u64 v[248:249], s[36:37], 0, v[162:163]
	ds_read_b128 v[210:213], v204 offset:32768
	ds_read_b128 v[214:217], v204 offset:33792
	ds_read_b128 v[218:221], v204 offset:34816
	ds_read_b128 v[222:225], v204 offset:35840
	ds_read_b128 v[226:229], v204 offset:36864
	ds_read_b128 v[230:233], v204 offset:37888
	ds_read_b128 v[234:237], v204 offset:38912
	ds_read_b128 v[238:241], v204 offset:39936
	global_load_lds_dwordx4 v[248:249], off
	v_lshl_add_u64 v[248:249], s[36:37], 0, v[166:167]
	s_mov_b32 m0, s31
	s_nop 0
	global_load_lds_dwordx4 v[248:249], off
	s_waitcnt vmcnt(8)
	s_waitcnt lgkmcnt(0)
	s_barrier
	s_setprio 1
	s_waitcnt lgkmcnt(0)
	v_mfma_f32_16x16x32_bf16 v[158:161], v[50:53], v[210:213], v[158:161]
	v_mfma_f32_16x16x32_bf16 v[154:157], v[66:69], v[210:213], v[154:157]
	v_mfma_f32_16x16x32_bf16 v[142:145], v[50:53], v[218:221], v[142:145]
	v_mfma_f32_16x16x32_bf16 v[138:141], v[66:69], v[218:221], v[138:141]
	v_mfma_f32_16x16x32_bf16 v[126:129], v[50:53], v[226:229], v[126:129]
	v_mfma_f32_16x16x32_bf16 v[122:125], v[66:69], v[226:229], v[122:125]
	v_mfma_f32_16x16x32_bf16 v[94:97], v[50:53], v[234:237], v[94:97]
	v_mfma_f32_16x16x32_bf16 v[90:93], v[66:69], v[234:237], v[90:93]
	v_mfma_f32_16x16x32_bf16 v[158:161], v[54:57], v[214:217], v[158:161]
	v_mfma_f32_16x16x32_bf16 v[154:157], v[70:73], v[214:217], v[154:157]
	v_mfma_f32_16x16x32_bf16 v[142:145], v[54:57], v[222:225], v[142:145]
	v_mfma_f32_16x16x32_bf16 v[138:141], v[70:73], v[222:225], v[138:141]
	v_mfma_f32_16x16x32_bf16 v[126:129], v[54:57], v[230:233], v[126:129]
	v_mfma_f32_16x16x32_bf16 v[122:125], v[70:73], v[230:233], v[122:125]
	v_mfma_f32_16x16x32_bf16 v[94:97], v[54:57], v[238:241], v[94:97]
	v_mfma_f32_16x16x32_bf16 v[90:93], v[70:73], v[238:241], v[90:93]
	s_setprio 0
	s_setprio 1
	v_mfma_f32_16x16x32_bf16 v[150:153], v[98:101], v[210:213], v[150:153]
	v_mfma_f32_16x16x32_bf16 v[146:149], v[106:109], v[210:213], v[146:149]
	v_mfma_f32_16x16x32_bf16 v[134:137], v[98:101], v[218:221], v[134:137]
	v_mfma_f32_16x16x32_bf16 v[130:133], v[106:109], v[218:221], v[130:133]
	v_mfma_f32_16x16x32_bf16 v[118:121], v[98:101], v[226:229], v[118:121]
	v_mfma_f32_16x16x32_bf16 v[114:117], v[106:109], v[226:229], v[114:117]
	v_mfma_f32_16x16x32_bf16 v[86:89], v[98:101], v[234:237], v[86:89]
	v_mfma_f32_16x16x32_bf16 v[82:85], v[106:109], v[234:237], v[82:85]
	v_mfma_f32_16x16x32_bf16 v[150:153], v[102:105], v[214:217], v[150:153]
	v_mfma_f32_16x16x32_bf16 v[146:149], v[110:113], v[214:217], v[146:149]
	v_mfma_f32_16x16x32_bf16 v[134:137], v[102:105], v[222:225], v[134:137]
	v_mfma_f32_16x16x32_bf16 v[130:133], v[110:113], v[222:225], v[130:133]
	v_mfma_f32_16x16x32_bf16 v[118:121], v[102:105], v[230:233], v[118:121]
	v_mfma_f32_16x16x32_bf16 v[114:117], v[110:113], v[230:233], v[114:117]
	v_mfma_f32_16x16x32_bf16 v[86:89], v[102:105], v[238:241], v[86:89]
	v_mfma_f32_16x16x32_bf16 v[82:85], v[110:113], v[238:241], v[82:85]
	s_setprio 0
	s_barrier
; #define PG8_STAGE(bufoff, gbase, voff) do { _Pragma("unroll") for (int _i = 0; _i < 2; ++_i) \
;         __builtin_amdgcn_global_load_lds((const unsigned*)((const char*)(gbase) + (voff)[_i]), (LAS unsigned*)(lds + (bufoff) + ldsw + _i * 8192), 16, 0, 0); } while (0)
; #define PG8_LDA(dst, b, h) do { _Pragma("unroll") for (int m = 0; m < 4; ++m) _Pragma("unroll") for (int k = 0; k < 2; ++k) dst[m][k] = *(const LAS bf16x8*)(lds + PG8_SA(b, h) + aoff + m * 2048 + k * 1024); } while (0)
; #define PG8_MMA(ai, bj, At, Bt) do { __builtin_amdgcn_s_setprio(1); _Pragma("unroll") for (int m = 0; m < 4; ++m) _Pragma("unroll") for (int n = 0; n < 2; ++n) _Pragma("unroll") for (int k = 0; k < 2; ++k) \
;         acc[ai][bj][m][n] = __builtin_amdgcn_mfma_f32_16x16x32_bf16(Bt[n][k], At[m][k], acc[ai][bj][m][n], 0, 0, 0); __builtin_amdgcn_s_setprio(0); } while (0)
; #define PG8_WAIT_V(n) asm volatile("s_waitcnt vmcnt(" #n ")" ::: "memory")
; #define PG8_WAIT_L(n) asm volatile("s_waitcnt lgkmcnt(" #n ")" ::: "memory")
; #define PG8_BAR __builtin_amdgcn_s_barrier()
; #define PG8_SCHED __builtin_amdgcn_sched_barrier(0)
; template <class Epi, class Sched, bool ALIGN_EPI = false, bool SP2 = false>
; __device__ __forceinline__ void gemm_phase(LAS unsigned char* lds, const Gemm g, const Sched& S, const Epi& E) {
;     ...
;         for (int t = 0; t < nt; t += 2) {
;             const bool last = (t == nt - 2);
;             const char* a1 = cA + (size_t)(t + 1) * kstep;
;             const char* a2 = last ? nA : cA + (size_t)(t + 2) * kstep; const char* b2 = last ? nB : cB + (size_t)(t + 2) * kstep;
;     ...
;             PG8_LDA(At, 1, 1); PG8_STAGE(PG8_SB(1, 0), b3, voffB); PG8_STAGE(PG8_SB(1, 1), b3 + hstepB, voffB); PG8_STAGE(PG8_SA(1, 0), a3, voffA);
;             PG8_WAIT_V(8); PG8_WAIT_L(0); PG8_BAR; PG8_MMA(1, 0, At, B0); PG8_MMA(1, 1, At, B1); PG8_BAR; PG8_SCHED;
	s_add_i32 s35, s35, s27
	v_lshl_add_u64 v[182:183], v[182:183], 0, s[4:5]
	s_mov_b32 m0, s35
	ds_read_b128 v[210:213], v204 offset:49152
	ds_read_b128 v[214:217], v204 offset:50176
	ds_read_b128 v[218:221], v204 offset:51200
	ds_read_b128 v[222:225], v204 offset:52224
	ds_read_b128 v[226:229], v204 offset:53248
	ds_read_b128 v[230:233], v204 offset:54272
	ds_read_b128 v[234:237], v204 offset:55296
	ds_read_b128 v[238:241], v204 offset:56320
	global_load_lds_dwordx4 v[182:183], off
	s_add_i32 m0, s35, 0x2000
	s_add_u32 s22, s22, 0x20080
	v_lshl_add_u64 v[182:183], v[242:243], 0, s[4:5]
	s_addc_u32 s23, s23, 0
	s_add_i32 s35, s46, s27
	global_load_lds_dwordx4 v[182:183], off
	v_lshl_add_u64 v[182:183], s[22:23], 0, v[164:165]
	s_mov_b32 m0, s35
	s_nop 0
	global_load_lds_dwordx4 v[182:183], off
	v_lshl_add_u64 v[182:183], s[22:23], 0, v[168:169]
	s_add_i32 m0, s35, 0x2000
	s_nop 0
	global_load_lds_dwordx4 v[182:183], off
	v_lshl_add_u64 v[182:183], v[244:245], 0, s[4:5]
	s_mov_b32 m0, s53
	s_nop 0
	global_load_lds_dwordx4 v[182:183], off
	v_lshl_add_u64 v[182:183], v[246:247], 0, s[4:5]
	s_mov_b32 m0, s54
	s_nop 0
	global_load_lds_dwordx4 v[182:183], off
	s_waitcnt vmcnt(8)
	s_waitcnt lgkmcnt(0)
	s_barrier
	s_setprio 1
	s_waitcnt lgkmcnt(0)
	v_mfma_f32_16x16x32_bf16 v[78:81], v[50:53], v[210:213], v[78:81]
	v_mfma_f32_16x16x32_bf16 v[74:77], v[66:69], v[210:213], v[74:77]
	v_mfma_f32_16x16x32_bf16 v[62:65], v[50:53], v[218:221], v[62:65]
	v_mfma_f32_16x16x32_bf16 v[58:61], v[66:69], v[218:221], v[58:61]
	v_mfma_f32_16x16x32_bf16 v[30:33], v[50:53], v[226:229], v[30:33]
	v_mfma_f32_16x16x32_bf16 v[26:29], v[66:69], v[226:229], v[26:29]
	v_mfma_f32_16x16x32_bf16 v[14:17], v[50:53], v[234:237], v[14:17]
	v_mfma_f32_16x16x32_bf16 v[10:13], v[66:69], v[234:237], v[10:13]
	v_mfma_f32_16x16x32_bf16 v[78:81], v[54:57], v[214:217], v[78:81]
	v_mfma_f32_16x16x32_bf16 v[74:77], v[70:73], v[214:217], v[74:77]
	v_mfma_f32_16x16x32_bf16 v[62:65], v[54:57], v[222:225], v[62:65]
	v_mfma_f32_16x16x32_bf16 v[58:61], v[70:73], v[222:225], v[58:61]
	v_mfma_f32_16x16x32_bf16 v[30:33], v[54:57], v[230:233], v[30:33]
	v_mfma_f32_16x16x32_bf16 v[26:29], v[70:73], v[230:233], v[26:29]
	v_mfma_f32_16x16x32_bf16 v[14:17], v[54:57], v[238:241], v[14:17]
	v_mfma_f32_16x16x32_bf16 v[10:13], v[70:73], v[238:241], v[10:13]
	s_setprio 0
	s_setprio 1
	v_mfma_f32_16x16x32_bf16 v[34:37], v[98:101], v[210:213], v[34:37]
	v_mfma_f32_16x16x32_bf16 v[70:73], v[102:105], v[214:217], v[34:37]
	v_mfma_f32_16x16x32_bf16 v[34:37], v[106:109], v[210:213], v[38:41]
	v_mfma_f32_16x16x32_bf16 v[66:69], v[110:113], v[214:217], v[34:37]
	v_mfma_f32_16x16x32_bf16 v[34:37], v[98:101], v[218:221], v[42:45]
	v_mfma_f32_16x16x32_bf16 v[54:57], v[102:105], v[222:225], v[34:37]
	v_mfma_f32_16x16x32_bf16 v[34:37], v[106:109], v[218:221], v[46:49]
	v_mfma_f32_16x16x32_bf16 v[22:25], v[98:101], v[226:229], v[22:25]
	v_mfma_f32_16x16x32_bf16 v[18:21], v[106:109], v[226:229], v[18:21]
	v_mfma_f32_16x16x32_bf16 v[6:9], v[98:101], v[234:237], v[6:9]
	v_mfma_f32_16x16x32_bf16 v[2:5], v[106:109], v[234:237], v[2:5]
	v_mfma_f32_16x16x32_bf16 v[50:53], v[110:113], v[222:225], v[34:37]
	v_mfma_f32_16x16x32_bf16 v[22:25], v[102:105], v[230:233], v[22:25]
	v_mfma_f32_16x16x32_bf16 v[18:21], v[110:113], v[230:233], v[18:21]
	v_mfma_f32_16x16x32_bf16 v[6:9], v[102:105], v[238:241], v[6:9]
	v_mfma_f32_16x16x32_bf16 v[2:5], v[110:113], v[238:241], v[2:5]
	s_setprio 0
	s_barrier
	s_add_i32 s34, s34, 2
	s_add_u32 s24, s24, 0x100
	s_addc_u32 s25, s25, 0
	s_add_u32 s20, s20, 0x100
	s_addc_u32 s21, s21, 0
	s_cmp_lt_u32 s34, 30

; #define LAS __attribute__((address_space(3)))
; #define PG8_STAGE(bufoff, gbase, voff) do { _Pragma("unroll") for (int _i = 0; _i < 2; ++_i) \
;         __builtin_amdgcn_global_load_lds((const unsigned*)((const char*)(gbase) + (voff)[_i]), (LAS unsigned*)(lds + (bufoff) + ldsw + _i * 8192), 16, 0, 0); } while (0)
; #define PG8_WAIT_V(n) asm volatile("s_waitcnt vmcnt(" #n ")" ::: "memory")
; #define PG8_BAR __builtin_amdgcn_s_barrier()
;     __device__ __forceinline__ void operator()(const f32x4 (&acc)[2][2][4][2], const Unit& u, int wr, int wc, int fr, int fq) const {
;         const int s = u.pm >> 5, lane = fq * 16 + fr, rr = lane >> 3, pc = lane & 7;
;         const float* __restrict__ xi = xin + (size_t)u.pm * BM * DM; float* __restrict__ xo = xout + (size_t)u.pm * BM * DM; bf16_t* __restrict__ ho = Hn + (size_t)u.pm * BM * DM;
;         LAS unsigned char* st = lds_epi + (wr * 4 + wc) * 2304;
;         LAS float* sst = (LAS float*)(lds_epi + 18432 + (wr * 4 + wc) * 512);
;         const int colr = u.pn * BM + wc * 64 + 4 * pc;
;         const unsigned eb = (unsigned)((wr * 64 + rr) * DM + colr);
;         f32x4 gv[2], gsn[2];
; #pragma unroll
;         for (int bj = 0; bj < 2; ++bj) { gv[bj] = *(const f32x4*)(gate + (size_t)s * MODW + colr + bj * 32) * (0.5f * GS2);
;             if (!PLAIN) gsn[bj] = *(const f32x4*)(gnext + colr + bj * 32) * (*(const f32x4*)(scnext + (size_t)s * MODW + colr + bj * 32) + 1.0f); else gsn[bj] = gv[bj]; }
;         const unsigned wr_off = (unsigned)(fr * 144 + 16 * fq), rd_off = (unsigned)(rr * 144 + pc * 16);
;         const bool odd = (rr & 1) != 0;
; template <class Epi, class Sched, bool ALIGN_EPI = false, bool SP2 = false>
; __device__ __forceinline__ void gemm_phase(LAS unsigned char* lds, const Gemm g, const Sched& S, const Epi& E) {
;     ...
;     if constexpr (SP2) {
;         PG8_STAGE(PG8_SB(0, 0), cB, voffB); PG8_STAGE(PG8_SB(0, 1), cB + hstepB, voffB); PG8_STAGE(PG8_SA(0, 0), cA, voffA); PG8_STAGE(PG8_SA(0, 1), cA + hstep, voffA);
;         if (wr == 1) PG8_BAR;
;         PG8_WAIT_V(2); PG8_BAR;
;         PG8_STAGE(PG8_SB(1, 0), cB + kstep, voffB); PG8_STAGE(PG8_SA(1, 0), cA + kstep, voffA); PG8_STAGE(PG8_SB(1, 1), cB + hstepB + kstep, voffB);
;         PG8_WAIT_V(6); PG8_BAR;
.LBB0_2756:
	s_add_u32 s44, s48, 0xa4000
	v_readlane_b32 s4, v253, 2
	s_addc_u32 s45, s49, 0
	v_readlane_b32 s6, v253, 4
	v_readlane_b32 s16, v253, 14
	v_readlane_b32 s7, v253, 5
	v_readlane_b32 s17, v253, 15
	s_add_u32 s6, s16, 0xa000
	v_readlane_b32 s8, v253, 6
	v_readlane_b32 s9, v253, 7
	s_addc_u32 s7, s17, 0
	s_add_u32 s46, s48, 0xa8000
	s_mov_b64 s[8:9], 0x80
	v_readlane_b32 s11, v253, 9
	v_readlane_b32 s13, v253, 11
	v_readlane_b32 s14, v253, 12
	s_addc_u32 s47, s49, 0
	s_and_b32 s3, s25, 3
	s_add_i32 m0, s28, 0x18000
	v_lshl_add_u64 v[8:9], v[8:9], 0, s[8:9]
	s_lshl_b32 s14, s36, 6
	s_lshl_b32 s11, s36, 13
	s_lshl_b32 s13, s3, 12
	s_waitcnt vmcnt(2)
	s_barrier
	global_load_lds_dwordx4 v[8:9], off
	v_lshl_add_u64 v[6:7], v[6:7], 0, s[8:9]
	s_add_i32 m0, s28, 0x1a000
	s_add_i32 s48, s28, 0x8000
	s_add_i32 s49, s28, 0xa000
	global_load_lds_dwordx4 v[6:7], off
	v_lshl_add_u64 v[2:3], v[2:3], 0, s[8:9]
	s_mov_b32 m0, s48
	s_add_u32 s16, s22, 0x20080
	global_load_lds_dwordx4 v[2:3], off
	v_lshl_add_u64 v[2:3], v[4:5], 0, s[8:9]
	s_mov_b32 m0, s49
	s_addc_u32 s17, s23, 0
	global_load_lds_dwordx4 v[2:3], off
	s_add_i32 m0, s28, 0x1c000
	v_lshl_add_u64 v[2:3], s[16:17], 0, v[156:157]
	global_load_lds_dwordx4 v[2:3], off
	v_lshl_add_u64 v[2:3], s[16:17], 0, v[160:161]
	s_add_i32 m0, s28, 0x1e000
	v_lshlrev_b32_e32 v4, 2, v10
	global_load_lds_dwordx4 v[2:3], off
	v_and_b32_e32 v2, 15, v10
	v_and_b32_e32 v3, 48, v10
	v_readlane_b32 s10, v253, 8
	v_readlane_b32 s12, v253, 10
	v_lshl_or_b32 v1, v2, 6, v3
	v_and_b32_e32 v4, 32, v4
	s_cmpk_lt_u32 s24, 0x100
	v_readlane_b32 s15, v253, 13
	v_bitop3_b32 v5, v1, s11, v4 bitop3:0xde
	s_cselect_b64 s[10:11], -1, 0
	s_lshl_b32 s12, s36, 2
	s_or_b32 s12, s12, s3
	s_ashr_i32 s15, s14, 31
	v_bitop3_b32 v1, v1, s13, v4 bitop3:0xde
	v_and_b32_e32 v7, 7, v10
	s_mul_i32 s16, s12, 0x900
	s_lshl_b32 s17, s12, 9
	s_ashr_i32 s50, s26, 31
	s_lshl_b64 s[12:13], s[14:15], 2
	v_and_b32_e32 v4, 63, v10
	v_lshlrev_b32_e32 v8, 2, v7
	s_add_u32 s12, s0, s12
	v_lshl_or_b32 v192, s3, 6, v8
	s_addc_u32 s13, s1, s13
	v_lshlrev_b32_e32 v162, 2, v4
	s_add_i32 s3, s16, 0
	v_lshl_add_u64 v[164:165], s[12:13], 0, v[162:163]
	s_add_i32 s3, s3, 0x20000
	s_add_i32 s12, s17, 0
	v_bfe_u32 v6, v10, 3, 3
	s_add_i32 s12, s12, 0x24800
	s_movk_i32 s13, 0x90
	v_mov_b32_e32 v4, s3
	v_or_b32_e32 v8, s14, v6
	v_cmp_gt_u32_e64 s[36:37], 8, v2
	v_cmp_lt_u32_e64 s[38:39], 7, v2
	v_mad_u32_u24 v2, v2, s13, v4
	v_mad_u32_u24 v4, v6, s13, v4
	v_lshl_add_u32 v194, v6, 2, s12
	v_lshlrev_b32_e32 v6, 15, v14
	v_and_b32_e32 v6, 0xffff0000, v6
	v_lshlrev_b32_e32 v193, 11, v8
	v_lshlrev_b32_e32 v8, 4, v7
	v_cmp_eq_u32_e64 s[40:41], 0, v7
	v_lshl_add_u32 v6, v15, 12, v6
	v_and_b32_e32 v7, 1, v14
	v_lshl_or_b32 v6, v7, 6, v6
	v_lshl_add_u32 v166, v16, 1, v6
	v_lshlrev_b32_e32 v6, 15, v11
	v_and_b32_e32 v6, 0xffff0000, v6
	s_waitcnt vmcnt(0)
	v_lshl_add_u32 v6, v12, 12, v6
	v_and_b32_e32 v7, 1, v11
	v_lshl_or_b32 v6, v7, 6, v6
	s_add_i32 s51, 0, 0x10000
	s_add_i32 s52, 0, 0x14000
	v_add_u32_e32 v198, 0, v5
	v_mbcnt_lo_u32_b32 v5, -1, 0
	v_add_u32_e32 v195, s12, v162
	v_mov_b32_e32 v167, v163
	v_lshl_add_u32 v168, v13, 1, v6
	v_mov_b32_e32 v169, v163
	v_mov_b64_e32 v[170:171], 0x400
	v_mov_b64_e32 v[172:173], 0x3ff
	v_add_u32_e32 v196, s51, v1
	v_add_u32_e32 v197, s52, v1
	v_mbcnt_hi_u32_b32 v199, -1, v5
	v_add_u32_e32 v200, v2, v3
	v_add_u32_e32 v201, v4, v8
	v_readlane_b32 s5, v253, 3
	v_readlane_b32 s18, v253, 16
	v_readlane_b32 s19, v253, 17
	s_barrier
	s_branch .LBB0_2759

;     __device__ bool next(int i, Unit& u) const { if (i != 0 || c >= 128) return false; const int t = c >> 2; u.pm = t & 3; u.pn = t >> 2; u.koff = koff_bytes; u.q = c & 3; return true; }
; #define PG8_STAGE(bufoff, gbase, voff) do { _Pragma("unroll") for (int _i = 0; _i < 2; ++_i) \
;         __builtin_amdgcn_global_load_lds((const unsigned*)((const char*)(gbase) + (voff)[_i]), (LAS unsigned*)(lds + (bufoff) + ldsw + _i * 8192), 16, 0, 0); } while (0)
; #define PG8_LDA(dst, b, h) do { _Pragma("unroll") for (int m = 0; m < 4; ++m) _Pragma("unroll") for (int k = 0; k < 2; ++k) dst[m][k] = *(const LAS bf16x8*)(lds + PG8_SA(b, h) + aoff + m * 2048 + k * 1024); } while (0)
; #define PG8_LDB(dst, b, h) do { _Pragma("unroll") for (int n = 0; n < 2; ++n) _Pragma("unroll") for (int k = 0; k < 2; ++k) dst[n][k] = *(const LAS bf16x8*)(lds + PG8_SB(b, h) + boff + n * 2048 + k * 1024); } while (0)
; #define PG8_WAIT_V(n) asm volatile("s_waitcnt vmcnt(" #n ")" ::: "memory")
; template <class Epi, class Sched, bool ALIGN_EPI = false, bool SP2 = false>
; __device__ __forceinline__ void gemm_phase(LAS unsigned char* lds, const Gemm g, const Sched& S, const Epi& E) {
;     ...
;         const bool has_next = S.next(ui + 1, nxt);
;         const char* nA = has_next ? (const char*)g.A + (size_t)nxt.pm * tstep + nxt.koff : cA; const char* nB = has_next ? (const char*)g.Bt + (size_t)nxt.pn * tstep + nxt.koff : cB;
;         for (int t = 0; t < nt; t += 2) {
;             const bool last = (t == nt - 2);
;             const char* a1 = cA + (size_t)(t + 1) * kstep;
;             const char* a2 = last ? nA : cA + (size_t)(t + 2) * kstep; const char* b2 = last ? nB : cB + (size_t)(t + 2) * kstep;
;             const char* a3 = a2 + kstep; const char* b3 = b2 + kstep;
;             if (last && has_next) S.a_ready(nxt);
;             if constexpr (SP2) {
;             PG8_LDB(B0, 0, 0); PG8_LDB(B1, 0, 1); PG8_SCHED; PG8_LDA(At, 0, 0); PG8_STAGE(PG8_SA(1, 1), a1 + hstep, voffA);
;             PG8_WAIT_V(8); PG8_WAIT_L(0); PG8_BAR; PG8_MMA(0, 0, At, B0); PG8_MMA(0, 1, At, B1); PG8_BAR; PG8_SCHED;
;             PG8_LDA(At, 0, 1); PG8_STAGE(PG8_SB(0, 0), b2, voffB); PG8_STAGE(PG8_SB(0, 1), b2 + hstepB, voffB); PG8_STAGE(PG8_SA(0, 0), a2, voffA);
;             PG8_WAIT_V(8); PG8_WAIT_L(0); PG8_BAR; PG8_MMA(1, 0, At, B0); PG8_MMA(1, 1, At, B1); PG8_BAR; PG8_SCHED;
.LBB0_2765:
	s_ashr_i32 s15, s14, 31
	v_cmp_lt_i64_e64 s[42:43], s[16:17], v[170:171]
	s_lshl_b64 s[16:17], s[14:15], 20
	v_readlane_b32 s3, v252, 25
	s_add_u32 s16, s3, s16
	v_readlane_b32 s3, v252, 26
	s_addc_u32 s17, s3, s17
	s_and_b64 s[18:19], s[42:43], exec
	s_cselect_b32 s3, s17, s35
	s_cselect_b32 s15, s16, s34
	s_ashr_i32 s13, s12, 31
	s_lshl_b64 s[18:19], s[12:13], 20
	v_readlane_b32 s4, v254, 56
	v_readlane_b32 s5, v254, 57
	s_add_u32 s18, s4, s18
	s_addc_u32 s19, s5, s19
	s_and_b64 s[24:25], s[42:43], exec
	s_cselect_b32 s13, s19, s23
	s_cselect_b32 s21, s18, s22
	s_add_u32 s53, s22, 0x100
	s_addc_u32 s54, s23, 0
	s_add_u32 s22, s34, 0x80080
	s_mov_b64 s[70:71], s[58:59]
	s_addc_u32 s23, s35, 0
	s_mov_b32 s55, -2
	s_waitcnt vmcnt(0)
	ds_read_b128 v[50:53], v196
	ds_read_b128 v[54:57], v196 offset:1024
	ds_read_b128 v[138:141], v196 offset:2048
	ds_read_b128 v[142:145], v196 offset:3072
	ds_read_b128 v[146:149], v197
	ds_read_b128 v[150:153], v197 offset:1024
	ds_read_b128 v[174:177], v197 offset:2048
	ds_read_b128 v[178:181], v197 offset:3072
	s_add_u32 s24, s22, 0xfff80080
	s_addc_u32 s25, s23, -1
	s_cmp_eq_u32 s55, 28
	s_cselect_b32 s35, s3, s25
	s_cselect_b32 s34, s15, s24
	s_cselect_b32 s25, s13, s54
	s_cselect_b32 s24, s21, s53
	v_lshl_add_u64 v[190:191], s[22:23], 0, v[168:169]
	s_add_i32 m0, s28, 0xc000
	ds_read_b128 v[182:185], v198
	ds_read_b128 v[186:189], v198 offset:1024
	ds_read_b128 v[202:205], v198 offset:2048
	ds_read_b128 v[206:209], v198 offset:3072
	ds_read_b128 v[210:213], v198 offset:4096
	ds_read_b128 v[214:217], v198 offset:5120
	ds_read_b128 v[218:221], v198 offset:6144
	ds_read_b128 v[222:225], v198 offset:7168
	global_load_lds_dwordx4 v[190:191], off
	v_lshl_add_u64 v[190:191], s[22:23], 0, v[166:167]
	s_add_i32 m0, s28, 0xe000
	s_nop 0
	global_load_lds_dwordx4 v[190:191], off
	s_waitcnt lgkmcnt(0)
	s_barrier
	s_setprio 1
	s_waitcnt lgkmcnt(0)
	v_mfma_f32_16x16x32_bf16 v[134:137], v[50:53], v[182:185], 0
	v_mfma_f32_16x16x32_bf16 v[130:133], v[138:141], v[182:185], 0
	v_mfma_f32_16x16x32_bf16 v[118:121], v[50:53], v[202:205], 0
	v_mfma_f32_16x16x32_bf16 v[114:117], v[138:141], v[202:205], 0
	v_mfma_f32_16x16x32_bf16 v[102:105], v[50:53], v[210:213], 0
	v_mfma_f32_16x16x32_bf16 v[98:101], v[138:141], v[210:213], 0
	v_mfma_f32_16x16x32_bf16 v[86:89], v[50:53], v[218:221], 0
	v_mfma_f32_16x16x32_bf16 v[82:85], v[138:141], v[218:221], 0
	v_mfma_f32_16x16x32_bf16 v[134:137], v[54:57], v[186:189], v[134:137]
	v_mfma_f32_16x16x32_bf16 v[130:133], v[142:145], v[186:189], v[130:133]
	v_mfma_f32_16x16x32_bf16 v[118:121], v[54:57], v[206:209], v[118:121]
	v_mfma_f32_16x16x32_bf16 v[114:117], v[142:145], v[206:209], v[114:117]
	v_mfma_f32_16x16x32_bf16 v[102:105], v[54:57], v[214:217], v[102:105]
	v_mfma_f32_16x16x32_bf16 v[98:101], v[142:145], v[214:217], v[98:101]
	v_mfma_f32_16x16x32_bf16 v[86:89], v[54:57], v[222:225], v[86:89]
	v_mfma_f32_16x16x32_bf16 v[82:85], v[142:145], v[222:225], v[82:85]
	s_setprio 0
	s_setprio 1
	v_mfma_f32_16x16x32_bf16 v[126:129], v[146:149], v[182:185], 0
	v_mfma_f32_16x16x32_bf16 v[122:125], v[174:177], v[182:185], 0
	v_mfma_f32_16x16x32_bf16 v[110:113], v[146:149], v[202:205], 0
	v_mfma_f32_16x16x32_bf16 v[106:109], v[174:177], v[202:205], 0
	v_mfma_f32_16x16x32_bf16 v[94:97], v[146:149], v[210:213], 0
	v_mfma_f32_16x16x32_bf16 v[90:93], v[174:177], v[210:213], 0
	v_mfma_f32_16x16x32_bf16 v[78:81], v[146:149], v[218:221], 0
	v_mfma_f32_16x16x32_bf16 v[74:77], v[174:177], v[218:221], 0
	v_mfma_f32_16x16x32_bf16 v[126:129], v[150:153], v[186:189], v[126:129]
	v_mfma_f32_16x16x32_bf16 v[122:125], v[178:181], v[186:189], v[122:125]
	v_mfma_f32_16x16x32_bf16 v[110:113], v[150:153], v[206:209], v[110:113]
	v_mfma_f32_16x16x32_bf16 v[106:109], v[178:181], v[206:209], v[106:109]
	v_mfma_f32_16x16x32_bf16 v[94:97], v[150:153], v[214:217], v[94:97]
	v_mfma_f32_16x16x32_bf16 v[90:93], v[178:181], v[214:217], v[90:93]
	v_mfma_f32_16x16x32_bf16 v[78:81], v[150:153], v[222:225], v[78:81]
	v_mfma_f32_16x16x32_bf16 v[74:77], v[178:181], v[222:225], v[74:77]
	s_setprio 0
	s_barrier
	s_add_i32 s56, s51, s27
	v_lshl_add_u64 v[190:191], s[24:25], 0, v[156:157]
	s_mov_b32 m0, s56
	ds_read_b128 v[182:185], v198 offset:16384
	ds_read_b128 v[186:189], v198 offset:17408
	ds_read_b128 v[202:205], v198 offset:18432
	ds_read_b128 v[206:209], v198 offset:19456
	ds_read_b128 v[210:213], v198 offset:20480
	ds_read_b128 v[214:217], v198 offset:21504
	ds_read_b128 v[218:221], v198 offset:22528
	ds_read_b128 v[222:225], v198 offset:23552
	global_load_lds_dwordx4 v[190:191], off
	s_add_i32 m0, s56, 0x2000
	s_add_u32 s56, s24, 0x20000
	v_lshl_add_u64 v[226:227], s[24:25], 0, v[160:161]
	s_addc_u32 s57, s25, 0
	s_add_i32 s58, s52, s27
	global_load_lds_dwordx4 v[226:227], off
	v_lshl_add_u64 v[228:229], s[56:57], 0, v[156:157]
	s_mov_b32 m0, s58
	v_lshl_add_u64 v[230:231], s[34:35], 0, v[158:159]
	global_load_lds_dwordx4 v[228:229], off
	v_lshl_add_u64 v[228:229], s[56:57], 0, v[160:161]
	s_add_i32 m0, s58, 0x2000
	s_nop 0
	global_load_lds_dwordx4 v[228:229], off
	v_lshl_add_u64 v[228:229], s[34:35], 0, v[154:155]
	s_mov_b32 m0, s28
	s_nop 0
	global_load_lds_dwordx4 v[228:229], off
	s_mov_b32 m0, s29
	s_nop 0
	global_load_lds_dwordx4 v[230:231], off
	s_waitcnt lgkmcnt(0)
	s_barrier
; #define PG8_STAGE(bufoff, gbase, voff) do { _Pragma("unroll") for (int _i = 0; _i < 2; ++_i) \
;         __builtin_amdgcn_global_load_lds((const unsigned*)((const char*)(gbase) + (voff)[_i]), (LAS unsigned*)(lds + (bufoff) + ldsw + _i * 8192), 16, 0, 0); } while (0)
; #define PG8_LDA(dst, b, h) do { _Pragma("unroll") for (int m = 0; m < 4; ++m) _Pragma("unroll") for (int k = 0; k < 2; ++k) dst[m][k] = *(const LAS bf16x8*)(lds + PG8_SA(b, h) + aoff + m * 2048 + k * 1024); } while (0)
; #define PG8_LDB(dst, b, h) do { _Pragma("unroll") for (int n = 0; n < 2; ++n) _Pragma("unroll") for (int k = 0; k < 2; ++k) dst[n][k] = *(const LAS bf16x8*)(lds + PG8_SB(b, h) + boff + n * 2048 + k * 1024); } while (0)
; #define PG8_MMA(ai, bj, At, Bt) do { __builtin_amdgcn_s_setprio(1); _Pragma("unroll") for (int m = 0; m < 4; ++m) _Pragma("unroll") for (int n = 0; n < 2; ++n) _Pragma("unroll") for (int k = 0; k < 2; ++k) \
;         acc[ai][bj][m][n] = __builtin_amdgcn_mfma_f32_16x16x32_bf16(Bt[n][k], At[m][k], acc[ai][bj][m][n], 0, 0, 0); __builtin_amdgcn_s_setprio(0); } while (0)
; #define PG8_WAIT_V(n) asm volatile("s_waitcnt vmcnt(" #n ")" ::: "memory")
; #define PG8_WAIT_L(n) asm volatile("s_waitcnt lgkmcnt(" #n ")" ::: "memory")
; #define PG8_BAR __builtin_amdgcn_s_barrier()
; #define PG8_SCHED __builtin_amdgcn_sched_barrier(0)
; template <class Epi, class Sched, bool ALIGN_EPI = false, bool SP2 = false>
; __device__ __forceinline__ void gemm_phase(LAS unsigned char* lds, const Gemm g, const Sched& S, const Epi& E) {
;     ...
;             PG8_WAIT_V(8); PG8_WAIT_L(0); PG8_BAR; PG8_MMA(1, 0, At, B0); PG8_MMA(1, 1, At, B1); PG8_BAR; PG8_SCHED;
;             PG8_LDB(B0, 1, 0); PG8_LDB(B1, 1, 1); PG8_SCHED; PG8_LDA(At, 1, 0); PG8_STAGE(PG8_SA(0, 1), a2 + hstep, voffA);
;             PG8_WAIT_V(8); PG8_WAIT_L(0); PG8_BAR; PG8_MMA(0, 0, At, B0); PG8_MMA(0, 1, At, B1); PG8_BAR; PG8_SCHED;
	s_setprio 1
	s_waitcnt lgkmcnt(0)
	v_mfma_f32_16x16x32_bf16 v[70:73], v[50:53], v[182:185], 0
	v_mfma_f32_16x16x32_bf16 v[66:69], v[138:141], v[182:185], 0
	v_mfma_f32_16x16x32_bf16 v[46:49], v[50:53], v[202:205], 0
	v_mfma_f32_16x16x32_bf16 v[42:45], v[138:141], v[202:205], 0
	v_mfma_f32_16x16x32_bf16 v[30:33], v[50:53], v[210:213], 0
	v_mfma_f32_16x16x32_bf16 v[26:29], v[138:141], v[210:213], 0
	v_mfma_f32_16x16x32_bf16 v[14:17], v[50:53], v[218:221], 0
	v_mfma_f32_16x16x32_bf16 v[10:13], v[138:141], v[218:221], 0
	v_mfma_f32_16x16x32_bf16 v[70:73], v[54:57], v[186:189], v[70:73]
	v_mfma_f32_16x16x32_bf16 v[66:69], v[142:145], v[186:189], v[66:69]
	v_mfma_f32_16x16x32_bf16 v[46:49], v[54:57], v[206:209], v[46:49]
	v_mfma_f32_16x16x32_bf16 v[42:45], v[142:145], v[206:209], v[42:45]
	v_mfma_f32_16x16x32_bf16 v[30:33], v[54:57], v[214:217], v[30:33]
	v_mfma_f32_16x16x32_bf16 v[26:29], v[142:145], v[214:217], v[26:29]
	v_mfma_f32_16x16x32_bf16 v[14:17], v[54:57], v[222:225], v[14:17]
	v_mfma_f32_16x16x32_bf16 v[10:13], v[142:145], v[222:225], v[10:13]
	s_setprio 0
	s_setprio 1
	v_mfma_f32_16x16x32_bf16 v[38:41], v[146:149], v[202:205], 0
	v_mfma_f32_16x16x32_bf16 v[34:37], v[174:177], v[202:205], 0
	v_mfma_f32_16x16x32_bf16 v[22:25], v[146:149], v[210:213], 0
	v_mfma_f32_16x16x32_bf16 v[18:21], v[174:177], v[210:213], 0
	v_mfma_f32_16x16x32_bf16 v[6:9], v[146:149], v[218:221], 0
	v_mfma_f32_16x16x32_bf16 v[2:5], v[174:177], v[218:221], 0
	v_mfma_f32_16x16x32_bf16 v[50:53], v[146:149], v[182:185], 0
	v_mfma_f32_16x16x32_bf16 v[54:57], v[174:177], v[182:185], 0
	v_mfma_f32_16x16x32_bf16 v[38:41], v[150:153], v[206:209], v[38:41]
	v_mfma_f32_16x16x32_bf16 v[34:37], v[178:181], v[206:209], v[34:37]
	v_mfma_f32_16x16x32_bf16 v[22:25], v[150:153], v[214:217], v[22:25]
	v_mfma_f32_16x16x32_bf16 v[18:21], v[178:181], v[214:217], v[18:21]
	v_mfma_f32_16x16x32_bf16 v[6:9], v[150:153], v[222:225], v[6:9]
	v_mfma_f32_16x16x32_bf16 v[2:5], v[178:181], v[222:225], v[2:5]
	v_mfma_f32_16x16x32_bf16 v[50:53], v[150:153], v[186:189], v[50:53]
	v_mfma_f32_16x16x32_bf16 v[54:57], v[178:181], v[186:189], v[54:57]
	s_setprio 0
	s_barrier
	s_add_i32 s56, 0, 0x18000
	s_add_i32 s57, 0, 0x1c000
	v_add_u32_e32 v142, s56, v1
	v_add_u32_e32 v162, s57, v1
	ds_read_b128 v[58:61], v142
	ds_read_b128 v[62:65], v142 offset:1024
	ds_read_b128 v[138:141], v142 offset:2048
	ds_read_b128 v[142:145], v142 offset:3072
	ds_read_b128 v[146:149], v162
	ds_read_b128 v[150:153], v162 offset:1024
	ds_read_b128 v[174:177], v162 offset:2048
	ds_read_b128 v[178:181], v162 offset:3072
	s_add_u32 s34, s34, 0x80000
	s_addc_u32 s35, s35, 0
	s_mov_b32 m0, s30
	v_lshl_add_u64 v[232:233], s[34:35], 0, v[154:155]
	ds_read_b128 v[182:185], v198 offset:32768
	ds_read_b128 v[186:189], v198 offset:33792
	ds_read_b128 v[202:205], v198 offset:34816
	ds_read_b128 v[206:209], v198 offset:35840
	ds_read_b128 v[210:213], v198 offset:36864
	ds_read_b128 v[214:217], v198 offset:37888
	ds_read_b128 v[218:221], v198 offset:38912
	ds_read_b128 v[222:225], v198 offset:39936
	global_load_lds_dwordx4 v[232:233], off
	v_lshl_add_u64 v[232:233], s[34:35], 0, v[158:159]
	s_mov_b32 m0, s31
	s_nop 0
	global_load_lds_dwordx4 v[232:233], off
	s_waitcnt vmcnt(8)
	s_waitcnt lgkmcnt(0)
	s_barrier
	s_setprio 1
	s_waitcnt lgkmcnt(0)
	v_mfma_f32_16x16x32_bf16 v[134:137], v[58:61], v[182:185], v[134:137]
	v_mfma_f32_16x16x32_bf16 v[130:133], v[138:141], v[182:185], v[130:133]
	v_mfma_f32_16x16x32_bf16 v[118:121], v[58:61], v[202:205], v[118:121]
	v_mfma_f32_16x16x32_bf16 v[114:117], v[138:141], v[202:205], v[114:117]
	v_mfma_f32_16x16x32_bf16 v[102:105], v[58:61], v[210:213], v[102:105]
	v_mfma_f32_16x16x32_bf16 v[98:101], v[138:141], v[210:213], v[98:101]
	v_mfma_f32_16x16x32_bf16 v[86:89], v[58:61], v[218:221], v[86:89]
	v_mfma_f32_16x16x32_bf16 v[82:85], v[138:141], v[218:221], v[82:85]
	v_mfma_f32_16x16x32_bf16 v[134:137], v[62:65], v[186:189], v[134:137]
	v_mfma_f32_16x16x32_bf16 v[130:133], v[142:145], v[186:189], v[130:133]
	v_mfma_f32_16x16x32_bf16 v[118:121], v[62:65], v[206:209], v[118:121]
	v_mfma_f32_16x16x32_bf16 v[114:117], v[142:145], v[206:209], v[114:117]
	v_mfma_f32_16x16x32_bf16 v[102:105], v[62:65], v[214:217], v[102:105]
	v_mfma_f32_16x16x32_bf16 v[98:101], v[142:145], v[214:217], v[98:101]
	v_mfma_f32_16x16x32_bf16 v[86:89], v[62:65], v[222:225], v[86:89]
	v_mfma_f32_16x16x32_bf16 v[82:85], v[142:145], v[222:225], v[82:85]
	s_setprio 0
	s_setprio 1
	v_mfma_f32_16x16x32_bf16 v[126:129], v[146:149], v[182:185], v[126:129]
	v_mfma_f32_16x16x32_bf16 v[122:125], v[174:177], v[182:185], v[122:125]
	v_mfma_f32_16x16x32_bf16 v[110:113], v[146:149], v[202:205], v[110:113]
	v_mfma_f32_16x16x32_bf16 v[106:109], v[174:177], v[202:205], v[106:109]
	v_mfma_f32_16x16x32_bf16 v[94:97], v[146:149], v[210:213], v[94:97]
	v_mfma_f32_16x16x32_bf16 v[90:93], v[174:177], v[210:213], v[90:93]
	v_mfma_f32_16x16x32_bf16 v[78:81], v[146:149], v[218:221], v[78:81]
	v_mfma_f32_16x16x32_bf16 v[74:77], v[174:177], v[218:221], v[74:77]
	v_mfma_f32_16x16x32_bf16 v[126:129], v[150:153], v[186:189], v[126:129]
	v_mfma_f32_16x16x32_bf16 v[122:125], v[178:181], v[186:189], v[122:125]
	v_mfma_f32_16x16x32_bf16 v[110:113], v[150:153], v[206:209], v[110:113]
	v_mfma_f32_16x16x32_bf16 v[106:109], v[178:181], v[206:209], v[106:109]
	v_mfma_f32_16x16x32_bf16 v[94:97], v[150:153], v[214:217], v[94:97]
	v_mfma_f32_16x16x32_bf16 v[90:93], v[178:181], v[214:217], v[90:93]
	v_mfma_f32_16x16x32_bf16 v[78:81], v[150:153], v[222:225], v[78:81]
	v_mfma_f32_16x16x32_bf16 v[74:77], v[178:181], v[222:225], v[74:77]
	s_setprio 0
	s_barrier
; #define PG8_STAGE(bufoff, gbase, voff) do { _Pragma("unroll") for (int _i = 0; _i < 2; ++_i) \
;         __builtin_amdgcn_global_load_lds((const unsigned*)((const char*)(gbase) + (voff)[_i]), (LAS unsigned*)(lds + (bufoff) + ldsw + _i * 8192), 16, 0, 0); } while (0)
; #define PG8_LDA(dst, b, h) do { _Pragma("unroll") for (int m = 0; m < 4; ++m) _Pragma("unroll") for (int k = 0; k < 2; ++k) dst[m][k] = *(const LAS bf16x8*)(lds + PG8_SA(b, h) + aoff + m * 2048 + k * 1024); } while (0)
; #define PG8_MMA(ai, bj, At, Bt) do { __builtin_amdgcn_s_setprio(1); _Pragma("unroll") for (int m = 0; m < 4; ++m) _Pragma("unroll") for (int n = 0; n < 2; ++n) _Pragma("unroll") for (int k = 0; k < 2; ++k) \
;         acc[ai][bj][m][n] = __builtin_amdgcn_mfma_f32_16x16x32_bf16(Bt[n][k], At[m][k], acc[ai][bj][m][n], 0, 0, 0); __builtin_amdgcn_s_setprio(0); } while (0)
; #define PG8_WAIT_V(n) asm volatile("s_waitcnt vmcnt(" #n ")" ::: "memory")
; #define PG8_WAIT_L(n) asm volatile("s_waitcnt lgkmcnt(" #n ")" ::: "memory")
; #define PG8_BAR __builtin_amdgcn_s_barrier()
; #define PG8_SCHED __builtin_amdgcn_sched_barrier(0)
; template <class Epi, class Sched, bool ALIGN_EPI = false, bool SP2 = false>
; __device__ __forceinline__ void gemm_phase(LAS unsigned char* lds, const Gemm g, const Sched& S, const Epi& E) {
;     ...
;         for (int t = 0; t < nt; t += 2) {
;             const bool last = (t == nt - 2);
;             const char* a1 = cA + (size_t)(t + 1) * kstep;
;             const char* a2 = last ? nA : cA + (size_t)(t + 2) * kstep; const char* b2 = last ? nB : cB + (size_t)(t + 2) * kstep;
;     ...
;             PG8_LDA(At, 1, 1); PG8_STAGE(PG8_SB(1, 0), b3, voffB); PG8_STAGE(PG8_SB(1, 1), b3 + hstepB, voffB); PG8_STAGE(PG8_SA(1, 0), a3, voffA);
;             PG8_WAIT_V(8); PG8_WAIT_L(0); PG8_BAR; PG8_MMA(1, 0, At, B0); PG8_MMA(1, 1, At, B1); PG8_BAR; PG8_SCHED;
	s_add_i32 s34, s56, s27
	v_lshl_add_u64 v[190:191], v[190:191], 0, s[8:9]
	s_mov_b32 m0, s34
	ds_read_b128 v[182:185], v198 offset:49152
	ds_read_b128 v[186:189], v198 offset:50176
	ds_read_b128 v[202:205], v198 offset:51200
	ds_read_b128 v[206:209], v198 offset:52224
	ds_read_b128 v[210:213], v198 offset:53248
	ds_read_b128 v[214:217], v198 offset:54272
	ds_read_b128 v[218:221], v198 offset:55296
	ds_read_b128 v[222:225], v198 offset:56320
	global_load_lds_dwordx4 v[190:191], off
	s_add_i32 m0, s34, 0x2000
	s_add_u32 s24, s24, 0x20080
	v_lshl_add_u64 v[190:191], v[226:227], 0, s[8:9]
	s_addc_u32 s25, s25, 0
	s_add_i32 s34, s57, s27
	global_load_lds_dwordx4 v[190:191], off
	v_lshl_add_u64 v[190:191], s[24:25], 0, v[156:157]
	s_mov_b32 m0, s34
	s_nop 0
	global_load_lds_dwordx4 v[190:191], off
	v_lshl_add_u64 v[190:191], s[24:25], 0, v[160:161]
	s_add_i32 m0, s34, 0x2000
	s_nop 0
	global_load_lds_dwordx4 v[190:191], off
	v_lshl_add_u64 v[190:191], v[228:229], 0, s[8:9]
	s_mov_b32 m0, s48
	s_nop 0
	global_load_lds_dwordx4 v[190:191], off
	v_lshl_add_u64 v[190:191], v[230:231], 0, s[8:9]
	s_mov_b32 m0, s49
	s_nop 0
	global_load_lds_dwordx4 v[190:191], off
	s_waitcnt vmcnt(8)
	s_waitcnt lgkmcnt(0)
	s_barrier
	s_setprio 1
	s_waitcnt lgkmcnt(0)
	v_mfma_f32_16x16x32_bf16 v[70:73], v[58:61], v[182:185], v[70:73]
	v_mfma_f32_16x16x32_bf16 v[66:69], v[138:141], v[182:185], v[66:69]
	v_mfma_f32_16x16x32_bf16 v[46:49], v[58:61], v[202:205], v[46:49]
	v_mfma_f32_16x16x32_bf16 v[42:45], v[138:141], v[202:205], v[42:45]
	v_mfma_f32_16x16x32_bf16 v[30:33], v[58:61], v[210:213], v[30:33]
	v_mfma_f32_16x16x32_bf16 v[26:29], v[138:141], v[210:213], v[26:29]
	v_mfma_f32_16x16x32_bf16 v[14:17], v[58:61], v[218:221], v[14:17]
	v_mfma_f32_16x16x32_bf16 v[10:13], v[138:141], v[218:221], v[10:13]
	v_mfma_f32_16x16x32_bf16 v[70:73], v[62:65], v[186:189], v[70:73]
	v_mfma_f32_16x16x32_bf16 v[66:69], v[142:145], v[186:189], v[66:69]
	v_mfma_f32_16x16x32_bf16 v[46:49], v[62:65], v[206:209], v[46:49]
	v_mfma_f32_16x16x32_bf16 v[42:45], v[142:145], v[206:209], v[42:45]
	v_mfma_f32_16x16x32_bf16 v[30:33], v[62:65], v[214:217], v[30:33]
	v_mfma_f32_16x16x32_bf16 v[26:29], v[142:145], v[214:217], v[26:29]
	v_mfma_f32_16x16x32_bf16 v[14:17], v[62:65], v[222:225], v[14:17]
	v_mfma_f32_16x16x32_bf16 v[10:13], v[142:145], v[222:225], v[10:13]
	s_setprio 0
	s_setprio 1
	v_mfma_f32_16x16x32_bf16 v[50:53], v[146:149], v[182:185], v[50:53]
	v_mfma_f32_16x16x32_bf16 v[62:65], v[150:153], v[186:189], v[50:53]
	v_mfma_f32_16x16x32_bf16 v[50:53], v[174:177], v[182:185], v[54:57]
	v_mfma_f32_16x16x32_bf16 v[38:41], v[146:149], v[202:205], v[38:41]
	v_mfma_f32_16x16x32_bf16 v[34:37], v[174:177], v[202:205], v[34:37]
	v_mfma_f32_16x16x32_bf16 v[22:25], v[146:149], v[210:213], v[22:25]
	v_mfma_f32_16x16x32_bf16 v[18:21], v[174:177], v[210:213], v[18:21]
	v_mfma_f32_16x16x32_bf16 v[6:9], v[146:149], v[218:221], v[6:9]
	v_mfma_f32_16x16x32_bf16 v[2:5], v[174:177], v[218:221], v[2:5]
	v_mfma_f32_16x16x32_bf16 v[58:61], v[178:181], v[186:189], v[50:53]
	v_mfma_f32_16x16x32_bf16 v[38:41], v[150:153], v[206:209], v[38:41]
	v_mfma_f32_16x16x32_bf16 v[34:37], v[178:181], v[206:209], v[34:37]
	v_mfma_f32_16x16x32_bf16 v[22:25], v[150:153], v[214:217], v[22:25]
	v_mfma_f32_16x16x32_bf16 v[18:21], v[178:181], v[214:217], v[18:21]
	v_mfma_f32_16x16x32_bf16 v[6:9], v[150:153], v[222:225], v[6:9]
	v_mfma_f32_16x16x32_bf16 v[2:5], v[178:181], v[222:225], v[2:5]
	s_setprio 0
	s_barrier
	s_add_i32 s55, s55, 2
	s_add_u32 s53, s53, 0x100
	s_addc_u32 s54, s54, 0
	s_add_u32 s22, s22, 0x100
	s_addc_u32 s23, s23, 0
	s_cmp_lt_u32 s55, 30

; #define PG8_STAGE(bufoff, gbase, voff) do { _Pragma("unroll") for (int _i = 0; _i < 2; ++_i) \
;         __builtin_amdgcn_global_load_lds((const unsigned*)((const char*)(gbase) + (voff)[_i]), (LAS unsigned*)(lds + (bufoff) + ldsw + _i * 8192), 16, 0, 0); } while (0)
; #define PG8_WAIT_V(n) asm volatile("s_waitcnt vmcnt(" #n ")" ::: "memory")
; #define PG8_BAR __builtin_amdgcn_s_barrier()
; template <class Epi, class Sched, bool ALIGN_EPI = false, bool SP2 = false>
; __device__ __forceinline__ void gemm_phase(LAS unsigned char* lds, const Gemm g, const Sched& S, const Epi& E) {
;     int tid = threadIdx.x; asm volatile("" : "+v"(tid));
;     const int wid = __builtin_amdgcn_readfirstlane(tid >> 6), lane = tid & 63, wr = wid >> 2, wc = wid & 3, fr = lane & 15, fq = lane >> 4;
;     const int K = g.ld, nt = g.K / BK;
;     unsigned voffA[2], voffB[2];
; #pragma unroll
;     for (int i = 0; i < 2; ++i) { int R, C; stage_rc(tid * 16 + i * 8192, R, C); const int Rb = (Epi::BCONT ? ((R >> 5) * 64) : (R & ~31)) + (Epi::PERM ? perm32(R & 31) : (R & 31));
;         voffA[i] = (unsigned)(R * K + C) * 2u; voffB[i] = (unsigned)(Rb * K + C) * 2u; }
;     const size_t kstep = (size_t)(BK * 2);
;     const size_t hstep = (size_t)HALF * K * 2;
;     const size_t hstepB = Epi::BCONT ? (size_t)32 * K * 2 : hstep;
;     const size_t tstep = 2 * hstep;
;     const unsigned ldsw = (unsigned)wid * 1024u;
;     const int aoff = lds_byte(wr * 64 + fr, fq * 8), boff = lds_byte(wc * 32 + fr, fq * 8);
;     ...
;     if constexpr (SP2) {
;         PG8_STAGE(PG8_SB(0, 0), cB, voffB); PG8_STAGE(PG8_SB(0, 1), cB + hstepB, voffB); PG8_STAGE(PG8_SA(0, 0), cA, voffA); PG8_STAGE(PG8_SA(0, 1), cA + hstep, voffA);
;         if (wr == 1) PG8_BAR;
;         PG8_WAIT_V(2); PG8_BAR;
;         PG8_STAGE(PG8_SB(1, 0), cB + kstep, voffB); PG8_STAGE(PG8_SA(1, 0), cA + kstep, voffA); PG8_STAGE(PG8_SB(1, 1), cB + hstepB + kstep, voffB);
;         PG8_WAIT_V(6); PG8_BAR;
.LBB0_2910:
	s_lshl_b32 s3, s6, 5
	s_and_b32 s13, s3, 0x60
	s_lshl_b32 s34, s7, 6
	s_lshl_b32 s12, s7, 13
	s_lshl_b32 s14, s13, 7
	s_add_u32 s35, s48, 0x323000
	s_mov_b64 s[6:7], 0x80
	s_addc_u32 s38, s49, 0
	s_add_i32 m0, s28, 0x18000
	v_lshl_add_u64 v[8:9], v[8:9], 0, s[6:7]
	s_waitcnt vmcnt(2)
	s_barrier
	global_load_lds_dwordx4 v[8:9], off
	v_lshl_add_u64 v[6:7], v[6:7], 0, s[6:7]
	s_add_i32 m0, s28, 0x1a000
	s_add_i32 s39, s28, 0x8000
	s_add_i32 s40, s28, 0xa000
	global_load_lds_dwordx4 v[6:7], off
	v_lshl_add_u64 v[2:3], v[2:3], 0, s[6:7]
	s_mov_b32 m0, s39
	s_add_u32 s10, s18, 0x80080
	global_load_lds_dwordx4 v[2:3], off
	v_lshl_add_u64 v[2:3], v[4:5], 0, s[6:7]
	s_mov_b32 m0, s40
	s_addc_u32 s11, s19, 0
	global_load_lds_dwordx4 v[2:3], off
	s_add_i32 m0, s28, 0x1c000
	v_lshl_add_u64 v[2:3], s[10:11], 0, v[150:151]
	global_load_lds_dwordx4 v[2:3], off
	v_lshl_add_u64 v[2:3], s[10:11], 0, v[146:147]
	s_add_i32 m0, s28, 0x1e000
	v_and_b32_e32 v1, 15, v10
	global_load_lds_dwordx4 v[2:3], off
	v_bfe_u32 v3, v10, 4, 2
	v_lshlrev_b32_e32 v2, 3, v3
	v_lshlrev_b32_e32 v3, 4, v3
	v_lshlrev_b32_e32 v4, 2, v10
	v_lshl_or_b32 v3, v1, 6, v3
	v_and_b32_e32 v4, 32, v4
	v_bitop3_b32 v5, v3, s12, v4 bitop3:0xde
	v_bitop3_b32 v169, v3, s14, v4 bitop3:0xde
	v_lshlrev_b32_e32 v3, 15, v11
	v_and_b32_e32 v3, 0xffff0000, v3
	v_lshl_add_u32 v3, v12, 12, v3
	v_and_b32_e32 v4, 1, v11
	v_lshl_or_b32 v3, v4, 6, v3
	v_lshl_add_u32 v154, v13, 1, v3
	v_lshlrev_b32_e32 v3, 15, v15
	v_or_b32_e32 v172, s13, v2
	v_and_b32_e32 v3, 0xffff0000, v3
	v_lshlrev_b32_e32 v176, 2, v2
	v_mbcnt_lo_u32_b32 v2, -1, 0
	s_waitcnt vmcnt(0)
	s_cmpk_lt_u32 s9, 0x100
	v_lshl_add_u32 v3, v14, 12, v3
	v_and_b32_e32 v4, 1, v15
	v_mbcnt_hi_u32_b32 v2, -1, v2
	s_sext_i32_i16 s3, s8
	s_cselect_b64 s[8:9], -1, 0
	v_and_b32_e32 v170, 63, v10
	v_lshl_or_b32 v3, v4, 6, v3
	s_add_i32 s41, 0, 0x10000
	s_add_i32 s42, 0, 0x14000
	v_and_or_b32 v2, v2, 64, v1
	v_or_b32_e32 v171, 0x80, v170
	v_mov_b32_e32 v155, v151
	v_lshl_add_u32 v156, v16, 1, v3
	v_mov_b32_e32 v157, v151
	v_mov_b64_e32 v[158:159], 0x1600
	v_mov_b64_e32 v[160:161], 0x15ff
	v_add_u32_e32 v173, s41, v169
	v_add_u32_e32 v174, s42, v169
	v_add_u32_e32 v175, 0, v5
	s_movk_i32 s43, 0x2c00
	s_lshl_b32 s44, s13, 2
	v_mov_b32_e32 v177, 0x358637bd
	s_mov_b32 s45, 0xf800000
	v_mov_b32_e32 v178, 0x260
	v_lshlrev_b32_e32 v179, 2, v2
	s_barrier
	s_branch .LBB0_2913

; __device__ __forceinline__ float row_rstd(const float* ss, int row) { return 1.0f / sqrtf(ss[row] * (1.0f / DM) + 1e-6f); }
; #define PG8_STAGE(bufoff, gbase, voff) do { _Pragma("unroll") for (int _i = 0; _i < 2; ++_i) \
;         __builtin_amdgcn_global_load_lds((const unsigned*)((const char*)(gbase) + (voff)[_i]), (LAS unsigned*)(lds + (bufoff) + ldsw + _i * 8192), 16, 0, 0); } while (0)
; #define PG8_LDA(dst, b, h) do { _Pragma("unroll") for (int m = 0; m < 4; ++m) _Pragma("unroll") for (int k = 0; k < 2; ++k) dst[m][k] = *(const LAS bf16x8*)(lds + PG8_SA(b, h) + aoff + m * 2048 + k * 1024); } while (0)
; #define PG8_WAIT_V(n) asm volatile("s_waitcnt vmcnt(" #n ")" ::: "memory")
;     __device__ __forceinline__ void operator()(const f32x4 (&acc)[2][2][4][2], const Unit& u, int wr, int wc, int fr, int fq) const {
;     ...
;         const float* bp = bias + (size_t)s * BIAS_N + u.pn * BM + wc * 32 + 8 * fq;
;         const f32x4 ba0 = *(const f32x4*)bp, ba1 = *(const f32x4*)(bp + 4), bb0 = *(const f32x4*)(bp + HALF), bb1 = *(const f32x4*)(bp + HALF + 4);
;         const int lane = fq * 16 + fr;
;         const float rsl0 = row_rstd(ss, u.pm * BM + wr * 64 + lane), rsl1 = row_rstd(ss, u.pm * BM + HALF + wr * 64 + lane);
; template <class Epi, class Sched, bool ALIGN_EPI = false, bool SP2 = false>
; __device__ __forceinline__ void gemm_phase(LAS unsigned char* lds, const Gemm g, const Sched& S, const Epi& E) {
;     ...
;         for (int t = 0; t < nt; t += 2) {
;             const bool last = (t == nt - 2);
;             const char* a1 = cA + (size_t)(t + 1) * kstep;
;             const char* a2 = last ? nA : cA + (size_t)(t + 2) * kstep; const char* b2 = last ? nB : cB + (size_t)(t + 2) * kstep;
;             const char* a3 = a2 + kstep; const char* b3 = b2 + kstep;
;             if (last && has_next) S.a_ready(nxt);
;             if constexpr (SP2) {
;             PG8_LDB(B0, 0, 0); PG8_LDB(B1, 0, 1); PG8_SCHED; PG8_LDA(At, 0, 0); PG8_STAGE(PG8_SA(1, 1), a1 + hstep, voffA);
;             PG8_WAIT_V(8); PG8_WAIT_L(0); PG8_BAR; PG8_MMA(0, 0, At, B0); PG8_MMA(0, 1, At, B1); PG8_BAR; PG8_SCHED;
;             PG8_LDA(At, 0, 1); PG8_STAGE(PG8_SB(0, 0), b2, voffB); PG8_STAGE(PG8_SB(0, 1), b2 + hstepB, voffB); PG8_STAGE(PG8_SA(0, 0), a2, voffA);
;             PG8_WAIT_V(8); PG8_WAIT_L(0); PG8_BAR; PG8_MMA(1, 0, At, B0); PG8_MMA(1, 1, At, B1); PG8_BAR; PG8_SCHED;
.Lpre_up2l1:
	s_lshl_b64 s[98:99], s[98:99], 2
	s_add_u32 s98, s35, s98
	s_addc_u32 s99, s38, s99
	s_lshl_b32 s100, s3, 8
	s_ashr_i32 s101, s100, 31
	s_lshl_b64 s[100:101], s[100:101], 2
	s_add_u32 s98, s98, s100
	s_addc_u32 s99, s99, s101
	s_add_u32 s98, s98, s44
	s_addc_u32 s99, s99, 0
	s_lshl_b32 s100, s2, 8
	s_add_i32 s100, s100, s34
	v_or_b32_e32 v162, s100, v170
	v_ashrrev_i32_e32 v163, 31, v162
	v_lshl_add_u64 v[162:163], v[162:163], 2, s[0:1]
	v_add_u32_e32 v164, s100, v171
	v_ashrrev_i32_e32 v165, 31, v164
	v_lshl_add_u64 v[164:165], v[164:165], 2, s[0:1]
	global_load_dwordx4 v[234:237], v176, s[98:99] offset:16
	global_load_dwordx4 v[238:241], v176, s[98:99]
	global_load_dwordx4 v[242:245], v176, s[98:99] offset:528
	global_load_dwordx4 v[246:249], v176, s[98:99] offset:512
	global_load_dword v250, v[162:163], off
	global_load_dword v251, v[164:165], off
	ds_read_b128 v[66:69], v173
	ds_read_b128 v[70:73], v173 offset:1024
	ds_read_b128 v[74:77], v173 offset:2048
	ds_read_b128 v[78:81], v173 offset:3072
	ds_read_b128 v[162:165], v174
	ds_read_b128 v[180:183], v174 offset:1024
	ds_read_b128 v[184:187], v174 offset:2048
	ds_read_b128 v[188:191], v174 offset:3072
	s_add_u32 s20, s18, 0xfff80080
	s_addc_u32 s21, s19, -1
	s_cmp_eq_u32 s50, 28
	s_cselect_b32 s23, s13, s21
	s_cselect_b32 s22, s46, s20
	s_cselect_b32 s21, s11, s49
	s_cselect_b32 s20, s47, s48
	v_lshl_add_u64 v[166:167], s[18:19], 0, v[156:157]
	s_add_i32 m0, s28, 0xc000
	ds_read_b128 v[192:195], v175
	ds_read_b128 v[196:199], v175 offset:1024
	ds_read_b128 v[200:203], v175 offset:2048
	ds_read_b128 v[204:207], v175 offset:3072
	ds_read_b128 v[208:211], v175 offset:4096
	ds_read_b128 v[212:215], v175 offset:5120
	ds_read_b128 v[216:219], v175 offset:6144
	ds_read_b128 v[220:223], v175 offset:7168
	global_load_lds_dwordx4 v[166:167], off
	v_lshl_add_u64 v[166:167], s[18:19], 0, v[154:155]
	s_add_i32 m0, s28, 0xe000
	s_nop 0
	global_load_lds_dwordx4 v[166:167], off
	s_waitcnt lgkmcnt(0)
	s_barrier
	s_setprio 1
	s_waitcnt lgkmcnt(0)
	v_mfma_f32_16x16x32_bf16 v[142:145], v[66:69], v[192:195], 0
	v_mfma_f32_16x16x32_bf16 v[138:141], v[74:77], v[192:195], 0
	v_mfma_f32_16x16x32_bf16 v[126:129], v[66:69], v[200:203], 0
	v_mfma_f32_16x16x32_bf16 v[122:125], v[74:77], v[200:203], 0
	v_mfma_f32_16x16x32_bf16 v[110:113], v[66:69], v[208:211], 0
	v_mfma_f32_16x16x32_bf16 v[106:109], v[74:77], v[208:211], 0
	v_mfma_f32_16x16x32_bf16 v[94:97], v[66:69], v[216:219], 0
	v_mfma_f32_16x16x32_bf16 v[90:93], v[74:77], v[216:219], 0
	v_mfma_f32_16x16x32_bf16 v[142:145], v[70:73], v[196:199], v[142:145]
	v_mfma_f32_16x16x32_bf16 v[138:141], v[78:81], v[196:199], v[138:141]
	v_mfma_f32_16x16x32_bf16 v[126:129], v[70:73], v[204:207], v[126:129]
	v_mfma_f32_16x16x32_bf16 v[122:125], v[78:81], v[204:207], v[122:125]
	v_mfma_f32_16x16x32_bf16 v[110:113], v[70:73], v[212:215], v[110:113]
	v_mfma_f32_16x16x32_bf16 v[106:109], v[78:81], v[212:215], v[106:109]
	v_mfma_f32_16x16x32_bf16 v[94:97], v[70:73], v[220:223], v[94:97]
	v_mfma_f32_16x16x32_bf16 v[90:93], v[78:81], v[220:223], v[90:93]
	s_setprio 0
	s_setprio 1
	v_mfma_f32_16x16x32_bf16 v[134:137], v[162:165], v[192:195], 0
	v_mfma_f32_16x16x32_bf16 v[130:133], v[184:187], v[192:195], 0
	v_mfma_f32_16x16x32_bf16 v[118:121], v[162:165], v[200:203], 0
	v_mfma_f32_16x16x32_bf16 v[114:117], v[184:187], v[200:203], 0
	v_mfma_f32_16x16x32_bf16 v[102:105], v[162:165], v[208:211], 0
	v_mfma_f32_16x16x32_bf16 v[98:101], v[184:187], v[208:211], 0
	v_mfma_f32_16x16x32_bf16 v[86:89], v[162:165], v[216:219], 0
	v_mfma_f32_16x16x32_bf16 v[82:85], v[184:187], v[216:219], 0
	v_mfma_f32_16x16x32_bf16 v[134:137], v[180:183], v[196:199], v[134:137]
	v_mfma_f32_16x16x32_bf16 v[130:133], v[188:191], v[196:199], v[130:133]
	v_mfma_f32_16x16x32_bf16 v[118:121], v[180:183], v[204:207], v[118:121]
	v_mfma_f32_16x16x32_bf16 v[114:117], v[188:191], v[204:207], v[114:117]
	v_mfma_f32_16x16x32_bf16 v[102:105], v[180:183], v[212:215], v[102:105]
	v_mfma_f32_16x16x32_bf16 v[98:101], v[188:191], v[212:215], v[98:101]
	v_mfma_f32_16x16x32_bf16 v[86:89], v[180:183], v[220:223], v[86:89]
	v_mfma_f32_16x16x32_bf16 v[82:85], v[188:191], v[220:223], v[82:85]
	s_setprio 0
	s_barrier
	s_add_i32 s51, s41, s25
	v_lshl_add_u64 v[166:167], s[20:21], 0, v[150:151]
	s_mov_b32 m0, s51
	ds_read_b128 v[192:195], v175 offset:16384
	ds_read_b128 v[196:199], v175 offset:17408
	ds_read_b128 v[200:203], v175 offset:18432
	ds_read_b128 v[204:207], v175 offset:19456
	ds_read_b128 v[208:211], v175 offset:20480
	ds_read_b128 v[212:215], v175 offset:21504
	ds_read_b128 v[216:219], v175 offset:22528
	ds_read_b128 v[220:223], v175 offset:23552
	global_load_lds_dwordx4 v[166:167], off
	s_add_i32 m0, s51, 0x2000
	s_add_u32 s52, s20, 0x80000
	v_lshl_add_u64 v[224:225], s[20:21], 0, v[146:147]
	s_addc_u32 s53, s21, 0
	s_add_i32 s51, s42, s25
	global_load_lds_dwordx4 v[224:225], off
	v_lshl_add_u64 v[226:227], s[52:53], 0, v[150:151]
	s_mov_b32 m0, s51
	v_lshl_add_u64 v[228:229], s[22:23], 0, v[148:149]
	global_load_lds_dwordx4 v[226:227], off
	v_lshl_add_u64 v[226:227], s[52:53], 0, v[146:147]
	s_add_i32 m0, s51, 0x2000
	s_nop 0
	global_load_lds_dwordx4 v[226:227], off
	v_lshl_add_u64 v[226:227], s[22:23], 0, v[152:153]
	s_mov_b32 m0, s28
	s_nop 0
	global_load_lds_dwordx4 v[226:227], off
	s_mov_b32 m0, s29
	s_nop 0
	global_load_lds_dwordx4 v[228:229], off
	s_waitcnt lgkmcnt(0)
	s_barrier
; #define PG8_STAGE(bufoff, gbase, voff) do { _Pragma("unroll") for (int _i = 0; _i < 2; ++_i) \
;         __builtin_amdgcn_global_load_lds((const unsigned*)((const char*)(gbase) + (voff)[_i]), (LAS unsigned*)(lds + (bufoff) + ldsw + _i * 8192), 16, 0, 0); } while (0)
; #define PG8_LDA(dst, b, h) do { _Pragma("unroll") for (int m = 0; m < 4; ++m) _Pragma("unroll") for (int k = 0; k < 2; ++k) dst[m][k] = *(const LAS bf16x8*)(lds + PG8_SA(b, h) + aoff + m * 2048 + k * 1024); } while (0)
; #define PG8_LDB(dst, b, h) do { _Pragma("unroll") for (int n = 0; n < 2; ++n) _Pragma("unroll") for (int k = 0; k < 2; ++k) dst[n][k] = *(const LAS bf16x8*)(lds + PG8_SB(b, h) + boff + n * 2048 + k * 1024); } while (0)
; #define PG8_MMA(ai, bj, At, Bt) do { __builtin_amdgcn_s_setprio(1); _Pragma("unroll") for (int m = 0; m < 4; ++m) _Pragma("unroll") for (int n = 0; n < 2; ++n) _Pragma("unroll") for (int k = 0; k < 2; ++k) \
;         acc[ai][bj][m][n] = __builtin_amdgcn_mfma_f32_16x16x32_bf16(Bt[n][k], At[m][k], acc[ai][bj][m][n], 0, 0, 0); __builtin_amdgcn_s_setprio(0); } while (0)
; #define PG8_WAIT_V(n) asm volatile("s_waitcnt vmcnt(" #n ")" ::: "memory")
; #define PG8_WAIT_L(n) asm volatile("s_waitcnt lgkmcnt(" #n ")" ::: "memory")
; #define PG8_BAR __builtin_amdgcn_s_barrier()
; #define PG8_SCHED __builtin_amdgcn_sched_barrier(0)
; template <class Epi, class Sched, bool ALIGN_EPI = false, bool SP2 = false>
; __device__ __forceinline__ void gemm_phase(LAS unsigned char* lds, const Gemm g, const Sched& S, const Epi& E) {
;     ...
;             PG8_WAIT_V(8); PG8_WAIT_L(0); PG8_BAR; PG8_MMA(1, 0, At, B0); PG8_MMA(1, 1, At, B1); PG8_BAR; PG8_SCHED;
;             PG8_LDB(B0, 1, 0); PG8_LDB(B1, 1, 1); PG8_SCHED; PG8_LDA(At, 1, 0); PG8_STAGE(PG8_SA(0, 1), a2 + hstep, voffA);
;             PG8_WAIT_V(8); PG8_WAIT_L(0); PG8_BAR; PG8_MMA(0, 0, At, B0); PG8_MMA(0, 1, At, B1); PG8_BAR; PG8_SCHED;
	s_setprio 1
	s_waitcnt lgkmcnt(0)
	v_mfma_f32_16x16x32_bf16 v[62:65], v[66:69], v[192:195], 0
	v_mfma_f32_16x16x32_bf16 v[58:61], v[74:77], v[192:195], 0
	v_mfma_f32_16x16x32_bf16 v[46:49], v[66:69], v[200:203], 0
	v_mfma_f32_16x16x32_bf16 v[42:45], v[74:77], v[200:203], 0
	v_mfma_f32_16x16x32_bf16 v[30:33], v[66:69], v[208:211], 0
	v_mfma_f32_16x16x32_bf16 v[26:29], v[74:77], v[208:211], 0
	v_mfma_f32_16x16x32_bf16 v[14:17], v[66:69], v[216:219], 0
	v_mfma_f32_16x16x32_bf16 v[10:13], v[74:77], v[216:219], 0
	v_mfma_f32_16x16x32_bf16 v[62:65], v[70:73], v[196:199], v[62:65]
	v_mfma_f32_16x16x32_bf16 v[58:61], v[78:81], v[196:199], v[58:61]
	v_mfma_f32_16x16x32_bf16 v[46:49], v[70:73], v[204:207], v[46:49]
	v_mfma_f32_16x16x32_bf16 v[42:45], v[78:81], v[204:207], v[42:45]
	v_mfma_f32_16x16x32_bf16 v[30:33], v[70:73], v[212:215], v[30:33]
	v_mfma_f32_16x16x32_bf16 v[26:29], v[78:81], v[212:215], v[26:29]
	v_mfma_f32_16x16x32_bf16 v[14:17], v[70:73], v[220:223], v[14:17]
	v_mfma_f32_16x16x32_bf16 v[10:13], v[78:81], v[220:223], v[10:13]
	s_setprio 0
	s_setprio 1
	v_mfma_f32_16x16x32_bf16 v[54:57], v[162:165], v[192:195], 0
	v_mfma_f32_16x16x32_bf16 v[50:53], v[184:187], v[192:195], 0
	v_mfma_f32_16x16x32_bf16 v[38:41], v[162:165], v[200:203], 0
	v_mfma_f32_16x16x32_bf16 v[34:37], v[184:187], v[200:203], 0
	v_mfma_f32_16x16x32_bf16 v[22:25], v[162:165], v[208:211], 0
	v_mfma_f32_16x16x32_bf16 v[18:21], v[184:187], v[208:211], 0
	v_mfma_f32_16x16x32_bf16 v[6:9], v[162:165], v[216:219], 0
	v_mfma_f32_16x16x32_bf16 v[2:5], v[184:187], v[216:219], 0
	v_mfma_f32_16x16x32_bf16 v[54:57], v[180:183], v[196:199], v[54:57]
	v_mfma_f32_16x16x32_bf16 v[50:53], v[188:191], v[196:199], v[50:53]
	v_mfma_f32_16x16x32_bf16 v[38:41], v[180:183], v[204:207], v[38:41]
	v_mfma_f32_16x16x32_bf16 v[34:37], v[188:191], v[204:207], v[34:37]
	v_mfma_f32_16x16x32_bf16 v[22:25], v[180:183], v[212:215], v[22:25]
	v_mfma_f32_16x16x32_bf16 v[18:21], v[188:191], v[212:215], v[18:21]
	v_mfma_f32_16x16x32_bf16 v[6:9], v[180:183], v[220:223], v[6:9]
	v_mfma_f32_16x16x32_bf16 v[2:5], v[188:191], v[220:223], v[2:5]
	s_setprio 0
	s_barrier
	s_add_i32 s51, 0, 0x18000
	s_add_i32 s52, 0, 0x1c000
	v_add_u32_e32 v78, s51, v169
	v_add_u32_e32 v168, s52, v169
	ds_read_b128 v[66:69], v78
	ds_read_b128 v[70:73], v78 offset:1024
	ds_read_b128 v[74:77], v78 offset:2048
	ds_read_b128 v[78:81], v78 offset:3072
	ds_read_b128 v[162:165], v168
	ds_read_b128 v[180:183], v168 offset:1024
	ds_read_b128 v[184:187], v168 offset:2048
	ds_read_b128 v[188:191], v168 offset:3072
	s_add_u32 s22, s22, 0x80000
	s_addc_u32 s23, s23, 0
	s_mov_b32 m0, s30
	v_lshl_add_u64 v[230:231], s[22:23], 0, v[152:153]
	ds_read_b128 v[192:195], v175 offset:32768
	ds_read_b128 v[196:199], v175 offset:33792
	ds_read_b128 v[200:203], v175 offset:34816
	ds_read_b128 v[204:207], v175 offset:35840
	ds_read_b128 v[208:211], v175 offset:36864
	ds_read_b128 v[212:215], v175 offset:37888
	ds_read_b128 v[216:219], v175 offset:38912
	ds_read_b128 v[220:223], v175 offset:39936
	global_load_lds_dwordx4 v[230:231], off
	v_lshl_add_u64 v[230:231], s[22:23], 0, v[148:149]
	s_mov_b32 m0, s31
	s_nop 0
	global_load_lds_dwordx4 v[230:231], off
	s_waitcnt vmcnt(8)
	s_waitcnt lgkmcnt(0)
	s_barrier
	s_setprio 1
	s_waitcnt lgkmcnt(0)
	v_mfma_f32_16x16x32_bf16 v[142:145], v[66:69], v[192:195], v[142:145]
	v_mfma_f32_16x16x32_bf16 v[138:141], v[74:77], v[192:195], v[138:141]
	v_mfma_f32_16x16x32_bf16 v[126:129], v[66:69], v[200:203], v[126:129]
	v_mfma_f32_16x16x32_bf16 v[122:125], v[74:77], v[200:203], v[122:125]
	v_mfma_f32_16x16x32_bf16 v[110:113], v[66:69], v[208:211], v[110:113]
	v_mfma_f32_16x16x32_bf16 v[106:109], v[74:77], v[208:211], v[106:109]
	v_mfma_f32_16x16x32_bf16 v[94:97], v[66:69], v[216:219], v[94:97]
	v_mfma_f32_16x16x32_bf16 v[90:93], v[74:77], v[216:219], v[90:93]
	v_mfma_f32_16x16x32_bf16 v[142:145], v[70:73], v[196:199], v[142:145]
	v_mfma_f32_16x16x32_bf16 v[138:141], v[78:81], v[196:199], v[138:141]
	v_mfma_f32_16x16x32_bf16 v[126:129], v[70:73], v[204:207], v[126:129]
	v_mfma_f32_16x16x32_bf16 v[122:125], v[78:81], v[204:207], v[122:125]
	v_mfma_f32_16x16x32_bf16 v[110:113], v[70:73], v[212:215], v[110:113]
	v_mfma_f32_16x16x32_bf16 v[106:109], v[78:81], v[212:215], v[106:109]
	v_mfma_f32_16x16x32_bf16 v[94:97], v[70:73], v[220:223], v[94:97]
	v_mfma_f32_16x16x32_bf16 v[90:93], v[78:81], v[220:223], v[90:93]
	s_setprio 0
	s_setprio 1
	v_mfma_f32_16x16x32_bf16 v[134:137], v[162:165], v[192:195], v[134:137]
	v_mfma_f32_16x16x32_bf16 v[130:133], v[184:187], v[192:195], v[130:133]
	v_mfma_f32_16x16x32_bf16 v[118:121], v[162:165], v[200:203], v[118:121]
	v_mfma_f32_16x16x32_bf16 v[114:117], v[184:187], v[200:203], v[114:117]
	v_mfma_f32_16x16x32_bf16 v[102:105], v[162:165], v[208:211], v[102:105]
	v_mfma_f32_16x16x32_bf16 v[98:101], v[184:187], v[208:211], v[98:101]
	v_mfma_f32_16x16x32_bf16 v[86:89], v[162:165], v[216:219], v[86:89]
	v_mfma_f32_16x16x32_bf16 v[82:85], v[184:187], v[216:219], v[82:85]
	v_mfma_f32_16x16x32_bf16 v[134:137], v[180:183], v[196:199], v[134:137]
	v_mfma_f32_16x16x32_bf16 v[130:133], v[188:191], v[196:199], v[130:133]
	v_mfma_f32_16x16x32_bf16 v[118:121], v[180:183], v[204:207], v[118:121]
	v_mfma_f32_16x16x32_bf16 v[114:117], v[188:191], v[204:207], v[114:117]
	v_mfma_f32_16x16x32_bf16 v[102:105], v[180:183], v[212:215], v[102:105]
	v_mfma_f32_16x16x32_bf16 v[98:101], v[188:191], v[212:215], v[98:101]
	v_mfma_f32_16x16x32_bf16 v[86:89], v[180:183], v[220:223], v[86:89]
	v_mfma_f32_16x16x32_bf16 v[82:85], v[188:191], v[220:223], v[82:85]
	s_setprio 0
	s_barrier
; #define PG8_STAGE(bufoff, gbase, voff) do { _Pragma("unroll") for (int _i = 0; _i < 2; ++_i) \
;         __builtin_amdgcn_global_load_lds((const unsigned*)((const char*)(gbase) + (voff)[_i]), (LAS unsigned*)(lds + (bufoff) + ldsw + _i * 8192), 16, 0, 0); } while (0)
; #define PG8_LDA(dst, b, h) do { _Pragma("unroll") for (int m = 0; m < 4; ++m) _Pragma("unroll") for (int k = 0; k < 2; ++k) dst[m][k] = *(const LAS bf16x8*)(lds + PG8_SA(b, h) + aoff + m * 2048 + k * 1024); } while (0)
; #define PG8_MMA(ai, bj, At, Bt) do { __builtin_amdgcn_s_setprio(1); _Pragma("unroll") for (int m = 0; m < 4; ++m) _Pragma("unroll") for (int n = 0; n < 2; ++n) _Pragma("unroll") for (int k = 0; k < 2; ++k) \
;         acc[ai][bj][m][n] = __builtin_amdgcn_mfma_f32_16x16x32_bf16(Bt[n][k], At[m][k], acc[ai][bj][m][n], 0, 0, 0); __builtin_amdgcn_s_setprio(0); } while (0)
; #define PG8_WAIT_V(n) asm volatile("s_waitcnt vmcnt(" #n ")" ::: "memory")
; #define PG8_WAIT_L(n) asm volatile("s_waitcnt lgkmcnt(" #n ")" ::: "memory")
; #define PG8_BAR __builtin_amdgcn_s_barrier()
; #define PG8_SCHED __builtin_amdgcn_sched_barrier(0)
; template <class Epi, class Sched, bool ALIGN_EPI = false, bool SP2 = false>
; __device__ __forceinline__ void gemm_phase(LAS unsigned char* lds, const Gemm g, const Sched& S, const Epi& E) {
;     ...
;         for (int t = 0; t < nt; t += 2) {
;             const bool last = (t == nt - 2);
;             const char* a1 = cA + (size_t)(t + 1) * kstep;
;             const char* a2 = last ? nA : cA + (size_t)(t + 2) * kstep; const char* b2 = last ? nB : cB + (size_t)(t + 2) * kstep;
;     ...
;             PG8_LDA(At, 1, 1); PG8_STAGE(PG8_SB(1, 0), b3, voffB); PG8_STAGE(PG8_SB(1, 1), b3 + hstepB, voffB); PG8_STAGE(PG8_SA(1, 0), a3, voffA);
;             PG8_WAIT_V(8); PG8_WAIT_L(0); PG8_BAR; PG8_MMA(1, 0, At, B0); PG8_MMA(1, 1, At, B1); PG8_BAR; PG8_SCHED;
	s_add_i32 s22, s51, s25
	v_lshl_add_u64 v[166:167], v[166:167], 0, s[6:7]
	s_mov_b32 m0, s22
	ds_read_b128 v[192:195], v175 offset:49152
	ds_read_b128 v[196:199], v175 offset:50176
	ds_read_b128 v[200:203], v175 offset:51200
	ds_read_b128 v[204:207], v175 offset:52224
	ds_read_b128 v[208:211], v175 offset:53248
	ds_read_b128 v[212:215], v175 offset:54272
	ds_read_b128 v[216:219], v175 offset:55296
	ds_read_b128 v[220:223], v175 offset:56320
	global_load_lds_dwordx4 v[166:167], off
	s_add_i32 m0, s22, 0x2000
	s_add_u32 s20, s20, 0x80080
	v_lshl_add_u64 v[166:167], v[224:225], 0, s[6:7]
	s_addc_u32 s21, s21, 0
	s_add_i32 s22, s52, s25
	global_load_lds_dwordx4 v[166:167], off
	v_lshl_add_u64 v[166:167], s[20:21], 0, v[150:151]
	s_mov_b32 m0, s22
	s_nop 0
	global_load_lds_dwordx4 v[166:167], off
	v_lshl_add_u64 v[166:167], s[20:21], 0, v[146:147]
	s_add_i32 m0, s22, 0x2000
	s_nop 0
	global_load_lds_dwordx4 v[166:167], off
	v_lshl_add_u64 v[166:167], v[226:227], 0, s[6:7]
	s_mov_b32 m0, s39
	s_nop 0
	global_load_lds_dwordx4 v[166:167], off
	v_lshl_add_u64 v[166:167], v[228:229], 0, s[6:7]
	s_mov_b32 m0, s40
	s_nop 0
	global_load_lds_dwordx4 v[166:167], off
	s_waitcnt vmcnt(8)
	s_waitcnt lgkmcnt(0)
	s_barrier
	s_setprio 1
	s_waitcnt lgkmcnt(0)
	v_mfma_f32_16x16x32_bf16 v[62:65], v[66:69], v[192:195], v[62:65]
	v_mfma_f32_16x16x32_bf16 v[58:61], v[74:77], v[192:195], v[58:61]
	v_mfma_f32_16x16x32_bf16 v[46:49], v[66:69], v[200:203], v[46:49]
	v_mfma_f32_16x16x32_bf16 v[42:45], v[74:77], v[200:203], v[42:45]
	v_mfma_f32_16x16x32_bf16 v[30:33], v[66:69], v[208:211], v[30:33]
	v_mfma_f32_16x16x32_bf16 v[26:29], v[74:77], v[208:211], v[26:29]
	v_mfma_f32_16x16x32_bf16 v[14:17], v[66:69], v[216:219], v[14:17]
	v_mfma_f32_16x16x32_bf16 v[10:13], v[74:77], v[216:219], v[10:13]
	v_mfma_f32_16x16x32_bf16 v[62:65], v[70:73], v[196:199], v[62:65]
	v_mfma_f32_16x16x32_bf16 v[58:61], v[78:81], v[196:199], v[58:61]
	v_mfma_f32_16x16x32_bf16 v[46:49], v[70:73], v[204:207], v[46:49]
	v_mfma_f32_16x16x32_bf16 v[42:45], v[78:81], v[204:207], v[42:45]
	v_mfma_f32_16x16x32_bf16 v[30:33], v[70:73], v[212:215], v[30:33]
	v_mfma_f32_16x16x32_bf16 v[26:29], v[78:81], v[212:215], v[26:29]
	v_mfma_f32_16x16x32_bf16 v[14:17], v[70:73], v[220:223], v[14:17]
	v_mfma_f32_16x16x32_bf16 v[10:13], v[78:81], v[220:223], v[10:13]
	s_setprio 0
	s_setprio 1
	v_mfma_f32_16x16x32_bf16 v[54:57], v[162:165], v[192:195], v[54:57]
	v_mfma_f32_16x16x32_bf16 v[50:53], v[184:187], v[192:195], v[50:53]
	v_mfma_f32_16x16x32_bf16 v[38:41], v[162:165], v[200:203], v[38:41]
	v_mfma_f32_16x16x32_bf16 v[34:37], v[184:187], v[200:203], v[34:37]
	v_mfma_f32_16x16x32_bf16 v[22:25], v[162:165], v[208:211], v[22:25]
	v_mfma_f32_16x16x32_bf16 v[18:21], v[184:187], v[208:211], v[18:21]
	v_mfma_f32_16x16x32_bf16 v[6:9], v[162:165], v[216:219], v[6:9]
	v_mfma_f32_16x16x32_bf16 v[2:5], v[184:187], v[216:219], v[2:5]
	v_mfma_f32_16x16x32_bf16 v[54:57], v[180:183], v[196:199], v[54:57]
	v_mfma_f32_16x16x32_bf16 v[50:53], v[188:191], v[196:199], v[50:53]
	v_mfma_f32_16x16x32_bf16 v[38:41], v[180:183], v[204:207], v[38:41]
	v_mfma_f32_16x16x32_bf16 v[34:37], v[188:191], v[204:207], v[34:37]
	v_mfma_f32_16x16x32_bf16 v[22:25], v[180:183], v[212:215], v[22:25]
	v_mfma_f32_16x16x32_bf16 v[18:21], v[188:191], v[212:215], v[18:21]
	v_mfma_f32_16x16x32_bf16 v[6:9], v[180:183], v[220:223], v[6:9]
	v_mfma_f32_16x16x32_bf16 v[2:5], v[188:191], v[220:223], v[2:5]
	s_setprio 0
	s_barrier
	s_add_i32 s50, s50, 2
	s_add_u32 s48, s48, 0x100
	s_addc_u32 s49, s49, 0
	s_add_u32 s18, s18, 0x100
	s_addc_u32 s19, s19, 0
	s_cmp_lt_u32 s50, 30

; #define LAS __attribute__((address_space(3)))
; #define PG8_STAGE(bufoff, gbase, voff) do { _Pragma("unroll") for (int _i = 0; _i < 2; ++_i) \
;         __builtin_amdgcn_global_load_lds((const unsigned*)((const char*)(gbase) + (voff)[_i]), (LAS unsigned*)(lds + (bufoff) + ldsw + _i * 8192), 16, 0, 0); } while (0)
; #define PG8_WAIT_V(n) asm volatile("s_waitcnt vmcnt(" #n ")" ::: "memory")
; #define PG8_BAR __builtin_amdgcn_s_barrier()
;     __device__ __forceinline__ void operator()(const f32x4 (&acc)[2][2][4][2], const Unit& u, int wr, int wc, int fr, int fq) const {
;         const int s = u.pm >> 5, lane = fq * 16 + fr, rr = lane >> 3, pc = lane & 7;
;         const float* __restrict__ xi = xin + (size_t)u.pm * BM * DM; float* __restrict__ xo = xout + (size_t)u.pm * BM * DM; bf16_t* __restrict__ ho = Hn + (size_t)u.pm * BM * DM;
;         LAS unsigned char* st = lds_epi + (wr * 4 + wc) * 2304;
;         LAS float* sst = (LAS float*)(lds_epi + 18432 + (wr * 4 + wc) * 512);
;         const int colr = u.pn * BM + wc * 64 + 4 * pc;
;         const unsigned eb = (unsigned)((wr * 64 + rr) * DM + colr);
;         f32x4 gv[2], gsn[2];
; #pragma unroll
;         for (int bj = 0; bj < 2; ++bj) { gv[bj] = *(const f32x4*)(gate + (size_t)s * MODW + colr + bj * 32) * (0.5f * GS2);
;             if (!PLAIN) gsn[bj] = *(const f32x4*)(gnext + colr + bj * 32) * (*(const f32x4*)(scnext + (size_t)s * MODW + colr + bj * 32) + 1.0f); else gsn[bj] = gv[bj]; }
;         const unsigned wr_off = (unsigned)(fr * 144 + 16 * fq), rd_off = (unsigned)(rr * 144 + pc * 16);
;         const bool odd = (rr & 1) != 0;
; template <class Epi, class Sched, bool ALIGN_EPI = false, bool SP2 = false>
; __device__ __forceinline__ void gemm_phase(LAS unsigned char* lds, const Gemm g, const Sched& S, const Epi& E) {
;     ...
;     if constexpr (SP2) {
;         PG8_STAGE(PG8_SB(0, 0), cB, voffB); PG8_STAGE(PG8_SB(0, 1), cB + hstepB, voffB); PG8_STAGE(PG8_SA(0, 0), cA, voffA); PG8_STAGE(PG8_SA(0, 1), cA + hstep, voffA);
;         if (wr == 1) PG8_BAR;
;         PG8_WAIT_V(2); PG8_BAR;
;         PG8_STAGE(PG8_SB(1, 0), cB + kstep, voffB); PG8_STAGE(PG8_SA(1, 0), cA + kstep, voffA); PG8_STAGE(PG8_SB(1, 1), cB + hstepB + kstep, voffB);
;         PG8_WAIT_V(6); PG8_BAR;
.LBB0_2988:
	s_add_u32 s29, s48, 0xaa000
	s_mov_b64 s[6:7], 0x80
	s_addc_u32 s30, s49, 0
	s_and_b32 s1, s1, 3
	s_add_i32 m0, s24, 0x18000
	v_lshl_add_u64 v[8:9], v[8:9], 0, s[6:7]
	s_lshl_b32 s9, s3, 13
	s_lshl_b32 s11, s1, 12
	s_waitcnt vmcnt(2)
	s_barrier
	global_load_lds_dwordx4 v[8:9], off
	v_lshl_add_u64 v[4:5], v[4:5], 0, s[6:7]
	s_add_i32 m0, s24, 0x1a000
	s_add_i32 s31, s24, 0x8000
	s_add_i32 s33, s24, 0xa000
	global_load_lds_dwordx4 v[4:5], off
	v_lshl_add_u64 v[2:3], v[2:3], 0, s[6:7]
	s_mov_b32 m0, s31
	s_add_u32 s18, s16, 0x58080
	global_load_lds_dwordx4 v[2:3], off
	v_lshl_add_u64 v[2:3], v[6:7], 0, s[6:7]
	s_mov_b32 m0, s33
	s_addc_u32 s19, s17, 0
	global_load_lds_dwordx4 v[2:3], off
	s_add_i32 m0, s24, 0x1c000
	v_lshl_add_u64 v[2:3], s[18:19], 0, v[130:131]
	global_load_lds_dwordx4 v[2:3], off
	v_lshl_add_u64 v[2:3], s[18:19], 0, v[134:135]
	s_add_i32 m0, s24, 0x1e000
	v_and_b32_e32 v4, 48, v0
	global_load_lds_dwordx4 v[2:3], off
	v_and_b32_e32 v2, 15, v0
	v_lshlrev_b32_e32 v5, 2, v0
	v_lshl_or_b32 v3, v2, 6, v4
	v_and_b32_e32 v5, 32, v5
	s_cmpk_lt_u32 s2, 0x100
	s_sext_i32_i8 s38, s8
	v_bitop3_b32 v6, v3, s9, v5 bitop3:0xde
	v_bitop3_b32 v144, v3, s11, v5 bitop3:0xde
	s_cselect_b64 s[8:9], -1, 0
	v_and_b32_e32 v3, 7, v0
	s_lshl_b32 s2, s3, 2
	s_or_b32 s2, s2, s1
	v_lshlrev_b32_e32 v5, 2, v3
	s_mulk_i32 s2, 0x900
	v_lshl_or_b32 v145, s1, 6, v5
	v_bfe_u32 v0, v0, 3, 3
	s_lshl_b32 s1, s3, 19
	v_lshl_or_b32 v146, v0, 13, s1
	s_add_i32 s1, s2, 0
	s_add_i32 s1, s1, 0x20000
	v_lshlrev_b32_e32 v5, 4, v3
	s_movk_i32 s2, 0x90
	v_mov_b32_e32 v3, s1
	v_mad_u32_u24 v7, v2, s2, v3
	v_mad_u32_u24 v8, v0, s2, v3
	v_lshrrev_b32_e32 v2, 1, v13
	v_mul_lo_u32 v0, v14, s0
	v_mad_u64_u32 v[2:3], s[2:3], v2, s10, v[0:1]
	v_or_b32_e32 v0, v2, v15
	v_add_lshl_u32 v2, v0, v16, 1
	v_lshrrev_b32_e32 v1, 1, v1
	v_mul_lo_u32 v0, v10, s0
	v_mad_u64_u32 v[0:1], s[0:1], v1, s10, v[0:1]
	s_waitcnt vmcnt(0)
	v_or_b32_e32 v0, v0, v11
	v_mov_b32_e32 v3, v131
	s_mov_b64 s[2:3], 0x160080
	v_add_lshl_u32 v0, v0, v12, 1
	v_mov_b32_e32 v1, v131
	s_add_i32 s34, 0, 0x10000
	s_add_i32 s35, 0, 0x14000
	v_lshl_add_u64 v[136:137], v[2:3], 0, s[2:3]
	v_lshl_add_u64 v[138:139], v[0:1], 0, s[2:3]
	v_mov_b64_e32 v[140:141], 0x400
	v_mov_b64_e32 v[142:143], 0x3ff
	v_add_u32_e32 v147, s34, v144
	v_add_u32_e32 v148, s35, v144
	v_add_u32_e32 v149, 0, v6
	v_add_u32_e32 v150, v7, v4
	v_add_u32_e32 v151, v8, v5
	s_barrier
	s_branch .LBB0_2991

; #define PG8_STAGE(bufoff, gbase, voff) do { _Pragma("unroll") for (int _i = 0; _i < 2; ++_i) \
;         __builtin_amdgcn_global_load_lds((const unsigned*)((const char*)(gbase) + (voff)[_i]), (LAS unsigned*)(lds + (bufoff) + ldsw + _i * 8192), 16, 0, 0); } while (0)
; #define PG8_LDA(dst, b, h) do { _Pragma("unroll") for (int m = 0; m < 4; ++m) _Pragma("unroll") for (int k = 0; k < 2; ++k) dst[m][k] = *(const LAS bf16x8*)(lds + PG8_SA(b, h) + aoff + m * 2048 + k * 1024); } while (0)
; #define PG8_LDB(dst, b, h) do { _Pragma("unroll") for (int n = 0; n < 2; ++n) _Pragma("unroll") for (int k = 0; k < 2; ++k) dst[n][k] = *(const LAS bf16x8*)(lds + PG8_SB(b, h) + boff + n * 2048 + k * 1024); } while (0)
; #define PG8_MMA(ai, bj, At, Bt) do { __builtin_amdgcn_s_setprio(1); _Pragma("unroll") for (int m = 0; m < 4; ++m) _Pragma("unroll") for (int n = 0; n < 2; ++n) _Pragma("unroll") for (int k = 0; k < 2; ++k) \
;         acc[ai][bj][m][n] = __builtin_amdgcn_mfma_f32_16x16x32_bf16(Bt[n][k], At[m][k], acc[ai][bj][m][n], 0, 0, 0); __builtin_amdgcn_s_setprio(0); } while (0)
; #define PG8_WAIT_V(n) asm volatile("s_waitcnt vmcnt(" #n ")" ::: "memory")
; #define PG8_WAIT_L(n) asm volatile("s_waitcnt lgkmcnt(" #n ")" ::: "memory")
; template <class Epi, class Sched, bool ALIGN_EPI = false, bool SP2 = false>
; __device__ __forceinline__ void gemm_phase(LAS unsigned char* lds, const Gemm g, const Sched& S, const Epi& E) {
;     ...
;         for (int t = 0; t < nt; t += 2) {
;             const bool last = (t == nt - 2);
;             const char* a1 = cA + (size_t)(t + 1) * kstep;
;             const char* a2 = last ? nA : cA + (size_t)(t + 2) * kstep; const char* b2 = last ? nB : cB + (size_t)(t + 2) * kstep;
;             const char* a3 = a2 + kstep; const char* b3 = b2 + kstep;
;             if (last && has_next) S.a_ready(nxt);
;             if constexpr (SP2) {
;             PG8_LDB(B0, 0, 0); PG8_LDB(B1, 0, 1); PG8_SCHED; PG8_LDA(At, 0, 0); PG8_STAGE(PG8_SA(1, 1), a1 + hstep, voffA);
;             PG8_WAIT_V(8); PG8_WAIT_L(0); PG8_BAR; PG8_MMA(0, 0, At, B0); PG8_MMA(0, 1, At, B1); PG8_BAR; PG8_SCHED;
;             PG8_LDA(At, 0, 1); PG8_STAGE(PG8_SB(0, 0), b2, voffB); PG8_STAGE(PG8_SB(0, 1), b2 + hstepB, voffB); PG8_STAGE(PG8_SA(0, 0), a2, voffA);
;             PG8_WAIT_V(8); PG8_WAIT_L(0); PG8_BAR; PG8_MMA(1, 0, At, B0); PG8_MMA(1, 1, At, B1); PG8_BAR; PG8_SCHED;
.LBB0_3001:
	s_add_u32 s13, s16, 0x100
	s_addc_u32 s39, s17, 0
	s_mov_b32 s40, -2
	s_waitcnt vmcnt(0)
	ds_read_b128 v[152:155], v147
	ds_read_b128 v[156:159], v147 offset:1024
	ds_read_b128 v[160:163], v147 offset:2048
	ds_read_b128 v[164:167], v147 offset:3072
	ds_read_b128 v[168:171], v148
	ds_read_b128 v[172:175], v148 offset:1024
	ds_read_b128 v[176:179], v148 offset:2048
	ds_read_b128 v[180:183], v148 offset:3072
	s_add_u32 s16, s14, 0x100
	s_addc_u32 s17, s15, 0
	s_cmpk_eq_i32 s40, 0x54
	s_cselect_b32 s21, s11, s17
	s_cselect_b32 s20, s10, s16
	s_cselect_b32 s19, s3, s39
	s_cselect_b32 s18, s2, s13
	v_lshl_add_u64 v[216:217], s[14:15], 0, v[138:139]
	s_add_i32 m0, s24, 0xc000
	ds_read_b128 v[184:187], v149
	ds_read_b128 v[188:191], v149 offset:1024
	ds_read_b128 v[192:195], v149 offset:2048
	ds_read_b128 v[196:199], v149 offset:3072
	ds_read_b128 v[200:203], v149 offset:4096
	ds_read_b128 v[204:207], v149 offset:5120
	ds_read_b128 v[208:211], v149 offset:6144
	ds_read_b128 v[212:215], v149 offset:7168
	global_load_lds_dwordx4 v[216:217], off
	v_lshl_add_u64 v[216:217], s[14:15], 0, v[136:137]
	s_add_i32 m0, s24, 0xe000
	s_nop 0
	global_load_lds_dwordx4 v[216:217], off
	s_waitcnt lgkmcnt(0)
	s_barrier
	s_setprio 1
	s_waitcnt lgkmcnt(0)
	v_mfma_f32_16x16x32_bf16 v[124:127], v[152:155], v[184:187], 0
	v_mfma_f32_16x16x32_bf16 v[120:123], v[160:163], v[184:187], 0
	v_mfma_f32_16x16x32_bf16 v[112:115], v[152:155], v[192:195], 0
	v_mfma_f32_16x16x32_bf16 v[104:107], v[160:163], v[192:195], 0
	v_mfma_f32_16x16x32_bf16 v[92:95], v[152:155], v[200:203], 0
	v_mfma_f32_16x16x32_bf16 v[88:91], v[160:163], v[200:203], 0
	v_mfma_f32_16x16x32_bf16 v[76:79], v[152:155], v[208:211], 0
	v_mfma_f32_16x16x32_bf16 v[72:75], v[160:163], v[208:211], 0
	v_mfma_f32_16x16x32_bf16 v[124:127], v[156:159], v[188:191], v[124:127]
	v_mfma_f32_16x16x32_bf16 v[120:123], v[164:167], v[188:191], v[120:123]
	v_mfma_f32_16x16x32_bf16 v[112:115], v[156:159], v[196:199], v[112:115]
	v_mfma_f32_16x16x32_bf16 v[104:107], v[164:167], v[196:199], v[104:107]
	v_mfma_f32_16x16x32_bf16 v[92:95], v[156:159], v[204:207], v[92:95]
	v_mfma_f32_16x16x32_bf16 v[88:91], v[164:167], v[204:207], v[88:91]
	v_mfma_f32_16x16x32_bf16 v[76:79], v[156:159], v[212:215], v[76:79]
	v_mfma_f32_16x16x32_bf16 v[72:75], v[164:167], v[212:215], v[72:75]
	s_setprio 0
	s_setprio 1
	v_mfma_f32_16x16x32_bf16 v[116:119], v[168:171], v[184:187], 0
	v_mfma_f32_16x16x32_bf16 v[108:111], v[176:179], v[184:187], 0
	v_mfma_f32_16x16x32_bf16 v[100:103], v[168:171], v[192:195], 0
	v_mfma_f32_16x16x32_bf16 v[96:99], v[176:179], v[192:195], 0
	v_mfma_f32_16x16x32_bf16 v[84:87], v[168:171], v[200:203], 0
	v_mfma_f32_16x16x32_bf16 v[80:83], v[176:179], v[200:203], 0
	v_mfma_f32_16x16x32_bf16 v[68:71], v[168:171], v[208:211], 0
	v_mfma_f32_16x16x32_bf16 v[64:67], v[176:179], v[208:211], 0
	v_mfma_f32_16x16x32_bf16 v[116:119], v[172:175], v[188:191], v[116:119]
	v_mfma_f32_16x16x32_bf16 v[108:111], v[180:183], v[188:191], v[108:111]
	v_mfma_f32_16x16x32_bf16 v[100:103], v[172:175], v[196:199], v[100:103]
	v_mfma_f32_16x16x32_bf16 v[96:99], v[180:183], v[196:199], v[96:99]
	v_mfma_f32_16x16x32_bf16 v[84:87], v[172:175], v[204:207], v[84:87]
	v_mfma_f32_16x16x32_bf16 v[80:83], v[180:183], v[204:207], v[80:83]
	v_mfma_f32_16x16x32_bf16 v[68:71], v[172:175], v[212:215], v[68:71]
	v_mfma_f32_16x16x32_bf16 v[64:67], v[180:183], v[212:215], v[64:67]
	s_setprio 0
	s_barrier
	s_add_i32 s14, s34, s23
	v_lshl_add_u64 v[216:217], s[18:19], 0, v[130:131]
	s_mov_b32 m0, s14
	ds_read_b128 v[184:187], v149 offset:16384
	ds_read_b128 v[188:191], v149 offset:17408
	ds_read_b128 v[192:195], v149 offset:18432
	ds_read_b128 v[196:199], v149 offset:19456
	ds_read_b128 v[200:203], v149 offset:20480
	ds_read_b128 v[204:207], v149 offset:21504
	ds_read_b128 v[208:211], v149 offset:22528
	ds_read_b128 v[212:215], v149 offset:23552
	global_load_lds_dwordx4 v[216:217], off
	s_add_i32 m0, s14, 0x2000
	s_add_u32 s14, s18, 0x58000
	v_lshl_add_u64 v[218:219], s[18:19], 0, v[134:135]
	s_addc_u32 s15, s19, 0
	s_add_i32 s41, s35, s23
	global_load_lds_dwordx4 v[218:219], off
	v_lshl_add_u64 v[220:221], s[14:15], 0, v[130:131]
	s_mov_b32 m0, s41
	v_lshl_add_u64 v[222:223], s[20:21], 0, v[132:133]
	global_load_lds_dwordx4 v[220:221], off
	v_lshl_add_u64 v[220:221], s[14:15], 0, v[134:135]
	s_add_i32 m0, s41, 0x2000
	s_nop 0
	global_load_lds_dwordx4 v[220:221], off
	v_lshl_add_u64 v[220:221], s[20:21], 0, v[128:129]
	s_mov_b32 m0, s24
	s_nop 0
	global_load_lds_dwordx4 v[220:221], off
	s_mov_b32 m0, s25
	s_nop 0
	global_load_lds_dwordx4 v[222:223], off
	s_waitcnt lgkmcnt(0)
	s_barrier
; #define PG8_STAGE(bufoff, gbase, voff) do { _Pragma("unroll") for (int _i = 0; _i < 2; ++_i) \
;         __builtin_amdgcn_global_load_lds((const unsigned*)((const char*)(gbase) + (voff)[_i]), (LAS unsigned*)(lds + (bufoff) + ldsw + _i * 8192), 16, 0, 0); } while (0)
; #define PG8_LDA(dst, b, h) do { _Pragma("unroll") for (int m = 0; m < 4; ++m) _Pragma("unroll") for (int k = 0; k < 2; ++k) dst[m][k] = *(const LAS bf16x8*)(lds + PG8_SA(b, h) + aoff + m * 2048 + k * 1024); } while (0)
; #define PG8_LDB(dst, b, h) do { _Pragma("unroll") for (int n = 0; n < 2; ++n) _Pragma("unroll") for (int k = 0; k < 2; ++k) dst[n][k] = *(const LAS bf16x8*)(lds + PG8_SB(b, h) + boff + n * 2048 + k * 1024); } while (0)
; #define PG8_MMA(ai, bj, At, Bt) do { __builtin_amdgcn_s_setprio(1); _Pragma("unroll") for (int m = 0; m < 4; ++m) _Pragma("unroll") for (int n = 0; n < 2; ++n) _Pragma("unroll") for (int k = 0; k < 2; ++k) \
;         acc[ai][bj][m][n] = __builtin_amdgcn_mfma_f32_16x16x32_bf16(Bt[n][k], At[m][k], acc[ai][bj][m][n], 0, 0, 0); __builtin_amdgcn_s_setprio(0); } while (0)
; #define PG8_WAIT_V(n) asm volatile("s_waitcnt vmcnt(" #n ")" ::: "memory")
; #define PG8_WAIT_L(n) asm volatile("s_waitcnt lgkmcnt(" #n ")" ::: "memory")
; #define PG8_BAR __builtin_amdgcn_s_barrier()
; #define PG8_SCHED __builtin_amdgcn_sched_barrier(0)
; template <class Epi, class Sched, bool ALIGN_EPI = false, bool SP2 = false>
; __device__ __forceinline__ void gemm_phase(LAS unsigned char* lds, const Gemm g, const Sched& S, const Epi& E) {
;     ...
;             PG8_WAIT_V(8); PG8_WAIT_L(0); PG8_BAR; PG8_MMA(1, 0, At, B0); PG8_MMA(1, 1, At, B1); PG8_BAR; PG8_SCHED;
;             PG8_LDB(B0, 1, 0); PG8_LDB(B1, 1, 1); PG8_SCHED; PG8_LDA(At, 1, 0); PG8_STAGE(PG8_SA(0, 1), a2 + hstep, voffA);
;             PG8_WAIT_V(8); PG8_WAIT_L(0); PG8_BAR; PG8_MMA(0, 0, At, B0); PG8_MMA(0, 1, At, B1); PG8_BAR; PG8_SCHED;
;             PG8_LDA(At, 1, 1); PG8_STAGE(PG8_SB(1, 0), b3, voffB); PG8_STAGE(PG8_SB(1, 1), b3 + hstepB, voffB); PG8_STAGE(PG8_SA(1, 0), a3, voffA);
	s_setprio 1
	s_waitcnt lgkmcnt(0)
	v_mfma_f32_16x16x32_bf16 v[60:63], v[152:155], v[184:187], 0
	v_mfma_f32_16x16x32_bf16 v[56:59], v[160:163], v[184:187], 0
	v_mfma_f32_16x16x32_bf16 v[44:47], v[152:155], v[192:195], 0
	v_mfma_f32_16x16x32_bf16 v[40:43], v[160:163], v[192:195], 0
	v_mfma_f32_16x16x32_bf16 v[28:31], v[152:155], v[200:203], 0
	v_mfma_f32_16x16x32_bf16 v[24:27], v[160:163], v[200:203], 0
	v_mfma_f32_16x16x32_bf16 v[12:15], v[152:155], v[208:211], 0
	v_mfma_f32_16x16x32_bf16 v[8:11], v[160:163], v[208:211], 0
	v_mfma_f32_16x16x32_bf16 v[60:63], v[156:159], v[188:191], v[60:63]
	v_mfma_f32_16x16x32_bf16 v[56:59], v[164:167], v[188:191], v[56:59]
	v_mfma_f32_16x16x32_bf16 v[44:47], v[156:159], v[196:199], v[44:47]
	v_mfma_f32_16x16x32_bf16 v[40:43], v[164:167], v[196:199], v[40:43]
	v_mfma_f32_16x16x32_bf16 v[28:31], v[156:159], v[204:207], v[28:31]
	v_mfma_f32_16x16x32_bf16 v[24:27], v[164:167], v[204:207], v[24:27]
	v_mfma_f32_16x16x32_bf16 v[12:15], v[156:159], v[212:215], v[12:15]
	v_mfma_f32_16x16x32_bf16 v[8:11], v[164:167], v[212:215], v[8:11]
	s_setprio 0
	s_setprio 1
	v_mfma_f32_16x16x32_bf16 v[52:55], v[168:171], v[184:187], 0
	v_mfma_f32_16x16x32_bf16 v[48:51], v[176:179], v[184:187], 0
	v_mfma_f32_16x16x32_bf16 v[36:39], v[168:171], v[192:195], 0
	v_mfma_f32_16x16x32_bf16 v[32:35], v[176:179], v[192:195], 0
	v_mfma_f32_16x16x32_bf16 v[20:23], v[168:171], v[200:203], 0
	v_mfma_f32_16x16x32_bf16 v[16:19], v[176:179], v[200:203], 0
	v_mfma_f32_16x16x32_bf16 v[4:7], v[168:171], v[208:211], 0
	v_mfma_f32_16x16x32_bf16 v[0:3], v[176:179], v[208:211], 0
	v_mfma_f32_16x16x32_bf16 v[52:55], v[172:175], v[188:191], v[52:55]
	v_mfma_f32_16x16x32_bf16 v[48:51], v[180:183], v[188:191], v[48:51]
	v_mfma_f32_16x16x32_bf16 v[36:39], v[172:175], v[196:199], v[36:39]
	v_mfma_f32_16x16x32_bf16 v[32:35], v[180:183], v[196:199], v[32:35]
	v_mfma_f32_16x16x32_bf16 v[20:23], v[172:175], v[204:207], v[20:23]
	v_mfma_f32_16x16x32_bf16 v[16:19], v[180:183], v[204:207], v[16:19]
	v_mfma_f32_16x16x32_bf16 v[4:7], v[172:175], v[212:215], v[4:7]
	v_mfma_f32_16x16x32_bf16 v[0:3], v[180:183], v[212:215], v[0:3]
	s_setprio 0
	s_barrier
	s_add_i32 s41, 0, 0x18000
	s_add_i32 s42, 0, 0x1c000
	v_add_u32_e32 v164, s41, v144
	v_add_u32_e32 v180, s42, v144
	ds_read_b128 v[152:155], v164
	ds_read_b128 v[156:159], v164 offset:1024
	ds_read_b128 v[160:163], v164 offset:2048
	ds_read_b128 v[164:167], v164 offset:3072
	ds_read_b128 v[168:171], v180
	ds_read_b128 v[172:175], v180 offset:1024
	ds_read_b128 v[176:179], v180 offset:2048
	ds_read_b128 v[180:183], v180 offset:3072
	s_add_u32 s14, s20, 0x160000
	s_addc_u32 s15, s21, 0
	s_mov_b32 m0, s26
	v_lshl_add_u64 v[224:225], s[14:15], 0, v[128:129]
	ds_read_b128 v[184:187], v149 offset:32768
	ds_read_b128 v[188:191], v149 offset:33792
	ds_read_b128 v[192:195], v149 offset:34816
	ds_read_b128 v[196:199], v149 offset:35840
	ds_read_b128 v[200:203], v149 offset:36864
	ds_read_b128 v[204:207], v149 offset:37888
	ds_read_b128 v[208:211], v149 offset:38912
	ds_read_b128 v[212:215], v149 offset:39936
	global_load_lds_dwordx4 v[224:225], off
	v_lshl_add_u64 v[224:225], s[14:15], 0, v[132:133]
	s_mov_b32 m0, s27
	s_nop 0
	global_load_lds_dwordx4 v[224:225], off
	s_waitcnt vmcnt(8)
	s_waitcnt lgkmcnt(0)
	s_barrier
	s_setprio 1
	s_waitcnt lgkmcnt(0)
	v_mfma_f32_16x16x32_bf16 v[124:127], v[152:155], v[184:187], v[124:127]
	v_mfma_f32_16x16x32_bf16 v[120:123], v[160:163], v[184:187], v[120:123]
	v_mfma_f32_16x16x32_bf16 v[112:115], v[152:155], v[192:195], v[112:115]
	v_mfma_f32_16x16x32_bf16 v[104:107], v[160:163], v[192:195], v[104:107]
	v_mfma_f32_16x16x32_bf16 v[92:95], v[152:155], v[200:203], v[92:95]
	v_mfma_f32_16x16x32_bf16 v[88:91], v[160:163], v[200:203], v[88:91]
	v_mfma_f32_16x16x32_bf16 v[76:79], v[152:155], v[208:211], v[76:79]
	v_mfma_f32_16x16x32_bf16 v[72:75], v[160:163], v[208:211], v[72:75]
	v_mfma_f32_16x16x32_bf16 v[124:127], v[156:159], v[188:191], v[124:127]
	v_mfma_f32_16x16x32_bf16 v[120:123], v[164:167], v[188:191], v[120:123]
	v_mfma_f32_16x16x32_bf16 v[112:115], v[156:159], v[196:199], v[112:115]
	v_mfma_f32_16x16x32_bf16 v[104:107], v[164:167], v[196:199], v[104:107]
	v_mfma_f32_16x16x32_bf16 v[92:95], v[156:159], v[204:207], v[92:95]
	v_mfma_f32_16x16x32_bf16 v[88:91], v[164:167], v[204:207], v[88:91]
	v_mfma_f32_16x16x32_bf16 v[76:79], v[156:159], v[212:215], v[76:79]
	v_mfma_f32_16x16x32_bf16 v[72:75], v[164:167], v[212:215], v[72:75]
	s_setprio 0
	s_setprio 1
	v_mfma_f32_16x16x32_bf16 v[116:119], v[168:171], v[184:187], v[116:119]
	v_mfma_f32_16x16x32_bf16 v[108:111], v[176:179], v[184:187], v[108:111]
	v_mfma_f32_16x16x32_bf16 v[100:103], v[168:171], v[192:195], v[100:103]
	v_mfma_f32_16x16x32_bf16 v[96:99], v[176:179], v[192:195], v[96:99]
	v_mfma_f32_16x16x32_bf16 v[84:87], v[168:171], v[200:203], v[84:87]
	v_mfma_f32_16x16x32_bf16 v[80:83], v[176:179], v[200:203], v[80:83]
	v_mfma_f32_16x16x32_bf16 v[68:71], v[168:171], v[208:211], v[68:71]
	v_mfma_f32_16x16x32_bf16 v[64:67], v[176:179], v[208:211], v[64:67]
	v_mfma_f32_16x16x32_bf16 v[116:119], v[172:175], v[188:191], v[116:119]
	v_mfma_f32_16x16x32_bf16 v[108:111], v[180:183], v[188:191], v[108:111]
	v_mfma_f32_16x16x32_bf16 v[100:103], v[172:175], v[196:199], v[100:103]
	v_mfma_f32_16x16x32_bf16 v[96:99], v[180:183], v[196:199], v[96:99]
	v_mfma_f32_16x16x32_bf16 v[84:87], v[172:175], v[204:207], v[84:87]
	v_mfma_f32_16x16x32_bf16 v[80:83], v[180:183], v[204:207], v[80:83]
	v_mfma_f32_16x16x32_bf16 v[68:71], v[172:175], v[212:215], v[68:71]
	v_mfma_f32_16x16x32_bf16 v[64:67], v[180:183], v[212:215], v[64:67]
	s_setprio 0
	s_barrier
; #define PG8_STAGE(bufoff, gbase, voff) do { _Pragma("unroll") for (int _i = 0; _i < 2; ++_i) \
;         __builtin_amdgcn_global_load_lds((const unsigned*)((const char*)(gbase) + (voff)[_i]), (LAS unsigned*)(lds + (bufoff) + ldsw + _i * 8192), 16, 0, 0); } while (0)
; #define PG8_LDA(dst, b, h) do { _Pragma("unroll") for (int m = 0; m < 4; ++m) _Pragma("unroll") for (int k = 0; k < 2; ++k) dst[m][k] = *(const LAS bf16x8*)(lds + PG8_SA(b, h) + aoff + m * 2048 + k * 1024); } while (0)
; #define PG8_MMA(ai, bj, At, Bt) do { __builtin_amdgcn_s_setprio(1); _Pragma("unroll") for (int m = 0; m < 4; ++m) _Pragma("unroll") for (int n = 0; n < 2; ++n) _Pragma("unroll") for (int k = 0; k < 2; ++k) \
;         acc[ai][bj][m][n] = __builtin_amdgcn_mfma_f32_16x16x32_bf16(Bt[n][k], At[m][k], acc[ai][bj][m][n], 0, 0, 0); __builtin_amdgcn_s_setprio(0); } while (0)
; #define PG8_WAIT_V(n) asm volatile("s_waitcnt vmcnt(" #n ")" ::: "memory")
; #define PG8_WAIT_L(n) asm volatile("s_waitcnt lgkmcnt(" #n ")" ::: "memory")
; #define PG8_BAR __builtin_amdgcn_s_barrier()
; #define PG8_SCHED __builtin_amdgcn_sched_barrier(0)
; template <class Epi, class Sched, bool ALIGN_EPI = false, bool SP2 = false>
; __device__ __forceinline__ void gemm_phase(LAS unsigned char* lds, const Gemm g, const Sched& S, const Epi& E) {
;     ...
;         for (int t = 0; t < nt; t += 2) {
;     ...
;             PG8_LDA(At, 1, 1); PG8_STAGE(PG8_SB(1, 0), b3, voffB); PG8_STAGE(PG8_SB(1, 1), b3 + hstepB, voffB); PG8_STAGE(PG8_SA(1, 0), a3, voffA);
;             PG8_WAIT_V(8); PG8_WAIT_L(0); PG8_BAR; PG8_MMA(1, 0, At, B0); PG8_MMA(1, 1, At, B1); PG8_BAR; PG8_SCHED;
	s_add_i32 s14, s41, s23
	v_lshl_add_u64 v[216:217], v[216:217], 0, s[6:7]
	s_mov_b32 m0, s14
	ds_read_b128 v[184:187], v149 offset:49152
	ds_read_b128 v[188:191], v149 offset:50176
	ds_read_b128 v[192:195], v149 offset:51200
	ds_read_b128 v[196:199], v149 offset:52224
	ds_read_b128 v[200:203], v149 offset:53248
	ds_read_b128 v[204:207], v149 offset:54272
	ds_read_b128 v[208:211], v149 offset:55296
	ds_read_b128 v[212:215], v149 offset:56320
	global_load_lds_dwordx4 v[216:217], off
	s_add_i32 m0, s14, 0x2000
	s_add_u32 s14, s18, 0x58080
	v_lshl_add_u64 v[216:217], v[218:219], 0, s[6:7]
	s_addc_u32 s15, s19, 0
	s_add_i32 s18, s42, s23
	global_load_lds_dwordx4 v[216:217], off
	v_lshl_add_u64 v[216:217], s[14:15], 0, v[130:131]
	s_mov_b32 m0, s18
	s_nop 0
	global_load_lds_dwordx4 v[216:217], off
	v_lshl_add_u64 v[216:217], s[14:15], 0, v[134:135]
	s_add_i32 m0, s18, 0x2000
	s_nop 0
	global_load_lds_dwordx4 v[216:217], off
	v_lshl_add_u64 v[216:217], v[220:221], 0, s[6:7]
	s_mov_b32 m0, s31
	s_nop 0
	global_load_lds_dwordx4 v[216:217], off
	v_lshl_add_u64 v[216:217], v[222:223], 0, s[6:7]
	s_mov_b32 m0, s33
	s_nop 0
	global_load_lds_dwordx4 v[216:217], off
	s_waitcnt vmcnt(8)
	s_waitcnt lgkmcnt(0)
	s_barrier
	s_setprio 1
	s_waitcnt lgkmcnt(0)
	v_mfma_f32_16x16x32_bf16 v[60:63], v[152:155], v[184:187], v[60:63]
	v_mfma_f32_16x16x32_bf16 v[56:59], v[160:163], v[184:187], v[56:59]
	v_mfma_f32_16x16x32_bf16 v[44:47], v[152:155], v[192:195], v[44:47]
	v_mfma_f32_16x16x32_bf16 v[40:43], v[160:163], v[192:195], v[40:43]
	v_mfma_f32_16x16x32_bf16 v[28:31], v[152:155], v[200:203], v[28:31]
	v_mfma_f32_16x16x32_bf16 v[24:27], v[160:163], v[200:203], v[24:27]
	v_mfma_f32_16x16x32_bf16 v[12:15], v[152:155], v[208:211], v[12:15]
	v_mfma_f32_16x16x32_bf16 v[8:11], v[160:163], v[208:211], v[8:11]
	v_mfma_f32_16x16x32_bf16 v[60:63], v[156:159], v[188:191], v[60:63]
	v_mfma_f32_16x16x32_bf16 v[56:59], v[164:167], v[188:191], v[56:59]
	v_mfma_f32_16x16x32_bf16 v[44:47], v[156:159], v[196:199], v[44:47]
	v_mfma_f32_16x16x32_bf16 v[40:43], v[164:167], v[196:199], v[40:43]
	v_mfma_f32_16x16x32_bf16 v[28:31], v[156:159], v[204:207], v[28:31]
	v_mfma_f32_16x16x32_bf16 v[24:27], v[164:167], v[204:207], v[24:27]
	v_mfma_f32_16x16x32_bf16 v[12:15], v[156:159], v[212:215], v[12:15]
	v_mfma_f32_16x16x32_bf16 v[8:11], v[164:167], v[212:215], v[8:11]
	s_setprio 0
	s_setprio 1
	v_mfma_f32_16x16x32_bf16 v[52:55], v[168:171], v[184:187], v[52:55]
	v_mfma_f32_16x16x32_bf16 v[48:51], v[176:179], v[184:187], v[48:51]
	v_mfma_f32_16x16x32_bf16 v[36:39], v[168:171], v[192:195], v[36:39]
	v_mfma_f32_16x16x32_bf16 v[32:35], v[176:179], v[192:195], v[32:35]
	v_mfma_f32_16x16x32_bf16 v[20:23], v[168:171], v[200:203], v[20:23]
	v_mfma_f32_16x16x32_bf16 v[16:19], v[176:179], v[200:203], v[16:19]
	v_mfma_f32_16x16x32_bf16 v[4:7], v[168:171], v[208:211], v[4:7]
	v_mfma_f32_16x16x32_bf16 v[0:3], v[176:179], v[208:211], v[0:3]
	v_mfma_f32_16x16x32_bf16 v[52:55], v[172:175], v[188:191], v[52:55]
	v_mfma_f32_16x16x32_bf16 v[48:51], v[180:183], v[188:191], v[48:51]
	v_mfma_f32_16x16x32_bf16 v[36:39], v[172:175], v[196:199], v[36:39]
	v_mfma_f32_16x16x32_bf16 v[32:35], v[180:183], v[196:199], v[32:35]
	v_mfma_f32_16x16x32_bf16 v[20:23], v[172:175], v[204:207], v[20:23]
	v_mfma_f32_16x16x32_bf16 v[16:19], v[180:183], v[204:207], v[16:19]
	v_mfma_f32_16x16x32_bf16 v[4:7], v[172:175], v[212:215], v[4:7]
	v_mfma_f32_16x16x32_bf16 v[0:3], v[180:183], v[212:215], v[0:3]
	s_setprio 0
	s_barrier
	s_add_i32 s40, s40, 2
	s_add_u32 s13, s13, 0x100
	s_addc_u32 s39, s39, 0
	s_cmpk_lt_u32 s40, 0x56
	s_mov_b64 s[14:15], s[16:17]
